# code placement: every MFMA run of the GEMM K loops starts 8-byte aligned (s_nop 0 before the segment barrier where needed)
# speedup vs baseline: 1.0052x; 1.0021x over previous
; #define PG8_STAGE(bufoff, gbase, voff) do { _Pragma("unroll") for (int _i = 0; _i < 2; ++_i) \
;         __builtin_amdgcn_global_load_lds((const unsigned*)((const char*)(gbase) + (voff)[_i]), (LAS unsigned*)(lds + (bufoff) + ldsw + _i * 8192), 16, 0, 0); } while (0)
; #define PG8_LDA(dst, b, h) do { _Pragma("unroll") for (int m = 0; m < 4; ++m) _Pragma("unroll") for (int k = 0; k < 2; ++k) dst[m][k] = *(const LAS bf16x8*)(lds + PG8_SA(b, h) + aoff + m * 2048 + k * 1024); } while (0)
; #define PG8_LDB(dst, b, h) do { _Pragma("unroll") for (int n = 0; n < 2; ++n) _Pragma("unroll") for (int k = 0; k < 2; ++k) dst[n][k] = *(const LAS bf16x8*)(lds + PG8_SB(b, h) + boff + n * 2048 + k * 1024); } while (0)
; #define PG8_MMA(ai, bj, At, Bt) do { __builtin_amdgcn_s_setprio(1); _Pragma("unroll") for (int m = 0; m < 4; ++m) _Pragma("unroll") for (int n = 0; n < 2; ++n) _Pragma("unroll") for (int k = 0; k < 2; ++k) \
;         acc[ai][bj][m][n] = __builtin_amdgcn_mfma_f32_16x16x32_bf16(Bt[n][k], At[m][k], acc[ai][bj][m][n], 0, 0, 0); __builtin_amdgcn_s_setprio(0); } while (0)
; #define PG8_BAR __builtin_amdgcn_s_barrier()
; template <class Epi>
; __device__ __forceinline__ void gemm_phase(LAS unsigned char* lds, const Gemm g, const StaticOrder& S, const Epi& E) {
;     ...
;         const bool has_next = S.next(ui + 1, nxt);
;         const char* nA = has_next ? (const char*)g.A + (size_t)nxt.pm * tstepA : cA; const char* nB = has_next ? (const char*)g.Bt + (size_t)nxt.pn * tstepB : cB;
; #pragma nounroll
;         for (int t = 0; t < nt; t += 2) {
;             const bool last = (t == nt - 2);
;             const char* a1 = cA + (size_t)(t + 1) * kstep;
;             const char* a2 = last ? nA : cA + (size_t)(t + 2) * kstep; const char* b2 = last ? nB : cB + (size_t)(t + 2) * kstep;
;             const char* a3 = a2 + kstep; const char* b3 = b2 + kstep;
;             PG8_LDB(B0, 0, 0); PG8_LDB(B1, 0, 1); PG8_SCHED; PG8_LDA(At, 0, 0); PG8_STAGE(PG8_SA(1, 1), a1 + hstepA, voffA);
;             PG8_WAIT_V(8); PG8_WAIT_L(0); PG8_BAR; PG8_MMA(0, 0, At, B0); PG8_MMA(0, 1, At, B1); PG8_BAR; PG8_SCHED;
;             PG8_LDA(At, 0, 1); PG8_STAGE(PG8_SB(0, 0), b2, voffB); PG8_STAGE(PG8_SB(0, 1), b2 + hstepB, voffB); PG8_STAGE(PG8_SA(0, 0), a2, voffA);
;             PG8_WAIT_V(8); PG8_WAIT_L(0); PG8_BAR; PG8_MMA(1, 0, At, B0); PG8_MMA(1, 1, At, B1); PG8_BAR; PG8_SCHED;
.LBB0_191:
	s_ashr_i32 s65, s64, 31
	s_lshl_b64 s[68:69], s[64:65], 19
	s_add_u32 s68, s24, s68
	s_addc_u32 s69, s25, s69
	s_and_b64 s[70:71], s[4:5], exec
	s_cselect_b32 s7, s69, s75
	s_cselect_b32 s65, s68, s74
	s_ashr_i32 s63, s62, 31
	s_lshl_b64 s[70:71], s[62:63], 19
	s_add_u32 s70, s10, s70
	s_addc_u32 s71, s11, s71
	s_and_b64 s[78:79], s[4:5], exec
	s_cselect_b32 s63, s71, s77
	s_cselect_b32 s73, s70, s76
	s_add_u32 s74, s74, 0x40080
	s_addc_u32 s75, s75, 0
	s_add_u32 s87, s76, 0x100
	s_addc_u32 s88, s77, 0
	s_mov_b32 s89, -2
	v_lshl_add_u32 v248, s72, 8, v150
	v_add_u32_e32 v248, s41, v248
	v_ashrrev_i32_e32 v249, 31, v248
	v_lshl_add_u64 v[248:249], v[248:249], 2, s[50:51]
	global_load_dword v240, v[248:249], off
	global_load_dword v241, v[248:249], off offset:64
	global_load_dword v242, v[248:249], off offset:128
	global_load_dword v243, v[248:249], off offset:192
	global_load_dword v244, v[248:249], off offset:512
	global_load_dword v245, v[248:249], off offset:576
	global_load_dword v246, v[248:249], off offset:640
	global_load_dword v247, v[248:249], off offset:704
	ds_read_b128 v[144:147], v153
	ds_read_b128 v[158:161], v153 offset:1024
	ds_read_b128 v[162:165], v153 offset:2048
	ds_read_b128 v[166:169], v153 offset:3072
	ds_read_b128 v[170:173], v154
	ds_read_b128 v[178:181], v154 offset:1024
	ds_read_b128 v[182:185], v154 offset:2048
	ds_read_b128 v[186:189], v154 offset:3072
	s_add_u32 s76, s74, 0xfffc0080
	s_addc_u32 s77, s75, -1
	s_cmp_eq_u32 s89, 12
	s_cselect_b32 s79, s7, s77
	s_cselect_b32 s78, s65, s76
	s_cselect_b32 s77, s63, s88
	s_cselect_b32 s76, s73, s87
	v_lshl_add_u64 v[148:149], s[74:75], 0, v[136:137]
	s_add_i32 m0, s19, 0xc000
	ds_read_b128 v[190:193], v155
	ds_read_b128 v[194:197], v155 offset:1024
	ds_read_b128 v[198:201], v155 offset:2048
	ds_read_b128 v[202:205], v155 offset:3072
	ds_read_b128 v[206:209], v155 offset:4096
	ds_read_b128 v[210:213], v155 offset:5120
	ds_read_b128 v[214:217], v155 offset:6144
	ds_read_b128 v[218:221], v155 offset:7168
	global_load_lds_dwordx4 v[148:149], off
	v_lshl_add_u64 v[148:149], s[74:75], 0, v[138:139]
	s_add_i32 m0, s19, 0xe000
	s_nop 0
	global_load_lds_dwordx4 v[148:149], off
	s_waitcnt vmcnt(8)
	s_waitcnt lgkmcnt(0)
	s_nop 0
	s_barrier
	s_setprio 1
	s_waitcnt lgkmcnt(0)
	v_mfma_f32_16x16x32_bf16 v[124:127], v[144:147], v[190:193], 0
	v_mfma_f32_16x16x32_bf16 v[120:123], v[162:165], v[190:193], 0
	v_mfma_f32_16x16x32_bf16 v[108:111], v[144:147], v[198:201], 0
	v_mfma_f32_16x16x32_bf16 v[104:107], v[162:165], v[198:201], 0
	v_mfma_f32_16x16x32_bf16 v[92:95], v[144:147], v[206:209], 0
	v_mfma_f32_16x16x32_bf16 v[88:91], v[162:165], v[206:209], 0
	v_mfma_f32_16x16x32_bf16 v[76:79], v[144:147], v[214:217], 0
	v_mfma_f32_16x16x32_bf16 v[72:75], v[162:165], v[214:217], 0
	v_mfma_f32_16x16x32_bf16 v[124:127], v[158:161], v[194:197], v[124:127]
	v_mfma_f32_16x16x32_bf16 v[120:123], v[166:169], v[194:197], v[120:123]
	v_mfma_f32_16x16x32_bf16 v[108:111], v[158:161], v[202:205], v[108:111]
	v_mfma_f32_16x16x32_bf16 v[104:107], v[166:169], v[202:205], v[104:107]
	v_mfma_f32_16x16x32_bf16 v[92:95], v[158:161], v[210:213], v[92:95]
	v_mfma_f32_16x16x32_bf16 v[88:91], v[166:169], v[210:213], v[88:91]
	v_mfma_f32_16x16x32_bf16 v[76:79], v[158:161], v[218:221], v[76:79]
	v_mfma_f32_16x16x32_bf16 v[72:75], v[166:169], v[218:221], v[72:75]
	s_setprio 0
	s_setprio 1
	v_mfma_f32_16x16x32_bf16 v[116:119], v[170:173], v[190:193], 0
	v_mfma_f32_16x16x32_bf16 v[112:115], v[182:185], v[190:193], 0
	v_mfma_f32_16x16x32_bf16 v[100:103], v[170:173], v[198:201], 0
	v_mfma_f32_16x16x32_bf16 v[96:99], v[182:185], v[198:201], 0
	v_mfma_f32_16x16x32_bf16 v[84:87], v[170:173], v[206:209], 0
	v_mfma_f32_16x16x32_bf16 v[80:83], v[182:185], v[206:209], 0
	v_mfma_f32_16x16x32_bf16 v[68:71], v[170:173], v[214:217], 0
	v_mfma_f32_16x16x32_bf16 v[64:67], v[182:185], v[214:217], 0
	v_mfma_f32_16x16x32_bf16 v[116:119], v[178:181], v[194:197], v[116:119]
	v_mfma_f32_16x16x32_bf16 v[112:115], v[186:189], v[194:197], v[112:115]
	v_mfma_f32_16x16x32_bf16 v[100:103], v[178:181], v[202:205], v[100:103]
	v_mfma_f32_16x16x32_bf16 v[96:99], v[186:189], v[202:205], v[96:99]
	v_mfma_f32_16x16x32_bf16 v[84:87], v[178:181], v[210:213], v[84:87]
	v_mfma_f32_16x16x32_bf16 v[80:83], v[186:189], v[210:213], v[80:83]
	v_mfma_f32_16x16x32_bf16 v[68:71], v[178:181], v[218:221], v[68:71]
	v_mfma_f32_16x16x32_bf16 v[64:67], v[186:189], v[218:221], v[64:67]
	s_setprio 0
	s_barrier
	s_add_i32 s90, s84, s3
	v_lshl_add_u64 v[148:149], s[76:77], 0, v[130:131]
	s_mov_b32 m0, s90
	ds_read_b128 v[190:193], v155 offset:16384
	ds_read_b128 v[194:197], v155 offset:17408
	ds_read_b128 v[198:201], v155 offset:18432
	ds_read_b128 v[202:205], v155 offset:19456
	ds_read_b128 v[206:209], v155 offset:20480
	ds_read_b128 v[210:213], v155 offset:21504
	ds_read_b128 v[214:217], v155 offset:22528
	ds_read_b128 v[218:221], v155 offset:23552
	global_load_lds_dwordx4 v[148:149], off
	s_add_i32 m0, s90, 0x2000
	s_add_u32 s90, s76, 0x40000
	v_lshl_add_u64 v[174:175], s[76:77], 0, v[134:135]
	s_addc_u32 s91, s77, 0
	s_add_i32 s92, s85, s3
	global_load_lds_dwordx4 v[174:175], off
	v_lshl_add_u64 v[222:223], s[90:91], 0, v[130:131]
	s_mov_b32 m0, s92
	v_lshl_add_u64 v[226:227], s[78:79], 0, v[132:133]
	global_load_lds_dwordx4 v[222:223], off
	v_lshl_add_u64 v[222:223], s[90:91], 0, v[134:135]
	s_add_i32 m0, s92, 0x2000
	s_nop 0
	global_load_lds_dwordx4 v[222:223], off
	v_lshl_add_u64 v[222:223], s[78:79], 0, v[128:129]
	s_mov_b32 m0, s19
	s_nop 0
	global_load_lds_dwordx4 v[222:223], off
	s_mov_b32 m0, s23
	s_nop 0
	global_load_lds_dwordx4 v[226:227], off
	s_waitcnt vmcnt(8)
	s_waitcnt lgkmcnt(0)
	s_nop 0
	s_barrier
; #define PG8_STAGE(bufoff, gbase, voff) do { _Pragma("unroll") for (int _i = 0; _i < 2; ++_i) \
;         __builtin_amdgcn_global_load_lds((const unsigned*)((const char*)(gbase) + (voff)[_i]), (LAS unsigned*)(lds + (bufoff) + ldsw + _i * 8192), 16, 0, 0); } while (0)
; #define PG8_LDA(dst, b, h) do { _Pragma("unroll") for (int m = 0; m < 4; ++m) _Pragma("unroll") for (int k = 0; k < 2; ++k) dst[m][k] = *(const LAS bf16x8*)(lds + PG8_SA(b, h) + aoff + m * 2048 + k * 1024); } while (0)
; #define PG8_LDB(dst, b, h) do { _Pragma("unroll") for (int n = 0; n < 2; ++n) _Pragma("unroll") for (int k = 0; k < 2; ++k) dst[n][k] = *(const LAS bf16x8*)(lds + PG8_SB(b, h) + boff + n * 2048 + k * 1024); } while (0)
; #define PG8_MMA(ai, bj, At, Bt) do { __builtin_amdgcn_s_setprio(1); _Pragma("unroll") for (int m = 0; m < 4; ++m) _Pragma("unroll") for (int n = 0; n < 2; ++n) _Pragma("unroll") for (int k = 0; k < 2; ++k) \
;         acc[ai][bj][m][n] = __builtin_amdgcn_mfma_f32_16x16x32_bf16(Bt[n][k], At[m][k], acc[ai][bj][m][n], 0, 0, 0); __builtin_amdgcn_s_setprio(0); } while (0)
; #define PG8_WAIT_V(n) asm volatile("s_waitcnt vmcnt(" #n ")" ::: "memory")
; #define PG8_WAIT_L(n) asm volatile("s_waitcnt lgkmcnt(" #n ")" ::: "memory")
; #define PG8_BAR __builtin_amdgcn_s_barrier()
; #define PG8_SCHED __builtin_amdgcn_sched_barrier(0)
; template <class Epi>
; __device__ __forceinline__ void gemm_phase(LAS unsigned char* lds, const Gemm g, const StaticOrder& S, const Epi& E) {
;     ...
;             PG8_WAIT_V(8); PG8_WAIT_L(0); PG8_BAR; PG8_MMA(1, 0, At, B0); PG8_MMA(1, 1, At, B1); PG8_BAR; PG8_SCHED;
;             PG8_LDB(B0, 1, 0); PG8_LDB(B1, 1, 1); PG8_SCHED; PG8_LDA(At, 1, 0); PG8_STAGE(PG8_SA(0, 1), a2 + hstepA, voffA);
;             PG8_WAIT_V(8); PG8_WAIT_L(0); PG8_BAR; PG8_MMA(0, 0, At, B0); PG8_MMA(0, 1, At, B1); PG8_BAR; PG8_SCHED;
;             PG8_LDA(At, 1, 1); PG8_STAGE(PG8_SB(1, 0), b3, voffB); PG8_STAGE(PG8_SB(1, 1), b3 + hstepB, voffB); PG8_STAGE(PG8_SA(1, 0), a3, voffA);
;             PG8_WAIT_V(8); PG8_WAIT_L(0); PG8_BAR; PG8_MMA(1, 0, At, B0); PG8_MMA(1, 1, At, B1); PG8_BAR; PG8_SCHED;
	s_setprio 1
	s_waitcnt lgkmcnt(0)
	v_mfma_f32_16x16x32_bf16 v[60:63], v[144:147], v[190:193], 0
	v_mfma_f32_16x16x32_bf16 v[56:59], v[162:165], v[190:193], 0
	v_mfma_f32_16x16x32_bf16 v[44:47], v[144:147], v[198:201], 0
	v_mfma_f32_16x16x32_bf16 v[40:43], v[162:165], v[198:201], 0
	v_mfma_f32_16x16x32_bf16 v[28:31], v[144:147], v[206:209], 0
	v_mfma_f32_16x16x32_bf16 v[24:27], v[162:165], v[206:209], 0
	v_mfma_f32_16x16x32_bf16 v[12:15], v[144:147], v[214:217], 0
	v_mfma_f32_16x16x32_bf16 v[8:11], v[162:165], v[214:217], 0
	v_mfma_f32_16x16x32_bf16 v[60:63], v[158:161], v[194:197], v[60:63]
	v_mfma_f32_16x16x32_bf16 v[56:59], v[166:169], v[194:197], v[56:59]
	v_mfma_f32_16x16x32_bf16 v[44:47], v[158:161], v[202:205], v[44:47]
	v_mfma_f32_16x16x32_bf16 v[40:43], v[166:169], v[202:205], v[40:43]
	v_mfma_f32_16x16x32_bf16 v[28:31], v[158:161], v[210:213], v[28:31]
	v_mfma_f32_16x16x32_bf16 v[24:27], v[166:169], v[210:213], v[24:27]
	v_mfma_f32_16x16x32_bf16 v[12:15], v[158:161], v[218:221], v[12:15]
	v_mfma_f32_16x16x32_bf16 v[8:11], v[166:169], v[218:221], v[8:11]
	s_setprio 0
	s_setprio 1
	v_mfma_f32_16x16x32_bf16 v[52:55], v[170:173], v[190:193], 0
	v_mfma_f32_16x16x32_bf16 v[48:51], v[182:185], v[190:193], 0
	v_mfma_f32_16x16x32_bf16 v[36:39], v[170:173], v[198:201], 0
	v_mfma_f32_16x16x32_bf16 v[32:35], v[182:185], v[198:201], 0
	v_mfma_f32_16x16x32_bf16 v[20:23], v[170:173], v[206:209], 0
	v_mfma_f32_16x16x32_bf16 v[16:19], v[182:185], v[206:209], 0
	v_mfma_f32_16x16x32_bf16 v[4:7], v[170:173], v[214:217], 0
	v_mfma_f32_16x16x32_bf16 v[0:3], v[182:185], v[214:217], 0
	v_mfma_f32_16x16x32_bf16 v[52:55], v[178:181], v[194:197], v[52:55]
	v_mfma_f32_16x16x32_bf16 v[48:51], v[186:189], v[194:197], v[48:51]
	v_mfma_f32_16x16x32_bf16 v[36:39], v[178:181], v[202:205], v[36:39]
	v_mfma_f32_16x16x32_bf16 v[32:35], v[186:189], v[202:205], v[32:35]
	v_mfma_f32_16x16x32_bf16 v[20:23], v[178:181], v[210:213], v[20:23]
	v_mfma_f32_16x16x32_bf16 v[16:19], v[186:189], v[210:213], v[16:19]
	v_mfma_f32_16x16x32_bf16 v[4:7], v[178:181], v[218:221], v[4:7]
	v_mfma_f32_16x16x32_bf16 v[0:3], v[186:189], v[218:221], v[0:3]
	s_setprio 0
	s_barrier
	s_add_i32 s90, 0, 0x18000
	v_add_u32_e32 v157, s90, v152
	s_add_i32 s91, 0, 0x1c000
	ds_read_b128 v[144:147], v157
	ds_read_b128 v[158:161], v157 offset:1024
	ds_read_b128 v[162:165], v157 offset:2048
	ds_read_b128 v[166:169], v157 offset:3072
	v_add_u32_e32 v157, s91, v152
	ds_read_b128 v[170:173], v157
	ds_read_b128 v[178:181], v157 offset:1024
	ds_read_b128 v[182:185], v157 offset:2048
	ds_read_b128 v[186:189], v157 offset:3072
	s_add_u32 s78, s78, 0x40000
	s_addc_u32 s79, s79, 0
	s_mov_b32 m0, s33
	v_lshl_add_u64 v[228:229], s[78:79], 0, v[128:129]
	ds_read_b128 v[190:193], v155 offset:32768
	ds_read_b128 v[194:197], v155 offset:33792
	ds_read_b128 v[198:201], v155 offset:34816
	ds_read_b128 v[202:205], v155 offset:35840
	ds_read_b128 v[206:209], v155 offset:36864
	ds_read_b128 v[210:213], v155 offset:37888
	ds_read_b128 v[214:217], v155 offset:38912
	ds_read_b128 v[218:221], v155 offset:39936
	global_load_lds_dwordx4 v[228:229], off
	v_lshl_add_u64 v[228:229], s[78:79], 0, v[132:133]
	s_mov_b32 m0, s35
	s_nop 0
	global_load_lds_dwordx4 v[228:229], off
	s_waitcnt vmcnt(8)
	s_waitcnt lgkmcnt(0)
	s_nop 0
	s_barrier
	s_setprio 1
	s_waitcnt lgkmcnt(0)
	v_mfma_f32_16x16x32_bf16 v[124:127], v[144:147], v[190:193], v[124:127]
	v_mfma_f32_16x16x32_bf16 v[120:123], v[162:165], v[190:193], v[120:123]
	v_mfma_f32_16x16x32_bf16 v[108:111], v[144:147], v[198:201], v[108:111]
	v_mfma_f32_16x16x32_bf16 v[104:107], v[162:165], v[198:201], v[104:107]
	v_mfma_f32_16x16x32_bf16 v[92:95], v[144:147], v[206:209], v[92:95]
	v_mfma_f32_16x16x32_bf16 v[88:91], v[162:165], v[206:209], v[88:91]
	v_mfma_f32_16x16x32_bf16 v[76:79], v[144:147], v[214:217], v[76:79]
	v_mfma_f32_16x16x32_bf16 v[72:75], v[162:165], v[214:217], v[72:75]
	v_mfma_f32_16x16x32_bf16 v[124:127], v[158:161], v[194:197], v[124:127]
	v_mfma_f32_16x16x32_bf16 v[120:123], v[166:169], v[194:197], v[120:123]
	v_mfma_f32_16x16x32_bf16 v[108:111], v[158:161], v[202:205], v[108:111]
	v_mfma_f32_16x16x32_bf16 v[104:107], v[166:169], v[202:205], v[104:107]
	v_mfma_f32_16x16x32_bf16 v[92:95], v[158:161], v[210:213], v[92:95]
	v_mfma_f32_16x16x32_bf16 v[88:91], v[166:169], v[210:213], v[88:91]
	v_mfma_f32_16x16x32_bf16 v[76:79], v[158:161], v[218:221], v[76:79]
	v_mfma_f32_16x16x32_bf16 v[72:75], v[166:169], v[218:221], v[72:75]
	s_setprio 0
	s_setprio 1
	v_mfma_f32_16x16x32_bf16 v[116:119], v[170:173], v[190:193], v[116:119]
	v_mfma_f32_16x16x32_bf16 v[112:115], v[182:185], v[190:193], v[112:115]
	v_mfma_f32_16x16x32_bf16 v[100:103], v[170:173], v[198:201], v[100:103]
	v_mfma_f32_16x16x32_bf16 v[96:99], v[182:185], v[198:201], v[96:99]
	v_mfma_f32_16x16x32_bf16 v[84:87], v[170:173], v[206:209], v[84:87]
	v_mfma_f32_16x16x32_bf16 v[80:83], v[182:185], v[206:209], v[80:83]
	v_mfma_f32_16x16x32_bf16 v[68:71], v[170:173], v[214:217], v[68:71]
	v_mfma_f32_16x16x32_bf16 v[64:67], v[182:185], v[214:217], v[64:67]
	v_mfma_f32_16x16x32_bf16 v[116:119], v[178:181], v[194:197], v[116:119]
	v_mfma_f32_16x16x32_bf16 v[112:115], v[186:189], v[194:197], v[112:115]
	v_mfma_f32_16x16x32_bf16 v[100:103], v[178:181], v[202:205], v[100:103]
	v_mfma_f32_16x16x32_bf16 v[96:99], v[186:189], v[202:205], v[96:99]
	v_mfma_f32_16x16x32_bf16 v[84:87], v[178:181], v[210:213], v[84:87]
	v_mfma_f32_16x16x32_bf16 v[80:83], v[186:189], v[210:213], v[80:83]
	v_mfma_f32_16x16x32_bf16 v[68:71], v[178:181], v[218:221], v[68:71]
	v_mfma_f32_16x16x32_bf16 v[64:67], v[186:189], v[218:221], v[64:67]
	s_setprio 0
	s_barrier
; #define PG8_STAGE(bufoff, gbase, voff) do { _Pragma("unroll") for (int _i = 0; _i < 2; ++_i) \
;         __builtin_amdgcn_global_load_lds((const unsigned*)((const char*)(gbase) + (voff)[_i]), (LAS unsigned*)(lds + (bufoff) + ldsw + _i * 8192), 16, 0, 0); } while (0)
; #define PG8_LDA(dst, b, h) do { _Pragma("unroll") for (int m = 0; m < 4; ++m) _Pragma("unroll") for (int k = 0; k < 2; ++k) dst[m][k] = *(const LAS bf16x8*)(lds + PG8_SA(b, h) + aoff + m * 2048 + k * 1024); } while (0)
; #define PG8_LDB(dst, b, h) do { _Pragma("unroll") for (int n = 0; n < 2; ++n) _Pragma("unroll") for (int k = 0; k < 2; ++k) dst[n][k] = *(const LAS bf16x8*)(lds + PG8_SB(b, h) + boff + n * 2048 + k * 1024); } while (0)
; #define PG8_MMA(ai, bj, At, Bt) do { __builtin_amdgcn_s_setprio(1); _Pragma("unroll") for (int m = 0; m < 4; ++m) _Pragma("unroll") for (int n = 0; n < 2; ++n) _Pragma("unroll") for (int k = 0; k < 2; ++k) \
;         acc[ai][bj][m][n] = __builtin_amdgcn_mfma_f32_16x16x32_bf16(Bt[n][k], At[m][k], acc[ai][bj][m][n], 0, 0, 0); __builtin_amdgcn_s_setprio(0); } while (0)
; #define PG8_WAIT_V(n) asm volatile("s_waitcnt vmcnt(" #n ")" ::: "memory")
; #define PG8_WAIT_L(n) asm volatile("s_waitcnt lgkmcnt(" #n ")" ::: "memory")
; #define PG8_BAR __builtin_amdgcn_s_barrier()
; #define PG8_SCHED __builtin_amdgcn_sched_barrier(0)
; template <class Epi>
; __device__ __forceinline__ void gemm_phase(LAS unsigned char* lds, const Gemm g, const StaticOrder& S, const Epi& E) {
;     ...
;         for (int t = 0; t < nt; t += 2) {
;             const bool last = (t == nt - 2);
;             const char* a1 = cA + (size_t)(t + 1) * kstep;
;             const char* a2 = last ? nA : cA + (size_t)(t + 2) * kstep; const char* b2 = last ? nB : cB + (size_t)(t + 2) * kstep;
;             const char* a3 = a2 + kstep; const char* b3 = b2 + kstep;
;             PG8_LDB(B0, 0, 0); PG8_LDB(B1, 0, 1); PG8_SCHED; PG8_LDA(At, 0, 0); PG8_STAGE(PG8_SA(1, 1), a1 + hstepA, voffA);
;             PG8_WAIT_V(8); PG8_WAIT_L(0); PG8_BAR; PG8_MMA(0, 0, At, B0); PG8_MMA(0, 1, At, B1); PG8_BAR; PG8_SCHED;
;     ...
;             PG8_LDA(At, 1, 1); PG8_STAGE(PG8_SB(1, 0), b3, voffB); PG8_STAGE(PG8_SB(1, 1), b3 + hstepB, voffB); PG8_STAGE(PG8_SA(1, 0), a3, voffA);
;             PG8_WAIT_V(8); PG8_WAIT_L(0); PG8_BAR; PG8_MMA(1, 0, At, B0); PG8_MMA(1, 1, At, B1); PG8_BAR; PG8_SCHED;
;         }
	s_add_i32 s78, s90, s3
	v_lshl_add_u64 v[148:149], v[148:149], 0, s[12:13]
	s_mov_b32 m0, s78
	ds_read_b128 v[190:193], v155 offset:49152
	ds_read_b128 v[194:197], v155 offset:50176
	ds_read_b128 v[198:201], v155 offset:51200
	ds_read_b128 v[202:205], v155 offset:52224
	ds_read_b128 v[206:209], v155 offset:53248
	ds_read_b128 v[210:213], v155 offset:54272
	ds_read_b128 v[214:217], v155 offset:55296
	ds_read_b128 v[218:221], v155 offset:56320
	global_load_lds_dwordx4 v[148:149], off
	s_add_i32 m0, s78, 0x2000
	s_add_u32 s76, s76, 0x40080
	v_lshl_add_u64 v[148:149], v[174:175], 0, s[12:13]
	s_addc_u32 s77, s77, 0
	s_add_i32 s78, s91, s3
	global_load_lds_dwordx4 v[148:149], off
	v_lshl_add_u64 v[148:149], s[76:77], 0, v[130:131]
	s_mov_b32 m0, s78
	s_nop 0
	global_load_lds_dwordx4 v[148:149], off
	v_lshl_add_u64 v[148:149], s[76:77], 0, v[134:135]
	s_add_i32 m0, s78, 0x2000
	s_nop 0
	global_load_lds_dwordx4 v[148:149], off
	v_lshl_add_u64 v[148:149], v[222:223], 0, s[12:13]
	s_mov_b32 m0, s57
	s_nop 0
	global_load_lds_dwordx4 v[148:149], off
	v_lshl_add_u64 v[148:149], v[226:227], 0, s[12:13]
	s_mov_b32 m0, s80
	s_nop 0
	global_load_lds_dwordx4 v[148:149], off
	s_waitcnt vmcnt(8)
	s_waitcnt lgkmcnt(0)
	s_barrier
	s_setprio 1
	s_waitcnt lgkmcnt(0)
	v_mfma_f32_16x16x32_bf16 v[60:63], v[144:147], v[190:193], v[60:63]
	v_mfma_f32_16x16x32_bf16 v[56:59], v[162:165], v[190:193], v[56:59]
	v_mfma_f32_16x16x32_bf16 v[44:47], v[144:147], v[198:201], v[44:47]
	v_mfma_f32_16x16x32_bf16 v[40:43], v[162:165], v[198:201], v[40:43]
	v_mfma_f32_16x16x32_bf16 v[28:31], v[144:147], v[206:209], v[28:31]
	v_mfma_f32_16x16x32_bf16 v[24:27], v[162:165], v[206:209], v[24:27]
	v_mfma_f32_16x16x32_bf16 v[12:15], v[144:147], v[214:217], v[12:15]
	v_mfma_f32_16x16x32_bf16 v[8:11], v[162:165], v[214:217], v[8:11]
	v_mfma_f32_16x16x32_bf16 v[60:63], v[158:161], v[194:197], v[60:63]
	v_mfma_f32_16x16x32_bf16 v[56:59], v[166:169], v[194:197], v[56:59]
	v_mfma_f32_16x16x32_bf16 v[44:47], v[158:161], v[202:205], v[44:47]
	v_mfma_f32_16x16x32_bf16 v[40:43], v[166:169], v[202:205], v[40:43]
	v_mfma_f32_16x16x32_bf16 v[28:31], v[158:161], v[210:213], v[28:31]
	v_mfma_f32_16x16x32_bf16 v[24:27], v[166:169], v[210:213], v[24:27]
	v_mfma_f32_16x16x32_bf16 v[12:15], v[158:161], v[218:221], v[12:15]
	v_mfma_f32_16x16x32_bf16 v[8:11], v[166:169], v[218:221], v[8:11]
	s_setprio 0
	s_setprio 1
	v_mfma_f32_16x16x32_bf16 v[52:55], v[170:173], v[190:193], v[52:55]
	v_mfma_f32_16x16x32_bf16 v[48:51], v[182:185], v[190:193], v[48:51]
	v_mfma_f32_16x16x32_bf16 v[36:39], v[170:173], v[198:201], v[36:39]
	v_mfma_f32_16x16x32_bf16 v[32:35], v[182:185], v[198:201], v[32:35]
	v_mfma_f32_16x16x32_bf16 v[20:23], v[170:173], v[206:209], v[20:23]
	v_mfma_f32_16x16x32_bf16 v[16:19], v[182:185], v[206:209], v[16:19]
	v_mfma_f32_16x16x32_bf16 v[4:7], v[170:173], v[214:217], v[4:7]
	v_mfma_f32_16x16x32_bf16 v[0:3], v[182:185], v[214:217], v[0:3]
	v_mfma_f32_16x16x32_bf16 v[52:55], v[178:181], v[194:197], v[52:55]
	v_mfma_f32_16x16x32_bf16 v[48:51], v[186:189], v[194:197], v[48:51]
	v_mfma_f32_16x16x32_bf16 v[36:39], v[178:181], v[202:205], v[36:39]
	v_mfma_f32_16x16x32_bf16 v[32:35], v[186:189], v[202:205], v[32:35]
	v_mfma_f32_16x16x32_bf16 v[20:23], v[178:181], v[210:213], v[20:23]
	v_mfma_f32_16x16x32_bf16 v[16:19], v[186:189], v[210:213], v[16:19]
	v_mfma_f32_16x16x32_bf16 v[4:7], v[178:181], v[218:221], v[4:7]
	v_mfma_f32_16x16x32_bf16 v[0:3], v[186:189], v[218:221], v[0:3]
	s_setprio 0
	s_barrier
	s_add_i32 s89, s89, 2
	s_add_u32 s74, s74, 0x100
	s_addc_u32 s75, s75, 0
	s_add_u32 s87, s87, 0x100
	s_addc_u32 s88, s88, 0
	s_cmp_gt_u32 s89, 13
.LBB0_192:
	ds_read_b128 v[144:147], v153
	ds_read_b128 v[158:161], v153 offset:1024
	ds_read_b128 v[162:165], v153 offset:2048
	ds_read_b128 v[166:169], v153 offset:3072
	ds_read_b128 v[170:173], v154
	ds_read_b128 v[178:181], v154 offset:1024
	ds_read_b128 v[182:185], v154 offset:2048
	ds_read_b128 v[186:189], v154 offset:3072
	s_add_u32 s76, s74, 0xfffc0080
	s_addc_u32 s77, s75, -1
	s_cmp_eq_u32 s89, 12
	s_cselect_b32 s79, s7, s77
	s_cselect_b32 s78, s65, s76
	s_cselect_b32 s77, s63, s88
	s_cselect_b32 s76, s73, s87
	v_lshl_add_u64 v[148:149], s[74:75], 0, v[136:137]
	s_add_i32 m0, s19, 0xc000
	ds_read_b128 v[190:193], v155
	ds_read_b128 v[194:197], v155 offset:1024
	ds_read_b128 v[198:201], v155 offset:2048
	ds_read_b128 v[202:205], v155 offset:3072
	ds_read_b128 v[206:209], v155 offset:4096
	ds_read_b128 v[210:213], v155 offset:5120
	ds_read_b128 v[214:217], v155 offset:6144
	ds_read_b128 v[218:221], v155 offset:7168
	global_load_lds_dwordx4 v[148:149], off
	v_lshl_add_u64 v[148:149], s[74:75], 0, v[138:139]
	s_add_i32 m0, s19, 0xe000
	s_nop 0
	global_load_lds_dwordx4 v[148:149], off
	s_waitcnt vmcnt(8)
	s_waitcnt lgkmcnt(0)
	s_barrier
; #define PG8_STAGE(bufoff, gbase, voff) do { _Pragma("unroll") for (int _i = 0; _i < 2; ++_i) \
;         __builtin_amdgcn_global_load_lds((const unsigned*)((const char*)(gbase) + (voff)[_i]), (LAS unsigned*)(lds + (bufoff) + ldsw + _i * 8192), 16, 0, 0); } while (0)
; #define PG8_LDA(dst, b, h) do { _Pragma("unroll") for (int m = 0; m < 4; ++m) _Pragma("unroll") for (int k = 0; k < 2; ++k) dst[m][k] = *(const LAS bf16x8*)(lds + PG8_SA(b, h) + aoff + m * 2048 + k * 1024); } while (0)
; #define PG8_LDB(dst, b, h) do { _Pragma("unroll") for (int n = 0; n < 2; ++n) _Pragma("unroll") for (int k = 0; k < 2; ++k) dst[n][k] = *(const LAS bf16x8*)(lds + PG8_SB(b, h) + boff + n * 2048 + k * 1024); } while (0)
; #define PG8_MMA(ai, bj, At, Bt) do { __builtin_amdgcn_s_setprio(1); _Pragma("unroll") for (int m = 0; m < 4; ++m) _Pragma("unroll") for (int n = 0; n < 2; ++n) _Pragma("unroll") for (int k = 0; k < 2; ++k) \
;         acc[ai][bj][m][n] = __builtin_amdgcn_mfma_f32_16x16x32_bf16(Bt[n][k], At[m][k], acc[ai][bj][m][n], 0, 0, 0); __builtin_amdgcn_s_setprio(0); } while (0)
; #define PG8_WAIT_V(n) asm volatile("s_waitcnt vmcnt(" #n ")" ::: "memory")
; #define PG8_WAIT_L(n) asm volatile("s_waitcnt lgkmcnt(" #n ")" ::: "memory")
; #define PG8_BAR __builtin_amdgcn_s_barrier()
; #define PG8_SCHED __builtin_amdgcn_sched_barrier(0)
; template <class Epi>
; __device__ __forceinline__ void gemm_phase(LAS unsigned char* lds, const Gemm g, const StaticOrder& S, const Epi& E) {
;     ...
;             PG8_WAIT_V(8); PG8_WAIT_L(0); PG8_BAR; PG8_MMA(0, 0, At, B0); PG8_MMA(0, 1, At, B1); PG8_BAR; PG8_SCHED;
;             PG8_LDA(At, 0, 1); PG8_STAGE(PG8_SB(0, 0), b2, voffB); PG8_STAGE(PG8_SB(0, 1), b2 + hstepB, voffB); PG8_STAGE(PG8_SA(0, 0), a2, voffA);
;             PG8_WAIT_V(8); PG8_WAIT_L(0); PG8_BAR; PG8_MMA(1, 0, At, B0); PG8_MMA(1, 1, At, B1); PG8_BAR; PG8_SCHED;
;             PG8_LDB(B0, 1, 0); PG8_LDB(B1, 1, 1); PG8_SCHED; PG8_LDA(At, 1, 0); PG8_STAGE(PG8_SA(0, 1), a2 + hstepA, voffA);
;             PG8_WAIT_V(8); PG8_WAIT_L(0); PG8_BAR; PG8_MMA(0, 0, At, B0); PG8_MMA(0, 1, At, B1); PG8_BAR; PG8_SCHED;
	s_setprio 1
	s_waitcnt lgkmcnt(0)
	v_mfma_f32_16x16x32_bf16 v[124:127], v[144:147], v[190:193], v[124:127]
	v_mfma_f32_16x16x32_bf16 v[120:123], v[162:165], v[190:193], v[120:123]
	v_mfma_f32_16x16x32_bf16 v[108:111], v[144:147], v[198:201], v[108:111]
	v_mfma_f32_16x16x32_bf16 v[104:107], v[162:165], v[198:201], v[104:107]
	v_mfma_f32_16x16x32_bf16 v[92:95], v[144:147], v[206:209], v[92:95]
	v_mfma_f32_16x16x32_bf16 v[88:91], v[162:165], v[206:209], v[88:91]
	v_mfma_f32_16x16x32_bf16 v[76:79], v[144:147], v[214:217], v[76:79]
	v_mfma_f32_16x16x32_bf16 v[72:75], v[162:165], v[214:217], v[72:75]
	v_mfma_f32_16x16x32_bf16 v[124:127], v[158:161], v[194:197], v[124:127]
	v_mfma_f32_16x16x32_bf16 v[120:123], v[166:169], v[194:197], v[120:123]
	v_mfma_f32_16x16x32_bf16 v[108:111], v[158:161], v[202:205], v[108:111]
	v_mfma_f32_16x16x32_bf16 v[104:107], v[166:169], v[202:205], v[104:107]
	v_mfma_f32_16x16x32_bf16 v[92:95], v[158:161], v[210:213], v[92:95]
	v_mfma_f32_16x16x32_bf16 v[88:91], v[166:169], v[210:213], v[88:91]
	v_mfma_f32_16x16x32_bf16 v[76:79], v[158:161], v[218:221], v[76:79]
	v_mfma_f32_16x16x32_bf16 v[72:75], v[166:169], v[218:221], v[72:75]
	s_setprio 0
	s_setprio 1
	v_mfma_f32_16x16x32_bf16 v[116:119], v[170:173], v[190:193], v[116:119]
	v_mfma_f32_16x16x32_bf16 v[112:115], v[182:185], v[190:193], v[112:115]
	v_mfma_f32_16x16x32_bf16 v[100:103], v[170:173], v[198:201], v[100:103]
	v_mfma_f32_16x16x32_bf16 v[96:99], v[182:185], v[198:201], v[96:99]
	v_mfma_f32_16x16x32_bf16 v[84:87], v[170:173], v[206:209], v[84:87]
	v_mfma_f32_16x16x32_bf16 v[80:83], v[182:185], v[206:209], v[80:83]
	v_mfma_f32_16x16x32_bf16 v[68:71], v[170:173], v[214:217], v[68:71]
	v_mfma_f32_16x16x32_bf16 v[64:67], v[182:185], v[214:217], v[64:67]
	v_mfma_f32_16x16x32_bf16 v[116:119], v[178:181], v[194:197], v[116:119]
	v_mfma_f32_16x16x32_bf16 v[112:115], v[186:189], v[194:197], v[112:115]
	v_mfma_f32_16x16x32_bf16 v[100:103], v[178:181], v[202:205], v[100:103]
	v_mfma_f32_16x16x32_bf16 v[96:99], v[186:189], v[202:205], v[96:99]
	v_mfma_f32_16x16x32_bf16 v[84:87], v[178:181], v[210:213], v[84:87]
	v_mfma_f32_16x16x32_bf16 v[80:83], v[186:189], v[210:213], v[80:83]
	v_mfma_f32_16x16x32_bf16 v[68:71], v[178:181], v[218:221], v[68:71]
	v_mfma_f32_16x16x32_bf16 v[64:67], v[186:189], v[218:221], v[64:67]
	s_setprio 0
	s_barrier
	s_add_i32 s90, s84, s3
	v_lshl_add_u64 v[148:149], s[76:77], 0, v[130:131]
	s_mov_b32 m0, s90
	ds_read_b128 v[190:193], v155 offset:16384
	ds_read_b128 v[194:197], v155 offset:17408
	ds_read_b128 v[198:201], v155 offset:18432
	ds_read_b128 v[202:205], v155 offset:19456
	ds_read_b128 v[206:209], v155 offset:20480
	ds_read_b128 v[210:213], v155 offset:21504
	ds_read_b128 v[214:217], v155 offset:22528
	ds_read_b128 v[218:221], v155 offset:23552
	global_load_lds_dwordx4 v[148:149], off
	s_add_i32 m0, s90, 0x2000
	s_add_u32 s90, s76, 0x40000
	v_lshl_add_u64 v[174:175], s[76:77], 0, v[134:135]
	s_addc_u32 s91, s77, 0
	s_add_i32 s92, s85, s3
	global_load_lds_dwordx4 v[174:175], off
	v_lshl_add_u64 v[222:223], s[90:91], 0, v[130:131]
	s_mov_b32 m0, s92
	v_lshl_add_u64 v[226:227], s[78:79], 0, v[132:133]
	global_load_lds_dwordx4 v[222:223], off
	v_lshl_add_u64 v[222:223], s[90:91], 0, v[134:135]
	s_add_i32 m0, s92, 0x2000
	s_nop 0
	global_load_lds_dwordx4 v[222:223], off
	v_lshl_add_u64 v[222:223], s[78:79], 0, v[128:129]
	s_mov_b32 m0, s19
	s_nop 0
	global_load_lds_dwordx4 v[222:223], off
	s_mov_b32 m0, s23
	s_nop 0
	global_load_lds_dwordx4 v[226:227], off
	s_waitcnt vmcnt(8)
	s_waitcnt lgkmcnt(0)
	s_nop 0
	s_barrier
	s_setprio 1
	s_waitcnt lgkmcnt(0)
	v_mfma_f32_16x16x32_bf16 v[60:63], v[144:147], v[190:193], v[60:63]
	v_mfma_f32_16x16x32_bf16 v[56:59], v[162:165], v[190:193], v[56:59]
	v_mfma_f32_16x16x32_bf16 v[44:47], v[144:147], v[198:201], v[44:47]
	v_mfma_f32_16x16x32_bf16 v[40:43], v[162:165], v[198:201], v[40:43]
	v_mfma_f32_16x16x32_bf16 v[28:31], v[144:147], v[206:209], v[28:31]
	v_mfma_f32_16x16x32_bf16 v[24:27], v[162:165], v[206:209], v[24:27]
	v_mfma_f32_16x16x32_bf16 v[12:15], v[144:147], v[214:217], v[12:15]
	v_mfma_f32_16x16x32_bf16 v[8:11], v[162:165], v[214:217], v[8:11]
	v_mfma_f32_16x16x32_bf16 v[60:63], v[158:161], v[194:197], v[60:63]
	v_mfma_f32_16x16x32_bf16 v[56:59], v[166:169], v[194:197], v[56:59]
	v_mfma_f32_16x16x32_bf16 v[44:47], v[158:161], v[202:205], v[44:47]
	v_mfma_f32_16x16x32_bf16 v[40:43], v[166:169], v[202:205], v[40:43]
	v_mfma_f32_16x16x32_bf16 v[28:31], v[158:161], v[210:213], v[28:31]
	v_mfma_f32_16x16x32_bf16 v[24:27], v[166:169], v[210:213], v[24:27]
	v_mfma_f32_16x16x32_bf16 v[12:15], v[158:161], v[218:221], v[12:15]
	v_mfma_f32_16x16x32_bf16 v[8:11], v[166:169], v[218:221], v[8:11]
	s_setprio 0
	s_setprio 1
	v_mfma_f32_16x16x32_bf16 v[52:55], v[170:173], v[190:193], v[52:55]
	v_mfma_f32_16x16x32_bf16 v[48:51], v[182:185], v[190:193], v[48:51]
	v_mfma_f32_16x16x32_bf16 v[36:39], v[170:173], v[198:201], v[36:39]
	v_mfma_f32_16x16x32_bf16 v[32:35], v[182:185], v[198:201], v[32:35]
	v_mfma_f32_16x16x32_bf16 v[20:23], v[170:173], v[206:209], v[20:23]
	v_mfma_f32_16x16x32_bf16 v[16:19], v[182:185], v[206:209], v[16:19]
	v_mfma_f32_16x16x32_bf16 v[4:7], v[170:173], v[214:217], v[4:7]
	v_mfma_f32_16x16x32_bf16 v[0:3], v[182:185], v[214:217], v[0:3]
	v_mfma_f32_16x16x32_bf16 v[52:55], v[178:181], v[194:197], v[52:55]
	v_mfma_f32_16x16x32_bf16 v[48:51], v[186:189], v[194:197], v[48:51]
	v_mfma_f32_16x16x32_bf16 v[36:39], v[178:181], v[202:205], v[36:39]
	v_mfma_f32_16x16x32_bf16 v[32:35], v[186:189], v[202:205], v[32:35]
	v_mfma_f32_16x16x32_bf16 v[20:23], v[178:181], v[210:213], v[20:23]
	v_mfma_f32_16x16x32_bf16 v[16:19], v[186:189], v[210:213], v[16:19]
	v_mfma_f32_16x16x32_bf16 v[4:7], v[178:181], v[218:221], v[4:7]
	v_mfma_f32_16x16x32_bf16 v[0:3], v[186:189], v[218:221], v[0:3]
	s_setprio 0
	s_barrier
; #define PG8_STAGE(bufoff, gbase, voff) do { _Pragma("unroll") for (int _i = 0; _i < 2; ++_i) \
;         __builtin_amdgcn_global_load_lds((const unsigned*)((const char*)(gbase) + (voff)[_i]), (LAS unsigned*)(lds + (bufoff) + ldsw + _i * 8192), 16, 0, 0); } while (0)
; #define PG8_LDA(dst, b, h) do { _Pragma("unroll") for (int m = 0; m < 4; ++m) _Pragma("unroll") for (int k = 0; k < 2; ++k) dst[m][k] = *(const LAS bf16x8*)(lds + PG8_SA(b, h) + aoff + m * 2048 + k * 1024); } while (0)
; #define PG8_MMA(ai, bj, At, Bt) do { __builtin_amdgcn_s_setprio(1); _Pragma("unroll") for (int m = 0; m < 4; ++m) _Pragma("unroll") for (int n = 0; n < 2; ++n) _Pragma("unroll") for (int k = 0; k < 2; ++k) \
;         acc[ai][bj][m][n] = __builtin_amdgcn_mfma_f32_16x16x32_bf16(Bt[n][k], At[m][k], acc[ai][bj][m][n], 0, 0, 0); __builtin_amdgcn_s_setprio(0); } while (0)
; #define PG8_WAIT_V(n) asm volatile("s_waitcnt vmcnt(" #n ")" ::: "memory")
; #define PG8_WAIT_L(n) asm volatile("s_waitcnt lgkmcnt(" #n ")" ::: "memory")
; #define PG8_BAR __builtin_amdgcn_s_barrier()
; #define PG8_SCHED __builtin_amdgcn_sched_barrier(0)
; template <class Epi>
; __device__ __forceinline__ void gemm_phase(LAS unsigned char* lds, const Gemm g, const StaticOrder& S, const Epi& E) {
;     ...
;             PG8_LDA(At, 1, 1); PG8_STAGE(PG8_SB(1, 0), b3, voffB); PG8_STAGE(PG8_SB(1, 1), b3 + hstepB, voffB); PG8_STAGE(PG8_SA(1, 0), a3, voffA);
;             PG8_WAIT_V(8); PG8_WAIT_L(0); PG8_BAR; PG8_MMA(1, 0, At, B0); PG8_MMA(1, 1, At, B1); PG8_BAR; PG8_SCHED;
	s_add_i32 s90, 0, 0x18000
	v_add_u32_e32 v157, s90, v152
	s_add_i32 s91, 0, 0x1c000
	ds_read_b128 v[144:147], v157
	ds_read_b128 v[158:161], v157 offset:1024
	ds_read_b128 v[162:165], v157 offset:2048
	ds_read_b128 v[166:169], v157 offset:3072
	v_add_u32_e32 v157, s91, v152
	ds_read_b128 v[170:173], v157
	ds_read_b128 v[178:181], v157 offset:1024
	ds_read_b128 v[182:185], v157 offset:2048
	ds_read_b128 v[186:189], v157 offset:3072
	s_add_u32 s78, s78, 0x40000
	s_addc_u32 s79, s79, 0
	s_mov_b32 m0, s33
	v_lshl_add_u64 v[228:229], s[78:79], 0, v[128:129]
	ds_read_b128 v[190:193], v155 offset:32768
	ds_read_b128 v[194:197], v155 offset:33792
	ds_read_b128 v[198:201], v155 offset:34816
	ds_read_b128 v[202:205], v155 offset:35840
	ds_read_b128 v[206:209], v155 offset:36864
	ds_read_b128 v[210:213], v155 offset:37888
	ds_read_b128 v[214:217], v155 offset:38912
	ds_read_b128 v[218:221], v155 offset:39936
	global_load_lds_dwordx4 v[228:229], off
	v_lshl_add_u64 v[228:229], s[78:79], 0, v[132:133]
	s_mov_b32 m0, s35
	s_nop 0
	global_load_lds_dwordx4 v[228:229], off
	s_waitcnt vmcnt(8)
	s_waitcnt lgkmcnt(0)
	s_nop 0
	s_barrier
	s_setprio 1
	s_waitcnt lgkmcnt(0)
	v_mfma_f32_16x16x32_bf16 v[124:127], v[144:147], v[190:193], v[124:127]
	v_mfma_f32_16x16x32_bf16 v[120:123], v[162:165], v[190:193], v[120:123]
	v_mfma_f32_16x16x32_bf16 v[108:111], v[144:147], v[198:201], v[108:111]
	v_mfma_f32_16x16x32_bf16 v[104:107], v[162:165], v[198:201], v[104:107]
	v_mfma_f32_16x16x32_bf16 v[92:95], v[144:147], v[206:209], v[92:95]
	v_mfma_f32_16x16x32_bf16 v[88:91], v[162:165], v[206:209], v[88:91]
	v_mfma_f32_16x16x32_bf16 v[76:79], v[144:147], v[214:217], v[76:79]
	v_mfma_f32_16x16x32_bf16 v[72:75], v[162:165], v[214:217], v[72:75]
	v_mfma_f32_16x16x32_bf16 v[124:127], v[158:161], v[194:197], v[124:127]
	v_mfma_f32_16x16x32_bf16 v[120:123], v[166:169], v[194:197], v[120:123]
	v_mfma_f32_16x16x32_bf16 v[108:111], v[158:161], v[202:205], v[108:111]
	v_mfma_f32_16x16x32_bf16 v[104:107], v[166:169], v[202:205], v[104:107]
	v_mfma_f32_16x16x32_bf16 v[92:95], v[158:161], v[210:213], v[92:95]
	v_mfma_f32_16x16x32_bf16 v[88:91], v[166:169], v[210:213], v[88:91]
	v_mfma_f32_16x16x32_bf16 v[76:79], v[158:161], v[218:221], v[76:79]
	v_mfma_f32_16x16x32_bf16 v[72:75], v[166:169], v[218:221], v[72:75]
	s_setprio 0
	s_setprio 1
	v_mfma_f32_16x16x32_bf16 v[116:119], v[170:173], v[190:193], v[116:119]
	v_mfma_f32_16x16x32_bf16 v[112:115], v[182:185], v[190:193], v[112:115]
	v_mfma_f32_16x16x32_bf16 v[100:103], v[170:173], v[198:201], v[100:103]
	v_mfma_f32_16x16x32_bf16 v[96:99], v[182:185], v[198:201], v[96:99]
	v_mfma_f32_16x16x32_bf16 v[84:87], v[170:173], v[206:209], v[84:87]
	v_mfma_f32_16x16x32_bf16 v[80:83], v[182:185], v[206:209], v[80:83]
	v_mfma_f32_16x16x32_bf16 v[68:71], v[170:173], v[214:217], v[68:71]
	v_mfma_f32_16x16x32_bf16 v[64:67], v[182:185], v[214:217], v[64:67]
	v_mfma_f32_16x16x32_bf16 v[116:119], v[178:181], v[194:197], v[116:119]
	v_mfma_f32_16x16x32_bf16 v[112:115], v[186:189], v[194:197], v[112:115]
	v_mfma_f32_16x16x32_bf16 v[100:103], v[178:181], v[202:205], v[100:103]
	v_mfma_f32_16x16x32_bf16 v[96:99], v[186:189], v[202:205], v[96:99]
	v_mfma_f32_16x16x32_bf16 v[84:87], v[178:181], v[210:213], v[84:87]
	v_mfma_f32_16x16x32_bf16 v[80:83], v[186:189], v[210:213], v[80:83]
	v_mfma_f32_16x16x32_bf16 v[68:71], v[178:181], v[218:221], v[68:71]
	v_mfma_f32_16x16x32_bf16 v[64:67], v[186:189], v[218:221], v[64:67]
	s_setprio 0
	s_barrier
; #define PG8_STAGE(bufoff, gbase, voff) do { _Pragma("unroll") for (int _i = 0; _i < 2; ++_i) \
;         __builtin_amdgcn_global_load_lds((const unsigned*)((const char*)(gbase) + (voff)[_i]), (LAS unsigned*)(lds + (bufoff) + ldsw + _i * 8192), 16, 0, 0); } while (0)
; #define PG8_LDA(dst, b, h) do { _Pragma("unroll") for (int m = 0; m < 4; ++m) _Pragma("unroll") for (int k = 0; k < 2; ++k) dst[m][k] = *(const LAS bf16x8*)(lds + PG8_SA(b, h) + aoff + m * 2048 + k * 1024); } while (0)
; #define PG8_MMA(ai, bj, At, Bt) do { __builtin_amdgcn_s_setprio(1); _Pragma("unroll") for (int m = 0; m < 4; ++m) _Pragma("unroll") for (int n = 0; n < 2; ++n) _Pragma("unroll") for (int k = 0; k < 2; ++k) \
;         acc[ai][bj][m][n] = __builtin_amdgcn_mfma_f32_16x16x32_bf16(Bt[n][k], At[m][k], acc[ai][bj][m][n], 0, 0, 0); __builtin_amdgcn_s_setprio(0); } while (0)
; #define PG8_WAIT_V(n) asm volatile("s_waitcnt vmcnt(" #n ")" ::: "memory")
; #define PG8_WAIT_L(n) asm volatile("s_waitcnt lgkmcnt(" #n ")" ::: "memory")
; #define PG8_BAR __builtin_amdgcn_s_barrier()
; #define PG8_SCHED __builtin_amdgcn_sched_barrier(0)
; template <class Epi>
; __device__ __forceinline__ void gemm_phase(LAS unsigned char* lds, const Gemm g, const StaticOrder& S, const Epi& E) {
;     ...
;             PG8_LDA(At, 1, 1); PG8_STAGE(PG8_SB(1, 0), b3, voffB); PG8_STAGE(PG8_SB(1, 1), b3 + hstepB, voffB); PG8_STAGE(PG8_SA(1, 0), a3, voffA);
;             PG8_WAIT_V(8); PG8_WAIT_L(0); PG8_BAR; PG8_MMA(1, 0, At, B0); PG8_MMA(1, 1, At, B1); PG8_BAR; PG8_SCHED;
;         }
;         if (wr == 0) PG8_BAR;
	s_add_i32 s78, s90, s3
	v_lshl_add_u64 v[148:149], v[148:149], 0, s[12:13]
	s_mov_b32 m0, s78
	ds_read_b128 v[190:193], v155 offset:49152
	ds_read_b128 v[194:197], v155 offset:50176
	ds_read_b128 v[198:201], v155 offset:51200
	ds_read_b128 v[202:205], v155 offset:52224
	ds_read_b128 v[206:209], v155 offset:53248
	ds_read_b128 v[210:213], v155 offset:54272
	ds_read_b128 v[214:217], v155 offset:55296
	ds_read_b128 v[218:221], v155 offset:56320
	global_load_lds_dwordx4 v[148:149], off
	s_add_i32 m0, s78, 0x2000
	s_add_u32 s76, s76, 0x40080
	v_lshl_add_u64 v[148:149], v[174:175], 0, s[12:13]
	s_addc_u32 s77, s77, 0
	s_add_i32 s78, s91, s3
	global_load_lds_dwordx4 v[148:149], off
	v_lshl_add_u64 v[148:149], s[76:77], 0, v[130:131]
	s_mov_b32 m0, s78
	s_nop 0
	global_load_lds_dwordx4 v[148:149], off
	v_lshl_add_u64 v[148:149], s[76:77], 0, v[134:135]
	s_add_i32 m0, s78, 0x2000
	s_nop 0
	global_load_lds_dwordx4 v[148:149], off
	v_lshl_add_u64 v[148:149], v[222:223], 0, s[12:13]
	s_mov_b32 m0, s57
	s_nop 0
	global_load_lds_dwordx4 v[148:149], off
	v_lshl_add_u64 v[148:149], v[226:227], 0, s[12:13]
	s_mov_b32 m0, s80
	s_nop 0
	global_load_lds_dwordx4 v[148:149], off
	s_waitcnt vmcnt(8)
	s_waitcnt lgkmcnt(0)
	s_barrier
	s_setprio 1
	s_waitcnt lgkmcnt(0)
	v_mfma_f32_16x16x32_bf16 v[60:63], v[144:147], v[190:193], v[60:63]
	v_mfma_f32_16x16x32_bf16 v[56:59], v[162:165], v[190:193], v[56:59]
	v_mfma_f32_16x16x32_bf16 v[44:47], v[144:147], v[198:201], v[44:47]
	v_mfma_f32_16x16x32_bf16 v[40:43], v[162:165], v[198:201], v[40:43]
	v_mfma_f32_16x16x32_bf16 v[28:31], v[144:147], v[206:209], v[28:31]
	v_mfma_f32_16x16x32_bf16 v[24:27], v[162:165], v[206:209], v[24:27]
	v_mfma_f32_16x16x32_bf16 v[12:15], v[144:147], v[214:217], v[12:15]
	v_mfma_f32_16x16x32_bf16 v[8:11], v[162:165], v[214:217], v[8:11]
	v_mfma_f32_16x16x32_bf16 v[60:63], v[158:161], v[194:197], v[60:63]
	v_mfma_f32_16x16x32_bf16 v[56:59], v[166:169], v[194:197], v[56:59]
	v_mfma_f32_16x16x32_bf16 v[44:47], v[158:161], v[202:205], v[44:47]
	v_mfma_f32_16x16x32_bf16 v[40:43], v[166:169], v[202:205], v[40:43]
	v_mfma_f32_16x16x32_bf16 v[28:31], v[158:161], v[210:213], v[28:31]
	v_mfma_f32_16x16x32_bf16 v[24:27], v[166:169], v[210:213], v[24:27]
	v_mfma_f32_16x16x32_bf16 v[12:15], v[158:161], v[218:221], v[12:15]
	v_mfma_f32_16x16x32_bf16 v[8:11], v[166:169], v[218:221], v[8:11]
	s_setprio 0
	s_setprio 1
	v_mfma_f32_16x16x32_bf16 v[52:55], v[170:173], v[190:193], v[52:55]
	v_mfma_f32_16x16x32_bf16 v[48:51], v[182:185], v[190:193], v[48:51]
	v_mfma_f32_16x16x32_bf16 v[36:39], v[170:173], v[198:201], v[36:39]
	v_mfma_f32_16x16x32_bf16 v[32:35], v[182:185], v[198:201], v[32:35]
	v_mfma_f32_16x16x32_bf16 v[20:23], v[170:173], v[206:209], v[20:23]
	v_mfma_f32_16x16x32_bf16 v[16:19], v[182:185], v[206:209], v[16:19]
	v_mfma_f32_16x16x32_bf16 v[4:7], v[170:173], v[214:217], v[4:7]
	v_mfma_f32_16x16x32_bf16 v[0:3], v[182:185], v[214:217], v[0:3]
	v_mfma_f32_16x16x32_bf16 v[52:55], v[178:181], v[194:197], v[52:55]
	v_mfma_f32_16x16x32_bf16 v[48:51], v[186:189], v[194:197], v[48:51]
	v_mfma_f32_16x16x32_bf16 v[36:39], v[178:181], v[202:205], v[36:39]
	v_mfma_f32_16x16x32_bf16 v[32:35], v[186:189], v[202:205], v[32:35]
	v_mfma_f32_16x16x32_bf16 v[20:23], v[178:181], v[210:213], v[20:23]
	v_mfma_f32_16x16x32_bf16 v[16:19], v[186:189], v[210:213], v[16:19]
	v_mfma_f32_16x16x32_bf16 v[4:7], v[178:181], v[218:221], v[4:7]
	v_mfma_f32_16x16x32_bf16 v[0:3], v[186:189], v[218:221], v[0:3]
	s_setprio 0
	s_barrier
	s_add_i32 s89, s89, 2
	s_add_u32 s74, s74, 0x100
	s_addc_u32 s75, s75, 0
	s_add_u32 s87, s87, 0x100
	s_addc_u32 s88, s88, 0
	s_cmp_gt_u32 s89, 13
	s_cbranch_scc0 .LBB0_192
	s_and_b64 vcc, exec, s[14:15]
	s_cbranch_vccz .LBB0_195
	s_barrier

; #define PG8_STAGE(bufoff, gbase, voff) do { _Pragma("unroll") for (int _i = 0; _i < 2; ++_i) \
;         __builtin_amdgcn_global_load_lds((const unsigned*)((const char*)(gbase) + (voff)[_i]), (LAS unsigned*)(lds + (bufoff) + ldsw + _i * 8192), 16, 0, 0); } while (0)
; #define PG8_LDA(dst, b, h) do { _Pragma("unroll") for (int m = 0; m < 4; ++m) _Pragma("unroll") for (int k = 0; k < 2; ++k) dst[m][k] = *(const LAS bf16x8*)(lds + PG8_SA(b, h) + aoff + m * 2048 + k * 1024); } while (0)
; #define PG8_LDB(dst, b, h) do { _Pragma("unroll") for (int n = 0; n < 2; ++n) _Pragma("unroll") for (int k = 0; k < 2; ++k) dst[n][k] = *(const LAS bf16x8*)(lds + PG8_SB(b, h) + boff + n * 2048 + k * 1024); } while (0)
; #define PG8_MMA(ai, bj, At, Bt) do { __builtin_amdgcn_s_setprio(1); _Pragma("unroll") for (int m = 0; m < 4; ++m) _Pragma("unroll") for (int n = 0; n < 2; ++n) _Pragma("unroll") for (int k = 0; k < 2; ++k) \
;         acc[ai][bj][m][n] = __builtin_amdgcn_mfma_f32_16x16x32_bf16(Bt[n][k], At[m][k], acc[ai][bj][m][n], 0, 0, 0); __builtin_amdgcn_s_setprio(0); } while (0)
; #define PG8_BAR __builtin_amdgcn_s_barrier()
; template <class Epi>
; __device__ __forceinline__ void gemm_phase(LAS unsigned char* lds, const Gemm g, const StaticOrder& S, const Epi& E) {
;     ...
;         const bool has_next = S.next(ui + 1, nxt);
;         const char* nA = has_next ? (const char*)g.A + (size_t)nxt.pm * tstepA : cA; const char* nB = has_next ? (const char*)g.Bt + (size_t)nxt.pn * tstepB : cB;
; #pragma nounroll
;         for (int t = 0; t < nt; t += 2) {
;             const bool last = (t == nt - 2);
;             const char* a1 = cA + (size_t)(t + 1) * kstep;
;             const char* a2 = last ? nA : cA + (size_t)(t + 2) * kstep; const char* b2 = last ? nB : cB + (size_t)(t + 2) * kstep;
;             const char* a3 = a2 + kstep; const char* b3 = b2 + kstep;
;             PG8_LDB(B0, 0, 0); PG8_LDB(B1, 0, 1); PG8_SCHED; PG8_LDA(At, 0, 0); PG8_STAGE(PG8_SA(1, 1), a1 + hstepA, voffA);
;             PG8_WAIT_V(8); PG8_WAIT_L(0); PG8_BAR; PG8_MMA(0, 0, At, B0); PG8_MMA(0, 1, At, B1); PG8_BAR; PG8_SCHED;
;             PG8_LDA(At, 0, 1); PG8_STAGE(PG8_SB(0, 0), b2, voffB); PG8_STAGE(PG8_SB(0, 1), b2 + hstepB, voffB); PG8_STAGE(PG8_SA(0, 0), a2, voffA);
;             PG8_WAIT_V(8); PG8_WAIT_L(0); PG8_BAR; PG8_MMA(1, 0, At, B0); PG8_MMA(1, 1, At, B1); PG8_BAR; PG8_SCHED;
.LBB0_456:
	s_ashr_i32 s23, s22, 31
	s_lshl_b64 s[28:29], s[22:23], 19
	s_add_u32 s28, s40, s28
	s_addc_u32 s29, s41, s29
	s_and_b64 s[30:31], s[4:5], exec
	s_cselect_b32 s1, s29, s39
	s_cselect_b32 s23, s28, s38
	s_ashr_i32 s19, s18, 31
	s_lshl_b64 s[30:31], s[18:19], 19
	s_add_u32 s30, s3, s30
	s_addc_u32 s31, s33, s31
	s_and_b64 s[52:53], s[4:5], exec
	s_cselect_b32 s19, s31, s43
	s_cselect_b32 s74, s30, s42
	s_add_u32 s38, s38, 0x40080
	s_addc_u32 s39, s39, 0
	s_add_u32 s75, s42, 0x100
	s_addc_u32 s76, s43, 0
	s_mov_b32 s77, -2
	s_waitcnt lgkmcnt(0)
	s_nop 0
	ds_read_b128 v[128:131], v173
	ds_read_b128 v[132:135], v173 offset:1024
	ds_read_b128 v[136:139], v173 offset:2048
	ds_read_b128 v[140:143], v173 offset:3072
	ds_read_b128 v[160:163], v174
	ds_read_b128 v[164:167], v174 offset:1024
	ds_read_b128 v[178:181], v174 offset:2048
	ds_read_b128 v[182:185], v174 offset:3072
	s_add_u32 s42, s38, 0xfffc0080
	s_addc_u32 s43, s39, -1
	s_cmp_eq_u32 s77, 12
	s_cselect_b32 s53, s1, s43
	s_cselect_b32 s52, s23, s42
	s_cselect_b32 s43, s19, s76
	s_cselect_b32 s42, s74, s75
	v_lshl_add_u64 v[168:169], s[38:39], 0, v[152:153]
	s_add_i32 m0, s35, 0xc000
	ds_read_b128 v[186:189], v175
	ds_read_b128 v[190:193], v175 offset:1024
	ds_read_b128 v[194:197], v175 offset:2048
	ds_read_b128 v[198:201], v175 offset:3072
	ds_read_b128 v[202:205], v175 offset:4096
	ds_read_b128 v[206:209], v175 offset:5120
	ds_read_b128 v[210:213], v175 offset:6144
	ds_read_b128 v[214:217], v175 offset:7168
	global_load_lds_dwordx4 v[168:169], off
	v_lshl_add_u64 v[168:169], s[38:39], 0, v[154:155]
	s_add_i32 m0, s35, 0xe000
	s_nop 0
	global_load_lds_dwordx4 v[168:169], off
	s_waitcnt vmcnt(8)
	s_waitcnt lgkmcnt(0)
	s_barrier
	s_setprio 1
	s_waitcnt lgkmcnt(0)
	v_mfma_f32_16x16x32_bf16 v[124:127], v[128:131], v[186:189], 0
	v_mfma_f32_16x16x32_bf16 v[120:123], v[136:139], v[186:189], 0
	v_mfma_f32_16x16x32_bf16 v[108:111], v[128:131], v[194:197], 0
	v_mfma_f32_16x16x32_bf16 v[104:107], v[136:139], v[194:197], 0
	v_mfma_f32_16x16x32_bf16 v[92:95], v[128:131], v[202:205], 0
	v_mfma_f32_16x16x32_bf16 v[88:91], v[136:139], v[202:205], 0
	v_mfma_f32_16x16x32_bf16 v[76:79], v[128:131], v[210:213], 0
	v_mfma_f32_16x16x32_bf16 v[72:75], v[136:139], v[210:213], 0
	v_mfma_f32_16x16x32_bf16 v[124:127], v[132:135], v[190:193], v[124:127]
	v_mfma_f32_16x16x32_bf16 v[120:123], v[140:143], v[190:193], v[120:123]
	v_mfma_f32_16x16x32_bf16 v[108:111], v[132:135], v[198:201], v[108:111]
	v_mfma_f32_16x16x32_bf16 v[104:107], v[140:143], v[198:201], v[104:107]
	v_mfma_f32_16x16x32_bf16 v[92:95], v[132:135], v[206:209], v[92:95]
	v_mfma_f32_16x16x32_bf16 v[88:91], v[140:143], v[206:209], v[88:91]
	v_mfma_f32_16x16x32_bf16 v[76:79], v[132:135], v[214:217], v[76:79]
	v_mfma_f32_16x16x32_bf16 v[72:75], v[140:143], v[214:217], v[72:75]
	s_setprio 0
	s_setprio 1
	v_mfma_f32_16x16x32_bf16 v[116:119], v[160:163], v[186:189], 0
	v_mfma_f32_16x16x32_bf16 v[112:115], v[178:181], v[186:189], 0
	v_mfma_f32_16x16x32_bf16 v[100:103], v[160:163], v[194:197], 0
	v_mfma_f32_16x16x32_bf16 v[96:99], v[178:181], v[194:197], 0
	v_mfma_f32_16x16x32_bf16 v[84:87], v[160:163], v[202:205], 0
	v_mfma_f32_16x16x32_bf16 v[80:83], v[178:181], v[202:205], 0
	v_mfma_f32_16x16x32_bf16 v[68:71], v[160:163], v[210:213], 0
	v_mfma_f32_16x16x32_bf16 v[64:67], v[178:181], v[210:213], 0
	v_mfma_f32_16x16x32_bf16 v[116:119], v[164:167], v[190:193], v[116:119]
	v_mfma_f32_16x16x32_bf16 v[112:115], v[182:185], v[190:193], v[112:115]
	v_mfma_f32_16x16x32_bf16 v[100:103], v[164:167], v[198:201], v[100:103]
	v_mfma_f32_16x16x32_bf16 v[96:99], v[182:185], v[198:201], v[96:99]
	v_mfma_f32_16x16x32_bf16 v[84:87], v[164:167], v[206:209], v[84:87]
	v_mfma_f32_16x16x32_bf16 v[80:83], v[182:185], v[206:209], v[80:83]
	v_mfma_f32_16x16x32_bf16 v[68:71], v[164:167], v[214:217], v[68:71]
	v_mfma_f32_16x16x32_bf16 v[64:67], v[182:185], v[214:217], v[64:67]
	s_setprio 0
	s_barrier
	s_add_i32 s78, s72, s54
	v_lshl_add_u64 v[168:169], s[42:43], 0, v[146:147]
	s_mov_b32 m0, s78
	ds_read_b128 v[186:189], v175 offset:16384
	ds_read_b128 v[190:193], v175 offset:17408
	ds_read_b128 v[194:197], v175 offset:18432
	ds_read_b128 v[198:201], v175 offset:19456
	ds_read_b128 v[202:205], v175 offset:20480
	ds_read_b128 v[206:209], v175 offset:21504
	ds_read_b128 v[210:213], v175 offset:22528
	ds_read_b128 v[214:217], v175 offset:23552
	global_load_lds_dwordx4 v[168:169], off
	s_add_i32 m0, s78, 0x2000
	s_add_u32 s78, s42, 0x40000
	v_lshl_add_u64 v[218:219], s[42:43], 0, v[150:151]
	s_addc_u32 s79, s43, 0
	s_add_i32 s80, s73, s54
	global_load_lds_dwordx4 v[218:219], off
	v_lshl_add_u64 v[220:221], s[78:79], 0, v[146:147]
	s_mov_b32 m0, s80
	v_lshl_add_u64 v[222:223], s[52:53], 0, v[148:149]
	global_load_lds_dwordx4 v[220:221], off
	v_lshl_add_u64 v[220:221], s[78:79], 0, v[150:151]
	s_add_i32 m0, s80, 0x2000
	s_nop 0
	global_load_lds_dwordx4 v[220:221], off
	v_lshl_add_u64 v[220:221], s[52:53], 0, v[144:145]
	s_mov_b32 m0, s35
	s_nop 0
	global_load_lds_dwordx4 v[220:221], off
	s_mov_b32 m0, s55
	s_nop 0
	global_load_lds_dwordx4 v[222:223], off
	s_waitcnt vmcnt(8)
	s_waitcnt lgkmcnt(0)
	s_nop 0
	s_barrier
; #define PG8_STAGE(bufoff, gbase, voff) do { _Pragma("unroll") for (int _i = 0; _i < 2; ++_i) \
;         __builtin_amdgcn_global_load_lds((const unsigned*)((const char*)(gbase) + (voff)[_i]), (LAS unsigned*)(lds + (bufoff) + ldsw + _i * 8192), 16, 0, 0); } while (0)
; #define PG8_LDA(dst, b, h) do { _Pragma("unroll") for (int m = 0; m < 4; ++m) _Pragma("unroll") for (int k = 0; k < 2; ++k) dst[m][k] = *(const LAS bf16x8*)(lds + PG8_SA(b, h) + aoff + m * 2048 + k * 1024); } while (0)
; #define PG8_LDB(dst, b, h) do { _Pragma("unroll") for (int n = 0; n < 2; ++n) _Pragma("unroll") for (int k = 0; k < 2; ++k) dst[n][k] = *(const LAS bf16x8*)(lds + PG8_SB(b, h) + boff + n * 2048 + k * 1024); } while (0)
; #define PG8_MMA(ai, bj, At, Bt) do { __builtin_amdgcn_s_setprio(1); _Pragma("unroll") for (int m = 0; m < 4; ++m) _Pragma("unroll") for (int n = 0; n < 2; ++n) _Pragma("unroll") for (int k = 0; k < 2; ++k) \
;         acc[ai][bj][m][n] = __builtin_amdgcn_mfma_f32_16x16x32_bf16(Bt[n][k], At[m][k], acc[ai][bj][m][n], 0, 0, 0); __builtin_amdgcn_s_setprio(0); } while (0)
; #define PG8_WAIT_V(n) asm volatile("s_waitcnt vmcnt(" #n ")" ::: "memory")
; #define PG8_WAIT_L(n) asm volatile("s_waitcnt lgkmcnt(" #n ")" ::: "memory")
; #define PG8_BAR __builtin_amdgcn_s_barrier()
; #define PG8_SCHED __builtin_amdgcn_sched_barrier(0)
; template <class Epi>
; __device__ __forceinline__ void gemm_phase(LAS unsigned char* lds, const Gemm g, const StaticOrder& S, const Epi& E) {
;     ...
;             PG8_WAIT_V(8); PG8_WAIT_L(0); PG8_BAR; PG8_MMA(1, 0, At, B0); PG8_MMA(1, 1, At, B1); PG8_BAR; PG8_SCHED;
;             PG8_LDB(B0, 1, 0); PG8_LDB(B1, 1, 1); PG8_SCHED; PG8_LDA(At, 1, 0); PG8_STAGE(PG8_SA(0, 1), a2 + hstepA, voffA);
;             PG8_WAIT_V(8); PG8_WAIT_L(0); PG8_BAR; PG8_MMA(0, 0, At, B0); PG8_MMA(0, 1, At, B1); PG8_BAR; PG8_SCHED;
;             PG8_LDA(At, 1, 1); PG8_STAGE(PG8_SB(1, 0), b3, voffB); PG8_STAGE(PG8_SB(1, 1), b3 + hstepB, voffB); PG8_STAGE(PG8_SA(1, 0), a3, voffA);
;             PG8_WAIT_V(8); PG8_WAIT_L(0); PG8_BAR; PG8_MMA(1, 0, At, B0); PG8_MMA(1, 1, At, B1); PG8_BAR; PG8_SCHED;
	s_setprio 1
	s_waitcnt lgkmcnt(0)
	v_mfma_f32_16x16x32_bf16 v[60:63], v[128:131], v[186:189], 0
	v_mfma_f32_16x16x32_bf16 v[56:59], v[136:139], v[186:189], 0
	v_mfma_f32_16x16x32_bf16 v[44:47], v[128:131], v[194:197], 0
	v_mfma_f32_16x16x32_bf16 v[40:43], v[136:139], v[194:197], 0
	v_mfma_f32_16x16x32_bf16 v[28:31], v[128:131], v[202:205], 0
	v_mfma_f32_16x16x32_bf16 v[24:27], v[136:139], v[202:205], 0
	v_mfma_f32_16x16x32_bf16 v[12:15], v[128:131], v[210:213], 0
	v_mfma_f32_16x16x32_bf16 v[8:11], v[136:139], v[210:213], 0
	v_mfma_f32_16x16x32_bf16 v[60:63], v[132:135], v[190:193], v[60:63]
	v_mfma_f32_16x16x32_bf16 v[56:59], v[140:143], v[190:193], v[56:59]
	v_mfma_f32_16x16x32_bf16 v[44:47], v[132:135], v[198:201], v[44:47]
	v_mfma_f32_16x16x32_bf16 v[40:43], v[140:143], v[198:201], v[40:43]
	v_mfma_f32_16x16x32_bf16 v[28:31], v[132:135], v[206:209], v[28:31]
	v_mfma_f32_16x16x32_bf16 v[24:27], v[140:143], v[206:209], v[24:27]
	v_mfma_f32_16x16x32_bf16 v[12:15], v[132:135], v[214:217], v[12:15]
	v_mfma_f32_16x16x32_bf16 v[8:11], v[140:143], v[214:217], v[8:11]
	s_setprio 0
	s_setprio 1
	v_mfma_f32_16x16x32_bf16 v[52:55], v[160:163], v[186:189], 0
	v_mfma_f32_16x16x32_bf16 v[48:51], v[178:181], v[186:189], 0
	v_mfma_f32_16x16x32_bf16 v[36:39], v[160:163], v[194:197], 0
	v_mfma_f32_16x16x32_bf16 v[32:35], v[178:181], v[194:197], 0
	v_mfma_f32_16x16x32_bf16 v[20:23], v[160:163], v[202:205], 0
	v_mfma_f32_16x16x32_bf16 v[16:19], v[178:181], v[202:205], 0
	v_mfma_f32_16x16x32_bf16 v[4:7], v[160:163], v[210:213], 0
	v_mfma_f32_16x16x32_bf16 v[0:3], v[178:181], v[210:213], 0
	v_mfma_f32_16x16x32_bf16 v[52:55], v[164:167], v[190:193], v[52:55]
	v_mfma_f32_16x16x32_bf16 v[48:51], v[182:185], v[190:193], v[48:51]
	v_mfma_f32_16x16x32_bf16 v[36:39], v[164:167], v[198:201], v[36:39]
	v_mfma_f32_16x16x32_bf16 v[32:35], v[182:185], v[198:201], v[32:35]
	v_mfma_f32_16x16x32_bf16 v[20:23], v[164:167], v[206:209], v[20:23]
	v_mfma_f32_16x16x32_bf16 v[16:19], v[182:185], v[206:209], v[16:19]
	v_mfma_f32_16x16x32_bf16 v[4:7], v[164:167], v[214:217], v[4:7]
	v_mfma_f32_16x16x32_bf16 v[0:3], v[182:185], v[214:217], v[0:3]
	s_setprio 0
	s_barrier
	s_add_i32 s78, 0, 0x18000
	s_add_i32 s79, 0, 0x1c000
	v_add_u32_e32 v140, s78, v172
	v_add_u32_e32 v182, s79, v172
	ds_read_b128 v[128:131], v140
	ds_read_b128 v[132:135], v140 offset:1024
	ds_read_b128 v[136:139], v140 offset:2048
	ds_read_b128 v[140:143], v140 offset:3072
	ds_read_b128 v[160:163], v182
	ds_read_b128 v[164:167], v182 offset:1024
	ds_read_b128 v[178:181], v182 offset:2048
	ds_read_b128 v[182:185], v182 offset:3072
	s_add_u32 s52, s52, 0x40000
	s_addc_u32 s53, s53, 0
	s_mov_b32 m0, s56
	v_lshl_add_u64 v[226:227], s[52:53], 0, v[144:145]
	ds_read_b128 v[186:189], v175 offset:32768
	ds_read_b128 v[190:193], v175 offset:33792
	ds_read_b128 v[194:197], v175 offset:34816
	ds_read_b128 v[198:201], v175 offset:35840
	ds_read_b128 v[202:205], v175 offset:36864
	ds_read_b128 v[206:209], v175 offset:37888
	ds_read_b128 v[210:213], v175 offset:38912
	ds_read_b128 v[214:217], v175 offset:39936
	global_load_lds_dwordx4 v[226:227], off
	v_lshl_add_u64 v[226:227], s[52:53], 0, v[148:149]
	s_mov_b32 m0, s57
	s_nop 0
	global_load_lds_dwordx4 v[226:227], off
	s_waitcnt vmcnt(8)
	s_waitcnt lgkmcnt(0)
	s_nop 0
	s_barrier
	s_setprio 1
	s_waitcnt lgkmcnt(0)
	v_mfma_f32_16x16x32_bf16 v[124:127], v[128:131], v[186:189], v[124:127]
	v_mfma_f32_16x16x32_bf16 v[120:123], v[136:139], v[186:189], v[120:123]
	v_mfma_f32_16x16x32_bf16 v[108:111], v[128:131], v[194:197], v[108:111]
	v_mfma_f32_16x16x32_bf16 v[104:107], v[136:139], v[194:197], v[104:107]
	v_mfma_f32_16x16x32_bf16 v[92:95], v[128:131], v[202:205], v[92:95]
	v_mfma_f32_16x16x32_bf16 v[88:91], v[136:139], v[202:205], v[88:91]
	v_mfma_f32_16x16x32_bf16 v[76:79], v[128:131], v[210:213], v[76:79]
	v_mfma_f32_16x16x32_bf16 v[72:75], v[136:139], v[210:213], v[72:75]
	v_mfma_f32_16x16x32_bf16 v[124:127], v[132:135], v[190:193], v[124:127]
	v_mfma_f32_16x16x32_bf16 v[120:123], v[140:143], v[190:193], v[120:123]
	v_mfma_f32_16x16x32_bf16 v[108:111], v[132:135], v[198:201], v[108:111]
	v_mfma_f32_16x16x32_bf16 v[104:107], v[140:143], v[198:201], v[104:107]
	v_mfma_f32_16x16x32_bf16 v[92:95], v[132:135], v[206:209], v[92:95]
	v_mfma_f32_16x16x32_bf16 v[88:91], v[140:143], v[206:209], v[88:91]
	v_mfma_f32_16x16x32_bf16 v[76:79], v[132:135], v[214:217], v[76:79]
	v_mfma_f32_16x16x32_bf16 v[72:75], v[140:143], v[214:217], v[72:75]
	s_setprio 0
	s_setprio 1
	v_mfma_f32_16x16x32_bf16 v[116:119], v[160:163], v[186:189], v[116:119]
	v_mfma_f32_16x16x32_bf16 v[112:115], v[178:181], v[186:189], v[112:115]
	v_mfma_f32_16x16x32_bf16 v[100:103], v[160:163], v[194:197], v[100:103]
	v_mfma_f32_16x16x32_bf16 v[96:99], v[178:181], v[194:197], v[96:99]
	v_mfma_f32_16x16x32_bf16 v[84:87], v[160:163], v[202:205], v[84:87]
	v_mfma_f32_16x16x32_bf16 v[80:83], v[178:181], v[202:205], v[80:83]
	v_mfma_f32_16x16x32_bf16 v[68:71], v[160:163], v[210:213], v[68:71]
	v_mfma_f32_16x16x32_bf16 v[64:67], v[178:181], v[210:213], v[64:67]
	v_mfma_f32_16x16x32_bf16 v[116:119], v[164:167], v[190:193], v[116:119]
	v_mfma_f32_16x16x32_bf16 v[112:115], v[182:185], v[190:193], v[112:115]
	v_mfma_f32_16x16x32_bf16 v[100:103], v[164:167], v[198:201], v[100:103]
	v_mfma_f32_16x16x32_bf16 v[96:99], v[182:185], v[198:201], v[96:99]
	v_mfma_f32_16x16x32_bf16 v[84:87], v[164:167], v[206:209], v[84:87]
	v_mfma_f32_16x16x32_bf16 v[80:83], v[182:185], v[206:209], v[80:83]
	v_mfma_f32_16x16x32_bf16 v[68:71], v[164:167], v[214:217], v[68:71]
	v_mfma_f32_16x16x32_bf16 v[64:67], v[182:185], v[214:217], v[64:67]
	s_setprio 0
	s_barrier
; #define PG8_STAGE(bufoff, gbase, voff) do { _Pragma("unroll") for (int _i = 0; _i < 2; ++_i) \
;         __builtin_amdgcn_global_load_lds((const unsigned*)((const char*)(gbase) + (voff)[_i]), (LAS unsigned*)(lds + (bufoff) + ldsw + _i * 8192), 16, 0, 0); } while (0)
; #define PG8_LDA(dst, b, h) do { _Pragma("unroll") for (int m = 0; m < 4; ++m) _Pragma("unroll") for (int k = 0; k < 2; ++k) dst[m][k] = *(const LAS bf16x8*)(lds + PG8_SA(b, h) + aoff + m * 2048 + k * 1024); } while (0)
; #define PG8_LDB(dst, b, h) do { _Pragma("unroll") for (int n = 0; n < 2; ++n) _Pragma("unroll") for (int k = 0; k < 2; ++k) dst[n][k] = *(const LAS bf16x8*)(lds + PG8_SB(b, h) + boff + n * 2048 + k * 1024); } while (0)
; #define PG8_MMA(ai, bj, At, Bt) do { __builtin_amdgcn_s_setprio(1); _Pragma("unroll") for (int m = 0; m < 4; ++m) _Pragma("unroll") for (int n = 0; n < 2; ++n) _Pragma("unroll") for (int k = 0; k < 2; ++k) \
;         acc[ai][bj][m][n] = __builtin_amdgcn_mfma_f32_16x16x32_bf16(Bt[n][k], At[m][k], acc[ai][bj][m][n], 0, 0, 0); __builtin_amdgcn_s_setprio(0); } while (0)
; #define PG8_WAIT_V(n) asm volatile("s_waitcnt vmcnt(" #n ")" ::: "memory")
; #define PG8_WAIT_L(n) asm volatile("s_waitcnt lgkmcnt(" #n ")" ::: "memory")
; #define PG8_BAR __builtin_amdgcn_s_barrier()
; #define PG8_SCHED __builtin_amdgcn_sched_barrier(0)
; template <class Epi>
; __device__ __forceinline__ void gemm_phase(LAS unsigned char* lds, const Gemm g, const StaticOrder& S, const Epi& E) {
;     ...
;         for (int t = 0; t < nt; t += 2) {
;             const bool last = (t == nt - 2);
;             const char* a1 = cA + (size_t)(t + 1) * kstep;
;             const char* a2 = last ? nA : cA + (size_t)(t + 2) * kstep; const char* b2 = last ? nB : cB + (size_t)(t + 2) * kstep;
;             const char* a3 = a2 + kstep; const char* b3 = b2 + kstep;
;             PG8_LDB(B0, 0, 0); PG8_LDB(B1, 0, 1); PG8_SCHED; PG8_LDA(At, 0, 0); PG8_STAGE(PG8_SA(1, 1), a1 + hstepA, voffA);
;             PG8_WAIT_V(8); PG8_WAIT_L(0); PG8_BAR; PG8_MMA(0, 0, At, B0); PG8_MMA(0, 1, At, B1); PG8_BAR; PG8_SCHED;
;     ...
;             PG8_LDA(At, 1, 1); PG8_STAGE(PG8_SB(1, 0), b3, voffB); PG8_STAGE(PG8_SB(1, 1), b3 + hstepB, voffB); PG8_STAGE(PG8_SA(1, 0), a3, voffA);
;             PG8_WAIT_V(8); PG8_WAIT_L(0); PG8_BAR; PG8_MMA(1, 0, At, B0); PG8_MMA(1, 1, At, B1); PG8_BAR; PG8_SCHED;
	s_add_i32 s52, s78, s54
	v_lshl_add_u64 v[168:169], v[168:169], 0, s[12:13]
	s_mov_b32 m0, s52
	ds_read_b128 v[186:189], v175 offset:49152
	ds_read_b128 v[190:193], v175 offset:50176
	ds_read_b128 v[194:197], v175 offset:51200
	ds_read_b128 v[198:201], v175 offset:52224
	ds_read_b128 v[202:205], v175 offset:53248
	ds_read_b128 v[206:209], v175 offset:54272
	ds_read_b128 v[210:213], v175 offset:55296
	ds_read_b128 v[214:217], v175 offset:56320
	global_load_lds_dwordx4 v[168:169], off
	s_add_i32 m0, s52, 0x2000
	s_add_u32 s42, s42, 0x40080
	v_lshl_add_u64 v[168:169], v[218:219], 0, s[12:13]
	s_addc_u32 s43, s43, 0
	s_add_i32 s52, s79, s54
	global_load_lds_dwordx4 v[168:169], off
	v_lshl_add_u64 v[168:169], s[42:43], 0, v[146:147]
	s_mov_b32 m0, s52
	s_nop 0
	global_load_lds_dwordx4 v[168:169], off
	v_lshl_add_u64 v[168:169], s[42:43], 0, v[150:151]
	s_add_i32 m0, s52, 0x2000
	s_nop 0
	global_load_lds_dwordx4 v[168:169], off
	v_lshl_add_u64 v[168:169], v[220:221], 0, s[12:13]
	s_mov_b32 m0, s65
	s_nop 0
	global_load_lds_dwordx4 v[168:169], off
	v_lshl_add_u64 v[168:169], v[222:223], 0, s[12:13]
	s_mov_b32 m0, s68
	s_nop 0
	global_load_lds_dwordx4 v[168:169], off
	s_waitcnt vmcnt(8)
	s_waitcnt lgkmcnt(0)
	s_barrier
	s_setprio 1
	s_waitcnt lgkmcnt(0)
	v_mfma_f32_16x16x32_bf16 v[60:63], v[128:131], v[186:189], v[60:63]
	v_mfma_f32_16x16x32_bf16 v[56:59], v[136:139], v[186:189], v[56:59]
	v_mfma_f32_16x16x32_bf16 v[44:47], v[128:131], v[194:197], v[44:47]
	v_mfma_f32_16x16x32_bf16 v[40:43], v[136:139], v[194:197], v[40:43]
	v_mfma_f32_16x16x32_bf16 v[28:31], v[128:131], v[202:205], v[28:31]
	v_mfma_f32_16x16x32_bf16 v[24:27], v[136:139], v[202:205], v[24:27]
	v_mfma_f32_16x16x32_bf16 v[12:15], v[128:131], v[210:213], v[12:15]
	v_mfma_f32_16x16x32_bf16 v[8:11], v[136:139], v[210:213], v[8:11]
	v_mfma_f32_16x16x32_bf16 v[60:63], v[132:135], v[190:193], v[60:63]
	v_mfma_f32_16x16x32_bf16 v[56:59], v[140:143], v[190:193], v[56:59]
	v_mfma_f32_16x16x32_bf16 v[44:47], v[132:135], v[198:201], v[44:47]
	v_mfma_f32_16x16x32_bf16 v[40:43], v[140:143], v[198:201], v[40:43]
	v_mfma_f32_16x16x32_bf16 v[28:31], v[132:135], v[206:209], v[28:31]
	v_mfma_f32_16x16x32_bf16 v[24:27], v[140:143], v[206:209], v[24:27]
	v_mfma_f32_16x16x32_bf16 v[12:15], v[132:135], v[214:217], v[12:15]
	v_mfma_f32_16x16x32_bf16 v[8:11], v[140:143], v[214:217], v[8:11]
	s_setprio 0
	s_setprio 1
	v_mfma_f32_16x16x32_bf16 v[52:55], v[160:163], v[186:189], v[52:55]
	v_mfma_f32_16x16x32_bf16 v[48:51], v[178:181], v[186:189], v[48:51]
	v_mfma_f32_16x16x32_bf16 v[36:39], v[160:163], v[194:197], v[36:39]
	v_mfma_f32_16x16x32_bf16 v[32:35], v[178:181], v[194:197], v[32:35]
	v_mfma_f32_16x16x32_bf16 v[20:23], v[160:163], v[202:205], v[20:23]
	v_mfma_f32_16x16x32_bf16 v[16:19], v[178:181], v[202:205], v[16:19]
	v_mfma_f32_16x16x32_bf16 v[4:7], v[160:163], v[210:213], v[4:7]
	v_mfma_f32_16x16x32_bf16 v[0:3], v[178:181], v[210:213], v[0:3]
	v_mfma_f32_16x16x32_bf16 v[52:55], v[164:167], v[190:193], v[52:55]
	v_mfma_f32_16x16x32_bf16 v[48:51], v[182:185], v[190:193], v[48:51]
	v_mfma_f32_16x16x32_bf16 v[36:39], v[164:167], v[198:201], v[36:39]
	v_mfma_f32_16x16x32_bf16 v[32:35], v[182:185], v[198:201], v[32:35]
	v_mfma_f32_16x16x32_bf16 v[20:23], v[164:167], v[206:209], v[20:23]
	v_mfma_f32_16x16x32_bf16 v[16:19], v[182:185], v[206:209], v[16:19]
	v_mfma_f32_16x16x32_bf16 v[4:7], v[164:167], v[214:217], v[4:7]
	v_mfma_f32_16x16x32_bf16 v[0:3], v[182:185], v[214:217], v[0:3]
	s_setprio 0
	s_barrier
	s_add_i32 s77, s77, 2
	s_add_u32 s38, s38, 0x100
	s_addc_u32 s39, s39, 0
	s_add_u32 s75, s75, 0x100
	s_addc_u32 s76, s76, 0
	s_cmp_gt_u32 s77, 13
.LBB0_457:
	ds_read_b128 v[128:131], v173
	ds_read_b128 v[132:135], v173 offset:1024
	ds_read_b128 v[136:139], v173 offset:2048
	ds_read_b128 v[140:143], v173 offset:3072
	ds_read_b128 v[160:163], v174
	ds_read_b128 v[164:167], v174 offset:1024
	ds_read_b128 v[178:181], v174 offset:2048
	ds_read_b128 v[182:185], v174 offset:3072
	s_add_u32 s42, s38, 0xfffc0080
	s_addc_u32 s43, s39, -1
	s_cmp_eq_u32 s77, 12
	s_cselect_b32 s53, s1, s43
	s_cselect_b32 s52, s23, s42
	s_cselect_b32 s43, s19, s76
	s_cselect_b32 s42, s74, s75
	v_lshl_add_u64 v[168:169], s[38:39], 0, v[152:153]
	s_add_i32 m0, s35, 0xc000
	ds_read_b128 v[186:189], v175
	ds_read_b128 v[190:193], v175 offset:1024
	ds_read_b128 v[194:197], v175 offset:2048
	ds_read_b128 v[198:201], v175 offset:3072
	ds_read_b128 v[202:205], v175 offset:4096
	ds_read_b128 v[206:209], v175 offset:5120
	ds_read_b128 v[210:213], v175 offset:6144
	ds_read_b128 v[214:217], v175 offset:7168
	global_load_lds_dwordx4 v[168:169], off
	v_lshl_add_u64 v[168:169], s[38:39], 0, v[154:155]
	s_add_i32 m0, s35, 0xe000
	s_nop 0
	global_load_lds_dwordx4 v[168:169], off
	s_waitcnt vmcnt(8)
	s_waitcnt lgkmcnt(0)
	s_barrier
; #define PG8_STAGE(bufoff, gbase, voff) do { _Pragma("unroll") for (int _i = 0; _i < 2; ++_i) \
;         __builtin_amdgcn_global_load_lds((const unsigned*)((const char*)(gbase) + (voff)[_i]), (LAS unsigned*)(lds + (bufoff) + ldsw + _i * 8192), 16, 0, 0); } while (0)
; #define PG8_LDA(dst, b, h) do { _Pragma("unroll") for (int m = 0; m < 4; ++m) _Pragma("unroll") for (int k = 0; k < 2; ++k) dst[m][k] = *(const LAS bf16x8*)(lds + PG8_SA(b, h) + aoff + m * 2048 + k * 1024); } while (0)
; #define PG8_LDB(dst, b, h) do { _Pragma("unroll") for (int n = 0; n < 2; ++n) _Pragma("unroll") for (int k = 0; k < 2; ++k) dst[n][k] = *(const LAS bf16x8*)(lds + PG8_SB(b, h) + boff + n * 2048 + k * 1024); } while (0)
; #define PG8_MMA(ai, bj, At, Bt) do { __builtin_amdgcn_s_setprio(1); _Pragma("unroll") for (int m = 0; m < 4; ++m) _Pragma("unroll") for (int n = 0; n < 2; ++n) _Pragma("unroll") for (int k = 0; k < 2; ++k) \
;         acc[ai][bj][m][n] = __builtin_amdgcn_mfma_f32_16x16x32_bf16(Bt[n][k], At[m][k], acc[ai][bj][m][n], 0, 0, 0); __builtin_amdgcn_s_setprio(0); } while (0)
; #define PG8_WAIT_V(n) asm volatile("s_waitcnt vmcnt(" #n ")" ::: "memory")
; #define PG8_WAIT_L(n) asm volatile("s_waitcnt lgkmcnt(" #n ")" ::: "memory")
; #define PG8_BAR __builtin_amdgcn_s_barrier()
; #define PG8_SCHED __builtin_amdgcn_sched_barrier(0)
; template <class Epi>
; __device__ __forceinline__ void gemm_phase(LAS unsigned char* lds, const Gemm g, const StaticOrder& S, const Epi& E) {
;     ...
;             PG8_WAIT_V(8); PG8_WAIT_L(0); PG8_BAR; PG8_MMA(0, 0, At, B0); PG8_MMA(0, 1, At, B1); PG8_BAR; PG8_SCHED;
;             PG8_LDA(At, 0, 1); PG8_STAGE(PG8_SB(0, 0), b2, voffB); PG8_STAGE(PG8_SB(0, 1), b2 + hstepB, voffB); PG8_STAGE(PG8_SA(0, 0), a2, voffA);
;             PG8_WAIT_V(8); PG8_WAIT_L(0); PG8_BAR; PG8_MMA(1, 0, At, B0); PG8_MMA(1, 1, At, B1); PG8_BAR; PG8_SCHED;
;             PG8_LDB(B0, 1, 0); PG8_LDB(B1, 1, 1); PG8_SCHED; PG8_LDA(At, 1, 0); PG8_STAGE(PG8_SA(0, 1), a2 + hstepA, voffA);
;             PG8_WAIT_V(8); PG8_WAIT_L(0); PG8_BAR; PG8_MMA(0, 0, At, B0); PG8_MMA(0, 1, At, B1); PG8_BAR; PG8_SCHED;
	s_setprio 1
	s_waitcnt lgkmcnt(0)
	v_mfma_f32_16x16x32_bf16 v[124:127], v[128:131], v[186:189], v[124:127]
	v_mfma_f32_16x16x32_bf16 v[120:123], v[136:139], v[186:189], v[120:123]
	v_mfma_f32_16x16x32_bf16 v[108:111], v[128:131], v[194:197], v[108:111]
	v_mfma_f32_16x16x32_bf16 v[104:107], v[136:139], v[194:197], v[104:107]
	v_mfma_f32_16x16x32_bf16 v[92:95], v[128:131], v[202:205], v[92:95]
	v_mfma_f32_16x16x32_bf16 v[88:91], v[136:139], v[202:205], v[88:91]
	v_mfma_f32_16x16x32_bf16 v[76:79], v[128:131], v[210:213], v[76:79]
	v_mfma_f32_16x16x32_bf16 v[72:75], v[136:139], v[210:213], v[72:75]
	v_mfma_f32_16x16x32_bf16 v[124:127], v[132:135], v[190:193], v[124:127]
	v_mfma_f32_16x16x32_bf16 v[120:123], v[140:143], v[190:193], v[120:123]
	v_mfma_f32_16x16x32_bf16 v[108:111], v[132:135], v[198:201], v[108:111]
	v_mfma_f32_16x16x32_bf16 v[104:107], v[140:143], v[198:201], v[104:107]
	v_mfma_f32_16x16x32_bf16 v[92:95], v[132:135], v[206:209], v[92:95]
	v_mfma_f32_16x16x32_bf16 v[88:91], v[140:143], v[206:209], v[88:91]
	v_mfma_f32_16x16x32_bf16 v[76:79], v[132:135], v[214:217], v[76:79]
	v_mfma_f32_16x16x32_bf16 v[72:75], v[140:143], v[214:217], v[72:75]
	s_setprio 0
	s_setprio 1
	v_mfma_f32_16x16x32_bf16 v[116:119], v[160:163], v[186:189], v[116:119]
	v_mfma_f32_16x16x32_bf16 v[112:115], v[178:181], v[186:189], v[112:115]
	v_mfma_f32_16x16x32_bf16 v[100:103], v[160:163], v[194:197], v[100:103]
	v_mfma_f32_16x16x32_bf16 v[96:99], v[178:181], v[194:197], v[96:99]
	v_mfma_f32_16x16x32_bf16 v[84:87], v[160:163], v[202:205], v[84:87]
	v_mfma_f32_16x16x32_bf16 v[80:83], v[178:181], v[202:205], v[80:83]
	v_mfma_f32_16x16x32_bf16 v[68:71], v[160:163], v[210:213], v[68:71]
	v_mfma_f32_16x16x32_bf16 v[64:67], v[178:181], v[210:213], v[64:67]
	v_mfma_f32_16x16x32_bf16 v[116:119], v[164:167], v[190:193], v[116:119]
	v_mfma_f32_16x16x32_bf16 v[112:115], v[182:185], v[190:193], v[112:115]
	v_mfma_f32_16x16x32_bf16 v[100:103], v[164:167], v[198:201], v[100:103]
	v_mfma_f32_16x16x32_bf16 v[96:99], v[182:185], v[198:201], v[96:99]
	v_mfma_f32_16x16x32_bf16 v[84:87], v[164:167], v[206:209], v[84:87]
	v_mfma_f32_16x16x32_bf16 v[80:83], v[182:185], v[206:209], v[80:83]
	v_mfma_f32_16x16x32_bf16 v[68:71], v[164:167], v[214:217], v[68:71]
	v_mfma_f32_16x16x32_bf16 v[64:67], v[182:185], v[214:217], v[64:67]
	s_setprio 0
	s_barrier
	s_add_i32 s78, s72, s54
	v_lshl_add_u64 v[168:169], s[42:43], 0, v[146:147]
	s_mov_b32 m0, s78
	ds_read_b128 v[186:189], v175 offset:16384
	ds_read_b128 v[190:193], v175 offset:17408
	ds_read_b128 v[194:197], v175 offset:18432
	ds_read_b128 v[198:201], v175 offset:19456
	ds_read_b128 v[202:205], v175 offset:20480
	ds_read_b128 v[206:209], v175 offset:21504
	ds_read_b128 v[210:213], v175 offset:22528
	ds_read_b128 v[214:217], v175 offset:23552
	global_load_lds_dwordx4 v[168:169], off
	s_add_i32 m0, s78, 0x2000
	s_add_u32 s78, s42, 0x40000
	v_lshl_add_u64 v[218:219], s[42:43], 0, v[150:151]
	s_addc_u32 s79, s43, 0
	s_add_i32 s80, s73, s54
	global_load_lds_dwordx4 v[218:219], off
	v_lshl_add_u64 v[220:221], s[78:79], 0, v[146:147]
	s_mov_b32 m0, s80
	v_lshl_add_u64 v[222:223], s[52:53], 0, v[148:149]
	global_load_lds_dwordx4 v[220:221], off
	v_lshl_add_u64 v[220:221], s[78:79], 0, v[150:151]
	s_add_i32 m0, s80, 0x2000
	s_nop 0
	global_load_lds_dwordx4 v[220:221], off
	v_lshl_add_u64 v[220:221], s[52:53], 0, v[144:145]
	s_mov_b32 m0, s35
	s_nop 0
	global_load_lds_dwordx4 v[220:221], off
	s_mov_b32 m0, s55
	s_nop 0
	global_load_lds_dwordx4 v[222:223], off
	s_waitcnt vmcnt(8)
	s_waitcnt lgkmcnt(0)
	s_nop 0
	s_barrier
	s_setprio 1
	s_waitcnt lgkmcnt(0)
	v_mfma_f32_16x16x32_bf16 v[60:63], v[128:131], v[186:189], v[60:63]
	v_mfma_f32_16x16x32_bf16 v[56:59], v[136:139], v[186:189], v[56:59]
	v_mfma_f32_16x16x32_bf16 v[44:47], v[128:131], v[194:197], v[44:47]
	v_mfma_f32_16x16x32_bf16 v[40:43], v[136:139], v[194:197], v[40:43]
	v_mfma_f32_16x16x32_bf16 v[28:31], v[128:131], v[202:205], v[28:31]
	v_mfma_f32_16x16x32_bf16 v[24:27], v[136:139], v[202:205], v[24:27]
	v_mfma_f32_16x16x32_bf16 v[12:15], v[128:131], v[210:213], v[12:15]
	v_mfma_f32_16x16x32_bf16 v[8:11], v[136:139], v[210:213], v[8:11]
	v_mfma_f32_16x16x32_bf16 v[60:63], v[132:135], v[190:193], v[60:63]
	v_mfma_f32_16x16x32_bf16 v[56:59], v[140:143], v[190:193], v[56:59]
	v_mfma_f32_16x16x32_bf16 v[44:47], v[132:135], v[198:201], v[44:47]
	v_mfma_f32_16x16x32_bf16 v[40:43], v[140:143], v[198:201], v[40:43]
	v_mfma_f32_16x16x32_bf16 v[28:31], v[132:135], v[206:209], v[28:31]
	v_mfma_f32_16x16x32_bf16 v[24:27], v[140:143], v[206:209], v[24:27]
	v_mfma_f32_16x16x32_bf16 v[12:15], v[132:135], v[214:217], v[12:15]
	v_mfma_f32_16x16x32_bf16 v[8:11], v[140:143], v[214:217], v[8:11]
	s_setprio 0
	s_setprio 1
	v_mfma_f32_16x16x32_bf16 v[52:55], v[160:163], v[186:189], v[52:55]
	v_mfma_f32_16x16x32_bf16 v[48:51], v[178:181], v[186:189], v[48:51]
	v_mfma_f32_16x16x32_bf16 v[36:39], v[160:163], v[194:197], v[36:39]
	v_mfma_f32_16x16x32_bf16 v[32:35], v[178:181], v[194:197], v[32:35]
	v_mfma_f32_16x16x32_bf16 v[20:23], v[160:163], v[202:205], v[20:23]
	v_mfma_f32_16x16x32_bf16 v[16:19], v[178:181], v[202:205], v[16:19]
	v_mfma_f32_16x16x32_bf16 v[4:7], v[160:163], v[210:213], v[4:7]
	v_mfma_f32_16x16x32_bf16 v[0:3], v[178:181], v[210:213], v[0:3]
	v_mfma_f32_16x16x32_bf16 v[52:55], v[164:167], v[190:193], v[52:55]
	v_mfma_f32_16x16x32_bf16 v[48:51], v[182:185], v[190:193], v[48:51]
	v_mfma_f32_16x16x32_bf16 v[36:39], v[164:167], v[198:201], v[36:39]
	v_mfma_f32_16x16x32_bf16 v[32:35], v[182:185], v[198:201], v[32:35]
	v_mfma_f32_16x16x32_bf16 v[20:23], v[164:167], v[206:209], v[20:23]
	v_mfma_f32_16x16x32_bf16 v[16:19], v[182:185], v[206:209], v[16:19]
	v_mfma_f32_16x16x32_bf16 v[4:7], v[164:167], v[214:217], v[4:7]
	v_mfma_f32_16x16x32_bf16 v[0:3], v[182:185], v[214:217], v[0:3]
	s_setprio 0
	s_barrier
; #define PG8_STAGE(bufoff, gbase, voff) do { _Pragma("unroll") for (int _i = 0; _i < 2; ++_i) \
;         __builtin_amdgcn_global_load_lds((const unsigned*)((const char*)(gbase) + (voff)[_i]), (LAS unsigned*)(lds + (bufoff) + ldsw + _i * 8192), 16, 0, 0); } while (0)
; #define PG8_LDA(dst, b, h) do { _Pragma("unroll") for (int m = 0; m < 4; ++m) _Pragma("unroll") for (int k = 0; k < 2; ++k) dst[m][k] = *(const LAS bf16x8*)(lds + PG8_SA(b, h) + aoff + m * 2048 + k * 1024); } while (0)
; #define PG8_LDB(dst, b, h) do { _Pragma("unroll") for (int n = 0; n < 2; ++n) _Pragma("unroll") for (int k = 0; k < 2; ++k) dst[n][k] = *(const LAS bf16x8*)(lds + PG8_SB(b, h) + boff + n * 2048 + k * 1024); } while (0)
; #define PG8_MMA(ai, bj, At, Bt) do { __builtin_amdgcn_s_setprio(1); _Pragma("unroll") for (int m = 0; m < 4; ++m) _Pragma("unroll") for (int n = 0; n < 2; ++n) _Pragma("unroll") for (int k = 0; k < 2; ++k) \
;         acc[ai][bj][m][n] = __builtin_amdgcn_mfma_f32_16x16x32_bf16(Bt[n][k], At[m][k], acc[ai][bj][m][n], 0, 0, 0); __builtin_amdgcn_s_setprio(0); } while (0)
; #define PG8_WAIT_V(n) asm volatile("s_waitcnt vmcnt(" #n ")" ::: "memory")
; #define PG8_WAIT_L(n) asm volatile("s_waitcnt lgkmcnt(" #n ")" ::: "memory")
; #define PG8_BAR __builtin_amdgcn_s_barrier()
; #define PG8_SCHED __builtin_amdgcn_sched_barrier(0)
; template <class Epi>
; __device__ __forceinline__ void gemm_phase(LAS unsigned char* lds, const Gemm g, const StaticOrder& S, const Epi& E) {
;     ...
;             PG8_LDB(B0, 1, 0); PG8_LDB(B1, 1, 1); PG8_SCHED; PG8_LDA(At, 1, 0); PG8_STAGE(PG8_SA(0, 1), a2 + hstepA, voffA);
;             PG8_WAIT_V(8); PG8_WAIT_L(0); PG8_BAR; PG8_MMA(0, 0, At, B0); PG8_MMA(0, 1, At, B1); PG8_BAR; PG8_SCHED;
	s_add_i32 s78, 0, 0x18000
	s_add_i32 s79, 0, 0x1c000
	v_add_u32_e32 v140, s78, v172
	v_add_u32_e32 v182, s79, v172
	ds_read_b128 v[128:131], v140
	ds_read_b128 v[132:135], v140 offset:1024
	ds_read_b128 v[136:139], v140 offset:2048
	ds_read_b128 v[140:143], v140 offset:3072
	ds_read_b128 v[160:163], v182
	ds_read_b128 v[164:167], v182 offset:1024
	ds_read_b128 v[178:181], v182 offset:2048
	ds_read_b128 v[182:185], v182 offset:3072
	s_add_u32 s52, s52, 0x40000
	s_addc_u32 s53, s53, 0
	s_mov_b32 m0, s56
	v_lshl_add_u64 v[226:227], s[52:53], 0, v[144:145]
	ds_read_b128 v[186:189], v175 offset:32768
	ds_read_b128 v[190:193], v175 offset:33792
	ds_read_b128 v[194:197], v175 offset:34816
	ds_read_b128 v[198:201], v175 offset:35840
	ds_read_b128 v[202:205], v175 offset:36864
	ds_read_b128 v[206:209], v175 offset:37888
	ds_read_b128 v[210:213], v175 offset:38912
	ds_read_b128 v[214:217], v175 offset:39936
	global_load_lds_dwordx4 v[226:227], off
	v_lshl_add_u64 v[226:227], s[52:53], 0, v[148:149]
	s_mov_b32 m0, s57
	s_nop 0
	global_load_lds_dwordx4 v[226:227], off
	s_waitcnt vmcnt(8)
	s_waitcnt lgkmcnt(0)
	s_nop 0
	s_barrier
	s_setprio 1
	s_waitcnt lgkmcnt(0)
	v_mfma_f32_16x16x32_bf16 v[124:127], v[128:131], v[186:189], v[124:127]
	v_mfma_f32_16x16x32_bf16 v[120:123], v[136:139], v[186:189], v[120:123]
	v_mfma_f32_16x16x32_bf16 v[108:111], v[128:131], v[194:197], v[108:111]
	v_mfma_f32_16x16x32_bf16 v[104:107], v[136:139], v[194:197], v[104:107]
	v_mfma_f32_16x16x32_bf16 v[92:95], v[128:131], v[202:205], v[92:95]
	v_mfma_f32_16x16x32_bf16 v[88:91], v[136:139], v[202:205], v[88:91]
	v_mfma_f32_16x16x32_bf16 v[76:79], v[128:131], v[210:213], v[76:79]
	v_mfma_f32_16x16x32_bf16 v[72:75], v[136:139], v[210:213], v[72:75]
	v_mfma_f32_16x16x32_bf16 v[124:127], v[132:135], v[190:193], v[124:127]
	v_mfma_f32_16x16x32_bf16 v[120:123], v[140:143], v[190:193], v[120:123]
	v_mfma_f32_16x16x32_bf16 v[108:111], v[132:135], v[198:201], v[108:111]
	v_mfma_f32_16x16x32_bf16 v[104:107], v[140:143], v[198:201], v[104:107]
	v_mfma_f32_16x16x32_bf16 v[92:95], v[132:135], v[206:209], v[92:95]
	v_mfma_f32_16x16x32_bf16 v[88:91], v[140:143], v[206:209], v[88:91]
	v_mfma_f32_16x16x32_bf16 v[76:79], v[132:135], v[214:217], v[76:79]
	v_mfma_f32_16x16x32_bf16 v[72:75], v[140:143], v[214:217], v[72:75]
	s_setprio 0
	s_setprio 1
	v_mfma_f32_16x16x32_bf16 v[116:119], v[160:163], v[186:189], v[116:119]
	v_mfma_f32_16x16x32_bf16 v[112:115], v[178:181], v[186:189], v[112:115]
	v_mfma_f32_16x16x32_bf16 v[100:103], v[160:163], v[194:197], v[100:103]
	v_mfma_f32_16x16x32_bf16 v[96:99], v[178:181], v[194:197], v[96:99]
	v_mfma_f32_16x16x32_bf16 v[84:87], v[160:163], v[202:205], v[84:87]
	v_mfma_f32_16x16x32_bf16 v[80:83], v[178:181], v[202:205], v[80:83]
	v_mfma_f32_16x16x32_bf16 v[68:71], v[160:163], v[210:213], v[68:71]
	v_mfma_f32_16x16x32_bf16 v[64:67], v[178:181], v[210:213], v[64:67]
	v_mfma_f32_16x16x32_bf16 v[116:119], v[164:167], v[190:193], v[116:119]
	v_mfma_f32_16x16x32_bf16 v[112:115], v[182:185], v[190:193], v[112:115]
	v_mfma_f32_16x16x32_bf16 v[100:103], v[164:167], v[198:201], v[100:103]
	v_mfma_f32_16x16x32_bf16 v[96:99], v[182:185], v[198:201], v[96:99]
	v_mfma_f32_16x16x32_bf16 v[84:87], v[164:167], v[206:209], v[84:87]
	v_mfma_f32_16x16x32_bf16 v[80:83], v[182:185], v[206:209], v[80:83]
	v_mfma_f32_16x16x32_bf16 v[68:71], v[164:167], v[214:217], v[68:71]
	v_mfma_f32_16x16x32_bf16 v[64:67], v[182:185], v[214:217], v[64:67]
	s_setprio 0
	s_barrier
; #define PG8_STAGE(bufoff, gbase, voff) do { _Pragma("unroll") for (int _i = 0; _i < 2; ++_i) \
;         __builtin_amdgcn_global_load_lds((const unsigned*)((const char*)(gbase) + (voff)[_i]), (LAS unsigned*)(lds + (bufoff) + ldsw + _i * 8192), 16, 0, 0); } while (0)
; #define PG8_LDA(dst, b, h) do { _Pragma("unroll") for (int m = 0; m < 4; ++m) _Pragma("unroll") for (int k = 0; k < 2; ++k) dst[m][k] = *(const LAS bf16x8*)(lds + PG8_SA(b, h) + aoff + m * 2048 + k * 1024); } while (0)
; #define PG8_MMA(ai, bj, At, Bt) do { __builtin_amdgcn_s_setprio(1); _Pragma("unroll") for (int m = 0; m < 4; ++m) _Pragma("unroll") for (int n = 0; n < 2; ++n) _Pragma("unroll") for (int k = 0; k < 2; ++k) \
;         acc[ai][bj][m][n] = __builtin_amdgcn_mfma_f32_16x16x32_bf16(Bt[n][k], At[m][k], acc[ai][bj][m][n], 0, 0, 0); __builtin_amdgcn_s_setprio(0); } while (0)
; #define PG8_WAIT_V(n) asm volatile("s_waitcnt vmcnt(" #n ")" ::: "memory")
; #define PG8_WAIT_L(n) asm volatile("s_waitcnt lgkmcnt(" #n ")" ::: "memory")
; #define PG8_BAR __builtin_amdgcn_s_barrier()
; #define PG8_SCHED __builtin_amdgcn_sched_barrier(0)
; template <class Epi>
; __device__ __forceinline__ void gemm_phase(LAS unsigned char* lds, const Gemm g, const StaticOrder& S, const Epi& E) {
;     ...
;             PG8_LDA(At, 1, 1); PG8_STAGE(PG8_SB(1, 0), b3, voffB); PG8_STAGE(PG8_SB(1, 1), b3 + hstepB, voffB); PG8_STAGE(PG8_SA(1, 0), a3, voffA);
;             PG8_WAIT_V(8); PG8_WAIT_L(0); PG8_BAR; PG8_MMA(1, 0, At, B0); PG8_MMA(1, 1, At, B1); PG8_BAR; PG8_SCHED;
;         }
;         if (wr == 0) PG8_BAR;
	s_add_i32 s52, s78, s54
	v_lshl_add_u64 v[168:169], v[168:169], 0, s[12:13]
	s_mov_b32 m0, s52
	ds_read_b128 v[186:189], v175 offset:49152
	ds_read_b128 v[190:193], v175 offset:50176
	ds_read_b128 v[194:197], v175 offset:51200
	ds_read_b128 v[198:201], v175 offset:52224
	ds_read_b128 v[202:205], v175 offset:53248
	ds_read_b128 v[206:209], v175 offset:54272
	ds_read_b128 v[210:213], v175 offset:55296
	ds_read_b128 v[214:217], v175 offset:56320
	global_load_lds_dwordx4 v[168:169], off
	s_add_i32 m0, s52, 0x2000
	s_add_u32 s42, s42, 0x40080
	v_lshl_add_u64 v[168:169], v[218:219], 0, s[12:13]
	s_addc_u32 s43, s43, 0
	s_add_i32 s52, s79, s54
	global_load_lds_dwordx4 v[168:169], off
	v_lshl_add_u64 v[168:169], s[42:43], 0, v[146:147]
	s_mov_b32 m0, s52
	s_nop 0
	global_load_lds_dwordx4 v[168:169], off
	v_lshl_add_u64 v[168:169], s[42:43], 0, v[150:151]
	s_add_i32 m0, s52, 0x2000
	s_nop 0
	global_load_lds_dwordx4 v[168:169], off
	v_lshl_add_u64 v[168:169], v[220:221], 0, s[12:13]
	s_mov_b32 m0, s65
	s_nop 0
	global_load_lds_dwordx4 v[168:169], off
	v_lshl_add_u64 v[168:169], v[222:223], 0, s[12:13]
	s_mov_b32 m0, s68
	s_nop 0
	global_load_lds_dwordx4 v[168:169], off
	s_waitcnt vmcnt(8)
	s_waitcnt lgkmcnt(0)
	s_barrier
	s_setprio 1
	s_waitcnt lgkmcnt(0)
	v_mfma_f32_16x16x32_bf16 v[60:63], v[128:131], v[186:189], v[60:63]
	v_mfma_f32_16x16x32_bf16 v[56:59], v[136:139], v[186:189], v[56:59]
	v_mfma_f32_16x16x32_bf16 v[44:47], v[128:131], v[194:197], v[44:47]
	v_mfma_f32_16x16x32_bf16 v[40:43], v[136:139], v[194:197], v[40:43]
	v_mfma_f32_16x16x32_bf16 v[28:31], v[128:131], v[202:205], v[28:31]
	v_mfma_f32_16x16x32_bf16 v[24:27], v[136:139], v[202:205], v[24:27]
	v_mfma_f32_16x16x32_bf16 v[12:15], v[128:131], v[210:213], v[12:15]
	v_mfma_f32_16x16x32_bf16 v[8:11], v[136:139], v[210:213], v[8:11]
	v_mfma_f32_16x16x32_bf16 v[60:63], v[132:135], v[190:193], v[60:63]
	v_mfma_f32_16x16x32_bf16 v[56:59], v[140:143], v[190:193], v[56:59]
	v_mfma_f32_16x16x32_bf16 v[44:47], v[132:135], v[198:201], v[44:47]
	v_mfma_f32_16x16x32_bf16 v[40:43], v[140:143], v[198:201], v[40:43]
	v_mfma_f32_16x16x32_bf16 v[28:31], v[132:135], v[206:209], v[28:31]
	v_mfma_f32_16x16x32_bf16 v[24:27], v[140:143], v[206:209], v[24:27]
	v_mfma_f32_16x16x32_bf16 v[12:15], v[132:135], v[214:217], v[12:15]
	v_mfma_f32_16x16x32_bf16 v[8:11], v[140:143], v[214:217], v[8:11]
	s_setprio 0
	s_setprio 1
	v_mfma_f32_16x16x32_bf16 v[52:55], v[160:163], v[186:189], v[52:55]
	v_mfma_f32_16x16x32_bf16 v[48:51], v[178:181], v[186:189], v[48:51]
	v_mfma_f32_16x16x32_bf16 v[36:39], v[160:163], v[194:197], v[36:39]
	v_mfma_f32_16x16x32_bf16 v[32:35], v[178:181], v[194:197], v[32:35]
	v_mfma_f32_16x16x32_bf16 v[20:23], v[160:163], v[202:205], v[20:23]
	v_mfma_f32_16x16x32_bf16 v[16:19], v[178:181], v[202:205], v[16:19]
	v_mfma_f32_16x16x32_bf16 v[4:7], v[160:163], v[210:213], v[4:7]
	v_mfma_f32_16x16x32_bf16 v[0:3], v[178:181], v[210:213], v[0:3]
	v_mfma_f32_16x16x32_bf16 v[52:55], v[164:167], v[190:193], v[52:55]
	v_mfma_f32_16x16x32_bf16 v[48:51], v[182:185], v[190:193], v[48:51]
	v_mfma_f32_16x16x32_bf16 v[36:39], v[164:167], v[198:201], v[36:39]
	v_mfma_f32_16x16x32_bf16 v[32:35], v[182:185], v[198:201], v[32:35]
	v_mfma_f32_16x16x32_bf16 v[20:23], v[164:167], v[206:209], v[20:23]
	v_mfma_f32_16x16x32_bf16 v[16:19], v[182:185], v[206:209], v[16:19]
	v_mfma_f32_16x16x32_bf16 v[4:7], v[164:167], v[214:217], v[4:7]
	v_mfma_f32_16x16x32_bf16 v[0:3], v[182:185], v[214:217], v[0:3]
	s_setprio 0
	s_barrier
	s_add_i32 s77, s77, 2
	s_add_u32 s38, s38, 0x100
	s_addc_u32 s39, s39, 0
	s_add_u32 s75, s75, 0x100
	s_addc_u32 s76, s76, 0
	s_cmp_gt_u32 s77, 13
	s_cbranch_scc0 .LBB0_457
	s_and_b64 vcc, exec, s[14:15]
	s_cbranch_vccz .LBB0_460
	s_barrier

; #define PG8_STAGE(bufoff, gbase, voff) do { _Pragma("unroll") for (int _i = 0; _i < 2; ++_i) \
;         __builtin_amdgcn_global_load_lds((const unsigned*)((const char*)(gbase) + (voff)[_i]), (LAS unsigned*)(lds + (bufoff) + ldsw + _i * 8192), 16, 0, 0); } while (0)
; #define PG8_LDA(dst, b, h) do { _Pragma("unroll") for (int m = 0; m < 4; ++m) _Pragma("unroll") for (int k = 0; k < 2; ++k) dst[m][k] = *(const LAS bf16x8*)(lds + PG8_SA(b, h) + aoff + m * 2048 + k * 1024); } while (0)
; #define PG8_LDB(dst, b, h) do { _Pragma("unroll") for (int n = 0; n < 2; ++n) _Pragma("unroll") for (int k = 0; k < 2; ++k) dst[n][k] = *(const LAS bf16x8*)(lds + PG8_SB(b, h) + boff + n * 2048 + k * 1024); } while (0)
; #define PG8_MMA(ai, bj, At, Bt) do { __builtin_amdgcn_s_setprio(1); _Pragma("unroll") for (int m = 0; m < 4; ++m) _Pragma("unroll") for (int n = 0; n < 2; ++n) _Pragma("unroll") for (int k = 0; k < 2; ++k) \
;         acc[ai][bj][m][n] = __builtin_amdgcn_mfma_f32_16x16x32_bf16(Bt[n][k], At[m][k], acc[ai][bj][m][n], 0, 0, 0); __builtin_amdgcn_s_setprio(0); } while (0)
; #define PG8_BAR __builtin_amdgcn_s_barrier()
; template <class Epi>
; __device__ __forceinline__ void gemm_phase(LAS unsigned char* lds, const Gemm g, const StaticOrder& S, const Epi& E) {
;     ...
;         const bool has_next = S.next(ui + 1, nxt);
;         const char* nA = has_next ? (const char*)g.A + (size_t)nxt.pm * tstepA : cA; const char* nB = has_next ? (const char*)g.Bt + (size_t)nxt.pn * tstepB : cB;
; #pragma nounroll
;         for (int t = 0; t < nt; t += 2) {
;             const bool last = (t == nt - 2);
;             const char* a1 = cA + (size_t)(t + 1) * kstep;
;             const char* a2 = last ? nA : cA + (size_t)(t + 2) * kstep; const char* b2 = last ? nB : cB + (size_t)(t + 2) * kstep;
;             const char* a3 = a2 + kstep; const char* b3 = b2 + kstep;
;             PG8_LDB(B0, 0, 0); PG8_LDB(B1, 0, 1); PG8_SCHED; PG8_LDA(At, 0, 0); PG8_STAGE(PG8_SA(1, 1), a1 + hstepA, voffA);
;             PG8_WAIT_V(8); PG8_WAIT_L(0); PG8_BAR; PG8_MMA(0, 0, At, B0); PG8_MMA(0, 1, At, B1); PG8_BAR; PG8_SCHED;
;             PG8_LDA(At, 0, 1); PG8_STAGE(PG8_SB(0, 0), b2, voffB); PG8_STAGE(PG8_SB(0, 1), b2 + hstepB, voffB); PG8_STAGE(PG8_SA(0, 0), a2, voffA);
;             PG8_WAIT_V(8); PG8_WAIT_L(0); PG8_BAR; PG8_MMA(1, 0, At, B0); PG8_MMA(1, 1, At, B1); PG8_BAR; PG8_SCHED;
.LBB0_545:
	s_ashr_i32 s71, s70, 31
	s_lshl_b64 s[12:13], s[70:71], 19
	s_add_u32 s72, s24, s12
	s_addc_u32 s73, s25, s13
	s_and_b64 s[12:13], s[4:5], exec
	s_cselect_b32 s1, s73, s9
	s_cselect_b32 s7, s72, s8
	s_ashr_i32 s69, s68, 31
	s_lshl_b64 s[12:13], s[68:69], 19
	s_add_u32 s74, s3, s12
	s_addc_u32 s75, s33, s13
	s_and_b64 s[12:13], s[4:5], exec
	s_cselect_b32 s69, s75, s11
	s_cselect_b32 s71, s74, s10
	s_add_u32 s8, s8, 0x40080
	s_addc_u32 s9, s9, 0
	s_add_u32 s76, s10, 0x100
	s_addc_u32 s77, s11, 0
	s_mov_b32 s89, -2
	s_nop 0
	v_lshl_add_u32 v248, s6, 8, v151
	v_add_u32_e32 v248, s65, v248
	v_ashrrev_i32_e32 v249, 31, v248
	v_lshl_add_u64 v[248:249], v[248:249], 2, s[22:23]
	global_load_dword v240, v[248:249], off
	global_load_dword v241, v[248:249], off offset:64
	global_load_dword v242, v[248:249], off offset:128
	global_load_dword v243, v[248:249], off offset:192
	global_load_dword v244, v[248:249], off offset:512
	global_load_dword v245, v[248:249], off offset:576
	global_load_dword v246, v[248:249], off offset:640
	global_load_dword v247, v[248:249], off offset:704
	ds_read_b128 v[146:149], v162
	ds_read_b128 v[166:169], v162 offset:1024
	ds_read_b128 v[170:173], v162 offset:2048
	ds_read_b128 v[178:181], v162 offset:3072
	ds_read_b128 v[182:185], v163
	ds_read_b128 v[186:189], v163 offset:1024
	ds_read_b128 v[190:193], v163 offset:2048
	ds_read_b128 v[194:197], v163 offset:3072
	s_add_u32 s10, s8, 0xfffc0080
	s_addc_u32 s11, s9, -1
	s_cmp_eq_u32 s89, 12
	s_cselect_b32 s13, s1, s11
	s_cselect_b32 s12, s7, s10
	s_cselect_b32 s11, s69, s77
	s_cselect_b32 s10, s71, s76
	v_lshl_add_u64 v[174:175], s[8:9], 0, v[138:139]
	s_add_i32 m0, s43, 0xc000
	ds_read_b128 v[198:201], v164
	ds_read_b128 v[202:205], v164 offset:1024
	ds_read_b128 v[206:209], v164 offset:2048
	ds_read_b128 v[210:213], v164 offset:3072
	ds_read_b128 v[214:217], v164 offset:4096
	ds_read_b128 v[218:221], v164 offset:5120
	ds_read_b128 v[226:229], v164 offset:6144
	ds_read_b128 v[230:233], v164 offset:7168
	global_load_lds_dwordx4 v[174:175], off
	v_lshl_add_u64 v[174:175], s[8:9], 0, v[140:141]
	s_add_i32 m0, s43, 0xe000
	s_nop 0
	global_load_lds_dwordx4 v[174:175], off
	s_waitcnt vmcnt(8)
	s_waitcnt lgkmcnt(0)
	s_barrier
	s_setprio 1
	s_waitcnt lgkmcnt(0)
	v_mfma_f32_16x16x32_bf16 v[124:127], v[146:149], v[198:201], 0
	v_mfma_f32_16x16x32_bf16 v[120:123], v[170:173], v[198:201], 0
	v_mfma_f32_16x16x32_bf16 v[112:115], v[146:149], v[206:209], 0
	v_mfma_f32_16x16x32_bf16 v[104:107], v[170:173], v[206:209], 0
	v_mfma_f32_16x16x32_bf16 v[100:103], v[146:149], v[214:217], 0
	v_mfma_f32_16x16x32_bf16 v[92:95], v[170:173], v[214:217], 0
	v_mfma_f32_16x16x32_bf16 v[84:87], v[146:149], v[226:229], 0
	v_mfma_f32_16x16x32_bf16 v[76:79], v[170:173], v[226:229], 0
	v_mfma_f32_16x16x32_bf16 v[124:127], v[166:169], v[202:205], v[124:127]
	v_mfma_f32_16x16x32_bf16 v[120:123], v[178:181], v[202:205], v[120:123]
	v_mfma_f32_16x16x32_bf16 v[112:115], v[166:169], v[210:213], v[112:115]
	v_mfma_f32_16x16x32_bf16 v[104:107], v[178:181], v[210:213], v[104:107]
	v_mfma_f32_16x16x32_bf16 v[100:103], v[166:169], v[218:221], v[100:103]
	v_mfma_f32_16x16x32_bf16 v[92:95], v[178:181], v[218:221], v[92:95]
	v_mfma_f32_16x16x32_bf16 v[84:87], v[166:169], v[230:233], v[84:87]
	v_mfma_f32_16x16x32_bf16 v[76:79], v[178:181], v[230:233], v[76:79]
	s_setprio 0
	s_setprio 1
	v_mfma_f32_16x16x32_bf16 v[116:119], v[182:185], v[198:201], 0
	v_mfma_f32_16x16x32_bf16 v[108:111], v[190:193], v[198:201], 0
	v_mfma_f32_16x16x32_bf16 v[96:99], v[182:185], v[206:209], 0
	v_mfma_f32_16x16x32_bf16 v[88:91], v[190:193], v[206:209], 0
	v_mfma_f32_16x16x32_bf16 v[80:83], v[182:185], v[214:217], 0
	v_mfma_f32_16x16x32_bf16 v[72:75], v[190:193], v[214:217], 0
	v_mfma_f32_16x16x32_bf16 v[68:71], v[182:185], v[226:229], 0
	v_mfma_f32_16x16x32_bf16 v[64:67], v[190:193], v[226:229], 0
	v_mfma_f32_16x16x32_bf16 v[116:119], v[186:189], v[202:205], v[116:119]
	v_mfma_f32_16x16x32_bf16 v[108:111], v[194:197], v[202:205], v[108:111]
	v_mfma_f32_16x16x32_bf16 v[96:99], v[186:189], v[210:213], v[96:99]
	v_mfma_f32_16x16x32_bf16 v[88:91], v[194:197], v[210:213], v[88:91]
	v_mfma_f32_16x16x32_bf16 v[80:83], v[186:189], v[218:221], v[80:83]
	v_mfma_f32_16x16x32_bf16 v[72:75], v[194:197], v[218:221], v[72:75]
	v_mfma_f32_16x16x32_bf16 v[68:71], v[186:189], v[230:233], v[68:71]
	v_mfma_f32_16x16x32_bf16 v[64:67], v[194:197], v[230:233], v[64:67]
	s_setprio 0
	s_barrier
	s_add_i32 s90, s85, s39
	v_lshl_add_u64 v[174:175], s[10:11], 0, v[130:131]
	s_mov_b32 m0, s90
	ds_read_b128 v[198:201], v164 offset:16384
	ds_read_b128 v[202:205], v164 offset:17408
	ds_read_b128 v[206:209], v164 offset:18432
	ds_read_b128 v[210:213], v164 offset:19456
	ds_read_b128 v[214:217], v164 offset:20480
	ds_read_b128 v[218:221], v164 offset:21504
	ds_read_b128 v[226:229], v164 offset:22528
	ds_read_b128 v[230:233], v164 offset:23552
	global_load_lds_dwordx4 v[174:175], off
	s_add_i32 m0, s90, 0x2000
	s_add_u32 s90, s10, 0x40000
	v_lshl_add_u64 v[222:223], s[10:11], 0, v[134:135]
	s_addc_u32 s91, s11, 0
	s_add_i32 s92, s86, s39
	global_load_lds_dwordx4 v[222:223], off
	v_lshl_add_u64 v[234:235], s[90:91], 0, v[130:131]
	s_mov_b32 m0, s92
	v_lshl_add_u64 v[236:237], s[12:13], 0, v[132:133]
	global_load_lds_dwordx4 v[234:235], off
	v_lshl_add_u64 v[234:235], s[90:91], 0, v[134:135]
	s_add_i32 m0, s92, 0x2000
	s_nop 0
	global_load_lds_dwordx4 v[234:235], off
	v_lshl_add_u64 v[234:235], s[12:13], 0, v[128:129]
	s_mov_b32 m0, s43
	s_nop 0
	global_load_lds_dwordx4 v[234:235], off
	s_mov_b32 m0, s53
	s_nop 0
	global_load_lds_dwordx4 v[236:237], off
	s_waitcnt vmcnt(8)
	s_waitcnt lgkmcnt(0)
	s_nop 0
	s_barrier
; #define PG8_STAGE(bufoff, gbase, voff) do { _Pragma("unroll") for (int _i = 0; _i < 2; ++_i) \
;         __builtin_amdgcn_global_load_lds((const unsigned*)((const char*)(gbase) + (voff)[_i]), (LAS unsigned*)(lds + (bufoff) + ldsw + _i * 8192), 16, 0, 0); } while (0)
; #define PG8_LDA(dst, b, h) do { _Pragma("unroll") for (int m = 0; m < 4; ++m) _Pragma("unroll") for (int k = 0; k < 2; ++k) dst[m][k] = *(const LAS bf16x8*)(lds + PG8_SA(b, h) + aoff + m * 2048 + k * 1024); } while (0)
; #define PG8_LDB(dst, b, h) do { _Pragma("unroll") for (int n = 0; n < 2; ++n) _Pragma("unroll") for (int k = 0; k < 2; ++k) dst[n][k] = *(const LAS bf16x8*)(lds + PG8_SB(b, h) + boff + n * 2048 + k * 1024); } while (0)
; #define PG8_MMA(ai, bj, At, Bt) do { __builtin_amdgcn_s_setprio(1); _Pragma("unroll") for (int m = 0; m < 4; ++m) _Pragma("unroll") for (int n = 0; n < 2; ++n) _Pragma("unroll") for (int k = 0; k < 2; ++k) \
;         acc[ai][bj][m][n] = __builtin_amdgcn_mfma_f32_16x16x32_bf16(Bt[n][k], At[m][k], acc[ai][bj][m][n], 0, 0, 0); __builtin_amdgcn_s_setprio(0); } while (0)
; #define PG8_WAIT_V(n) asm volatile("s_waitcnt vmcnt(" #n ")" ::: "memory")
; #define PG8_WAIT_L(n) asm volatile("s_waitcnt lgkmcnt(" #n ")" ::: "memory")
; #define PG8_BAR __builtin_amdgcn_s_barrier()
; #define PG8_SCHED __builtin_amdgcn_sched_barrier(0)
; template <class Epi>
; __device__ __forceinline__ void gemm_phase(LAS unsigned char* lds, const Gemm g, const StaticOrder& S, const Epi& E) {
;     ...
;             PG8_WAIT_V(8); PG8_WAIT_L(0); PG8_BAR; PG8_MMA(1, 0, At, B0); PG8_MMA(1, 1, At, B1); PG8_BAR; PG8_SCHED;
;             PG8_LDB(B0, 1, 0); PG8_LDB(B1, 1, 1); PG8_SCHED; PG8_LDA(At, 1, 0); PG8_STAGE(PG8_SA(0, 1), a2 + hstepA, voffA);
;             PG8_WAIT_V(8); PG8_WAIT_L(0); PG8_BAR; PG8_MMA(0, 0, At, B0); PG8_MMA(0, 1, At, B1); PG8_BAR; PG8_SCHED;
;             PG8_LDA(At, 1, 1); PG8_STAGE(PG8_SB(1, 0), b3, voffB); PG8_STAGE(PG8_SB(1, 1), b3 + hstepB, voffB); PG8_STAGE(PG8_SA(1, 0), a3, voffA);
;             PG8_WAIT_V(8); PG8_WAIT_L(0); PG8_BAR; PG8_MMA(1, 0, At, B0); PG8_MMA(1, 1, At, B1); PG8_BAR; PG8_SCHED;
	s_setprio 1
	s_waitcnt lgkmcnt(0)
	v_mfma_f32_16x16x32_bf16 v[60:63], v[146:149], v[198:201], 0
	v_mfma_f32_16x16x32_bf16 v[56:59], v[170:173], v[198:201], 0
	v_mfma_f32_16x16x32_bf16 v[52:55], v[146:149], v[206:209], 0
	v_mfma_f32_16x16x32_bf16 v[44:47], v[170:173], v[206:209], 0
	v_mfma_f32_16x16x32_bf16 v[36:39], v[146:149], v[214:217], 0
	v_mfma_f32_16x16x32_bf16 v[28:31], v[170:173], v[214:217], 0
	v_mfma_f32_16x16x32_bf16 v[20:23], v[146:149], v[226:229], 0
	v_mfma_f32_16x16x32_bf16 v[12:15], v[170:173], v[226:229], 0
	v_mfma_f32_16x16x32_bf16 v[60:63], v[166:169], v[202:205], v[60:63]
	v_mfma_f32_16x16x32_bf16 v[56:59], v[178:181], v[202:205], v[56:59]
	v_mfma_f32_16x16x32_bf16 v[52:55], v[166:169], v[210:213], v[52:55]
	v_mfma_f32_16x16x32_bf16 v[44:47], v[178:181], v[210:213], v[44:47]
	v_mfma_f32_16x16x32_bf16 v[36:39], v[166:169], v[218:221], v[36:39]
	v_mfma_f32_16x16x32_bf16 v[28:31], v[178:181], v[218:221], v[28:31]
	v_mfma_f32_16x16x32_bf16 v[20:23], v[166:169], v[230:233], v[20:23]
	v_mfma_f32_16x16x32_bf16 v[12:15], v[178:181], v[230:233], v[12:15]
	s_setprio 0
	s_setprio 1
	v_mfma_f32_16x16x32_bf16 v[48:51], v[182:185], v[198:201], 0
	v_mfma_f32_16x16x32_bf16 v[40:43], v[190:193], v[198:201], 0
	v_mfma_f32_16x16x32_bf16 v[32:35], v[182:185], v[206:209], 0
	v_mfma_f32_16x16x32_bf16 v[24:27], v[190:193], v[206:209], 0
	v_mfma_f32_16x16x32_bf16 v[16:19], v[182:185], v[214:217], 0
	v_mfma_f32_16x16x32_bf16 v[8:11], v[190:193], v[214:217], 0
	v_mfma_f32_16x16x32_bf16 v[4:7], v[182:185], v[226:229], 0
	v_mfma_f32_16x16x32_bf16 v[0:3], v[190:193], v[226:229], 0
	v_mfma_f32_16x16x32_bf16 v[48:51], v[186:189], v[202:205], v[48:51]
	v_mfma_f32_16x16x32_bf16 v[40:43], v[194:197], v[202:205], v[40:43]
	v_mfma_f32_16x16x32_bf16 v[32:35], v[186:189], v[210:213], v[32:35]
	v_mfma_f32_16x16x32_bf16 v[24:27], v[194:197], v[210:213], v[24:27]
	v_mfma_f32_16x16x32_bf16 v[16:19], v[186:189], v[218:221], v[16:19]
	v_mfma_f32_16x16x32_bf16 v[8:11], v[194:197], v[218:221], v[8:11]
	v_mfma_f32_16x16x32_bf16 v[4:7], v[186:189], v[230:233], v[4:7]
	v_mfma_f32_16x16x32_bf16 v[0:3], v[194:197], v[230:233], v[0:3]
	s_setprio 0
	s_barrier
	s_add_i32 s90, 0, 0x18000
	v_add_u32_e32 v136, s90, v161
	s_add_i32 s91, 0, 0x1c000
	ds_read_b128 v[146:149], v136
	ds_read_b128 v[166:169], v136 offset:1024
	ds_read_b128 v[170:173], v136 offset:2048
	ds_read_b128 v[178:181], v136 offset:3072
	v_add_u32_e32 v136, s91, v161
	ds_read_b128 v[182:185], v136
	ds_read_b128 v[186:189], v136 offset:1024
	ds_read_b128 v[190:193], v136 offset:2048
	ds_read_b128 v[194:197], v136 offset:3072
	s_add_u32 s12, s12, 0x40000
	s_addc_u32 s13, s13, 0
	s_mov_b32 m0, s55
	v_lshl_add_u64 v[238:239], s[12:13], 0, v[128:129]
	ds_read_b128 v[198:201], v164 offset:32768
	ds_read_b128 v[202:205], v164 offset:33792
	ds_read_b128 v[206:209], v164 offset:34816
	ds_read_b128 v[210:213], v164 offset:35840
	ds_read_b128 v[214:217], v164 offset:36864
	ds_read_b128 v[218:221], v164 offset:37888
	ds_read_b128 v[226:229], v164 offset:38912
	ds_read_b128 v[230:233], v164 offset:39936
	global_load_lds_dwordx4 v[238:239], off
	v_lshl_add_u64 v[238:239], s[12:13], 0, v[132:133]
	s_mov_b32 m0, s57
	s_nop 0
	global_load_lds_dwordx4 v[238:239], off
	s_waitcnt vmcnt(8)
	s_waitcnt lgkmcnt(0)
	s_nop 0
	s_barrier
	s_setprio 1
	s_waitcnt lgkmcnt(0)
	v_mfma_f32_16x16x32_bf16 v[124:127], v[146:149], v[198:201], v[124:127]
	v_mfma_f32_16x16x32_bf16 v[120:123], v[170:173], v[198:201], v[120:123]
	v_mfma_f32_16x16x32_bf16 v[112:115], v[146:149], v[206:209], v[112:115]
	v_mfma_f32_16x16x32_bf16 v[104:107], v[170:173], v[206:209], v[104:107]
	v_mfma_f32_16x16x32_bf16 v[100:103], v[146:149], v[214:217], v[100:103]
	v_mfma_f32_16x16x32_bf16 v[92:95], v[170:173], v[214:217], v[92:95]
	v_mfma_f32_16x16x32_bf16 v[84:87], v[146:149], v[226:229], v[84:87]
	v_mfma_f32_16x16x32_bf16 v[76:79], v[170:173], v[226:229], v[76:79]
	v_mfma_f32_16x16x32_bf16 v[124:127], v[166:169], v[202:205], v[124:127]
	v_mfma_f32_16x16x32_bf16 v[120:123], v[178:181], v[202:205], v[120:123]
	v_mfma_f32_16x16x32_bf16 v[112:115], v[166:169], v[210:213], v[112:115]
	v_mfma_f32_16x16x32_bf16 v[104:107], v[178:181], v[210:213], v[104:107]
	v_mfma_f32_16x16x32_bf16 v[100:103], v[166:169], v[218:221], v[100:103]
	v_mfma_f32_16x16x32_bf16 v[92:95], v[178:181], v[218:221], v[92:95]
	v_mfma_f32_16x16x32_bf16 v[84:87], v[166:169], v[230:233], v[84:87]
	v_mfma_f32_16x16x32_bf16 v[76:79], v[178:181], v[230:233], v[76:79]
	s_setprio 0
	s_setprio 1
	v_mfma_f32_16x16x32_bf16 v[116:119], v[182:185], v[198:201], v[116:119]
	v_mfma_f32_16x16x32_bf16 v[108:111], v[190:193], v[198:201], v[108:111]
	v_mfma_f32_16x16x32_bf16 v[96:99], v[182:185], v[206:209], v[96:99]
	v_mfma_f32_16x16x32_bf16 v[88:91], v[190:193], v[206:209], v[88:91]
	v_mfma_f32_16x16x32_bf16 v[80:83], v[182:185], v[214:217], v[80:83]
	v_mfma_f32_16x16x32_bf16 v[72:75], v[190:193], v[214:217], v[72:75]
	v_mfma_f32_16x16x32_bf16 v[68:71], v[182:185], v[226:229], v[68:71]
	v_mfma_f32_16x16x32_bf16 v[64:67], v[190:193], v[226:229], v[64:67]
	v_mfma_f32_16x16x32_bf16 v[116:119], v[186:189], v[202:205], v[116:119]
	v_mfma_f32_16x16x32_bf16 v[108:111], v[194:197], v[202:205], v[108:111]
	v_mfma_f32_16x16x32_bf16 v[96:99], v[186:189], v[210:213], v[96:99]
	v_mfma_f32_16x16x32_bf16 v[88:91], v[194:197], v[210:213], v[88:91]
	v_mfma_f32_16x16x32_bf16 v[80:83], v[186:189], v[218:221], v[80:83]
	v_mfma_f32_16x16x32_bf16 v[72:75], v[194:197], v[218:221], v[72:75]
	v_mfma_f32_16x16x32_bf16 v[68:71], v[186:189], v[230:233], v[68:71]
	v_mfma_f32_16x16x32_bf16 v[64:67], v[194:197], v[230:233], v[64:67]
	s_setprio 0
	s_barrier
; #define PG8_STAGE(bufoff, gbase, voff) do { _Pragma("unroll") for (int _i = 0; _i < 2; ++_i) \
;         __builtin_amdgcn_global_load_lds((const unsigned*)((const char*)(gbase) + (voff)[_i]), (LAS unsigned*)(lds + (bufoff) + ldsw + _i * 8192), 16, 0, 0); } while (0)
; #define PG8_LDA(dst, b, h) do { _Pragma("unroll") for (int m = 0; m < 4; ++m) _Pragma("unroll") for (int k = 0; k < 2; ++k) dst[m][k] = *(const LAS bf16x8*)(lds + PG8_SA(b, h) + aoff + m * 2048 + k * 1024); } while (0)
; #define PG8_LDB(dst, b, h) do { _Pragma("unroll") for (int n = 0; n < 2; ++n) _Pragma("unroll") for (int k = 0; k < 2; ++k) dst[n][k] = *(const LAS bf16x8*)(lds + PG8_SB(b, h) + boff + n * 2048 + k * 1024); } while (0)
; #define PG8_MMA(ai, bj, At, Bt) do { __builtin_amdgcn_s_setprio(1); _Pragma("unroll") for (int m = 0; m < 4; ++m) _Pragma("unroll") for (int n = 0; n < 2; ++n) _Pragma("unroll") for (int k = 0; k < 2; ++k) \
;         acc[ai][bj][m][n] = __builtin_amdgcn_mfma_f32_16x16x32_bf16(Bt[n][k], At[m][k], acc[ai][bj][m][n], 0, 0, 0); __builtin_amdgcn_s_setprio(0); } while (0)
; #define PG8_WAIT_V(n) asm volatile("s_waitcnt vmcnt(" #n ")" ::: "memory")
; #define PG8_WAIT_L(n) asm volatile("s_waitcnt lgkmcnt(" #n ")" ::: "memory")
; #define PG8_BAR __builtin_amdgcn_s_barrier()
; #define PG8_SCHED __builtin_amdgcn_sched_barrier(0)
; template <class Epi>
; __device__ __forceinline__ void gemm_phase(LAS unsigned char* lds, const Gemm g, const StaticOrder& S, const Epi& E) {
;     ...
;         for (int t = 0; t < nt; t += 2) {
;             const bool last = (t == nt - 2);
;             const char* a1 = cA + (size_t)(t + 1) * kstep;
;             const char* a2 = last ? nA : cA + (size_t)(t + 2) * kstep; const char* b2 = last ? nB : cB + (size_t)(t + 2) * kstep;
;             const char* a3 = a2 + kstep; const char* b3 = b2 + kstep;
;             PG8_LDB(B0, 0, 0); PG8_LDB(B1, 0, 1); PG8_SCHED; PG8_LDA(At, 0, 0); PG8_STAGE(PG8_SA(1, 1), a1 + hstepA, voffA);
;             PG8_WAIT_V(8); PG8_WAIT_L(0); PG8_BAR; PG8_MMA(0, 0, At, B0); PG8_MMA(0, 1, At, B1); PG8_BAR; PG8_SCHED;
;     ...
;             PG8_LDA(At, 1, 1); PG8_STAGE(PG8_SB(1, 0), b3, voffB); PG8_STAGE(PG8_SB(1, 1), b3 + hstepB, voffB); PG8_STAGE(PG8_SA(1, 0), a3, voffA);
;             PG8_WAIT_V(8); PG8_WAIT_L(0); PG8_BAR; PG8_MMA(1, 0, At, B0); PG8_MMA(1, 1, At, B1); PG8_BAR; PG8_SCHED;
	s_add_i32 s12, s90, s39
	v_lshl_add_u64 v[174:175], v[174:175], 0, s[30:31]
	s_mov_b32 m0, s12
	ds_read_b128 v[198:201], v164 offset:49152
	ds_read_b128 v[202:205], v164 offset:50176
	ds_read_b128 v[206:209], v164 offset:51200
	ds_read_b128 v[210:213], v164 offset:52224
	ds_read_b128 v[214:217], v164 offset:53248
	ds_read_b128 v[218:221], v164 offset:54272
	ds_read_b128 v[226:229], v164 offset:55296
	ds_read_b128 v[230:233], v164 offset:56320
	global_load_lds_dwordx4 v[174:175], off
	s_add_i32 m0, s12, 0x2000
	s_add_u32 s10, s10, 0x40080
	v_lshl_add_u64 v[174:175], v[222:223], 0, s[30:31]
	s_addc_u32 s11, s11, 0
	s_add_i32 s12, s91, s39
	global_load_lds_dwordx4 v[174:175], off
	v_lshl_add_u64 v[174:175], s[10:11], 0, v[130:131]
	s_mov_b32 m0, s12
	s_nop 0
	global_load_lds_dwordx4 v[174:175], off
	v_lshl_add_u64 v[174:175], s[10:11], 0, v[134:135]
	s_add_i32 m0, s12, 0x2000
	s_nop 0
	global_load_lds_dwordx4 v[174:175], off
	v_lshl_add_u64 v[174:175], v[234:235], 0, s[30:31]
	s_mov_b32 m0, s79
	s_nop 0
	global_load_lds_dwordx4 v[174:175], off
	v_lshl_add_u64 v[174:175], v[236:237], 0, s[30:31]
	s_mov_b32 m0, s80
	s_nop 0
	global_load_lds_dwordx4 v[174:175], off
	s_waitcnt vmcnt(8)
	s_waitcnt lgkmcnt(0)
	s_barrier
	s_setprio 1
	s_waitcnt lgkmcnt(0)
	v_mfma_f32_16x16x32_bf16 v[60:63], v[146:149], v[198:201], v[60:63]
	v_mfma_f32_16x16x32_bf16 v[56:59], v[170:173], v[198:201], v[56:59]
	v_mfma_f32_16x16x32_bf16 v[52:55], v[146:149], v[206:209], v[52:55]
	v_mfma_f32_16x16x32_bf16 v[44:47], v[170:173], v[206:209], v[44:47]
	v_mfma_f32_16x16x32_bf16 v[36:39], v[146:149], v[214:217], v[36:39]
	v_mfma_f32_16x16x32_bf16 v[28:31], v[170:173], v[214:217], v[28:31]
	v_mfma_f32_16x16x32_bf16 v[20:23], v[146:149], v[226:229], v[20:23]
	v_mfma_f32_16x16x32_bf16 v[12:15], v[170:173], v[226:229], v[12:15]
	v_mfma_f32_16x16x32_bf16 v[60:63], v[166:169], v[202:205], v[60:63]
	v_mfma_f32_16x16x32_bf16 v[56:59], v[178:181], v[202:205], v[56:59]
	v_mfma_f32_16x16x32_bf16 v[52:55], v[166:169], v[210:213], v[52:55]
	v_mfma_f32_16x16x32_bf16 v[44:47], v[178:181], v[210:213], v[44:47]
	v_mfma_f32_16x16x32_bf16 v[36:39], v[166:169], v[218:221], v[36:39]
	v_mfma_f32_16x16x32_bf16 v[28:31], v[178:181], v[218:221], v[28:31]
	v_mfma_f32_16x16x32_bf16 v[20:23], v[166:169], v[230:233], v[20:23]
	v_mfma_f32_16x16x32_bf16 v[12:15], v[178:181], v[230:233], v[12:15]
	s_setprio 0
	s_setprio 1
	v_mfma_f32_16x16x32_bf16 v[48:51], v[182:185], v[198:201], v[48:51]
	v_mfma_f32_16x16x32_bf16 v[40:43], v[190:193], v[198:201], v[40:43]
	v_mfma_f32_16x16x32_bf16 v[32:35], v[182:185], v[206:209], v[32:35]
	v_mfma_f32_16x16x32_bf16 v[24:27], v[190:193], v[206:209], v[24:27]
	v_mfma_f32_16x16x32_bf16 v[16:19], v[182:185], v[214:217], v[16:19]
	v_mfma_f32_16x16x32_bf16 v[8:11], v[190:193], v[214:217], v[8:11]
	v_mfma_f32_16x16x32_bf16 v[4:7], v[182:185], v[226:229], v[4:7]
	v_mfma_f32_16x16x32_bf16 v[0:3], v[190:193], v[226:229], v[0:3]
	v_mfma_f32_16x16x32_bf16 v[48:51], v[186:189], v[202:205], v[48:51]
	v_mfma_f32_16x16x32_bf16 v[40:43], v[194:197], v[202:205], v[40:43]
	v_mfma_f32_16x16x32_bf16 v[32:35], v[186:189], v[210:213], v[32:35]
	v_mfma_f32_16x16x32_bf16 v[24:27], v[194:197], v[210:213], v[24:27]
	v_mfma_f32_16x16x32_bf16 v[16:19], v[186:189], v[218:221], v[16:19]
	v_mfma_f32_16x16x32_bf16 v[8:11], v[194:197], v[218:221], v[8:11]
	v_mfma_f32_16x16x32_bf16 v[4:7], v[186:189], v[230:233], v[4:7]
	v_mfma_f32_16x16x32_bf16 v[0:3], v[194:197], v[230:233], v[0:3]
	s_setprio 0
	s_barrier
	s_add_i32 s89, s89, 2
	s_add_u32 s8, s8, 0x100
	s_addc_u32 s9, s9, 0
	s_add_u32 s76, s76, 0x100
	s_addc_u32 s77, s77, 0
	s_cmp_gt_u32 s89, 13
.LBB0_546:
	ds_read_b128 v[146:149], v162
	ds_read_b128 v[166:169], v162 offset:1024
	ds_read_b128 v[170:173], v162 offset:2048
	ds_read_b128 v[178:181], v162 offset:3072
	ds_read_b128 v[182:185], v163
	ds_read_b128 v[186:189], v163 offset:1024
	ds_read_b128 v[190:193], v163 offset:2048
	ds_read_b128 v[194:197], v163 offset:3072
	s_add_u32 s10, s8, 0xfffc0080
	s_addc_u32 s11, s9, -1
	s_cmp_eq_u32 s89, 12
	s_cselect_b32 s13, s1, s11
	s_cselect_b32 s12, s7, s10
	s_cselect_b32 s11, s69, s77
	s_cselect_b32 s10, s71, s76
	v_lshl_add_u64 v[174:175], s[8:9], 0, v[138:139]
	s_add_i32 m0, s43, 0xc000
	ds_read_b128 v[198:201], v164
	ds_read_b128 v[202:205], v164 offset:1024
	ds_read_b128 v[206:209], v164 offset:2048
	ds_read_b128 v[210:213], v164 offset:3072
	ds_read_b128 v[214:217], v164 offset:4096
	ds_read_b128 v[218:221], v164 offset:5120
	ds_read_b128 v[226:229], v164 offset:6144
	ds_read_b128 v[230:233], v164 offset:7168
	global_load_lds_dwordx4 v[174:175], off
	v_lshl_add_u64 v[174:175], s[8:9], 0, v[140:141]
	s_add_i32 m0, s43, 0xe000
	s_nop 0
	global_load_lds_dwordx4 v[174:175], off
	s_waitcnt vmcnt(8)
	s_waitcnt lgkmcnt(0)
	s_barrier
; #define PG8_STAGE(bufoff, gbase, voff) do { _Pragma("unroll") for (int _i = 0; _i < 2; ++_i) \
;         __builtin_amdgcn_global_load_lds((const unsigned*)((const char*)(gbase) + (voff)[_i]), (LAS unsigned*)(lds + (bufoff) + ldsw + _i * 8192), 16, 0, 0); } while (0)
; #define PG8_LDA(dst, b, h) do { _Pragma("unroll") for (int m = 0; m < 4; ++m) _Pragma("unroll") for (int k = 0; k < 2; ++k) dst[m][k] = *(const LAS bf16x8*)(lds + PG8_SA(b, h) + aoff + m * 2048 + k * 1024); } while (0)
; #define PG8_LDB(dst, b, h) do { _Pragma("unroll") for (int n = 0; n < 2; ++n) _Pragma("unroll") for (int k = 0; k < 2; ++k) dst[n][k] = *(const LAS bf16x8*)(lds + PG8_SB(b, h) + boff + n * 2048 + k * 1024); } while (0)
; #define PG8_MMA(ai, bj, At, Bt) do { __builtin_amdgcn_s_setprio(1); _Pragma("unroll") for (int m = 0; m < 4; ++m) _Pragma("unroll") for (int n = 0; n < 2; ++n) _Pragma("unroll") for (int k = 0; k < 2; ++k) \
;         acc[ai][bj][m][n] = __builtin_amdgcn_mfma_f32_16x16x32_bf16(Bt[n][k], At[m][k], acc[ai][bj][m][n], 0, 0, 0); __builtin_amdgcn_s_setprio(0); } while (0)
; #define PG8_WAIT_V(n) asm volatile("s_waitcnt vmcnt(" #n ")" ::: "memory")
; #define PG8_WAIT_L(n) asm volatile("s_waitcnt lgkmcnt(" #n ")" ::: "memory")
; #define PG8_BAR __builtin_amdgcn_s_barrier()
; #define PG8_SCHED __builtin_amdgcn_sched_barrier(0)
; template <class Epi>
; __device__ __forceinline__ void gemm_phase(LAS unsigned char* lds, const Gemm g, const StaticOrder& S, const Epi& E) {
;     ...
;             PG8_WAIT_V(8); PG8_WAIT_L(0); PG8_BAR; PG8_MMA(0, 0, At, B0); PG8_MMA(0, 1, At, B1); PG8_BAR; PG8_SCHED;
;             PG8_LDA(At, 0, 1); PG8_STAGE(PG8_SB(0, 0), b2, voffB); PG8_STAGE(PG8_SB(0, 1), b2 + hstepB, voffB); PG8_STAGE(PG8_SA(0, 0), a2, voffA);
;             PG8_WAIT_V(8); PG8_WAIT_L(0); PG8_BAR; PG8_MMA(1, 0, At, B0); PG8_MMA(1, 1, At, B1); PG8_BAR; PG8_SCHED;
;             PG8_LDB(B0, 1, 0); PG8_LDB(B1, 1, 1); PG8_SCHED; PG8_LDA(At, 1, 0); PG8_STAGE(PG8_SA(0, 1), a2 + hstepA, voffA);
;             PG8_WAIT_V(8); PG8_WAIT_L(0); PG8_BAR; PG8_MMA(0, 0, At, B0); PG8_MMA(0, 1, At, B1); PG8_BAR; PG8_SCHED;
	s_setprio 1
	s_waitcnt lgkmcnt(0)
	v_mfma_f32_16x16x32_bf16 v[124:127], v[146:149], v[198:201], v[124:127]
	v_mfma_f32_16x16x32_bf16 v[120:123], v[170:173], v[198:201], v[120:123]
	v_mfma_f32_16x16x32_bf16 v[112:115], v[146:149], v[206:209], v[112:115]
	v_mfma_f32_16x16x32_bf16 v[104:107], v[170:173], v[206:209], v[104:107]
	v_mfma_f32_16x16x32_bf16 v[100:103], v[146:149], v[214:217], v[100:103]
	v_mfma_f32_16x16x32_bf16 v[92:95], v[170:173], v[214:217], v[92:95]
	v_mfma_f32_16x16x32_bf16 v[84:87], v[146:149], v[226:229], v[84:87]
	v_mfma_f32_16x16x32_bf16 v[76:79], v[170:173], v[226:229], v[76:79]
	v_mfma_f32_16x16x32_bf16 v[124:127], v[166:169], v[202:205], v[124:127]
	v_mfma_f32_16x16x32_bf16 v[120:123], v[178:181], v[202:205], v[120:123]
	v_mfma_f32_16x16x32_bf16 v[112:115], v[166:169], v[210:213], v[112:115]
	v_mfma_f32_16x16x32_bf16 v[104:107], v[178:181], v[210:213], v[104:107]
	v_mfma_f32_16x16x32_bf16 v[100:103], v[166:169], v[218:221], v[100:103]
	v_mfma_f32_16x16x32_bf16 v[92:95], v[178:181], v[218:221], v[92:95]
	v_mfma_f32_16x16x32_bf16 v[84:87], v[166:169], v[230:233], v[84:87]
	v_mfma_f32_16x16x32_bf16 v[76:79], v[178:181], v[230:233], v[76:79]
	s_setprio 0
	s_setprio 1
	v_mfma_f32_16x16x32_bf16 v[116:119], v[182:185], v[198:201], v[116:119]
	v_mfma_f32_16x16x32_bf16 v[108:111], v[190:193], v[198:201], v[108:111]
	v_mfma_f32_16x16x32_bf16 v[96:99], v[182:185], v[206:209], v[96:99]
	v_mfma_f32_16x16x32_bf16 v[88:91], v[190:193], v[206:209], v[88:91]
	v_mfma_f32_16x16x32_bf16 v[80:83], v[182:185], v[214:217], v[80:83]
	v_mfma_f32_16x16x32_bf16 v[72:75], v[190:193], v[214:217], v[72:75]
	v_mfma_f32_16x16x32_bf16 v[68:71], v[182:185], v[226:229], v[68:71]
	v_mfma_f32_16x16x32_bf16 v[64:67], v[190:193], v[226:229], v[64:67]
	v_mfma_f32_16x16x32_bf16 v[116:119], v[186:189], v[202:205], v[116:119]
	v_mfma_f32_16x16x32_bf16 v[108:111], v[194:197], v[202:205], v[108:111]
	v_mfma_f32_16x16x32_bf16 v[96:99], v[186:189], v[210:213], v[96:99]
	v_mfma_f32_16x16x32_bf16 v[88:91], v[194:197], v[210:213], v[88:91]
	v_mfma_f32_16x16x32_bf16 v[80:83], v[186:189], v[218:221], v[80:83]
	v_mfma_f32_16x16x32_bf16 v[72:75], v[194:197], v[218:221], v[72:75]
	v_mfma_f32_16x16x32_bf16 v[68:71], v[186:189], v[230:233], v[68:71]
	v_mfma_f32_16x16x32_bf16 v[64:67], v[194:197], v[230:233], v[64:67]
	s_setprio 0
	s_barrier
	s_add_i32 s90, s85, s39
	v_lshl_add_u64 v[174:175], s[10:11], 0, v[130:131]
	s_mov_b32 m0, s90
	ds_read_b128 v[198:201], v164 offset:16384
	ds_read_b128 v[202:205], v164 offset:17408
	ds_read_b128 v[206:209], v164 offset:18432
	ds_read_b128 v[210:213], v164 offset:19456
	ds_read_b128 v[214:217], v164 offset:20480
	ds_read_b128 v[218:221], v164 offset:21504
	ds_read_b128 v[226:229], v164 offset:22528
	ds_read_b128 v[230:233], v164 offset:23552
	global_load_lds_dwordx4 v[174:175], off
	s_add_i32 m0, s90, 0x2000
	s_add_u32 s90, s10, 0x40000
	v_lshl_add_u64 v[222:223], s[10:11], 0, v[134:135]
	s_addc_u32 s91, s11, 0
	s_add_i32 s92, s86, s39
	global_load_lds_dwordx4 v[222:223], off
	v_lshl_add_u64 v[234:235], s[90:91], 0, v[130:131]
	s_mov_b32 m0, s92
	v_lshl_add_u64 v[236:237], s[12:13], 0, v[132:133]
	global_load_lds_dwordx4 v[234:235], off
	v_lshl_add_u64 v[234:235], s[90:91], 0, v[134:135]
	s_add_i32 m0, s92, 0x2000
	s_nop 0
	global_load_lds_dwordx4 v[234:235], off
	v_lshl_add_u64 v[234:235], s[12:13], 0, v[128:129]
	s_mov_b32 m0, s43
	s_nop 0
	global_load_lds_dwordx4 v[234:235], off
	s_mov_b32 m0, s53
	s_nop 0
	global_load_lds_dwordx4 v[236:237], off
	s_waitcnt vmcnt(8)
	s_waitcnt lgkmcnt(0)
	s_nop 0
	s_barrier
	s_setprio 1
	s_waitcnt lgkmcnt(0)
	v_mfma_f32_16x16x32_bf16 v[60:63], v[146:149], v[198:201], v[60:63]
	v_mfma_f32_16x16x32_bf16 v[56:59], v[170:173], v[198:201], v[56:59]
	v_mfma_f32_16x16x32_bf16 v[52:55], v[146:149], v[206:209], v[52:55]
	v_mfma_f32_16x16x32_bf16 v[44:47], v[170:173], v[206:209], v[44:47]
	v_mfma_f32_16x16x32_bf16 v[36:39], v[146:149], v[214:217], v[36:39]
	v_mfma_f32_16x16x32_bf16 v[28:31], v[170:173], v[214:217], v[28:31]
	v_mfma_f32_16x16x32_bf16 v[20:23], v[146:149], v[226:229], v[20:23]
	v_mfma_f32_16x16x32_bf16 v[12:15], v[170:173], v[226:229], v[12:15]
	v_mfma_f32_16x16x32_bf16 v[60:63], v[166:169], v[202:205], v[60:63]
	v_mfma_f32_16x16x32_bf16 v[56:59], v[178:181], v[202:205], v[56:59]
	v_mfma_f32_16x16x32_bf16 v[52:55], v[166:169], v[210:213], v[52:55]
	v_mfma_f32_16x16x32_bf16 v[44:47], v[178:181], v[210:213], v[44:47]
	v_mfma_f32_16x16x32_bf16 v[36:39], v[166:169], v[218:221], v[36:39]
	v_mfma_f32_16x16x32_bf16 v[28:31], v[178:181], v[218:221], v[28:31]
	v_mfma_f32_16x16x32_bf16 v[20:23], v[166:169], v[230:233], v[20:23]
	v_mfma_f32_16x16x32_bf16 v[12:15], v[178:181], v[230:233], v[12:15]
	s_setprio 0
	s_setprio 1
	v_mfma_f32_16x16x32_bf16 v[48:51], v[182:185], v[198:201], v[48:51]
	v_mfma_f32_16x16x32_bf16 v[40:43], v[190:193], v[198:201], v[40:43]
	v_mfma_f32_16x16x32_bf16 v[32:35], v[182:185], v[206:209], v[32:35]
	v_mfma_f32_16x16x32_bf16 v[24:27], v[190:193], v[206:209], v[24:27]
	v_mfma_f32_16x16x32_bf16 v[16:19], v[182:185], v[214:217], v[16:19]
	v_mfma_f32_16x16x32_bf16 v[8:11], v[190:193], v[214:217], v[8:11]
	v_mfma_f32_16x16x32_bf16 v[4:7], v[182:185], v[226:229], v[4:7]
	v_mfma_f32_16x16x32_bf16 v[0:3], v[190:193], v[226:229], v[0:3]
	v_mfma_f32_16x16x32_bf16 v[48:51], v[186:189], v[202:205], v[48:51]
	v_mfma_f32_16x16x32_bf16 v[40:43], v[194:197], v[202:205], v[40:43]
	v_mfma_f32_16x16x32_bf16 v[32:35], v[186:189], v[210:213], v[32:35]
	v_mfma_f32_16x16x32_bf16 v[24:27], v[194:197], v[210:213], v[24:27]
	v_mfma_f32_16x16x32_bf16 v[16:19], v[186:189], v[218:221], v[16:19]
	v_mfma_f32_16x16x32_bf16 v[8:11], v[194:197], v[218:221], v[8:11]
	v_mfma_f32_16x16x32_bf16 v[4:7], v[186:189], v[230:233], v[4:7]
	v_mfma_f32_16x16x32_bf16 v[0:3], v[194:197], v[230:233], v[0:3]
	s_setprio 0
	s_barrier
; #define PG8_STAGE(bufoff, gbase, voff) do { _Pragma("unroll") for (int _i = 0; _i < 2; ++_i) \
;         __builtin_amdgcn_global_load_lds((const unsigned*)((const char*)(gbase) + (voff)[_i]), (LAS unsigned*)(lds + (bufoff) + ldsw + _i * 8192), 16, 0, 0); } while (0)
; #define PG8_LDA(dst, b, h) do { _Pragma("unroll") for (int m = 0; m < 4; ++m) _Pragma("unroll") for (int k = 0; k < 2; ++k) dst[m][k] = *(const LAS bf16x8*)(lds + PG8_SA(b, h) + aoff + m * 2048 + k * 1024); } while (0)
; #define PG8_LDB(dst, b, h) do { _Pragma("unroll") for (int n = 0; n < 2; ++n) _Pragma("unroll") for (int k = 0; k < 2; ++k) dst[n][k] = *(const LAS bf16x8*)(lds + PG8_SB(b, h) + boff + n * 2048 + k * 1024); } while (0)
; #define PG8_MMA(ai, bj, At, Bt) do { __builtin_amdgcn_s_setprio(1); _Pragma("unroll") for (int m = 0; m < 4; ++m) _Pragma("unroll") for (int n = 0; n < 2; ++n) _Pragma("unroll") for (int k = 0; k < 2; ++k) \
;         acc[ai][bj][m][n] = __builtin_amdgcn_mfma_f32_16x16x32_bf16(Bt[n][k], At[m][k], acc[ai][bj][m][n], 0, 0, 0); __builtin_amdgcn_s_setprio(0); } while (0)
; #define PG8_WAIT_V(n) asm volatile("s_waitcnt vmcnt(" #n ")" ::: "memory")
; #define PG8_WAIT_L(n) asm volatile("s_waitcnt lgkmcnt(" #n ")" ::: "memory")
; #define PG8_BAR __builtin_amdgcn_s_barrier()
; #define PG8_SCHED __builtin_amdgcn_sched_barrier(0)
; template <class Epi>
; __device__ __forceinline__ void gemm_phase(LAS unsigned char* lds, const Gemm g, const StaticOrder& S, const Epi& E) {
;     ...
;             PG8_LDB(B0, 1, 0); PG8_LDB(B1, 1, 1); PG8_SCHED; PG8_LDA(At, 1, 0); PG8_STAGE(PG8_SA(0, 1), a2 + hstepA, voffA);
;             PG8_WAIT_V(8); PG8_WAIT_L(0); PG8_BAR; PG8_MMA(0, 0, At, B0); PG8_MMA(0, 1, At, B1); PG8_BAR; PG8_SCHED;
	s_add_i32 s90, 0, 0x18000
	v_add_u32_e32 v136, s90, v161
	s_add_i32 s91, 0, 0x1c000
	ds_read_b128 v[146:149], v136
	ds_read_b128 v[166:169], v136 offset:1024
	ds_read_b128 v[170:173], v136 offset:2048
	ds_read_b128 v[178:181], v136 offset:3072
	v_add_u32_e32 v136, s91, v161
	ds_read_b128 v[182:185], v136
	ds_read_b128 v[186:189], v136 offset:1024
	ds_read_b128 v[190:193], v136 offset:2048
	ds_read_b128 v[194:197], v136 offset:3072
	s_add_u32 s12, s12, 0x40000
	s_addc_u32 s13, s13, 0
	s_mov_b32 m0, s55
	v_lshl_add_u64 v[238:239], s[12:13], 0, v[128:129]
	ds_read_b128 v[198:201], v164 offset:32768
	ds_read_b128 v[202:205], v164 offset:33792
	ds_read_b128 v[206:209], v164 offset:34816
	ds_read_b128 v[210:213], v164 offset:35840
	ds_read_b128 v[214:217], v164 offset:36864
	ds_read_b128 v[218:221], v164 offset:37888
	ds_read_b128 v[226:229], v164 offset:38912
	ds_read_b128 v[230:233], v164 offset:39936
	global_load_lds_dwordx4 v[238:239], off
	v_lshl_add_u64 v[238:239], s[12:13], 0, v[132:133]
	s_mov_b32 m0, s57
	s_nop 0
	global_load_lds_dwordx4 v[238:239], off
	s_waitcnt vmcnt(8)
	s_waitcnt lgkmcnt(0)
	s_nop 0
	s_barrier
	s_setprio 1
	s_waitcnt lgkmcnt(0)
	v_mfma_f32_16x16x32_bf16 v[124:127], v[146:149], v[198:201], v[124:127]
	v_mfma_f32_16x16x32_bf16 v[120:123], v[170:173], v[198:201], v[120:123]
	v_mfma_f32_16x16x32_bf16 v[112:115], v[146:149], v[206:209], v[112:115]
	v_mfma_f32_16x16x32_bf16 v[104:107], v[170:173], v[206:209], v[104:107]
	v_mfma_f32_16x16x32_bf16 v[100:103], v[146:149], v[214:217], v[100:103]
	v_mfma_f32_16x16x32_bf16 v[92:95], v[170:173], v[214:217], v[92:95]
	v_mfma_f32_16x16x32_bf16 v[84:87], v[146:149], v[226:229], v[84:87]
	v_mfma_f32_16x16x32_bf16 v[76:79], v[170:173], v[226:229], v[76:79]
	v_mfma_f32_16x16x32_bf16 v[124:127], v[166:169], v[202:205], v[124:127]
	v_mfma_f32_16x16x32_bf16 v[120:123], v[178:181], v[202:205], v[120:123]
	v_mfma_f32_16x16x32_bf16 v[112:115], v[166:169], v[210:213], v[112:115]
	v_mfma_f32_16x16x32_bf16 v[104:107], v[178:181], v[210:213], v[104:107]
	v_mfma_f32_16x16x32_bf16 v[100:103], v[166:169], v[218:221], v[100:103]
	v_mfma_f32_16x16x32_bf16 v[92:95], v[178:181], v[218:221], v[92:95]
	v_mfma_f32_16x16x32_bf16 v[84:87], v[166:169], v[230:233], v[84:87]
	v_mfma_f32_16x16x32_bf16 v[76:79], v[178:181], v[230:233], v[76:79]
	s_setprio 0
	s_setprio 1
	v_mfma_f32_16x16x32_bf16 v[116:119], v[182:185], v[198:201], v[116:119]
	v_mfma_f32_16x16x32_bf16 v[108:111], v[190:193], v[198:201], v[108:111]
	v_mfma_f32_16x16x32_bf16 v[96:99], v[182:185], v[206:209], v[96:99]
	v_mfma_f32_16x16x32_bf16 v[88:91], v[190:193], v[206:209], v[88:91]
	v_mfma_f32_16x16x32_bf16 v[80:83], v[182:185], v[214:217], v[80:83]
	v_mfma_f32_16x16x32_bf16 v[72:75], v[190:193], v[214:217], v[72:75]
	v_mfma_f32_16x16x32_bf16 v[68:71], v[182:185], v[226:229], v[68:71]
	v_mfma_f32_16x16x32_bf16 v[64:67], v[190:193], v[226:229], v[64:67]
	v_mfma_f32_16x16x32_bf16 v[116:119], v[186:189], v[202:205], v[116:119]
	v_mfma_f32_16x16x32_bf16 v[108:111], v[194:197], v[202:205], v[108:111]
	v_mfma_f32_16x16x32_bf16 v[96:99], v[186:189], v[210:213], v[96:99]
	v_mfma_f32_16x16x32_bf16 v[88:91], v[194:197], v[210:213], v[88:91]
	v_mfma_f32_16x16x32_bf16 v[80:83], v[186:189], v[218:221], v[80:83]
	v_mfma_f32_16x16x32_bf16 v[72:75], v[194:197], v[218:221], v[72:75]
	v_mfma_f32_16x16x32_bf16 v[68:71], v[186:189], v[230:233], v[68:71]
	v_mfma_f32_16x16x32_bf16 v[64:67], v[194:197], v[230:233], v[64:67]
	s_setprio 0
	s_barrier
; #define PG8_STAGE(bufoff, gbase, voff) do { _Pragma("unroll") for (int _i = 0; _i < 2; ++_i) \
;         __builtin_amdgcn_global_load_lds((const unsigned*)((const char*)(gbase) + (voff)[_i]), (LAS unsigned*)(lds + (bufoff) + ldsw + _i * 8192), 16, 0, 0); } while (0)
; #define PG8_LDA(dst, b, h) do { _Pragma("unroll") for (int m = 0; m < 4; ++m) _Pragma("unroll") for (int k = 0; k < 2; ++k) dst[m][k] = *(const LAS bf16x8*)(lds + PG8_SA(b, h) + aoff + m * 2048 + k * 1024); } while (0)
; #define PG8_MMA(ai, bj, At, Bt) do { __builtin_amdgcn_s_setprio(1); _Pragma("unroll") for (int m = 0; m < 4; ++m) _Pragma("unroll") for (int n = 0; n < 2; ++n) _Pragma("unroll") for (int k = 0; k < 2; ++k) \
;         acc[ai][bj][m][n] = __builtin_amdgcn_mfma_f32_16x16x32_bf16(Bt[n][k], At[m][k], acc[ai][bj][m][n], 0, 0, 0); __builtin_amdgcn_s_setprio(0); } while (0)
; #define PG8_WAIT_V(n) asm volatile("s_waitcnt vmcnt(" #n ")" ::: "memory")
; #define PG8_WAIT_L(n) asm volatile("s_waitcnt lgkmcnt(" #n ")" ::: "memory")
; #define PG8_BAR __builtin_amdgcn_s_barrier()
; #define PG8_SCHED __builtin_amdgcn_sched_barrier(0)
; template <class Epi>
; __device__ __forceinline__ void gemm_phase(LAS unsigned char* lds, const Gemm g, const StaticOrder& S, const Epi& E) {
;     ...
;             PG8_LDA(At, 1, 1); PG8_STAGE(PG8_SB(1, 0), b3, voffB); PG8_STAGE(PG8_SB(1, 1), b3 + hstepB, voffB); PG8_STAGE(PG8_SA(1, 0), a3, voffA);
;             PG8_WAIT_V(8); PG8_WAIT_L(0); PG8_BAR; PG8_MMA(1, 0, At, B0); PG8_MMA(1, 1, At, B1); PG8_BAR; PG8_SCHED;
;         }
;         if (wr == 0) PG8_BAR;
	s_add_i32 s12, s90, s39
	v_lshl_add_u64 v[174:175], v[174:175], 0, s[30:31]
	s_mov_b32 m0, s12
	ds_read_b128 v[198:201], v164 offset:49152
	ds_read_b128 v[202:205], v164 offset:50176
	ds_read_b128 v[206:209], v164 offset:51200
	ds_read_b128 v[210:213], v164 offset:52224
	ds_read_b128 v[214:217], v164 offset:53248
	ds_read_b128 v[218:221], v164 offset:54272
	ds_read_b128 v[226:229], v164 offset:55296
	ds_read_b128 v[230:233], v164 offset:56320
	global_load_lds_dwordx4 v[174:175], off
	s_add_i32 m0, s12, 0x2000
	s_add_u32 s10, s10, 0x40080
	v_lshl_add_u64 v[174:175], v[222:223], 0, s[30:31]
	s_addc_u32 s11, s11, 0
	s_add_i32 s12, s91, s39
	global_load_lds_dwordx4 v[174:175], off
	v_lshl_add_u64 v[174:175], s[10:11], 0, v[130:131]
	s_mov_b32 m0, s12
	s_nop 0
	global_load_lds_dwordx4 v[174:175], off
	v_lshl_add_u64 v[174:175], s[10:11], 0, v[134:135]
	s_add_i32 m0, s12, 0x2000
	s_nop 0
	global_load_lds_dwordx4 v[174:175], off
	v_lshl_add_u64 v[174:175], v[234:235], 0, s[30:31]
	s_mov_b32 m0, s79
	s_nop 0
	global_load_lds_dwordx4 v[174:175], off
	v_lshl_add_u64 v[174:175], v[236:237], 0, s[30:31]
	s_mov_b32 m0, s80
	s_nop 0
	global_load_lds_dwordx4 v[174:175], off
	s_waitcnt vmcnt(8)
	s_waitcnt lgkmcnt(0)
	s_barrier
	s_setprio 1
	s_waitcnt lgkmcnt(0)
	v_mfma_f32_16x16x32_bf16 v[60:63], v[146:149], v[198:201], v[60:63]
	v_mfma_f32_16x16x32_bf16 v[56:59], v[170:173], v[198:201], v[56:59]
	v_mfma_f32_16x16x32_bf16 v[52:55], v[146:149], v[206:209], v[52:55]
	v_mfma_f32_16x16x32_bf16 v[44:47], v[170:173], v[206:209], v[44:47]
	v_mfma_f32_16x16x32_bf16 v[36:39], v[146:149], v[214:217], v[36:39]
	v_mfma_f32_16x16x32_bf16 v[28:31], v[170:173], v[214:217], v[28:31]
	v_mfma_f32_16x16x32_bf16 v[20:23], v[146:149], v[226:229], v[20:23]
	v_mfma_f32_16x16x32_bf16 v[12:15], v[170:173], v[226:229], v[12:15]
	v_mfma_f32_16x16x32_bf16 v[60:63], v[166:169], v[202:205], v[60:63]
	v_mfma_f32_16x16x32_bf16 v[56:59], v[178:181], v[202:205], v[56:59]
	v_mfma_f32_16x16x32_bf16 v[52:55], v[166:169], v[210:213], v[52:55]
	v_mfma_f32_16x16x32_bf16 v[44:47], v[178:181], v[210:213], v[44:47]
	v_mfma_f32_16x16x32_bf16 v[36:39], v[166:169], v[218:221], v[36:39]
	v_mfma_f32_16x16x32_bf16 v[28:31], v[178:181], v[218:221], v[28:31]
	v_mfma_f32_16x16x32_bf16 v[20:23], v[166:169], v[230:233], v[20:23]
	v_mfma_f32_16x16x32_bf16 v[12:15], v[178:181], v[230:233], v[12:15]
	s_setprio 0
	s_setprio 1
	v_mfma_f32_16x16x32_bf16 v[48:51], v[182:185], v[198:201], v[48:51]
	v_mfma_f32_16x16x32_bf16 v[40:43], v[190:193], v[198:201], v[40:43]
	v_mfma_f32_16x16x32_bf16 v[32:35], v[182:185], v[206:209], v[32:35]
	v_mfma_f32_16x16x32_bf16 v[24:27], v[190:193], v[206:209], v[24:27]
	v_mfma_f32_16x16x32_bf16 v[16:19], v[182:185], v[214:217], v[16:19]
	v_mfma_f32_16x16x32_bf16 v[8:11], v[190:193], v[214:217], v[8:11]
	v_mfma_f32_16x16x32_bf16 v[4:7], v[182:185], v[226:229], v[4:7]
	v_mfma_f32_16x16x32_bf16 v[0:3], v[190:193], v[226:229], v[0:3]
	v_mfma_f32_16x16x32_bf16 v[48:51], v[186:189], v[202:205], v[48:51]
	v_mfma_f32_16x16x32_bf16 v[40:43], v[194:197], v[202:205], v[40:43]
	v_mfma_f32_16x16x32_bf16 v[32:35], v[186:189], v[210:213], v[32:35]
	v_mfma_f32_16x16x32_bf16 v[24:27], v[194:197], v[210:213], v[24:27]
	v_mfma_f32_16x16x32_bf16 v[16:19], v[186:189], v[218:221], v[16:19]
	v_mfma_f32_16x16x32_bf16 v[8:11], v[194:197], v[218:221], v[8:11]
	v_mfma_f32_16x16x32_bf16 v[4:7], v[186:189], v[230:233], v[4:7]
	v_mfma_f32_16x16x32_bf16 v[0:3], v[194:197], v[230:233], v[0:3]
	s_setprio 0
	s_barrier
	s_add_i32 s89, s89, 2
	s_add_u32 s8, s8, 0x100
	s_addc_u32 s9, s9, 0
	s_add_u32 s76, s76, 0x100
	s_addc_u32 s77, s77, 0
	s_cmp_gt_u32 s89, 13
	s_cbranch_scc0 .LBB0_546
	s_and_b64 vcc, exec, s[34:35]
	s_cbranch_vccz .LBB0_549
	s_barrier

; #define PG8_STAGE(bufoff, gbase, voff) do { _Pragma("unroll") for (int _i = 0; _i < 2; ++_i) \
;         __builtin_amdgcn_global_load_lds((const unsigned*)((const char*)(gbase) + (voff)[_i]), (LAS unsigned*)(lds + (bufoff) + ldsw + _i * 8192), 16, 0, 0); } while (0)
; #define PG8_LDA(dst, b, h) do { _Pragma("unroll") for (int m = 0; m < 4; ++m) _Pragma("unroll") for (int k = 0; k < 2; ++k) dst[m][k] = *(const LAS bf16x8*)(lds + PG8_SA(b, h) + aoff + m * 2048 + k * 1024); } while (0)
; #define PG8_LDB(dst, b, h) do { _Pragma("unroll") for (int n = 0; n < 2; ++n) _Pragma("unroll") for (int k = 0; k < 2; ++k) dst[n][k] = *(const LAS bf16x8*)(lds + PG8_SB(b, h) + boff + n * 2048 + k * 1024); } while (0)
; #define PG8_MMA(ai, bj, At, Bt) do { __builtin_amdgcn_s_setprio(1); _Pragma("unroll") for (int m = 0; m < 4; ++m) _Pragma("unroll") for (int n = 0; n < 2; ++n) _Pragma("unroll") for (int k = 0; k < 2; ++k) \
;         acc[ai][bj][m][n] = __builtin_amdgcn_mfma_f32_16x16x32_bf16(Bt[n][k], At[m][k], acc[ai][bj][m][n], 0, 0, 0); __builtin_amdgcn_s_setprio(0); } while (0)
; #define PG8_WAIT_V(n) asm volatile("s_waitcnt vmcnt(" #n ")" ::: "memory")
; #define PG8_WAIT_L(n) asm volatile("s_waitcnt lgkmcnt(" #n ")" ::: "memory")
; #define PG8_BAR __builtin_amdgcn_s_barrier()
; #define PG8_SCHED __builtin_amdgcn_sched_barrier(0)
; template <class Epi>
; __device__ __forceinline__ void gemm_phase(LAS unsigned char* lds, const Gemm g, const StaticOrder& S, const Epi& E) {
;     ...
;         for (int t = 0; t < nt; t += 2) {
;             const bool last = (t == nt - 2);
;             const char* a1 = cA + (size_t)(t + 1) * kstep;
;             const char* a2 = last ? nA : cA + (size_t)(t + 2) * kstep; const char* b2 = last ? nB : cB + (size_t)(t + 2) * kstep;
;             const char* a3 = a2 + kstep; const char* b3 = b2 + kstep;
;             PG8_LDB(B0, 0, 0); PG8_LDB(B1, 0, 1); PG8_SCHED; PG8_LDA(At, 0, 0); PG8_STAGE(PG8_SA(1, 1), a1 + hstepA, voffA);
;             PG8_WAIT_V(8); PG8_WAIT_L(0); PG8_BAR; PG8_MMA(0, 0, At, B0); PG8_MMA(0, 1, At, B1); PG8_BAR; PG8_SCHED;
;             PG8_LDA(At, 0, 1); PG8_STAGE(PG8_SB(0, 0), b2, voffB); PG8_STAGE(PG8_SB(0, 1), b2 + hstepB, voffB); PG8_STAGE(PG8_SA(0, 0), a2, voffA);
;             PG8_WAIT_V(8); PG8_WAIT_L(0); PG8_BAR; PG8_MMA(1, 0, At, B0); PG8_MMA(1, 1, At, B1); PG8_BAR; PG8_SCHED;
.LBB0_612:
	s_add_u32 s68, s42, s56
	s_addc_u32 s69, s43, s57
	s_add_u32 s64, s68, 0x100
	s_addc_u32 s65, s69, 0
	s_and_b64 s[62:63], s[54:55], exec
	s_cselect_b32 s63, s1, s65
	s_cselect_b32 s62, s19, s64
	s_add_u32 s56, s38, s56
	s_addc_u32 s57, s39, s57
	s_add_u32 s56, s56, 0x100
	s_addc_u32 s57, s57, 0
	s_and_b64 s[54:55], s[54:55], exec
	s_cselect_b32 s65, s13, s57
	s_cselect_b32 s64, s88, s56
	s_add_u32 s70, s68, 0x10080
	ds_read_b128 v[140:143], v145
	ds_read_b128 v[154:157], v145 offset:1024
	ds_read_b128 v[158:161], v145 offset:2048
	ds_read_b128 v[162:165], v145 offset:3072
	ds_read_b128 v[166:169], v146
	ds_read_b128 v[170:173], v146 offset:1024
	ds_read_b128 v[178:181], v146 offset:2048
	ds_read_b128 v[182:185], v146 offset:3072
	s_addc_u32 s71, s69, 0
	s_add_i32 vcc_lo, s86, s72
	s_add_i32 m0, s35, 0xc000
	s_add_i32 vcc_hi, s35, 0xe000
	s_add_i32 s95, vcc_lo, 0x2000
	s_add_u32 s68, s64, 0x10000
	s_addc_u32 s69, s65, 0
	s_add_i32 s97, s87, s72
	s_add_i32 s96, s97, 0x2000
	s_add_i32 s94, 0, 0x18000
	s_add_i32 s93, 0, 0x1c000
	s_add_u32 s56, s62, 0x10000
	s_addc_u32 s57, s63, 0
	s_add_i32 s92, s94, s72
	s_add_i32 s90, s92, 0x2000
	s_add_u32 s54, s64, 0x10080
	s_addc_u32 s55, s65, 0
	s_add_i32 s91, s93, s72
	s_add_i32 s89, s91, 0x2000
	v_lshl_add_u64 v[174:175], s[70:71], 0, v[128:129]
	ds_read_b128 v[186:189], v147
	ds_read_b128 v[190:193], v147 offset:1024
	ds_read_b128 v[194:197], v147 offset:2048
	ds_read_b128 v[198:201], v147 offset:3072
	ds_read_b128 v[202:205], v147 offset:4096
	ds_read_b128 v[206:209], v147 offset:5120
	ds_read_b128 v[210:213], v147 offset:6144
	ds_read_b128 v[214:217], v147 offset:7168
	global_load_lds_dwordx4 v[174:175], off
	v_lshl_add_u64 v[174:175], s[70:71], 0, v[132:133]
	s_mov_b32 m0, vcc_hi
	s_nop 0
	global_load_lds_dwordx4 v[174:175], off
	s_waitcnt vmcnt(8)
	s_waitcnt lgkmcnt(0)
	s_nop 0
	s_barrier
	s_setprio 1
	s_waitcnt lgkmcnt(0)
	v_mfma_f32_16x16x32_bf16 v[124:127], v[140:143], v[186:189], v[124:127]
	v_mfma_f32_16x16x32_bf16 v[120:123], v[158:161], v[186:189], v[120:123]
	v_mfma_f32_16x16x32_bf16 v[108:111], v[140:143], v[194:197], v[108:111]
	v_mfma_f32_16x16x32_bf16 v[104:107], v[158:161], v[194:197], v[104:107]
	v_mfma_f32_16x16x32_bf16 v[92:95], v[140:143], v[202:205], v[92:95]
	v_mfma_f32_16x16x32_bf16 v[88:91], v[158:161], v[202:205], v[88:91]
	v_mfma_f32_16x16x32_bf16 v[76:79], v[140:143], v[210:213], v[76:79]
	v_mfma_f32_16x16x32_bf16 v[72:75], v[158:161], v[210:213], v[72:75]
	v_mfma_f32_16x16x32_bf16 v[124:127], v[154:157], v[190:193], v[124:127]
	v_mfma_f32_16x16x32_bf16 v[120:123], v[162:165], v[190:193], v[120:123]
	v_mfma_f32_16x16x32_bf16 v[108:111], v[154:157], v[198:201], v[108:111]
	v_mfma_f32_16x16x32_bf16 v[104:107], v[162:165], v[198:201], v[104:107]
	v_mfma_f32_16x16x32_bf16 v[92:95], v[154:157], v[206:209], v[92:95]
	v_mfma_f32_16x16x32_bf16 v[88:91], v[162:165], v[206:209], v[88:91]
	v_mfma_f32_16x16x32_bf16 v[76:79], v[154:157], v[214:217], v[76:79]
	v_mfma_f32_16x16x32_bf16 v[72:75], v[162:165], v[214:217], v[72:75]
	s_setprio 0
	s_setprio 1
	v_mfma_f32_16x16x32_bf16 v[116:119], v[166:169], v[186:189], v[116:119]
	v_mfma_f32_16x16x32_bf16 v[112:115], v[178:181], v[186:189], v[112:115]
	v_mfma_f32_16x16x32_bf16 v[100:103], v[166:169], v[194:197], v[100:103]
	v_mfma_f32_16x16x32_bf16 v[96:99], v[178:181], v[194:197], v[96:99]
	v_mfma_f32_16x16x32_bf16 v[84:87], v[166:169], v[202:205], v[84:87]
	v_mfma_f32_16x16x32_bf16 v[80:83], v[178:181], v[202:205], v[80:83]
	v_mfma_f32_16x16x32_bf16 v[68:71], v[166:169], v[210:213], v[68:71]
	v_mfma_f32_16x16x32_bf16 v[64:67], v[178:181], v[210:213], v[64:67]
	v_mfma_f32_16x16x32_bf16 v[116:119], v[170:173], v[190:193], v[116:119]
	v_mfma_f32_16x16x32_bf16 v[112:115], v[182:185], v[190:193], v[112:115]
	v_mfma_f32_16x16x32_bf16 v[100:103], v[170:173], v[198:201], v[100:103]
	v_mfma_f32_16x16x32_bf16 v[96:99], v[182:185], v[198:201], v[96:99]
	v_mfma_f32_16x16x32_bf16 v[84:87], v[170:173], v[206:209], v[84:87]
	v_mfma_f32_16x16x32_bf16 v[80:83], v[182:185], v[206:209], v[80:83]
	v_mfma_f32_16x16x32_bf16 v[68:71], v[170:173], v[214:217], v[68:71]
	v_mfma_f32_16x16x32_bf16 v[64:67], v[182:185], v[214:217], v[64:67]
	s_setprio 0
	s_barrier
	s_mov_b32 m0, vcc_lo
	v_lshl_add_u64 v[174:175], s[64:65], 0, v[130:131]
	ds_read_b128 v[186:189], v147 offset:16384
	ds_read_b128 v[190:193], v147 offset:17408
	ds_read_b128 v[194:197], v147 offset:18432
	ds_read_b128 v[198:201], v147 offset:19456
	ds_read_b128 v[202:205], v147 offset:20480
	ds_read_b128 v[206:209], v147 offset:21504
	ds_read_b128 v[210:213], v147 offset:22528
	ds_read_b128 v[214:217], v147 offset:23552
	global_load_lds_dwordx4 v[174:175], off
	v_lshl_add_u64 v[218:219], s[64:65], 0, v[134:135]
	s_mov_b32 m0, s95
	v_lshl_add_u64 v[220:221], s[68:69], 0, v[130:131]
	global_load_lds_dwordx4 v[218:219], off
	s_mov_b32 m0, s97
	v_lshl_add_u64 v[222:223], s[62:63], 0, v[132:133]
	global_load_lds_dwordx4 v[220:221], off
	v_lshl_add_u64 v[220:221], s[68:69], 0, v[134:135]
	s_mov_b32 m0, s96
	s_nop 0
	global_load_lds_dwordx4 v[220:221], off
	v_lshl_add_u64 v[220:221], s[62:63], 0, v[128:129]
	s_mov_b32 m0, s35
	s_nop 0
	global_load_lds_dwordx4 v[220:221], off
	s_mov_b32 m0, s75
	s_nop 0
	global_load_lds_dwordx4 v[222:223], off
	s_waitcnt vmcnt(8)
	s_waitcnt lgkmcnt(0)
	s_barrier
; #define PG8_STAGE(bufoff, gbase, voff) do { _Pragma("unroll") for (int _i = 0; _i < 2; ++_i) \
;         __builtin_amdgcn_global_load_lds((const unsigned*)((const char*)(gbase) + (voff)[_i]), (LAS unsigned*)(lds + (bufoff) + ldsw + _i * 8192), 16, 0, 0); } while (0)
; #define PG8_LDA(dst, b, h) do { _Pragma("unroll") for (int m = 0; m < 4; ++m) _Pragma("unroll") for (int k = 0; k < 2; ++k) dst[m][k] = *(const LAS bf16x8*)(lds + PG8_SA(b, h) + aoff + m * 2048 + k * 1024); } while (0)
; #define PG8_LDB(dst, b, h) do { _Pragma("unroll") for (int n = 0; n < 2; ++n) _Pragma("unroll") for (int k = 0; k < 2; ++k) dst[n][k] = *(const LAS bf16x8*)(lds + PG8_SB(b, h) + boff + n * 2048 + k * 1024); } while (0)
; #define PG8_MMA(ai, bj, At, Bt) do { __builtin_amdgcn_s_setprio(1); _Pragma("unroll") for (int m = 0; m < 4; ++m) _Pragma("unroll") for (int n = 0; n < 2; ++n) _Pragma("unroll") for (int k = 0; k < 2; ++k) \
;         acc[ai][bj][m][n] = __builtin_amdgcn_mfma_f32_16x16x32_bf16(Bt[n][k], At[m][k], acc[ai][bj][m][n], 0, 0, 0); __builtin_amdgcn_s_setprio(0); } while (0)
; #define PG8_WAIT_V(n) asm volatile("s_waitcnt vmcnt(" #n ")" ::: "memory")
; #define PG8_WAIT_L(n) asm volatile("s_waitcnt lgkmcnt(" #n ")" ::: "memory")
; #define PG8_BAR __builtin_amdgcn_s_barrier()
; #define PG8_SCHED __builtin_amdgcn_sched_barrier(0)
; template <class Epi>
; __device__ __forceinline__ void gemm_phase(LAS unsigned char* lds, const Gemm g, const StaticOrder& S, const Epi& E) {
;     ...
;             PG8_WAIT_V(8); PG8_WAIT_L(0); PG8_BAR; PG8_MMA(1, 0, At, B0); PG8_MMA(1, 1, At, B1); PG8_BAR; PG8_SCHED;
;             PG8_LDB(B0, 1, 0); PG8_LDB(B1, 1, 1); PG8_SCHED; PG8_LDA(At, 1, 0); PG8_STAGE(PG8_SA(0, 1), a2 + hstepA, voffA);
;             PG8_WAIT_V(8); PG8_WAIT_L(0); PG8_BAR; PG8_MMA(0, 0, At, B0); PG8_MMA(0, 1, At, B1); PG8_BAR; PG8_SCHED;
;             PG8_LDA(At, 1, 1); PG8_STAGE(PG8_SB(1, 0), b3, voffB); PG8_STAGE(PG8_SB(1, 1), b3 + hstepB, voffB); PG8_STAGE(PG8_SA(1, 0), a3, voffA);
;             PG8_WAIT_V(8); PG8_WAIT_L(0); PG8_BAR; PG8_MMA(1, 0, At, B0); PG8_MMA(1, 1, At, B1); PG8_BAR; PG8_SCHED;
	s_setprio 1
	s_waitcnt lgkmcnt(0)
	v_mfma_f32_16x16x32_bf16 v[60:63], v[140:143], v[186:189], v[60:63]
	v_mfma_f32_16x16x32_bf16 v[56:59], v[158:161], v[186:189], v[56:59]
	v_mfma_f32_16x16x32_bf16 v[44:47], v[140:143], v[194:197], v[44:47]
	v_mfma_f32_16x16x32_bf16 v[40:43], v[158:161], v[194:197], v[40:43]
	v_mfma_f32_16x16x32_bf16 v[28:31], v[140:143], v[202:205], v[28:31]
	v_mfma_f32_16x16x32_bf16 v[24:27], v[158:161], v[202:205], v[24:27]
	v_mfma_f32_16x16x32_bf16 v[12:15], v[140:143], v[210:213], v[12:15]
	v_mfma_f32_16x16x32_bf16 v[8:11], v[158:161], v[210:213], v[8:11]
	v_mfma_f32_16x16x32_bf16 v[60:63], v[154:157], v[190:193], v[60:63]
	v_mfma_f32_16x16x32_bf16 v[56:59], v[162:165], v[190:193], v[56:59]
	v_mfma_f32_16x16x32_bf16 v[44:47], v[154:157], v[198:201], v[44:47]
	v_mfma_f32_16x16x32_bf16 v[40:43], v[162:165], v[198:201], v[40:43]
	v_mfma_f32_16x16x32_bf16 v[28:31], v[154:157], v[206:209], v[28:31]
	v_mfma_f32_16x16x32_bf16 v[24:27], v[162:165], v[206:209], v[24:27]
	v_mfma_f32_16x16x32_bf16 v[12:15], v[154:157], v[214:217], v[12:15]
	v_mfma_f32_16x16x32_bf16 v[8:11], v[162:165], v[214:217], v[8:11]
	s_setprio 0
	s_setprio 1
	v_mfma_f32_16x16x32_bf16 v[52:55], v[166:169], v[186:189], v[52:55]
	v_mfma_f32_16x16x32_bf16 v[48:51], v[178:181], v[186:189], v[48:51]
	v_mfma_f32_16x16x32_bf16 v[36:39], v[166:169], v[194:197], v[36:39]
	v_mfma_f32_16x16x32_bf16 v[32:35], v[178:181], v[194:197], v[32:35]
	v_mfma_f32_16x16x32_bf16 v[20:23], v[166:169], v[202:205], v[20:23]
	v_mfma_f32_16x16x32_bf16 v[16:19], v[178:181], v[202:205], v[16:19]
	v_mfma_f32_16x16x32_bf16 v[4:7], v[166:169], v[210:213], v[4:7]
	v_mfma_f32_16x16x32_bf16 v[0:3], v[178:181], v[210:213], v[0:3]
	v_mfma_f32_16x16x32_bf16 v[52:55], v[170:173], v[190:193], v[52:55]
	v_mfma_f32_16x16x32_bf16 v[48:51], v[182:185], v[190:193], v[48:51]
	v_mfma_f32_16x16x32_bf16 v[36:39], v[170:173], v[198:201], v[36:39]
	v_mfma_f32_16x16x32_bf16 v[32:35], v[182:185], v[198:201], v[32:35]
	v_mfma_f32_16x16x32_bf16 v[20:23], v[170:173], v[206:209], v[20:23]
	v_mfma_f32_16x16x32_bf16 v[16:19], v[182:185], v[206:209], v[16:19]
	v_mfma_f32_16x16x32_bf16 v[4:7], v[170:173], v[214:217], v[4:7]
	v_mfma_f32_16x16x32_bf16 v[0:3], v[182:185], v[214:217], v[0:3]
	s_setprio 0
	s_barrier
	v_add_u32_e32 v149, s94, v144
	ds_read_b128 v[140:143], v149
	ds_read_b128 v[154:157], v149 offset:1024
	ds_read_b128 v[158:161], v149 offset:2048
	ds_read_b128 v[162:165], v149 offset:3072
	v_add_u32_e32 v149, s93, v144
	ds_read_b128 v[166:169], v149
	ds_read_b128 v[170:173], v149 offset:1024
	ds_read_b128 v[178:181], v149 offset:2048
	ds_read_b128 v[182:185], v149 offset:3072
	s_mov_b32 m0, s76
	v_lshl_add_u64 v[226:227], s[56:57], 0, v[128:129]
	ds_read_b128 v[186:189], v147 offset:32768
	ds_read_b128 v[190:193], v147 offset:33792
	ds_read_b128 v[194:197], v147 offset:34816
	ds_read_b128 v[198:201], v147 offset:35840
	ds_read_b128 v[202:205], v147 offset:36864
	ds_read_b128 v[206:209], v147 offset:37888
	ds_read_b128 v[210:213], v147 offset:38912
	ds_read_b128 v[214:217], v147 offset:39936
	global_load_lds_dwordx4 v[226:227], off
	v_lshl_add_u64 v[226:227], s[56:57], 0, v[132:133]
	s_mov_b32 m0, s77
	s_nop 0
	global_load_lds_dwordx4 v[226:227], off
	s_waitcnt vmcnt(8)
	s_waitcnt lgkmcnt(0)
	s_barrier
	s_setprio 1
	s_waitcnt lgkmcnt(0)
	v_mfma_f32_16x16x32_bf16 v[124:127], v[140:143], v[186:189], v[124:127]
	v_mfma_f32_16x16x32_bf16 v[120:123], v[158:161], v[186:189], v[120:123]
	v_mfma_f32_16x16x32_bf16 v[108:111], v[140:143], v[194:197], v[108:111]
	v_mfma_f32_16x16x32_bf16 v[104:107], v[158:161], v[194:197], v[104:107]
	v_mfma_f32_16x16x32_bf16 v[92:95], v[140:143], v[202:205], v[92:95]
	v_mfma_f32_16x16x32_bf16 v[88:91], v[158:161], v[202:205], v[88:91]
	v_mfma_f32_16x16x32_bf16 v[76:79], v[140:143], v[210:213], v[76:79]
	v_mfma_f32_16x16x32_bf16 v[72:75], v[158:161], v[210:213], v[72:75]
	v_mfma_f32_16x16x32_bf16 v[124:127], v[154:157], v[190:193], v[124:127]
	v_mfma_f32_16x16x32_bf16 v[120:123], v[162:165], v[190:193], v[120:123]
	v_mfma_f32_16x16x32_bf16 v[108:111], v[154:157], v[198:201], v[108:111]
	v_mfma_f32_16x16x32_bf16 v[104:107], v[162:165], v[198:201], v[104:107]
	v_mfma_f32_16x16x32_bf16 v[92:95], v[154:157], v[206:209], v[92:95]
	v_mfma_f32_16x16x32_bf16 v[88:91], v[162:165], v[206:209], v[88:91]
	v_mfma_f32_16x16x32_bf16 v[76:79], v[154:157], v[214:217], v[76:79]
	v_mfma_f32_16x16x32_bf16 v[72:75], v[162:165], v[214:217], v[72:75]
	s_setprio 0
	s_setprio 1
	v_mfma_f32_16x16x32_bf16 v[116:119], v[166:169], v[186:189], v[116:119]
	v_mfma_f32_16x16x32_bf16 v[112:115], v[178:181], v[186:189], v[112:115]
	v_mfma_f32_16x16x32_bf16 v[100:103], v[166:169], v[194:197], v[100:103]
	v_mfma_f32_16x16x32_bf16 v[96:99], v[178:181], v[194:197], v[96:99]
	v_mfma_f32_16x16x32_bf16 v[84:87], v[166:169], v[202:205], v[84:87]
	v_mfma_f32_16x16x32_bf16 v[80:83], v[178:181], v[202:205], v[80:83]
	v_mfma_f32_16x16x32_bf16 v[68:71], v[166:169], v[210:213], v[68:71]
	v_mfma_f32_16x16x32_bf16 v[64:67], v[178:181], v[210:213], v[64:67]
	v_mfma_f32_16x16x32_bf16 v[116:119], v[170:173], v[190:193], v[116:119]
	v_mfma_f32_16x16x32_bf16 v[112:115], v[182:185], v[190:193], v[112:115]
	v_mfma_f32_16x16x32_bf16 v[100:103], v[170:173], v[198:201], v[100:103]
	v_mfma_f32_16x16x32_bf16 v[96:99], v[182:185], v[198:201], v[96:99]
	v_mfma_f32_16x16x32_bf16 v[84:87], v[170:173], v[206:209], v[84:87]
	v_mfma_f32_16x16x32_bf16 v[80:83], v[182:185], v[206:209], v[80:83]
	v_mfma_f32_16x16x32_bf16 v[68:71], v[170:173], v[214:217], v[68:71]
	v_mfma_f32_16x16x32_bf16 v[64:67], v[182:185], v[214:217], v[64:67]
	s_setprio 0
	s_barrier
; #define PG8_STAGE(bufoff, gbase, voff) do { _Pragma("unroll") for (int _i = 0; _i < 2; ++_i) \
;         __builtin_amdgcn_global_load_lds((const unsigned*)((const char*)(gbase) + (voff)[_i]), (LAS unsigned*)(lds + (bufoff) + ldsw + _i * 8192), 16, 0, 0); } while (0)
; #define PG8_LDA(dst, b, h) do { _Pragma("unroll") for (int m = 0; m < 4; ++m) _Pragma("unroll") for (int k = 0; k < 2; ++k) dst[m][k] = *(const LAS bf16x8*)(lds + PG8_SA(b, h) + aoff + m * 2048 + k * 1024); } while (0)
; #define PG8_MMA(ai, bj, At, Bt) do { __builtin_amdgcn_s_setprio(1); _Pragma("unroll") for (int m = 0; m < 4; ++m) _Pragma("unroll") for (int n = 0; n < 2; ++n) _Pragma("unroll") for (int k = 0; k < 2; ++k) \
;         acc[ai][bj][m][n] = __builtin_amdgcn_mfma_f32_16x16x32_bf16(Bt[n][k], At[m][k], acc[ai][bj][m][n], 0, 0, 0); __builtin_amdgcn_s_setprio(0); } while (0)
; #define PG8_WAIT_V(n) asm volatile("s_waitcnt vmcnt(" #n ")" ::: "memory")
; #define PG8_WAIT_L(n) asm volatile("s_waitcnt lgkmcnt(" #n ")" ::: "memory")
; #define PG8_BAR __builtin_amdgcn_s_barrier()
; #define PG8_SCHED __builtin_amdgcn_sched_barrier(0)
; template <class Epi>
; __device__ __forceinline__ void gemm_phase(LAS unsigned char* lds, const Gemm g, const StaticOrder& S, const Epi& E) {
;     ...
;             PG8_LDA(At, 1, 1); PG8_STAGE(PG8_SB(1, 0), b3, voffB); PG8_STAGE(PG8_SB(1, 1), b3 + hstepB, voffB); PG8_STAGE(PG8_SA(1, 0), a3, voffA);
;             PG8_WAIT_V(8); PG8_WAIT_L(0); PG8_BAR; PG8_MMA(1, 0, At, B0); PG8_MMA(1, 1, At, B1); PG8_BAR; PG8_SCHED;
;         }
;         if (wr == 0) PG8_BAR;
	s_mov_b32 m0, s92
	v_lshl_add_u64 v[174:175], v[174:175], 0, s[8:9]
	ds_read_b128 v[186:189], v147 offset:49152
	ds_read_b128 v[190:193], v147 offset:50176
	ds_read_b128 v[194:197], v147 offset:51200
	ds_read_b128 v[198:201], v147 offset:52224
	ds_read_b128 v[202:205], v147 offset:53248
	ds_read_b128 v[206:209], v147 offset:54272
	ds_read_b128 v[210:213], v147 offset:55296
	ds_read_b128 v[214:217], v147 offset:56320
	global_load_lds_dwordx4 v[174:175], off
	v_lshl_add_u64 v[174:175], v[218:219], 0, s[8:9]
	s_mov_b32 m0, s90
	s_nop 0
	global_load_lds_dwordx4 v[174:175], off
	v_lshl_add_u64 v[174:175], s[54:55], 0, v[130:131]
	s_mov_b32 m0, s91
	s_nop 0
	global_load_lds_dwordx4 v[174:175], off
	v_lshl_add_u64 v[174:175], s[54:55], 0, v[134:135]
	s_mov_b32 m0, s89
	s_nop 0
	global_load_lds_dwordx4 v[174:175], off
	v_lshl_add_u64 v[174:175], v[220:221], 0, s[8:9]
	s_mov_b32 m0, s81
	s_nop 0
	global_load_lds_dwordx4 v[174:175], off
	v_lshl_add_u64 v[174:175], v[222:223], 0, s[8:9]
	s_mov_b32 m0, s82
	s_nop 0
	global_load_lds_dwordx4 v[174:175], off
	s_waitcnt vmcnt(8)
	s_waitcnt lgkmcnt(0)
	s_barrier
	s_setprio 1
	s_waitcnt lgkmcnt(0)
	v_mfma_f32_16x16x32_bf16 v[60:63], v[140:143], v[186:189], v[60:63]
	v_mfma_f32_16x16x32_bf16 v[56:59], v[158:161], v[186:189], v[56:59]
	v_mfma_f32_16x16x32_bf16 v[44:47], v[140:143], v[194:197], v[44:47]
	v_mfma_f32_16x16x32_bf16 v[40:43], v[158:161], v[194:197], v[40:43]
	v_mfma_f32_16x16x32_bf16 v[28:31], v[140:143], v[202:205], v[28:31]
	v_mfma_f32_16x16x32_bf16 v[24:27], v[158:161], v[202:205], v[24:27]
	v_mfma_f32_16x16x32_bf16 v[12:15], v[140:143], v[210:213], v[12:15]
	v_mfma_f32_16x16x32_bf16 v[8:11], v[158:161], v[210:213], v[8:11]
	v_mfma_f32_16x16x32_bf16 v[60:63], v[154:157], v[190:193], v[60:63]
	v_mfma_f32_16x16x32_bf16 v[56:59], v[162:165], v[190:193], v[56:59]
	v_mfma_f32_16x16x32_bf16 v[44:47], v[154:157], v[198:201], v[44:47]
	v_mfma_f32_16x16x32_bf16 v[40:43], v[162:165], v[198:201], v[40:43]
	v_mfma_f32_16x16x32_bf16 v[28:31], v[154:157], v[206:209], v[28:31]
	v_mfma_f32_16x16x32_bf16 v[24:27], v[162:165], v[206:209], v[24:27]
	v_mfma_f32_16x16x32_bf16 v[12:15], v[154:157], v[214:217], v[12:15]
	v_mfma_f32_16x16x32_bf16 v[8:11], v[162:165], v[214:217], v[8:11]
	s_setprio 0
	s_setprio 1
	v_mfma_f32_16x16x32_bf16 v[52:55], v[166:169], v[186:189], v[52:55]
	v_mfma_f32_16x16x32_bf16 v[48:51], v[178:181], v[186:189], v[48:51]
	v_mfma_f32_16x16x32_bf16 v[36:39], v[166:169], v[194:197], v[36:39]
	v_mfma_f32_16x16x32_bf16 v[32:35], v[178:181], v[194:197], v[32:35]
	v_mfma_f32_16x16x32_bf16 v[20:23], v[166:169], v[202:205], v[20:23]
	v_mfma_f32_16x16x32_bf16 v[16:19], v[178:181], v[202:205], v[16:19]
	v_mfma_f32_16x16x32_bf16 v[4:7], v[166:169], v[210:213], v[4:7]
	v_mfma_f32_16x16x32_bf16 v[0:3], v[178:181], v[210:213], v[0:3]
	v_mfma_f32_16x16x32_bf16 v[52:55], v[170:173], v[190:193], v[52:55]
	v_mfma_f32_16x16x32_bf16 v[48:51], v[182:185], v[190:193], v[48:51]
	v_mfma_f32_16x16x32_bf16 v[36:39], v[170:173], v[198:201], v[36:39]
	v_mfma_f32_16x16x32_bf16 v[32:35], v[182:185], v[198:201], v[32:35]
	v_mfma_f32_16x16x32_bf16 v[20:23], v[170:173], v[206:209], v[20:23]
	v_mfma_f32_16x16x32_bf16 v[16:19], v[182:185], v[206:209], v[16:19]
	v_mfma_f32_16x16x32_bf16 v[4:7], v[170:173], v[214:217], v[4:7]
	v_mfma_f32_16x16x32_bf16 v[0:3], v[182:185], v[214:217], v[0:3]
	s_setprio 0
	s_barrier
	s_andn2_b64 vcc, exec, s[52:53]
	s_mov_b64 s[54:55], -1
	s_mov_b64 s[52:53], 0
	s_mov_b64 s[56:57], 0x100
	s_cbranch_vccz .LBB0_612
	s_and_b64 vcc, exec, s[10:11]
	s_cbranch_vccz .LBB0_615
	s_barrier

; #define PG8_STAGE(bufoff, gbase, voff) do { _Pragma("unroll") for (int _i = 0; _i < 2; ++_i) \
;         __builtin_amdgcn_global_load_lds((const unsigned*)((const char*)(gbase) + (voff)[_i]), (LAS unsigned*)(lds + (bufoff) + ldsw + _i * 8192), 16, 0, 0); } while (0)
; #define PG8_LDA(dst, b, h) do { _Pragma("unroll") for (int m = 0; m < 4; ++m) _Pragma("unroll") for (int k = 0; k < 2; ++k) dst[m][k] = *(const LAS bf16x8*)(lds + PG8_SA(b, h) + aoff + m * 2048 + k * 1024); } while (0)
; #define PG8_LDB(dst, b, h) do { _Pragma("unroll") for (int n = 0; n < 2; ++n) _Pragma("unroll") for (int k = 0; k < 2; ++k) dst[n][k] = *(const LAS bf16x8*)(lds + PG8_SB(b, h) + boff + n * 2048 + k * 1024); } while (0)
; #define PG8_MMA(ai, bj, At, Bt) do { __builtin_amdgcn_s_setprio(1); _Pragma("unroll") for (int m = 0; m < 4; ++m) _Pragma("unroll") for (int n = 0; n < 2; ++n) _Pragma("unroll") for (int k = 0; k < 2; ++k) \
;         acc[ai][bj][m][n] = __builtin_amdgcn_mfma_f32_16x16x32_bf16(Bt[n][k], At[m][k], acc[ai][bj][m][n], 0, 0, 0); __builtin_amdgcn_s_setprio(0); } while (0)
; #define PG8_BAR __builtin_amdgcn_s_barrier()
; template <class Epi>
; __device__ __forceinline__ void gemm_phase(LAS unsigned char* lds, const Gemm g, const StaticOrder& S, const Epi& E) {
;     ...
;         const bool has_next = S.next(ui + 1, nxt);
;         const char* nA = has_next ? (const char*)g.A + (size_t)nxt.pm * tstepA : cA; const char* nB = has_next ? (const char*)g.Bt + (size_t)nxt.pn * tstepB : cB;
; #pragma nounroll
;         for (int t = 0; t < nt; t += 2) {
;             const bool last = (t == nt - 2);
;             const char* a1 = cA + (size_t)(t + 1) * kstep;
;             const char* a2 = last ? nA : cA + (size_t)(t + 2) * kstep; const char* b2 = last ? nB : cB + (size_t)(t + 2) * kstep;
;             const char* a3 = a2 + kstep; const char* b3 = b2 + kstep;
;             PG8_LDB(B0, 0, 0); PG8_LDB(B1, 0, 1); PG8_SCHED; PG8_LDA(At, 0, 0); PG8_STAGE(PG8_SA(1, 1), a1 + hstepA, voffA);
;             PG8_WAIT_V(8); PG8_WAIT_L(0); PG8_BAR; PG8_MMA(0, 0, At, B0); PG8_MMA(0, 1, At, B1); PG8_BAR; PG8_SCHED;
;             PG8_LDA(At, 0, 1); PG8_STAGE(PG8_SB(0, 0), b2, voffB); PG8_STAGE(PG8_SB(0, 1), b2 + hstepB, voffB); PG8_STAGE(PG8_SA(0, 0), a2, voffA);
;             PG8_WAIT_V(8); PG8_WAIT_L(0); PG8_BAR; PG8_MMA(1, 0, At, B0); PG8_MMA(1, 1, At, B1); PG8_BAR; PG8_SCHED;
.LBB0_791:
	s_add_u32 s0, s0, 0xb0080
	s_addc_u32 s1, s1, 0
	s_add_u32 s75, s34, 0x100
	s_addc_u32 s76, s35, 0
	s_mov_b32 s77, -2
	s_waitcnt lgkmcnt(0)
	s_nop 0
	ds_read_b128 v[128:131], v182
	ds_read_b128 v[132:135], v182 offset:1024
	ds_read_b128 v[136:139], v182 offset:2048
	ds_read_b128 v[140:143], v182 offset:3072
	ds_read_b128 v[160:163], v183
	ds_read_b128 v[164:167], v183 offset:1024
	ds_read_b128 v[168:171], v183 offset:2048
	ds_read_b128 v[172:175], v183 offset:3072
	s_add_u32 s34, s0, 0xfff50080
	s_addc_u32 s35, s1, -1
	s_cmp_eq_u32 s77, 40
	s_cselect_b32 s39, s7, s35
	s_cselect_b32 s38, s6, s34
	s_cselect_b32 s35, s23, s76
	s_cselect_b32 s34, s22, s75
	v_lshl_add_u64 v[178:179], s[0:1], 0, v[152:153]
	s_add_i32 m0, s43, 0xc000
	ds_read_b128 v[186:189], v184
	ds_read_b128 v[190:193], v184 offset:1024
	ds_read_b128 v[194:197], v184 offset:2048
	ds_read_b128 v[198:201], v184 offset:3072
	ds_read_b128 v[202:205], v184 offset:4096
	ds_read_b128 v[206:209], v184 offset:5120
	ds_read_b128 v[210:213], v184 offset:6144
	ds_read_b128 v[214:217], v184 offset:7168
	global_load_lds_dwordx4 v[178:179], off
	v_lshl_add_u64 v[178:179], s[0:1], 0, v[154:155]
	s_add_i32 m0, s43, 0xe000
	s_nop 0
	global_load_lds_dwordx4 v[178:179], off
	s_waitcnt vmcnt(8)
	s_waitcnt lgkmcnt(0)
	s_nop 0
	s_barrier
	s_setprio 1
	s_waitcnt lgkmcnt(0)
	v_mfma_f32_16x16x32_bf16 v[124:127], v[128:131], v[186:189], 0
	v_mfma_f32_16x16x32_bf16 v[120:123], v[136:139], v[186:189], 0
	v_mfma_f32_16x16x32_bf16 v[108:111], v[128:131], v[194:197], 0
	v_mfma_f32_16x16x32_bf16 v[104:107], v[136:139], v[194:197], 0
	v_mfma_f32_16x16x32_bf16 v[92:95], v[128:131], v[202:205], 0
	v_mfma_f32_16x16x32_bf16 v[88:91], v[136:139], v[202:205], 0
	v_mfma_f32_16x16x32_bf16 v[76:79], v[128:131], v[210:213], 0
	v_mfma_f32_16x16x32_bf16 v[72:75], v[136:139], v[210:213], 0
	v_mfma_f32_16x16x32_bf16 v[124:127], v[132:135], v[190:193], v[124:127]
	v_mfma_f32_16x16x32_bf16 v[120:123], v[140:143], v[190:193], v[120:123]
	v_mfma_f32_16x16x32_bf16 v[108:111], v[132:135], v[198:201], v[108:111]
	v_mfma_f32_16x16x32_bf16 v[104:107], v[140:143], v[198:201], v[104:107]
	v_mfma_f32_16x16x32_bf16 v[92:95], v[132:135], v[206:209], v[92:95]
	v_mfma_f32_16x16x32_bf16 v[88:91], v[140:143], v[206:209], v[88:91]
	v_mfma_f32_16x16x32_bf16 v[76:79], v[132:135], v[214:217], v[76:79]
	v_mfma_f32_16x16x32_bf16 v[72:75], v[140:143], v[214:217], v[72:75]
	s_setprio 0
	s_setprio 1
	v_mfma_f32_16x16x32_bf16 v[116:119], v[160:163], v[186:189], 0
	v_mfma_f32_16x16x32_bf16 v[112:115], v[168:171], v[186:189], 0
	v_mfma_f32_16x16x32_bf16 v[100:103], v[160:163], v[194:197], 0
	v_mfma_f32_16x16x32_bf16 v[96:99], v[168:171], v[194:197], 0
	v_mfma_f32_16x16x32_bf16 v[84:87], v[160:163], v[202:205], 0
	v_mfma_f32_16x16x32_bf16 v[80:83], v[168:171], v[202:205], 0
	v_mfma_f32_16x16x32_bf16 v[68:71], v[160:163], v[210:213], 0
	v_mfma_f32_16x16x32_bf16 v[64:67], v[168:171], v[210:213], 0
	v_mfma_f32_16x16x32_bf16 v[116:119], v[164:167], v[190:193], v[116:119]
	v_mfma_f32_16x16x32_bf16 v[112:115], v[172:175], v[190:193], v[112:115]
	v_mfma_f32_16x16x32_bf16 v[100:103], v[164:167], v[198:201], v[100:103]
	v_mfma_f32_16x16x32_bf16 v[96:99], v[172:175], v[198:201], v[96:99]
	v_mfma_f32_16x16x32_bf16 v[84:87], v[164:167], v[206:209], v[84:87]
	v_mfma_f32_16x16x32_bf16 v[80:83], v[172:175], v[206:209], v[80:83]
	v_mfma_f32_16x16x32_bf16 v[68:71], v[164:167], v[214:217], v[68:71]
	v_mfma_f32_16x16x32_bf16 v[64:67], v[172:175], v[214:217], v[64:67]
	s_setprio 0
	s_barrier
	s_add_i32 s78, s69, s42
	v_lshl_add_u64 v[178:179], s[34:35], 0, v[146:147]
	s_mov_b32 m0, s78
	ds_read_b128 v[186:189], v184 offset:16384
	ds_read_b128 v[190:193], v184 offset:17408
	ds_read_b128 v[194:197], v184 offset:18432
	ds_read_b128 v[198:201], v184 offset:19456
	ds_read_b128 v[202:205], v184 offset:20480
	ds_read_b128 v[206:209], v184 offset:21504
	ds_read_b128 v[210:213], v184 offset:22528
	ds_read_b128 v[214:217], v184 offset:23552
	global_load_lds_dwordx4 v[178:179], off
	s_add_i32 m0, s78, 0x2000
	s_add_u32 s78, s34, 0xb0000
	v_lshl_add_u64 v[218:219], s[34:35], 0, v[150:151]
	s_addc_u32 s79, s35, 0
	s_add_i32 s80, s70, s42
	global_load_lds_dwordx4 v[218:219], off
	v_lshl_add_u64 v[220:221], s[78:79], 0, v[146:147]
	s_mov_b32 m0, s80
	v_lshl_add_u64 v[222:223], s[38:39], 0, v[148:149]
	global_load_lds_dwordx4 v[220:221], off
	v_lshl_add_u64 v[220:221], s[78:79], 0, v[150:151]
	s_add_i32 m0, s80, 0x2000
	s_nop 0
	global_load_lds_dwordx4 v[220:221], off
	v_lshl_add_u64 v[220:221], s[38:39], 0, v[144:145]
	s_mov_b32 m0, s43
	s_nop 0
	global_load_lds_dwordx4 v[220:221], off
	s_mov_b32 m0, s52
	s_nop 0
	global_load_lds_dwordx4 v[222:223], off
	s_waitcnt vmcnt(8)
	s_waitcnt lgkmcnt(0)
	s_nop 0
	s_barrier
; #define PG8_STAGE(bufoff, gbase, voff) do { _Pragma("unroll") for (int _i = 0; _i < 2; ++_i) \
;         __builtin_amdgcn_global_load_lds((const unsigned*)((const char*)(gbase) + (voff)[_i]), (LAS unsigned*)(lds + (bufoff) + ldsw + _i * 8192), 16, 0, 0); } while (0)
; #define PG8_LDA(dst, b, h) do { _Pragma("unroll") for (int m = 0; m < 4; ++m) _Pragma("unroll") for (int k = 0; k < 2; ++k) dst[m][k] = *(const LAS bf16x8*)(lds + PG8_SA(b, h) + aoff + m * 2048 + k * 1024); } while (0)
; #define PG8_LDB(dst, b, h) do { _Pragma("unroll") for (int n = 0; n < 2; ++n) _Pragma("unroll") for (int k = 0; k < 2; ++k) dst[n][k] = *(const LAS bf16x8*)(lds + PG8_SB(b, h) + boff + n * 2048 + k * 1024); } while (0)
; #define PG8_MMA(ai, bj, At, Bt) do { __builtin_amdgcn_s_setprio(1); _Pragma("unroll") for (int m = 0; m < 4; ++m) _Pragma("unroll") for (int n = 0; n < 2; ++n) _Pragma("unroll") for (int k = 0; k < 2; ++k) \
;         acc[ai][bj][m][n] = __builtin_amdgcn_mfma_f32_16x16x32_bf16(Bt[n][k], At[m][k], acc[ai][bj][m][n], 0, 0, 0); __builtin_amdgcn_s_setprio(0); } while (0)
; #define PG8_WAIT_V(n) asm volatile("s_waitcnt vmcnt(" #n ")" ::: "memory")
; #define PG8_WAIT_L(n) asm volatile("s_waitcnt lgkmcnt(" #n ")" ::: "memory")
; #define PG8_BAR __builtin_amdgcn_s_barrier()
; #define PG8_SCHED __builtin_amdgcn_sched_barrier(0)
; template <class Epi>
; __device__ __forceinline__ void gemm_phase(LAS unsigned char* lds, const Gemm g, const StaticOrder& S, const Epi& E) {
;     ...
;             PG8_WAIT_V(8); PG8_WAIT_L(0); PG8_BAR; PG8_MMA(1, 0, At, B0); PG8_MMA(1, 1, At, B1); PG8_BAR; PG8_SCHED;
;             PG8_LDB(B0, 1, 0); PG8_LDB(B1, 1, 1); PG8_SCHED; PG8_LDA(At, 1, 0); PG8_STAGE(PG8_SA(0, 1), a2 + hstepA, voffA);
;             PG8_WAIT_V(8); PG8_WAIT_L(0); PG8_BAR; PG8_MMA(0, 0, At, B0); PG8_MMA(0, 1, At, B1); PG8_BAR; PG8_SCHED;
;             PG8_LDA(At, 1, 1); PG8_STAGE(PG8_SB(1, 0), b3, voffB); PG8_STAGE(PG8_SB(1, 1), b3 + hstepB, voffB); PG8_STAGE(PG8_SA(1, 0), a3, voffA);
;             PG8_WAIT_V(8); PG8_WAIT_L(0); PG8_BAR; PG8_MMA(1, 0, At, B0); PG8_MMA(1, 1, At, B1); PG8_BAR; PG8_SCHED;
	s_setprio 1
	s_waitcnt lgkmcnt(0)
	v_mfma_f32_16x16x32_bf16 v[60:63], v[128:131], v[186:189], 0
	v_mfma_f32_16x16x32_bf16 v[56:59], v[136:139], v[186:189], 0
	v_mfma_f32_16x16x32_bf16 v[44:47], v[128:131], v[194:197], 0
	v_mfma_f32_16x16x32_bf16 v[40:43], v[136:139], v[194:197], 0
	v_mfma_f32_16x16x32_bf16 v[28:31], v[128:131], v[202:205], 0
	v_mfma_f32_16x16x32_bf16 v[24:27], v[136:139], v[202:205], 0
	v_mfma_f32_16x16x32_bf16 v[12:15], v[128:131], v[210:213], 0
	v_mfma_f32_16x16x32_bf16 v[8:11], v[136:139], v[210:213], 0
	v_mfma_f32_16x16x32_bf16 v[60:63], v[132:135], v[190:193], v[60:63]
	v_mfma_f32_16x16x32_bf16 v[56:59], v[140:143], v[190:193], v[56:59]
	v_mfma_f32_16x16x32_bf16 v[44:47], v[132:135], v[198:201], v[44:47]
	v_mfma_f32_16x16x32_bf16 v[40:43], v[140:143], v[198:201], v[40:43]
	v_mfma_f32_16x16x32_bf16 v[28:31], v[132:135], v[206:209], v[28:31]
	v_mfma_f32_16x16x32_bf16 v[24:27], v[140:143], v[206:209], v[24:27]
	v_mfma_f32_16x16x32_bf16 v[12:15], v[132:135], v[214:217], v[12:15]
	v_mfma_f32_16x16x32_bf16 v[8:11], v[140:143], v[214:217], v[8:11]
	s_setprio 0
	s_setprio 1
	v_mfma_f32_16x16x32_bf16 v[52:55], v[160:163], v[186:189], 0
	v_mfma_f32_16x16x32_bf16 v[48:51], v[168:171], v[186:189], 0
	v_mfma_f32_16x16x32_bf16 v[36:39], v[160:163], v[194:197], 0
	v_mfma_f32_16x16x32_bf16 v[32:35], v[168:171], v[194:197], 0
	v_mfma_f32_16x16x32_bf16 v[20:23], v[160:163], v[202:205], 0
	v_mfma_f32_16x16x32_bf16 v[16:19], v[168:171], v[202:205], 0
	v_mfma_f32_16x16x32_bf16 v[4:7], v[160:163], v[210:213], 0
	v_mfma_f32_16x16x32_bf16 v[0:3], v[168:171], v[210:213], 0
	v_mfma_f32_16x16x32_bf16 v[52:55], v[164:167], v[190:193], v[52:55]
	v_mfma_f32_16x16x32_bf16 v[48:51], v[172:175], v[190:193], v[48:51]
	v_mfma_f32_16x16x32_bf16 v[36:39], v[164:167], v[198:201], v[36:39]
	v_mfma_f32_16x16x32_bf16 v[32:35], v[172:175], v[198:201], v[32:35]
	v_mfma_f32_16x16x32_bf16 v[20:23], v[164:167], v[206:209], v[20:23]
	v_mfma_f32_16x16x32_bf16 v[16:19], v[172:175], v[206:209], v[16:19]
	v_mfma_f32_16x16x32_bf16 v[4:7], v[164:167], v[214:217], v[4:7]
	v_mfma_f32_16x16x32_bf16 v[0:3], v[172:175], v[214:217], v[0:3]
	s_setprio 0
	s_barrier
	s_add_i32 s78, 0, 0x18000
	s_add_i32 s79, 0, 0x1c000
	v_add_u32_e32 v140, s78, v181
	v_add_u32_e32 v172, s79, v181
	ds_read_b128 v[128:131], v140
	ds_read_b128 v[132:135], v140 offset:1024
	ds_read_b128 v[136:139], v140 offset:2048
	ds_read_b128 v[140:143], v140 offset:3072
	ds_read_b128 v[160:163], v172
	ds_read_b128 v[164:167], v172 offset:1024
	ds_read_b128 v[168:171], v172 offset:2048
	ds_read_b128 v[172:175], v172 offset:3072
	s_add_u32 s38, s38, 0xb0000
	s_addc_u32 s39, s39, 0
	s_mov_b32 m0, s53
	v_lshl_add_u64 v[226:227], s[38:39], 0, v[144:145]
	ds_read_b128 v[186:189], v184 offset:32768
	ds_read_b128 v[190:193], v184 offset:33792
	ds_read_b128 v[194:197], v184 offset:34816
	ds_read_b128 v[198:201], v184 offset:35840
	ds_read_b128 v[202:205], v184 offset:36864
	ds_read_b128 v[206:209], v184 offset:37888
	ds_read_b128 v[210:213], v184 offset:38912
	ds_read_b128 v[214:217], v184 offset:39936
	global_load_lds_dwordx4 v[226:227], off
	v_lshl_add_u64 v[226:227], s[38:39], 0, v[148:149]
	s_mov_b32 m0, s54
	s_nop 0
	global_load_lds_dwordx4 v[226:227], off
	s_waitcnt vmcnt(8)
	s_waitcnt lgkmcnt(0)
	s_nop 0
	s_barrier
	s_setprio 1
	s_waitcnt lgkmcnt(0)
	v_mfma_f32_16x16x32_bf16 v[124:127], v[128:131], v[186:189], v[124:127]
	v_mfma_f32_16x16x32_bf16 v[120:123], v[136:139], v[186:189], v[120:123]
	v_mfma_f32_16x16x32_bf16 v[108:111], v[128:131], v[194:197], v[108:111]
	v_mfma_f32_16x16x32_bf16 v[104:107], v[136:139], v[194:197], v[104:107]
	v_mfma_f32_16x16x32_bf16 v[92:95], v[128:131], v[202:205], v[92:95]
	v_mfma_f32_16x16x32_bf16 v[88:91], v[136:139], v[202:205], v[88:91]
	v_mfma_f32_16x16x32_bf16 v[76:79], v[128:131], v[210:213], v[76:79]
	v_mfma_f32_16x16x32_bf16 v[72:75], v[136:139], v[210:213], v[72:75]
	v_mfma_f32_16x16x32_bf16 v[124:127], v[132:135], v[190:193], v[124:127]
	v_mfma_f32_16x16x32_bf16 v[120:123], v[140:143], v[190:193], v[120:123]
	v_mfma_f32_16x16x32_bf16 v[108:111], v[132:135], v[198:201], v[108:111]
	v_mfma_f32_16x16x32_bf16 v[104:107], v[140:143], v[198:201], v[104:107]
	v_mfma_f32_16x16x32_bf16 v[92:95], v[132:135], v[206:209], v[92:95]
	v_mfma_f32_16x16x32_bf16 v[88:91], v[140:143], v[206:209], v[88:91]
	v_mfma_f32_16x16x32_bf16 v[76:79], v[132:135], v[214:217], v[76:79]
	v_mfma_f32_16x16x32_bf16 v[72:75], v[140:143], v[214:217], v[72:75]
	s_setprio 0
	s_setprio 1
	v_mfma_f32_16x16x32_bf16 v[116:119], v[160:163], v[186:189], v[116:119]
	v_mfma_f32_16x16x32_bf16 v[112:115], v[168:171], v[186:189], v[112:115]
	v_mfma_f32_16x16x32_bf16 v[100:103], v[160:163], v[194:197], v[100:103]
	v_mfma_f32_16x16x32_bf16 v[96:99], v[168:171], v[194:197], v[96:99]
	v_mfma_f32_16x16x32_bf16 v[84:87], v[160:163], v[202:205], v[84:87]
	v_mfma_f32_16x16x32_bf16 v[80:83], v[168:171], v[202:205], v[80:83]
	v_mfma_f32_16x16x32_bf16 v[68:71], v[160:163], v[210:213], v[68:71]
	v_mfma_f32_16x16x32_bf16 v[64:67], v[168:171], v[210:213], v[64:67]
	v_mfma_f32_16x16x32_bf16 v[116:119], v[164:167], v[190:193], v[116:119]
	v_mfma_f32_16x16x32_bf16 v[112:115], v[172:175], v[190:193], v[112:115]
	v_mfma_f32_16x16x32_bf16 v[100:103], v[164:167], v[198:201], v[100:103]
	v_mfma_f32_16x16x32_bf16 v[96:99], v[172:175], v[198:201], v[96:99]
	v_mfma_f32_16x16x32_bf16 v[84:87], v[164:167], v[206:209], v[84:87]
	v_mfma_f32_16x16x32_bf16 v[80:83], v[172:175], v[206:209], v[80:83]
	v_mfma_f32_16x16x32_bf16 v[68:71], v[164:167], v[214:217], v[68:71]
	v_mfma_f32_16x16x32_bf16 v[64:67], v[172:175], v[214:217], v[64:67]
	s_setprio 0
	s_barrier
; #define PG8_STAGE(bufoff, gbase, voff) do { _Pragma("unroll") for (int _i = 0; _i < 2; ++_i) \
;         __builtin_amdgcn_global_load_lds((const unsigned*)((const char*)(gbase) + (voff)[_i]), (LAS unsigned*)(lds + (bufoff) + ldsw + _i * 8192), 16, 0, 0); } while (0)
; #define PG8_LDA(dst, b, h) do { _Pragma("unroll") for (int m = 0; m < 4; ++m) _Pragma("unroll") for (int k = 0; k < 2; ++k) dst[m][k] = *(const LAS bf16x8*)(lds + PG8_SA(b, h) + aoff + m * 2048 + k * 1024); } while (0)
; #define PG8_LDB(dst, b, h) do { _Pragma("unroll") for (int n = 0; n < 2; ++n) _Pragma("unroll") for (int k = 0; k < 2; ++k) dst[n][k] = *(const LAS bf16x8*)(lds + PG8_SB(b, h) + boff + n * 2048 + k * 1024); } while (0)
; #define PG8_MMA(ai, bj, At, Bt) do { __builtin_amdgcn_s_setprio(1); _Pragma("unroll") for (int m = 0; m < 4; ++m) _Pragma("unroll") for (int n = 0; n < 2; ++n) _Pragma("unroll") for (int k = 0; k < 2; ++k) \
;         acc[ai][bj][m][n] = __builtin_amdgcn_mfma_f32_16x16x32_bf16(Bt[n][k], At[m][k], acc[ai][bj][m][n], 0, 0, 0); __builtin_amdgcn_s_setprio(0); } while (0)
; #define PG8_WAIT_V(n) asm volatile("s_waitcnt vmcnt(" #n ")" ::: "memory")
; #define PG8_WAIT_L(n) asm volatile("s_waitcnt lgkmcnt(" #n ")" ::: "memory")
; #define PG8_BAR __builtin_amdgcn_s_barrier()
; #define PG8_SCHED __builtin_amdgcn_sched_barrier(0)
; template <class Epi>
; __device__ __forceinline__ void gemm_phase(LAS unsigned char* lds, const Gemm g, const StaticOrder& S, const Epi& E) {
;     ...
;         for (int t = 0; t < nt; t += 2) {
;             const bool last = (t == nt - 2);
;             const char* a1 = cA + (size_t)(t + 1) * kstep;
;             const char* a2 = last ? nA : cA + (size_t)(t + 2) * kstep; const char* b2 = last ? nB : cB + (size_t)(t + 2) * kstep;
;             const char* a3 = a2 + kstep; const char* b3 = b2 + kstep;
;             PG8_LDB(B0, 0, 0); PG8_LDB(B1, 0, 1); PG8_SCHED; PG8_LDA(At, 0, 0); PG8_STAGE(PG8_SA(1, 1), a1 + hstepA, voffA);
;             PG8_WAIT_V(8); PG8_WAIT_L(0); PG8_BAR; PG8_MMA(0, 0, At, B0); PG8_MMA(0, 1, At, B1); PG8_BAR; PG8_SCHED;
;     ...
;             PG8_LDA(At, 1, 1); PG8_STAGE(PG8_SB(1, 0), b3, voffB); PG8_STAGE(PG8_SB(1, 1), b3 + hstepB, voffB); PG8_STAGE(PG8_SA(1, 0), a3, voffA);
;             PG8_WAIT_V(8); PG8_WAIT_L(0); PG8_BAR; PG8_MMA(1, 0, At, B0); PG8_MMA(1, 1, At, B1); PG8_BAR; PG8_SCHED;
	s_add_i32 s38, s78, s42
	v_lshl_add_u64 v[178:179], v[178:179], 0, s[16:17]
	s_mov_b32 m0, s38
	ds_read_b128 v[186:189], v184 offset:49152
	ds_read_b128 v[190:193], v184 offset:50176
	ds_read_b128 v[194:197], v184 offset:51200
	ds_read_b128 v[198:201], v184 offset:52224
	ds_read_b128 v[202:205], v184 offset:53248
	ds_read_b128 v[206:209], v184 offset:54272
	ds_read_b128 v[210:213], v184 offset:55296
	ds_read_b128 v[214:217], v184 offset:56320
	global_load_lds_dwordx4 v[178:179], off
	s_add_i32 m0, s38, 0x2000
	s_add_u32 s34, s34, 0xb0080
	v_lshl_add_u64 v[178:179], v[218:219], 0, s[16:17]
	s_addc_u32 s35, s35, 0
	s_add_i32 s38, s79, s42
	global_load_lds_dwordx4 v[178:179], off
	v_lshl_add_u64 v[178:179], s[34:35], 0, v[146:147]
	s_mov_b32 m0, s38
	s_nop 0
	global_load_lds_dwordx4 v[178:179], off
	v_lshl_add_u64 v[178:179], s[34:35], 0, v[150:151]
	s_add_i32 m0, s38, 0x2000
	s_nop 0
	global_load_lds_dwordx4 v[178:179], off
	v_lshl_add_u64 v[178:179], v[220:221], 0, s[16:17]
	s_mov_b32 m0, s62
	s_nop 0
	global_load_lds_dwordx4 v[178:179], off
	v_lshl_add_u64 v[178:179], v[222:223], 0, s[16:17]
	s_mov_b32 m0, s63
	s_nop 0
	global_load_lds_dwordx4 v[178:179], off
	s_waitcnt vmcnt(8)
	s_waitcnt lgkmcnt(0)
	s_barrier
	s_setprio 1
	s_waitcnt lgkmcnt(0)
	v_mfma_f32_16x16x32_bf16 v[60:63], v[128:131], v[186:189], v[60:63]
	v_mfma_f32_16x16x32_bf16 v[56:59], v[136:139], v[186:189], v[56:59]
	v_mfma_f32_16x16x32_bf16 v[44:47], v[128:131], v[194:197], v[44:47]
	v_mfma_f32_16x16x32_bf16 v[40:43], v[136:139], v[194:197], v[40:43]
	v_mfma_f32_16x16x32_bf16 v[28:31], v[128:131], v[202:205], v[28:31]
	v_mfma_f32_16x16x32_bf16 v[24:27], v[136:139], v[202:205], v[24:27]
	v_mfma_f32_16x16x32_bf16 v[12:15], v[128:131], v[210:213], v[12:15]
	v_mfma_f32_16x16x32_bf16 v[8:11], v[136:139], v[210:213], v[8:11]
	v_mfma_f32_16x16x32_bf16 v[60:63], v[132:135], v[190:193], v[60:63]
	v_mfma_f32_16x16x32_bf16 v[56:59], v[140:143], v[190:193], v[56:59]
	v_mfma_f32_16x16x32_bf16 v[44:47], v[132:135], v[198:201], v[44:47]
	v_mfma_f32_16x16x32_bf16 v[40:43], v[140:143], v[198:201], v[40:43]
	v_mfma_f32_16x16x32_bf16 v[28:31], v[132:135], v[206:209], v[28:31]
	v_mfma_f32_16x16x32_bf16 v[24:27], v[140:143], v[206:209], v[24:27]
	v_mfma_f32_16x16x32_bf16 v[12:15], v[132:135], v[214:217], v[12:15]
	v_mfma_f32_16x16x32_bf16 v[8:11], v[140:143], v[214:217], v[8:11]
	s_setprio 0
	s_setprio 1
	v_mfma_f32_16x16x32_bf16 v[52:55], v[160:163], v[186:189], v[52:55]
	v_mfma_f32_16x16x32_bf16 v[48:51], v[168:171], v[186:189], v[48:51]
	v_mfma_f32_16x16x32_bf16 v[36:39], v[160:163], v[194:197], v[36:39]
	v_mfma_f32_16x16x32_bf16 v[32:35], v[168:171], v[194:197], v[32:35]
	v_mfma_f32_16x16x32_bf16 v[20:23], v[160:163], v[202:205], v[20:23]
	v_mfma_f32_16x16x32_bf16 v[16:19], v[168:171], v[202:205], v[16:19]
	v_mfma_f32_16x16x32_bf16 v[4:7], v[160:163], v[210:213], v[4:7]
	v_mfma_f32_16x16x32_bf16 v[0:3], v[168:171], v[210:213], v[0:3]
	v_mfma_f32_16x16x32_bf16 v[52:55], v[164:167], v[190:193], v[52:55]
	v_mfma_f32_16x16x32_bf16 v[48:51], v[172:175], v[190:193], v[48:51]
	v_mfma_f32_16x16x32_bf16 v[36:39], v[164:167], v[198:201], v[36:39]
	v_mfma_f32_16x16x32_bf16 v[32:35], v[172:175], v[198:201], v[32:35]
	v_mfma_f32_16x16x32_bf16 v[20:23], v[164:167], v[206:209], v[20:23]
	v_mfma_f32_16x16x32_bf16 v[16:19], v[172:175], v[206:209], v[16:19]
	v_mfma_f32_16x16x32_bf16 v[4:7], v[164:167], v[214:217], v[4:7]
	v_mfma_f32_16x16x32_bf16 v[0:3], v[172:175], v[214:217], v[0:3]
	s_setprio 0
	s_barrier
	s_add_i32 s77, s77, 2
	s_add_u32 s0, s0, 0x100
	s_addc_u32 s1, s1, 0
	s_add_u32 s75, s75, 0x100
	s_addc_u32 s76, s76, 0
	s_cmp_gt_u32 s77, 41
.LBB0_792:
	ds_read_b128 v[128:131], v182
	ds_read_b128 v[132:135], v182 offset:1024
	ds_read_b128 v[136:139], v182 offset:2048
	ds_read_b128 v[140:143], v182 offset:3072
	ds_read_b128 v[160:163], v183
	ds_read_b128 v[164:167], v183 offset:1024
	ds_read_b128 v[168:171], v183 offset:2048
	ds_read_b128 v[172:175], v183 offset:3072
	s_add_u32 s34, s0, 0xfff50080
	s_addc_u32 s35, s1, -1
	s_cmp_eq_u32 s77, 40
	s_cselect_b32 s39, s7, s35
	s_cselect_b32 s38, s6, s34
	s_cselect_b32 s35, s23, s76
	s_cselect_b32 s34, s22, s75
	v_lshl_add_u64 v[178:179], s[0:1], 0, v[152:153]
	s_add_i32 m0, s43, 0xc000
	ds_read_b128 v[186:189], v184
	ds_read_b128 v[190:193], v184 offset:1024
	ds_read_b128 v[194:197], v184 offset:2048
	ds_read_b128 v[198:201], v184 offset:3072
	ds_read_b128 v[202:205], v184 offset:4096
	ds_read_b128 v[206:209], v184 offset:5120
	ds_read_b128 v[210:213], v184 offset:6144
	ds_read_b128 v[214:217], v184 offset:7168
	global_load_lds_dwordx4 v[178:179], off
	v_lshl_add_u64 v[178:179], s[0:1], 0, v[154:155]
	s_add_i32 m0, s43, 0xe000
	s_nop 0
	global_load_lds_dwordx4 v[178:179], off
	s_waitcnt vmcnt(8)
	s_waitcnt lgkmcnt(0)
	s_barrier
; #define PG8_STAGE(bufoff, gbase, voff) do { _Pragma("unroll") for (int _i = 0; _i < 2; ++_i) \
;         __builtin_amdgcn_global_load_lds((const unsigned*)((const char*)(gbase) + (voff)[_i]), (LAS unsigned*)(lds + (bufoff) + ldsw + _i * 8192), 16, 0, 0); } while (0)
; #define PG8_LDA(dst, b, h) do { _Pragma("unroll") for (int m = 0; m < 4; ++m) _Pragma("unroll") for (int k = 0; k < 2; ++k) dst[m][k] = *(const LAS bf16x8*)(lds + PG8_SA(b, h) + aoff + m * 2048 + k * 1024); } while (0)
; #define PG8_LDB(dst, b, h) do { _Pragma("unroll") for (int n = 0; n < 2; ++n) _Pragma("unroll") for (int k = 0; k < 2; ++k) dst[n][k] = *(const LAS bf16x8*)(lds + PG8_SB(b, h) + boff + n * 2048 + k * 1024); } while (0)
; #define PG8_MMA(ai, bj, At, Bt) do { __builtin_amdgcn_s_setprio(1); _Pragma("unroll") for (int m = 0; m < 4; ++m) _Pragma("unroll") for (int n = 0; n < 2; ++n) _Pragma("unroll") for (int k = 0; k < 2; ++k) \
;         acc[ai][bj][m][n] = __builtin_amdgcn_mfma_f32_16x16x32_bf16(Bt[n][k], At[m][k], acc[ai][bj][m][n], 0, 0, 0); __builtin_amdgcn_s_setprio(0); } while (0)
; #define PG8_WAIT_V(n) asm volatile("s_waitcnt vmcnt(" #n ")" ::: "memory")
; #define PG8_WAIT_L(n) asm volatile("s_waitcnt lgkmcnt(" #n ")" ::: "memory")
; #define PG8_BAR __builtin_amdgcn_s_barrier()
; #define PG8_SCHED __builtin_amdgcn_sched_barrier(0)
; template <class Epi>
; __device__ __forceinline__ void gemm_phase(LAS unsigned char* lds, const Gemm g, const StaticOrder& S, const Epi& E) {
;     ...
;             PG8_WAIT_V(8); PG8_WAIT_L(0); PG8_BAR; PG8_MMA(0, 0, At, B0); PG8_MMA(0, 1, At, B1); PG8_BAR; PG8_SCHED;
;             PG8_LDA(At, 0, 1); PG8_STAGE(PG8_SB(0, 0), b2, voffB); PG8_STAGE(PG8_SB(0, 1), b2 + hstepB, voffB); PG8_STAGE(PG8_SA(0, 0), a2, voffA);
;             PG8_WAIT_V(8); PG8_WAIT_L(0); PG8_BAR; PG8_MMA(1, 0, At, B0); PG8_MMA(1, 1, At, B1); PG8_BAR; PG8_SCHED;
;             PG8_LDB(B0, 1, 0); PG8_LDB(B1, 1, 1); PG8_SCHED; PG8_LDA(At, 1, 0); PG8_STAGE(PG8_SA(0, 1), a2 + hstepA, voffA);
;             PG8_WAIT_V(8); PG8_WAIT_L(0); PG8_BAR; PG8_MMA(0, 0, At, B0); PG8_MMA(0, 1, At, B1); PG8_BAR; PG8_SCHED;
	s_setprio 1
	s_waitcnt lgkmcnt(0)
	v_mfma_f32_16x16x32_bf16 v[124:127], v[128:131], v[186:189], v[124:127]
	v_mfma_f32_16x16x32_bf16 v[120:123], v[136:139], v[186:189], v[120:123]
	v_mfma_f32_16x16x32_bf16 v[108:111], v[128:131], v[194:197], v[108:111]
	v_mfma_f32_16x16x32_bf16 v[104:107], v[136:139], v[194:197], v[104:107]
	v_mfma_f32_16x16x32_bf16 v[92:95], v[128:131], v[202:205], v[92:95]
	v_mfma_f32_16x16x32_bf16 v[88:91], v[136:139], v[202:205], v[88:91]
	v_mfma_f32_16x16x32_bf16 v[76:79], v[128:131], v[210:213], v[76:79]
	v_mfma_f32_16x16x32_bf16 v[72:75], v[136:139], v[210:213], v[72:75]
	v_mfma_f32_16x16x32_bf16 v[124:127], v[132:135], v[190:193], v[124:127]
	v_mfma_f32_16x16x32_bf16 v[120:123], v[140:143], v[190:193], v[120:123]
	v_mfma_f32_16x16x32_bf16 v[108:111], v[132:135], v[198:201], v[108:111]
	v_mfma_f32_16x16x32_bf16 v[104:107], v[140:143], v[198:201], v[104:107]
	v_mfma_f32_16x16x32_bf16 v[92:95], v[132:135], v[206:209], v[92:95]
	v_mfma_f32_16x16x32_bf16 v[88:91], v[140:143], v[206:209], v[88:91]
	v_mfma_f32_16x16x32_bf16 v[76:79], v[132:135], v[214:217], v[76:79]
	v_mfma_f32_16x16x32_bf16 v[72:75], v[140:143], v[214:217], v[72:75]
	s_setprio 0
	s_setprio 1
	v_mfma_f32_16x16x32_bf16 v[116:119], v[160:163], v[186:189], v[116:119]
	v_mfma_f32_16x16x32_bf16 v[112:115], v[168:171], v[186:189], v[112:115]
	v_mfma_f32_16x16x32_bf16 v[100:103], v[160:163], v[194:197], v[100:103]
	v_mfma_f32_16x16x32_bf16 v[96:99], v[168:171], v[194:197], v[96:99]
	v_mfma_f32_16x16x32_bf16 v[84:87], v[160:163], v[202:205], v[84:87]
	v_mfma_f32_16x16x32_bf16 v[80:83], v[168:171], v[202:205], v[80:83]
	v_mfma_f32_16x16x32_bf16 v[68:71], v[160:163], v[210:213], v[68:71]
	v_mfma_f32_16x16x32_bf16 v[64:67], v[168:171], v[210:213], v[64:67]
	v_mfma_f32_16x16x32_bf16 v[116:119], v[164:167], v[190:193], v[116:119]
	v_mfma_f32_16x16x32_bf16 v[112:115], v[172:175], v[190:193], v[112:115]
	v_mfma_f32_16x16x32_bf16 v[100:103], v[164:167], v[198:201], v[100:103]
	v_mfma_f32_16x16x32_bf16 v[96:99], v[172:175], v[198:201], v[96:99]
	v_mfma_f32_16x16x32_bf16 v[84:87], v[164:167], v[206:209], v[84:87]
	v_mfma_f32_16x16x32_bf16 v[80:83], v[172:175], v[206:209], v[80:83]
	v_mfma_f32_16x16x32_bf16 v[68:71], v[164:167], v[214:217], v[68:71]
	v_mfma_f32_16x16x32_bf16 v[64:67], v[172:175], v[214:217], v[64:67]
	s_setprio 0
	s_barrier
	s_add_i32 s78, s69, s42
	v_lshl_add_u64 v[178:179], s[34:35], 0, v[146:147]
	s_mov_b32 m0, s78
	ds_read_b128 v[186:189], v184 offset:16384
	ds_read_b128 v[190:193], v184 offset:17408
	ds_read_b128 v[194:197], v184 offset:18432
	ds_read_b128 v[198:201], v184 offset:19456
	ds_read_b128 v[202:205], v184 offset:20480
	ds_read_b128 v[206:209], v184 offset:21504
	ds_read_b128 v[210:213], v184 offset:22528
	ds_read_b128 v[214:217], v184 offset:23552
	global_load_lds_dwordx4 v[178:179], off
	s_add_i32 m0, s78, 0x2000
	s_add_u32 s78, s34, 0xb0000
	v_lshl_add_u64 v[218:219], s[34:35], 0, v[150:151]
	s_addc_u32 s79, s35, 0
	s_add_i32 s80, s70, s42
	global_load_lds_dwordx4 v[218:219], off
	v_lshl_add_u64 v[220:221], s[78:79], 0, v[146:147]
	s_mov_b32 m0, s80
	v_lshl_add_u64 v[222:223], s[38:39], 0, v[148:149]
	global_load_lds_dwordx4 v[220:221], off
	v_lshl_add_u64 v[220:221], s[78:79], 0, v[150:151]
	s_add_i32 m0, s80, 0x2000
	s_nop 0
	global_load_lds_dwordx4 v[220:221], off
	v_lshl_add_u64 v[220:221], s[38:39], 0, v[144:145]
	s_mov_b32 m0, s43
	s_nop 0
	global_load_lds_dwordx4 v[220:221], off
	s_mov_b32 m0, s52
	s_nop 0
	global_load_lds_dwordx4 v[222:223], off
	s_waitcnt vmcnt(8)
	s_waitcnt lgkmcnt(0)
	s_nop 0
	s_barrier
	s_setprio 1
	s_waitcnt lgkmcnt(0)
	v_mfma_f32_16x16x32_bf16 v[60:63], v[128:131], v[186:189], v[60:63]
	v_mfma_f32_16x16x32_bf16 v[56:59], v[136:139], v[186:189], v[56:59]
	v_mfma_f32_16x16x32_bf16 v[44:47], v[128:131], v[194:197], v[44:47]
	v_mfma_f32_16x16x32_bf16 v[40:43], v[136:139], v[194:197], v[40:43]
	v_mfma_f32_16x16x32_bf16 v[28:31], v[128:131], v[202:205], v[28:31]
	v_mfma_f32_16x16x32_bf16 v[24:27], v[136:139], v[202:205], v[24:27]
	v_mfma_f32_16x16x32_bf16 v[12:15], v[128:131], v[210:213], v[12:15]
	v_mfma_f32_16x16x32_bf16 v[8:11], v[136:139], v[210:213], v[8:11]
	v_mfma_f32_16x16x32_bf16 v[60:63], v[132:135], v[190:193], v[60:63]
	v_mfma_f32_16x16x32_bf16 v[56:59], v[140:143], v[190:193], v[56:59]
	v_mfma_f32_16x16x32_bf16 v[44:47], v[132:135], v[198:201], v[44:47]
	v_mfma_f32_16x16x32_bf16 v[40:43], v[140:143], v[198:201], v[40:43]
	v_mfma_f32_16x16x32_bf16 v[28:31], v[132:135], v[206:209], v[28:31]
	v_mfma_f32_16x16x32_bf16 v[24:27], v[140:143], v[206:209], v[24:27]
	v_mfma_f32_16x16x32_bf16 v[12:15], v[132:135], v[214:217], v[12:15]
	v_mfma_f32_16x16x32_bf16 v[8:11], v[140:143], v[214:217], v[8:11]
	s_setprio 0
	s_setprio 1
	v_mfma_f32_16x16x32_bf16 v[52:55], v[160:163], v[186:189], v[52:55]
	v_mfma_f32_16x16x32_bf16 v[48:51], v[168:171], v[186:189], v[48:51]
	v_mfma_f32_16x16x32_bf16 v[36:39], v[160:163], v[194:197], v[36:39]
	v_mfma_f32_16x16x32_bf16 v[32:35], v[168:171], v[194:197], v[32:35]
	v_mfma_f32_16x16x32_bf16 v[20:23], v[160:163], v[202:205], v[20:23]
	v_mfma_f32_16x16x32_bf16 v[16:19], v[168:171], v[202:205], v[16:19]
	v_mfma_f32_16x16x32_bf16 v[4:7], v[160:163], v[210:213], v[4:7]
	v_mfma_f32_16x16x32_bf16 v[0:3], v[168:171], v[210:213], v[0:3]
	v_mfma_f32_16x16x32_bf16 v[52:55], v[164:167], v[190:193], v[52:55]
	v_mfma_f32_16x16x32_bf16 v[48:51], v[172:175], v[190:193], v[48:51]
	v_mfma_f32_16x16x32_bf16 v[36:39], v[164:167], v[198:201], v[36:39]
	v_mfma_f32_16x16x32_bf16 v[32:35], v[172:175], v[198:201], v[32:35]
	v_mfma_f32_16x16x32_bf16 v[20:23], v[164:167], v[206:209], v[20:23]
	v_mfma_f32_16x16x32_bf16 v[16:19], v[172:175], v[206:209], v[16:19]
	v_mfma_f32_16x16x32_bf16 v[4:7], v[164:167], v[214:217], v[4:7]
	v_mfma_f32_16x16x32_bf16 v[0:3], v[172:175], v[214:217], v[0:3]
	s_setprio 0
	s_barrier
; #define PG8_STAGE(bufoff, gbase, voff) do { _Pragma("unroll") for (int _i = 0; _i < 2; ++_i) \
;         __builtin_amdgcn_global_load_lds((const unsigned*)((const char*)(gbase) + (voff)[_i]), (LAS unsigned*)(lds + (bufoff) + ldsw + _i * 8192), 16, 0, 0); } while (0)
; #define PG8_LDA(dst, b, h) do { _Pragma("unroll") for (int m = 0; m < 4; ++m) _Pragma("unroll") for (int k = 0; k < 2; ++k) dst[m][k] = *(const LAS bf16x8*)(lds + PG8_SA(b, h) + aoff + m * 2048 + k * 1024); } while (0)
; #define PG8_LDB(dst, b, h) do { _Pragma("unroll") for (int n = 0; n < 2; ++n) _Pragma("unroll") for (int k = 0; k < 2; ++k) dst[n][k] = *(const LAS bf16x8*)(lds + PG8_SB(b, h) + boff + n * 2048 + k * 1024); } while (0)
; #define PG8_MMA(ai, bj, At, Bt) do { __builtin_amdgcn_s_setprio(1); _Pragma("unroll") for (int m = 0; m < 4; ++m) _Pragma("unroll") for (int n = 0; n < 2; ++n) _Pragma("unroll") for (int k = 0; k < 2; ++k) \
;         acc[ai][bj][m][n] = __builtin_amdgcn_mfma_f32_16x16x32_bf16(Bt[n][k], At[m][k], acc[ai][bj][m][n], 0, 0, 0); __builtin_amdgcn_s_setprio(0); } while (0)
; #define PG8_WAIT_V(n) asm volatile("s_waitcnt vmcnt(" #n ")" ::: "memory")
; #define PG8_WAIT_L(n) asm volatile("s_waitcnt lgkmcnt(" #n ")" ::: "memory")
; #define PG8_BAR __builtin_amdgcn_s_barrier()
; #define PG8_SCHED __builtin_amdgcn_sched_barrier(0)
; template <class Epi>
; __device__ __forceinline__ void gemm_phase(LAS unsigned char* lds, const Gemm g, const StaticOrder& S, const Epi& E) {
;     ...
;             PG8_LDB(B0, 1, 0); PG8_LDB(B1, 1, 1); PG8_SCHED; PG8_LDA(At, 1, 0); PG8_STAGE(PG8_SA(0, 1), a2 + hstepA, voffA);
;             PG8_WAIT_V(8); PG8_WAIT_L(0); PG8_BAR; PG8_MMA(0, 0, At, B0); PG8_MMA(0, 1, At, B1); PG8_BAR; PG8_SCHED;
	s_add_i32 s78, 0, 0x18000
	s_add_i32 s79, 0, 0x1c000
	v_add_u32_e32 v140, s78, v181
	v_add_u32_e32 v172, s79, v181
	ds_read_b128 v[128:131], v140
	ds_read_b128 v[132:135], v140 offset:1024
	ds_read_b128 v[136:139], v140 offset:2048
	ds_read_b128 v[140:143], v140 offset:3072
	ds_read_b128 v[160:163], v172
	ds_read_b128 v[164:167], v172 offset:1024
	ds_read_b128 v[168:171], v172 offset:2048
	ds_read_b128 v[172:175], v172 offset:3072
	s_add_u32 s38, s38, 0xb0000
	s_addc_u32 s39, s39, 0
	s_mov_b32 m0, s53
	v_lshl_add_u64 v[226:227], s[38:39], 0, v[144:145]
	ds_read_b128 v[186:189], v184 offset:32768
	ds_read_b128 v[190:193], v184 offset:33792
	ds_read_b128 v[194:197], v184 offset:34816
	ds_read_b128 v[198:201], v184 offset:35840
	ds_read_b128 v[202:205], v184 offset:36864
	ds_read_b128 v[206:209], v184 offset:37888
	ds_read_b128 v[210:213], v184 offset:38912
	ds_read_b128 v[214:217], v184 offset:39936
	global_load_lds_dwordx4 v[226:227], off
	v_lshl_add_u64 v[226:227], s[38:39], 0, v[148:149]
	s_mov_b32 m0, s54
	s_nop 0
	global_load_lds_dwordx4 v[226:227], off
	s_waitcnt vmcnt(8)
	s_waitcnt lgkmcnt(0)
	s_nop 0
	s_barrier
	s_setprio 1
	s_waitcnt lgkmcnt(0)
	v_mfma_f32_16x16x32_bf16 v[124:127], v[128:131], v[186:189], v[124:127]
	v_mfma_f32_16x16x32_bf16 v[120:123], v[136:139], v[186:189], v[120:123]
	v_mfma_f32_16x16x32_bf16 v[108:111], v[128:131], v[194:197], v[108:111]
	v_mfma_f32_16x16x32_bf16 v[104:107], v[136:139], v[194:197], v[104:107]
	v_mfma_f32_16x16x32_bf16 v[92:95], v[128:131], v[202:205], v[92:95]
	v_mfma_f32_16x16x32_bf16 v[88:91], v[136:139], v[202:205], v[88:91]
	v_mfma_f32_16x16x32_bf16 v[76:79], v[128:131], v[210:213], v[76:79]
	v_mfma_f32_16x16x32_bf16 v[72:75], v[136:139], v[210:213], v[72:75]
	v_mfma_f32_16x16x32_bf16 v[124:127], v[132:135], v[190:193], v[124:127]
	v_mfma_f32_16x16x32_bf16 v[120:123], v[140:143], v[190:193], v[120:123]
	v_mfma_f32_16x16x32_bf16 v[108:111], v[132:135], v[198:201], v[108:111]
	v_mfma_f32_16x16x32_bf16 v[104:107], v[140:143], v[198:201], v[104:107]
	v_mfma_f32_16x16x32_bf16 v[92:95], v[132:135], v[206:209], v[92:95]
	v_mfma_f32_16x16x32_bf16 v[88:91], v[140:143], v[206:209], v[88:91]
	v_mfma_f32_16x16x32_bf16 v[76:79], v[132:135], v[214:217], v[76:79]
	v_mfma_f32_16x16x32_bf16 v[72:75], v[140:143], v[214:217], v[72:75]
	s_setprio 0
	s_setprio 1
	v_mfma_f32_16x16x32_bf16 v[116:119], v[160:163], v[186:189], v[116:119]
	v_mfma_f32_16x16x32_bf16 v[112:115], v[168:171], v[186:189], v[112:115]
	v_mfma_f32_16x16x32_bf16 v[100:103], v[160:163], v[194:197], v[100:103]
	v_mfma_f32_16x16x32_bf16 v[96:99], v[168:171], v[194:197], v[96:99]
	v_mfma_f32_16x16x32_bf16 v[84:87], v[160:163], v[202:205], v[84:87]
	v_mfma_f32_16x16x32_bf16 v[80:83], v[168:171], v[202:205], v[80:83]
	v_mfma_f32_16x16x32_bf16 v[68:71], v[160:163], v[210:213], v[68:71]
	v_mfma_f32_16x16x32_bf16 v[64:67], v[168:171], v[210:213], v[64:67]
	v_mfma_f32_16x16x32_bf16 v[116:119], v[164:167], v[190:193], v[116:119]
	v_mfma_f32_16x16x32_bf16 v[112:115], v[172:175], v[190:193], v[112:115]
	v_mfma_f32_16x16x32_bf16 v[100:103], v[164:167], v[198:201], v[100:103]
	v_mfma_f32_16x16x32_bf16 v[96:99], v[172:175], v[198:201], v[96:99]
	v_mfma_f32_16x16x32_bf16 v[84:87], v[164:167], v[206:209], v[84:87]
	v_mfma_f32_16x16x32_bf16 v[80:83], v[172:175], v[206:209], v[80:83]
	v_mfma_f32_16x16x32_bf16 v[68:71], v[164:167], v[214:217], v[68:71]
	v_mfma_f32_16x16x32_bf16 v[64:67], v[172:175], v[214:217], v[64:67]
	s_setprio 0
	s_barrier
; #define PG8_STAGE(bufoff, gbase, voff) do { _Pragma("unroll") for (int _i = 0; _i < 2; ++_i) \
;         __builtin_amdgcn_global_load_lds((const unsigned*)((const char*)(gbase) + (voff)[_i]), (LAS unsigned*)(lds + (bufoff) + ldsw + _i * 8192), 16, 0, 0); } while (0)
; #define PG8_LDA(dst, b, h) do { _Pragma("unroll") for (int m = 0; m < 4; ++m) _Pragma("unroll") for (int k = 0; k < 2; ++k) dst[m][k] = *(const LAS bf16x8*)(lds + PG8_SA(b, h) + aoff + m * 2048 + k * 1024); } while (0)
; #define PG8_MMA(ai, bj, At, Bt) do { __builtin_amdgcn_s_setprio(1); _Pragma("unroll") for (int m = 0; m < 4; ++m) _Pragma("unroll") for (int n = 0; n < 2; ++n) _Pragma("unroll") for (int k = 0; k < 2; ++k) \
;         acc[ai][bj][m][n] = __builtin_amdgcn_mfma_f32_16x16x32_bf16(Bt[n][k], At[m][k], acc[ai][bj][m][n], 0, 0, 0); __builtin_amdgcn_s_setprio(0); } while (0)
; #define PG8_WAIT_V(n) asm volatile("s_waitcnt vmcnt(" #n ")" ::: "memory")
; #define PG8_WAIT_L(n) asm volatile("s_waitcnt lgkmcnt(" #n ")" ::: "memory")
; #define PG8_BAR __builtin_amdgcn_s_barrier()
; #define PG8_SCHED __builtin_amdgcn_sched_barrier(0)
; template <class Epi>
; __device__ __forceinline__ void gemm_phase(LAS unsigned char* lds, const Gemm g, const StaticOrder& S, const Epi& E) {
;     ...
;             PG8_LDA(At, 1, 1); PG8_STAGE(PG8_SB(1, 0), b3, voffB); PG8_STAGE(PG8_SB(1, 1), b3 + hstepB, voffB); PG8_STAGE(PG8_SA(1, 0), a3, voffA);
;             PG8_WAIT_V(8); PG8_WAIT_L(0); PG8_BAR; PG8_MMA(1, 0, At, B0); PG8_MMA(1, 1, At, B1); PG8_BAR; PG8_SCHED;
;         }
;         if (wr == 0) PG8_BAR;
	s_add_i32 s38, s78, s42
	v_lshl_add_u64 v[178:179], v[178:179], 0, s[16:17]
	s_mov_b32 m0, s38
	ds_read_b128 v[186:189], v184 offset:49152
	ds_read_b128 v[190:193], v184 offset:50176
	ds_read_b128 v[194:197], v184 offset:51200
	ds_read_b128 v[198:201], v184 offset:52224
	ds_read_b128 v[202:205], v184 offset:53248
	ds_read_b128 v[206:209], v184 offset:54272
	ds_read_b128 v[210:213], v184 offset:55296
	ds_read_b128 v[214:217], v184 offset:56320
	global_load_lds_dwordx4 v[178:179], off
	s_add_i32 m0, s38, 0x2000
	s_add_u32 s34, s34, 0xb0080
	v_lshl_add_u64 v[178:179], v[218:219], 0, s[16:17]
	s_addc_u32 s35, s35, 0
	s_add_i32 s38, s79, s42
	global_load_lds_dwordx4 v[178:179], off
	v_lshl_add_u64 v[178:179], s[34:35], 0, v[146:147]
	s_mov_b32 m0, s38
	s_nop 0
	global_load_lds_dwordx4 v[178:179], off
	v_lshl_add_u64 v[178:179], s[34:35], 0, v[150:151]
	s_add_i32 m0, s38, 0x2000
	s_nop 0
	global_load_lds_dwordx4 v[178:179], off
	v_lshl_add_u64 v[178:179], v[220:221], 0, s[16:17]
	s_mov_b32 m0, s62
	s_nop 0
	global_load_lds_dwordx4 v[178:179], off
	v_lshl_add_u64 v[178:179], v[222:223], 0, s[16:17]
	s_mov_b32 m0, s63
	s_nop 0
	global_load_lds_dwordx4 v[178:179], off
	s_waitcnt vmcnt(8)
	s_waitcnt lgkmcnt(0)
	s_barrier
	s_setprio 1
	s_waitcnt lgkmcnt(0)
	v_mfma_f32_16x16x32_bf16 v[60:63], v[128:131], v[186:189], v[60:63]
	v_mfma_f32_16x16x32_bf16 v[56:59], v[136:139], v[186:189], v[56:59]
	v_mfma_f32_16x16x32_bf16 v[44:47], v[128:131], v[194:197], v[44:47]
	v_mfma_f32_16x16x32_bf16 v[40:43], v[136:139], v[194:197], v[40:43]
	v_mfma_f32_16x16x32_bf16 v[28:31], v[128:131], v[202:205], v[28:31]
	v_mfma_f32_16x16x32_bf16 v[24:27], v[136:139], v[202:205], v[24:27]
	v_mfma_f32_16x16x32_bf16 v[12:15], v[128:131], v[210:213], v[12:15]
	v_mfma_f32_16x16x32_bf16 v[8:11], v[136:139], v[210:213], v[8:11]
	v_mfma_f32_16x16x32_bf16 v[60:63], v[132:135], v[190:193], v[60:63]
	v_mfma_f32_16x16x32_bf16 v[56:59], v[140:143], v[190:193], v[56:59]
	v_mfma_f32_16x16x32_bf16 v[44:47], v[132:135], v[198:201], v[44:47]
	v_mfma_f32_16x16x32_bf16 v[40:43], v[140:143], v[198:201], v[40:43]
	v_mfma_f32_16x16x32_bf16 v[28:31], v[132:135], v[206:209], v[28:31]
	v_mfma_f32_16x16x32_bf16 v[24:27], v[140:143], v[206:209], v[24:27]
	v_mfma_f32_16x16x32_bf16 v[12:15], v[132:135], v[214:217], v[12:15]
	v_mfma_f32_16x16x32_bf16 v[8:11], v[140:143], v[214:217], v[8:11]
	s_setprio 0
	s_setprio 1
	v_mfma_f32_16x16x32_bf16 v[52:55], v[160:163], v[186:189], v[52:55]
	v_mfma_f32_16x16x32_bf16 v[48:51], v[168:171], v[186:189], v[48:51]
	v_mfma_f32_16x16x32_bf16 v[36:39], v[160:163], v[194:197], v[36:39]
	v_mfma_f32_16x16x32_bf16 v[32:35], v[168:171], v[194:197], v[32:35]
	v_mfma_f32_16x16x32_bf16 v[20:23], v[160:163], v[202:205], v[20:23]
	v_mfma_f32_16x16x32_bf16 v[16:19], v[168:171], v[202:205], v[16:19]
	v_mfma_f32_16x16x32_bf16 v[4:7], v[160:163], v[210:213], v[4:7]
	v_mfma_f32_16x16x32_bf16 v[0:3], v[168:171], v[210:213], v[0:3]
	v_mfma_f32_16x16x32_bf16 v[52:55], v[164:167], v[190:193], v[52:55]
	v_mfma_f32_16x16x32_bf16 v[48:51], v[172:175], v[190:193], v[48:51]
	v_mfma_f32_16x16x32_bf16 v[36:39], v[164:167], v[198:201], v[36:39]
	v_mfma_f32_16x16x32_bf16 v[32:35], v[172:175], v[198:201], v[32:35]
	v_mfma_f32_16x16x32_bf16 v[20:23], v[164:167], v[206:209], v[20:23]
	v_mfma_f32_16x16x32_bf16 v[16:19], v[172:175], v[206:209], v[16:19]
	v_mfma_f32_16x16x32_bf16 v[4:7], v[164:167], v[214:217], v[4:7]
	v_mfma_f32_16x16x32_bf16 v[0:3], v[172:175], v[214:217], v[0:3]
	s_setprio 0
	s_barrier
	s_add_i32 s77, s77, 2
	s_add_u32 s0, s0, 0x100
	s_addc_u32 s1, s1, 0
	s_add_u32 s75, s75, 0x100
	s_addc_u32 s76, s76, 0
	s_cmp_gt_u32 s77, 41
	s_cbranch_scc0 .LBB0_792
	s_and_b64 vcc, exec, s[18:19]
	s_cbranch_vccz .LBB0_795
	s_barrier

; #define PG8_STAGE(bufoff, gbase, voff) do { _Pragma("unroll") for (int _i = 0; _i < 2; ++_i) \
;         __builtin_amdgcn_global_load_lds((const unsigned*)((const char*)(gbase) + (voff)[_i]), (LAS unsigned*)(lds + (bufoff) + ldsw + _i * 8192), 16, 0, 0); } while (0)
; #define PG8_LDA(dst, b, h) do { _Pragma("unroll") for (int m = 0; m < 4; ++m) _Pragma("unroll") for (int k = 0; k < 2; ++k) dst[m][k] = *(const LAS bf16x8*)(lds + PG8_SA(b, h) + aoff + m * 2048 + k * 1024); } while (0)
; #define PG8_LDB(dst, b, h) do { _Pragma("unroll") for (int n = 0; n < 2; ++n) _Pragma("unroll") for (int k = 0; k < 2; ++k) dst[n][k] = *(const LAS bf16x8*)(lds + PG8_SB(b, h) + boff + n * 2048 + k * 1024); } while (0)
; #define PG8_MMA(ai, bj, At, Bt) do { __builtin_amdgcn_s_setprio(1); _Pragma("unroll") for (int m = 0; m < 4; ++m) _Pragma("unroll") for (int n = 0; n < 2; ++n) _Pragma("unroll") for (int k = 0; k < 2; ++k) \
;         acc[ai][bj][m][n] = __builtin_amdgcn_mfma_f32_16x16x32_bf16(Bt[n][k], At[m][k], acc[ai][bj][m][n], 0, 0, 0); __builtin_amdgcn_s_setprio(0); } while (0)
; #define PG8_BAR __builtin_amdgcn_s_barrier()
; template <class Epi>
; __device__ __forceinline__ void gemm_phase(LAS unsigned char* lds, const Gemm g, const StaticOrder& S, const Epi& E) {
;     ...
;         const bool has_next = S.next(ui + 1, nxt);
;         const char* nA = has_next ? (const char*)g.A + (size_t)nxt.pm * tstepA : cA; const char* nB = has_next ? (const char*)g.Bt + (size_t)nxt.pn * tstepB : cB;
; #pragma nounroll
;         for (int t = 0; t < nt; t += 2) {
;             const bool last = (t == nt - 2);
;             const char* a1 = cA + (size_t)(t + 1) * kstep;
;             const char* a2 = last ? nA : cA + (size_t)(t + 2) * kstep; const char* b2 = last ? nB : cB + (size_t)(t + 2) * kstep;
;             const char* a3 = a2 + kstep; const char* b3 = b2 + kstep;
;             PG8_LDB(B0, 0, 0); PG8_LDB(B1, 0, 1); PG8_SCHED; PG8_LDA(At, 0, 0); PG8_STAGE(PG8_SA(1, 1), a1 + hstepA, voffA);
;             PG8_WAIT_V(8); PG8_WAIT_L(0); PG8_BAR; PG8_MMA(0, 0, At, B0); PG8_MMA(0, 1, At, B1); PG8_BAR; PG8_SCHED;
;             PG8_LDA(At, 0, 1); PG8_STAGE(PG8_SB(0, 0), b2, voffB); PG8_STAGE(PG8_SB(0, 1), b2 + hstepB, voffB); PG8_STAGE(PG8_SA(0, 0), a2, voffA);
;             PG8_WAIT_V(8); PG8_WAIT_L(0); PG8_BAR; PG8_MMA(1, 0, At, B0); PG8_MMA(1, 1, At, B1); PG8_BAR; PG8_SCHED;
.LBB0_888:
	s_ashr_i32 s43, s42, 31
	s_lshl_b64 s[52:53], s[42:43], 19
	s_add_u32 s52, s30, s52
	s_addc_u32 s53, s31, s53
	s_and_b64 s[54:55], s[4:5], exec
	s_cselect_b32 s7, s53, s57
	s_cselect_b32 s9, s52, s56
	s_ashr_i32 s39, s38, 31
	s_lshl_b64 s[54:55], s[38:39], 19
	s_add_u32 s54, s3, s54
	s_addc_u32 s55, s33, s55
	s_and_b64 s[64:65], s[4:5], exec
	s_cselect_b32 s39, s55, s63
	s_cselect_b32 s43, s54, s62
	s_add_u32 s56, s56, 0x40080
	s_addc_u32 s57, s57, 0
	s_add_u32 s83, s62, 0x100
	s_addc_u32 s84, s63, 0
	s_mov_b32 s85, -2
	s_waitcnt lgkmcnt(0)
	s_nop 0
	ds_read_b128 v[40:43], v208
	ds_read_b128 v[44:47], v208 offset:1024
	ds_read_b128 v[56:59], v208 offset:2048
	ds_read_b128 v[60:63], v208 offset:3072
	ds_read_b128 v[144:147], v209
	ds_read_b128 v[148:151], v209 offset:1024
	ds_read_b128 v[152:155], v209 offset:2048
	ds_read_b128 v[156:159], v209 offset:3072
	s_add_u32 s62, s56, 0xfffc0080
	s_addc_u32 s63, s57, -1
	s_cmp_eq_u32 s85, 12
	s_cselect_b32 s65, s7, s63
	s_cselect_b32 s64, s9, s62
	s_cselect_b32 s63, s39, s84
	s_cselect_b32 s62, s43, s83
	v_lshl_add_u64 v[218:219], s[56:57], 0, v[178:179]
	s_add_i32 m0, s69, 0xc000
	ds_read_b128 v[160:163], v210
	ds_read_b128 v[164:167], v210 offset:1024
	ds_read_b128 v[186:189], v210 offset:2048
	ds_read_b128 v[190:193], v210 offset:3072
	ds_read_b128 v[194:197], v210 offset:4096
	ds_read_b128 v[198:201], v210 offset:5120
	ds_read_b128 v[202:205], v210 offset:6144
	ds_read_b128 v[214:217], v210 offset:7168
	global_load_lds_dwordx4 v[218:219], off
	v_lshl_add_u64 v[218:219], s[56:57], 0, v[180:181]
	s_add_i32 m0, s69, 0xe000
	s_nop 0
	global_load_lds_dwordx4 v[218:219], off
	s_waitcnt vmcnt(8)
	s_waitcnt lgkmcnt(0)
	s_nop 0
	s_barrier
	s_setprio 1
	s_waitcnt lgkmcnt(0)
	v_mfma_f32_16x16x32_bf16 v[140:143], v[40:43], v[160:163], 0
	v_mfma_f32_16x16x32_bf16 v[136:139], v[56:59], v[160:163], 0
	v_mfma_f32_16x16x32_bf16 v[124:127], v[40:43], v[186:189], 0
	v_mfma_f32_16x16x32_bf16 v[120:123], v[56:59], v[186:189], 0
	v_mfma_f32_16x16x32_bf16 v[108:111], v[40:43], v[194:197], 0
	v_mfma_f32_16x16x32_bf16 v[104:107], v[56:59], v[194:197], 0
	v_mfma_f32_16x16x32_bf16 v[92:95], v[40:43], v[202:205], 0
	v_mfma_f32_16x16x32_bf16 v[88:91], v[56:59], v[202:205], 0
	v_mfma_f32_16x16x32_bf16 v[140:143], v[44:47], v[164:167], v[140:143]
	v_mfma_f32_16x16x32_bf16 v[136:139], v[60:63], v[164:167], v[136:139]
	v_mfma_f32_16x16x32_bf16 v[124:127], v[44:47], v[190:193], v[124:127]
	v_mfma_f32_16x16x32_bf16 v[120:123], v[60:63], v[190:193], v[120:123]
	v_mfma_f32_16x16x32_bf16 v[108:111], v[44:47], v[198:201], v[108:111]
	v_mfma_f32_16x16x32_bf16 v[104:107], v[60:63], v[198:201], v[104:107]
	v_mfma_f32_16x16x32_bf16 v[92:95], v[44:47], v[214:217], v[92:95]
	v_mfma_f32_16x16x32_bf16 v[88:91], v[60:63], v[214:217], v[88:91]
	s_setprio 0
	s_setprio 1
	v_mfma_f32_16x16x32_bf16 v[132:135], v[144:147], v[160:163], 0
	v_mfma_f32_16x16x32_bf16 v[128:131], v[152:155], v[160:163], 0
	v_mfma_f32_16x16x32_bf16 v[116:119], v[144:147], v[186:189], 0
	v_mfma_f32_16x16x32_bf16 v[112:115], v[152:155], v[186:189], 0
	v_mfma_f32_16x16x32_bf16 v[100:103], v[144:147], v[194:197], 0
	v_mfma_f32_16x16x32_bf16 v[96:99], v[152:155], v[194:197], 0
	v_mfma_f32_16x16x32_bf16 v[84:87], v[144:147], v[202:205], 0
	v_mfma_f32_16x16x32_bf16 v[80:83], v[152:155], v[202:205], 0
	v_mfma_f32_16x16x32_bf16 v[132:135], v[148:151], v[164:167], v[132:135]
	v_mfma_f32_16x16x32_bf16 v[128:131], v[156:159], v[164:167], v[128:131]
	v_mfma_f32_16x16x32_bf16 v[116:119], v[148:151], v[190:193], v[116:119]
	v_mfma_f32_16x16x32_bf16 v[112:115], v[156:159], v[190:193], v[112:115]
	v_mfma_f32_16x16x32_bf16 v[100:103], v[148:151], v[198:201], v[100:103]
	v_mfma_f32_16x16x32_bf16 v[96:99], v[156:159], v[198:201], v[96:99]
	v_mfma_f32_16x16x32_bf16 v[84:87], v[148:151], v[214:217], v[84:87]
	v_mfma_f32_16x16x32_bf16 v[80:83], v[156:159], v[214:217], v[80:83]
	s_setprio 0
	s_barrier
	s_add_i32 s86, s81, s68
	v_lshl_add_u64 v[218:219], s[62:63], 0, v[170:171]
	s_mov_b32 m0, s86
	ds_read_b128 v[160:163], v210 offset:16384
	ds_read_b128 v[164:167], v210 offset:17408
	ds_read_b128 v[186:189], v210 offset:18432
	ds_read_b128 v[190:193], v210 offset:19456
	ds_read_b128 v[194:197], v210 offset:20480
	ds_read_b128 v[198:201], v210 offset:21504
	ds_read_b128 v[202:205], v210 offset:22528
	ds_read_b128 v[214:217], v210 offset:23552
	global_load_lds_dwordx4 v[218:219], off
	s_add_i32 m0, s86, 0x2000
	s_add_u32 s86, s62, 0x40000
	v_lshl_add_u64 v[220:221], s[62:63], 0, v[174:175]
	s_addc_u32 s87, s63, 0
	s_add_i32 s88, s82, s68
	global_load_lds_dwordx4 v[220:221], off
	v_lshl_add_u64 v[222:223], s[86:87], 0, v[170:171]
	s_mov_b32 m0, s88
	v_lshl_add_u64 v[226:227], s[64:65], 0, v[172:173]
	global_load_lds_dwordx4 v[222:223], off
	v_lshl_add_u64 v[222:223], s[86:87], 0, v[174:175]
	s_add_i32 m0, s88, 0x2000
	s_nop 0
	global_load_lds_dwordx4 v[222:223], off
	v_lshl_add_u64 v[222:223], s[64:65], 0, v[168:169]
	s_mov_b32 m0, s69
	s_nop 0
	global_load_lds_dwordx4 v[222:223], off
	s_mov_b32 m0, s70
	s_nop 0
	global_load_lds_dwordx4 v[226:227], off
	s_waitcnt vmcnt(8)
	s_waitcnt lgkmcnt(0)
	s_nop 0
	s_barrier
; #define PG8_STAGE(bufoff, gbase, voff) do { _Pragma("unroll") for (int _i = 0; _i < 2; ++_i) \
;         __builtin_amdgcn_global_load_lds((const unsigned*)((const char*)(gbase) + (voff)[_i]), (LAS unsigned*)(lds + (bufoff) + ldsw + _i * 8192), 16, 0, 0); } while (0)
; #define PG8_LDA(dst, b, h) do { _Pragma("unroll") for (int m = 0; m < 4; ++m) _Pragma("unroll") for (int k = 0; k < 2; ++k) dst[m][k] = *(const LAS bf16x8*)(lds + PG8_SA(b, h) + aoff + m * 2048 + k * 1024); } while (0)
; #define PG8_LDB(dst, b, h) do { _Pragma("unroll") for (int n = 0; n < 2; ++n) _Pragma("unroll") for (int k = 0; k < 2; ++k) dst[n][k] = *(const LAS bf16x8*)(lds + PG8_SB(b, h) + boff + n * 2048 + k * 1024); } while (0)
; #define PG8_MMA(ai, bj, At, Bt) do { __builtin_amdgcn_s_setprio(1); _Pragma("unroll") for (int m = 0; m < 4; ++m) _Pragma("unroll") for (int n = 0; n < 2; ++n) _Pragma("unroll") for (int k = 0; k < 2; ++k) \
;         acc[ai][bj][m][n] = __builtin_amdgcn_mfma_f32_16x16x32_bf16(Bt[n][k], At[m][k], acc[ai][bj][m][n], 0, 0, 0); __builtin_amdgcn_s_setprio(0); } while (0)
; #define PG8_WAIT_V(n) asm volatile("s_waitcnt vmcnt(" #n ")" ::: "memory")
; #define PG8_WAIT_L(n) asm volatile("s_waitcnt lgkmcnt(" #n ")" ::: "memory")
; #define PG8_BAR __builtin_amdgcn_s_barrier()
; #define PG8_SCHED __builtin_amdgcn_sched_barrier(0)
; template <class Epi>
; __device__ __forceinline__ void gemm_phase(LAS unsigned char* lds, const Gemm g, const StaticOrder& S, const Epi& E) {
;     ...
;             PG8_WAIT_V(8); PG8_WAIT_L(0); PG8_BAR; PG8_MMA(1, 0, At, B0); PG8_MMA(1, 1, At, B1); PG8_BAR; PG8_SCHED;
;             PG8_LDB(B0, 1, 0); PG8_LDB(B1, 1, 1); PG8_SCHED; PG8_LDA(At, 1, 0); PG8_STAGE(PG8_SA(0, 1), a2 + hstepA, voffA);
;             PG8_WAIT_V(8); PG8_WAIT_L(0); PG8_BAR; PG8_MMA(0, 0, At, B0); PG8_MMA(0, 1, At, B1); PG8_BAR; PG8_SCHED;
;             PG8_LDA(At, 1, 1); PG8_STAGE(PG8_SB(1, 0), b3, voffB); PG8_STAGE(PG8_SB(1, 1), b3 + hstepB, voffB); PG8_STAGE(PG8_SA(1, 0), a3, voffA);
;             PG8_WAIT_V(8); PG8_WAIT_L(0); PG8_BAR; PG8_MMA(1, 0, At, B0); PG8_MMA(1, 1, At, B1); PG8_BAR; PG8_SCHED;
	s_setprio 1
	s_waitcnt lgkmcnt(0)
	v_mfma_f32_16x16x32_bf16 v[76:79], v[40:43], v[160:163], 0
	v_mfma_f32_16x16x32_bf16 v[72:75], v[56:59], v[160:163], 0
	v_mfma_f32_16x16x32_bf16 v[52:55], v[40:43], v[186:189], 0
	v_mfma_f32_16x16x32_bf16 v[48:51], v[56:59], v[186:189], 0
	v_mfma_f32_16x16x32_bf16 v[28:31], v[40:43], v[194:197], 0
	v_mfma_f32_16x16x32_bf16 v[24:27], v[56:59], v[194:197], 0
	v_mfma_f32_16x16x32_bf16 v[12:15], v[40:43], v[202:205], 0
	v_mfma_f32_16x16x32_bf16 v[8:11], v[56:59], v[202:205], 0
	v_mfma_f32_16x16x32_bf16 v[76:79], v[44:47], v[164:167], v[76:79]
	v_mfma_f32_16x16x32_bf16 v[72:75], v[60:63], v[164:167], v[72:75]
	v_mfma_f32_16x16x32_bf16 v[52:55], v[44:47], v[190:193], v[52:55]
	v_mfma_f32_16x16x32_bf16 v[48:51], v[60:63], v[190:193], v[48:51]
	v_mfma_f32_16x16x32_bf16 v[28:31], v[44:47], v[198:201], v[28:31]
	v_mfma_f32_16x16x32_bf16 v[24:27], v[60:63], v[198:201], v[24:27]
	v_mfma_f32_16x16x32_bf16 v[12:15], v[44:47], v[214:217], v[12:15]
	v_mfma_f32_16x16x32_bf16 v[8:11], v[60:63], v[214:217], v[8:11]
	s_setprio 0
	s_setprio 1
	v_mfma_f32_16x16x32_bf16 v[36:39], v[144:147], v[186:189], 0
	v_mfma_f32_16x16x32_bf16 v[32:35], v[152:155], v[186:189], 0
	v_mfma_f32_16x16x32_bf16 v[20:23], v[144:147], v[194:197], 0
	v_mfma_f32_16x16x32_bf16 v[16:19], v[152:155], v[194:197], 0
	v_mfma_f32_16x16x32_bf16 v[4:7], v[144:147], v[202:205], 0
	v_mfma_f32_16x16x32_bf16 v[0:3], v[152:155], v[202:205], 0
	v_mfma_f32_16x16x32_bf16 v[40:43], v[144:147], v[160:163], 0
	v_mfma_f32_16x16x32_bf16 v[44:47], v[152:155], v[160:163], 0
	v_mfma_f32_16x16x32_bf16 v[36:39], v[148:151], v[190:193], v[36:39]
	v_mfma_f32_16x16x32_bf16 v[32:35], v[156:159], v[190:193], v[32:35]
	v_mfma_f32_16x16x32_bf16 v[20:23], v[148:151], v[198:201], v[20:23]
	v_mfma_f32_16x16x32_bf16 v[16:19], v[156:159], v[198:201], v[16:19]
	v_mfma_f32_16x16x32_bf16 v[4:7], v[148:151], v[214:217], v[4:7]
	v_mfma_f32_16x16x32_bf16 v[0:3], v[156:159], v[214:217], v[0:3]
	v_mfma_f32_16x16x32_bf16 v[40:43], v[148:151], v[164:167], v[40:43]
	v_mfma_f32_16x16x32_bf16 v[44:47], v[156:159], v[164:167], v[44:47]
	s_setprio 0
	s_barrier
	s_add_i32 s86, 0, 0x18000
	s_add_i32 s87, 0, 0x1c000
	v_add_u32_e32 v68, s86, v207
	v_add_u32_e32 v156, s87, v207
	ds_read_b128 v[56:59], v68
	ds_read_b128 v[60:63], v68 offset:1024
	ds_read_b128 v[64:67], v68 offset:2048
	ds_read_b128 v[68:71], v68 offset:3072
	ds_read_b128 v[144:147], v156
	ds_read_b128 v[148:151], v156 offset:1024
	ds_read_b128 v[152:155], v156 offset:2048
	ds_read_b128 v[156:159], v156 offset:3072
	s_add_u32 s64, s64, 0x40000
	s_addc_u32 s65, s65, 0
	s_mov_b32 m0, s71
	v_lshl_add_u64 v[228:229], s[64:65], 0, v[168:169]
	ds_read_b128 v[160:163], v210 offset:32768
	ds_read_b128 v[164:167], v210 offset:33792
	ds_read_b128 v[186:189], v210 offset:34816
	ds_read_b128 v[190:193], v210 offset:35840
	ds_read_b128 v[194:197], v210 offset:36864
	ds_read_b128 v[198:201], v210 offset:37888
	ds_read_b128 v[202:205], v210 offset:38912
	ds_read_b128 v[214:217], v210 offset:39936
	global_load_lds_dwordx4 v[228:229], off
	v_lshl_add_u64 v[228:229], s[64:65], 0, v[172:173]
	s_mov_b32 m0, s72
	s_nop 0
	global_load_lds_dwordx4 v[228:229], off
	s_waitcnt vmcnt(8)
	s_waitcnt lgkmcnt(0)
	s_nop 0
	s_barrier
	s_setprio 1
	s_waitcnt lgkmcnt(0)
	v_mfma_f32_16x16x32_bf16 v[140:143], v[56:59], v[160:163], v[140:143]
	v_mfma_f32_16x16x32_bf16 v[136:139], v[64:67], v[160:163], v[136:139]
	v_mfma_f32_16x16x32_bf16 v[124:127], v[56:59], v[186:189], v[124:127]
	v_mfma_f32_16x16x32_bf16 v[120:123], v[64:67], v[186:189], v[120:123]
	v_mfma_f32_16x16x32_bf16 v[108:111], v[56:59], v[194:197], v[108:111]
	v_mfma_f32_16x16x32_bf16 v[104:107], v[64:67], v[194:197], v[104:107]
	v_mfma_f32_16x16x32_bf16 v[92:95], v[56:59], v[202:205], v[92:95]
	v_mfma_f32_16x16x32_bf16 v[88:91], v[64:67], v[202:205], v[88:91]
	v_mfma_f32_16x16x32_bf16 v[140:143], v[60:63], v[164:167], v[140:143]
	v_mfma_f32_16x16x32_bf16 v[136:139], v[68:71], v[164:167], v[136:139]
	v_mfma_f32_16x16x32_bf16 v[124:127], v[60:63], v[190:193], v[124:127]
	v_mfma_f32_16x16x32_bf16 v[120:123], v[68:71], v[190:193], v[120:123]
	v_mfma_f32_16x16x32_bf16 v[108:111], v[60:63], v[198:201], v[108:111]
	v_mfma_f32_16x16x32_bf16 v[104:107], v[68:71], v[198:201], v[104:107]
	v_mfma_f32_16x16x32_bf16 v[92:95], v[60:63], v[214:217], v[92:95]
	v_mfma_f32_16x16x32_bf16 v[88:91], v[68:71], v[214:217], v[88:91]
	s_setprio 0
	s_setprio 1
	v_mfma_f32_16x16x32_bf16 v[132:135], v[144:147], v[160:163], v[132:135]
	v_mfma_f32_16x16x32_bf16 v[128:131], v[152:155], v[160:163], v[128:131]
	v_mfma_f32_16x16x32_bf16 v[116:119], v[144:147], v[186:189], v[116:119]
	v_mfma_f32_16x16x32_bf16 v[112:115], v[152:155], v[186:189], v[112:115]
	v_mfma_f32_16x16x32_bf16 v[100:103], v[144:147], v[194:197], v[100:103]
	v_mfma_f32_16x16x32_bf16 v[96:99], v[152:155], v[194:197], v[96:99]
	v_mfma_f32_16x16x32_bf16 v[84:87], v[144:147], v[202:205], v[84:87]
	v_mfma_f32_16x16x32_bf16 v[80:83], v[152:155], v[202:205], v[80:83]
	v_mfma_f32_16x16x32_bf16 v[132:135], v[148:151], v[164:167], v[132:135]
	v_mfma_f32_16x16x32_bf16 v[128:131], v[156:159], v[164:167], v[128:131]
	v_mfma_f32_16x16x32_bf16 v[116:119], v[148:151], v[190:193], v[116:119]
	v_mfma_f32_16x16x32_bf16 v[112:115], v[156:159], v[190:193], v[112:115]
	v_mfma_f32_16x16x32_bf16 v[100:103], v[148:151], v[198:201], v[100:103]
	v_mfma_f32_16x16x32_bf16 v[96:99], v[156:159], v[198:201], v[96:99]
	v_mfma_f32_16x16x32_bf16 v[84:87], v[148:151], v[214:217], v[84:87]
	v_mfma_f32_16x16x32_bf16 v[80:83], v[156:159], v[214:217], v[80:83]
	s_setprio 0
	s_barrier
; #define PG8_STAGE(bufoff, gbase, voff) do { _Pragma("unroll") for (int _i = 0; _i < 2; ++_i) \
;         __builtin_amdgcn_global_load_lds((const unsigned*)((const char*)(gbase) + (voff)[_i]), (LAS unsigned*)(lds + (bufoff) + ldsw + _i * 8192), 16, 0, 0); } while (0)
; #define PG8_LDA(dst, b, h) do { _Pragma("unroll") for (int m = 0; m < 4; ++m) _Pragma("unroll") for (int k = 0; k < 2; ++k) dst[m][k] = *(const LAS bf16x8*)(lds + PG8_SA(b, h) + aoff + m * 2048 + k * 1024); } while (0)
; #define PG8_LDB(dst, b, h) do { _Pragma("unroll") for (int n = 0; n < 2; ++n) _Pragma("unroll") for (int k = 0; k < 2; ++k) dst[n][k] = *(const LAS bf16x8*)(lds + PG8_SB(b, h) + boff + n * 2048 + k * 1024); } while (0)
; #define PG8_MMA(ai, bj, At, Bt) do { __builtin_amdgcn_s_setprio(1); _Pragma("unroll") for (int m = 0; m < 4; ++m) _Pragma("unroll") for (int n = 0; n < 2; ++n) _Pragma("unroll") for (int k = 0; k < 2; ++k) \
;         acc[ai][bj][m][n] = __builtin_amdgcn_mfma_f32_16x16x32_bf16(Bt[n][k], At[m][k], acc[ai][bj][m][n], 0, 0, 0); __builtin_amdgcn_s_setprio(0); } while (0)
; #define PG8_WAIT_V(n) asm volatile("s_waitcnt vmcnt(" #n ")" ::: "memory")
; #define PG8_WAIT_L(n) asm volatile("s_waitcnt lgkmcnt(" #n ")" ::: "memory")
; #define PG8_BAR __builtin_amdgcn_s_barrier()
; #define PG8_SCHED __builtin_amdgcn_sched_barrier(0)
; template <class Epi>
; __device__ __forceinline__ void gemm_phase(LAS unsigned char* lds, const Gemm g, const StaticOrder& S, const Epi& E) {
;     ...
;         for (int t = 0; t < nt; t += 2) {
;             const bool last = (t == nt - 2);
;             const char* a1 = cA + (size_t)(t + 1) * kstep;
;             const char* a2 = last ? nA : cA + (size_t)(t + 2) * kstep; const char* b2 = last ? nB : cB + (size_t)(t + 2) * kstep;
;             const char* a3 = a2 + kstep; const char* b3 = b2 + kstep;
;             PG8_LDB(B0, 0, 0); PG8_LDB(B1, 0, 1); PG8_SCHED; PG8_LDA(At, 0, 0); PG8_STAGE(PG8_SA(1, 1), a1 + hstepA, voffA);
;             PG8_WAIT_V(8); PG8_WAIT_L(0); PG8_BAR; PG8_MMA(0, 0, At, B0); PG8_MMA(0, 1, At, B1); PG8_BAR; PG8_SCHED;
;     ...
;             PG8_LDA(At, 1, 1); PG8_STAGE(PG8_SB(1, 0), b3, voffB); PG8_STAGE(PG8_SB(1, 1), b3 + hstepB, voffB); PG8_STAGE(PG8_SA(1, 0), a3, voffA);
;             PG8_WAIT_V(8); PG8_WAIT_L(0); PG8_BAR; PG8_MMA(1, 0, At, B0); PG8_MMA(1, 1, At, B1); PG8_BAR; PG8_SCHED;
	s_add_i32 s64, s86, s68
	v_lshl_add_u64 v[218:219], v[218:219], 0, s[18:19]
	s_mov_b32 m0, s64
	ds_read_b128 v[160:163], v210 offset:49152
	ds_read_b128 v[164:167], v210 offset:50176
	ds_read_b128 v[186:189], v210 offset:51200
	ds_read_b128 v[190:193], v210 offset:52224
	ds_read_b128 v[194:197], v210 offset:53248
	ds_read_b128 v[198:201], v210 offset:54272
	ds_read_b128 v[202:205], v210 offset:55296
	ds_read_b128 v[214:217], v210 offset:56320
	global_load_lds_dwordx4 v[218:219], off
	s_add_i32 m0, s64, 0x2000
	s_add_u32 s62, s62, 0x40080
	v_lshl_add_u64 v[218:219], v[220:221], 0, s[18:19]
	s_addc_u32 s63, s63, 0
	s_add_i32 s64, s87, s68
	global_load_lds_dwordx4 v[218:219], off
	v_lshl_add_u64 v[218:219], s[62:63], 0, v[170:171]
	s_mov_b32 m0, s64
	s_nop 0
	global_load_lds_dwordx4 v[218:219], off
	v_lshl_add_u64 v[218:219], s[62:63], 0, v[174:175]
	s_add_i32 m0, s64, 0x2000
	s_nop 0
	global_load_lds_dwordx4 v[218:219], off
	v_lshl_add_u64 v[218:219], v[222:223], 0, s[18:19]
	s_mov_b32 m0, s76
	s_nop 0
	global_load_lds_dwordx4 v[218:219], off
	v_lshl_add_u64 v[218:219], v[226:227], 0, s[18:19]
	s_mov_b32 m0, s77
	s_nop 0
	global_load_lds_dwordx4 v[218:219], off
	s_waitcnt vmcnt(8)
	s_waitcnt lgkmcnt(0)
	s_barrier
	s_setprio 1
	s_waitcnt lgkmcnt(0)
	v_mfma_f32_16x16x32_bf16 v[76:79], v[56:59], v[160:163], v[76:79]
	v_mfma_f32_16x16x32_bf16 v[72:75], v[64:67], v[160:163], v[72:75]
	v_mfma_f32_16x16x32_bf16 v[52:55], v[56:59], v[186:189], v[52:55]
	v_mfma_f32_16x16x32_bf16 v[48:51], v[64:67], v[186:189], v[48:51]
	v_mfma_f32_16x16x32_bf16 v[28:31], v[56:59], v[194:197], v[28:31]
	v_mfma_f32_16x16x32_bf16 v[24:27], v[64:67], v[194:197], v[24:27]
	v_mfma_f32_16x16x32_bf16 v[12:15], v[56:59], v[202:205], v[12:15]
	v_mfma_f32_16x16x32_bf16 v[8:11], v[64:67], v[202:205], v[8:11]
	v_mfma_f32_16x16x32_bf16 v[76:79], v[60:63], v[164:167], v[76:79]
	v_mfma_f32_16x16x32_bf16 v[72:75], v[68:71], v[164:167], v[72:75]
	v_mfma_f32_16x16x32_bf16 v[52:55], v[60:63], v[190:193], v[52:55]
	v_mfma_f32_16x16x32_bf16 v[48:51], v[68:71], v[190:193], v[48:51]
	v_mfma_f32_16x16x32_bf16 v[28:31], v[60:63], v[198:201], v[28:31]
	v_mfma_f32_16x16x32_bf16 v[24:27], v[68:71], v[198:201], v[24:27]
	v_mfma_f32_16x16x32_bf16 v[12:15], v[60:63], v[214:217], v[12:15]
	v_mfma_f32_16x16x32_bf16 v[8:11], v[68:71], v[214:217], v[8:11]
	s_setprio 0
	s_setprio 1
	v_mfma_f32_16x16x32_bf16 v[40:43], v[144:147], v[160:163], v[40:43]
	v_mfma_f32_16x16x32_bf16 v[68:71], v[148:151], v[164:167], v[40:43]
	v_mfma_f32_16x16x32_bf16 v[40:43], v[152:155], v[160:163], v[44:47]
	v_mfma_f32_16x16x32_bf16 v[36:39], v[144:147], v[186:189], v[36:39]
	v_mfma_f32_16x16x32_bf16 v[32:35], v[152:155], v[186:189], v[32:35]
	v_mfma_f32_16x16x32_bf16 v[20:23], v[144:147], v[194:197], v[20:23]
	v_mfma_f32_16x16x32_bf16 v[16:19], v[152:155], v[194:197], v[16:19]
	v_mfma_f32_16x16x32_bf16 v[4:7], v[144:147], v[202:205], v[4:7]
	v_mfma_f32_16x16x32_bf16 v[0:3], v[152:155], v[202:205], v[0:3]
	v_mfma_f32_16x16x32_bf16 v[64:67], v[156:159], v[164:167], v[40:43]
	v_mfma_f32_16x16x32_bf16 v[36:39], v[148:151], v[190:193], v[36:39]
	v_mfma_f32_16x16x32_bf16 v[32:35], v[156:159], v[190:193], v[32:35]
	v_mfma_f32_16x16x32_bf16 v[20:23], v[148:151], v[198:201], v[20:23]
	v_mfma_f32_16x16x32_bf16 v[16:19], v[156:159], v[198:201], v[16:19]
	v_mfma_f32_16x16x32_bf16 v[4:7], v[148:151], v[214:217], v[4:7]
	v_mfma_f32_16x16x32_bf16 v[0:3], v[156:159], v[214:217], v[0:3]
	s_setprio 0
	s_barrier
	s_add_i32 s85, s85, 2
	s_add_u32 s56, s56, 0x100
	s_addc_u32 s57, s57, 0
	s_add_u32 s83, s83, 0x100
	s_addc_u32 s84, s84, 0
	s_cmp_gt_u32 s85, 13
.LBB0_889:
	ds_read_b128 v[40:43], v208
	ds_read_b128 v[44:47], v208 offset:1024
	ds_read_b128 v[56:59], v208 offset:2048
	ds_read_b128 v[60:63], v208 offset:3072
	ds_read_b128 v[144:147], v209
	ds_read_b128 v[148:151], v209 offset:1024
	ds_read_b128 v[152:155], v209 offset:2048
	ds_read_b128 v[156:159], v209 offset:3072
	s_add_u32 s62, s56, 0xfffc0080
	s_addc_u32 s63, s57, -1
	s_cmp_eq_u32 s85, 12
	s_cselect_b32 s65, s7, s63
	s_cselect_b32 s64, s9, s62
	s_cselect_b32 s63, s39, s84
	s_cselect_b32 s62, s43, s83
	v_lshl_add_u64 v[218:219], s[56:57], 0, v[178:179]
	s_add_i32 m0, s69, 0xc000
	ds_read_b128 v[160:163], v210
	ds_read_b128 v[164:167], v210 offset:1024
	ds_read_b128 v[186:189], v210 offset:2048
	ds_read_b128 v[190:193], v210 offset:3072
	ds_read_b128 v[194:197], v210 offset:4096
	ds_read_b128 v[198:201], v210 offset:5120
	ds_read_b128 v[202:205], v210 offset:6144
	ds_read_b128 v[214:217], v210 offset:7168
	global_load_lds_dwordx4 v[218:219], off
	v_lshl_add_u64 v[218:219], s[56:57], 0, v[180:181]
	s_add_i32 m0, s69, 0xe000
	s_nop 0
	global_load_lds_dwordx4 v[218:219], off
	s_waitcnt vmcnt(8)
	s_waitcnt lgkmcnt(0)
	s_barrier
; #define PG8_STAGE(bufoff, gbase, voff) do { _Pragma("unroll") for (int _i = 0; _i < 2; ++_i) \
;         __builtin_amdgcn_global_load_lds((const unsigned*)((const char*)(gbase) + (voff)[_i]), (LAS unsigned*)(lds + (bufoff) + ldsw + _i * 8192), 16, 0, 0); } while (0)
; #define PG8_LDA(dst, b, h) do { _Pragma("unroll") for (int m = 0; m < 4; ++m) _Pragma("unroll") for (int k = 0; k < 2; ++k) dst[m][k] = *(const LAS bf16x8*)(lds + PG8_SA(b, h) + aoff + m * 2048 + k * 1024); } while (0)
; #define PG8_LDB(dst, b, h) do { _Pragma("unroll") for (int n = 0; n < 2; ++n) _Pragma("unroll") for (int k = 0; k < 2; ++k) dst[n][k] = *(const LAS bf16x8*)(lds + PG8_SB(b, h) + boff + n * 2048 + k * 1024); } while (0)
; #define PG8_MMA(ai, bj, At, Bt) do { __builtin_amdgcn_s_setprio(1); _Pragma("unroll") for (int m = 0; m < 4; ++m) _Pragma("unroll") for (int n = 0; n < 2; ++n) _Pragma("unroll") for (int k = 0; k < 2; ++k) \
;         acc[ai][bj][m][n] = __builtin_amdgcn_mfma_f32_16x16x32_bf16(Bt[n][k], At[m][k], acc[ai][bj][m][n], 0, 0, 0); __builtin_amdgcn_s_setprio(0); } while (0)
; #define PG8_WAIT_V(n) asm volatile("s_waitcnt vmcnt(" #n ")" ::: "memory")
; #define PG8_WAIT_L(n) asm volatile("s_waitcnt lgkmcnt(" #n ")" ::: "memory")
; #define PG8_BAR __builtin_amdgcn_s_barrier()
; #define PG8_SCHED __builtin_amdgcn_sched_barrier(0)
; template <class Epi>
; __device__ __forceinline__ void gemm_phase(LAS unsigned char* lds, const Gemm g, const StaticOrder& S, const Epi& E) {
;     ...
;             PG8_LDB(B0, 0, 0); PG8_LDB(B1, 0, 1); PG8_SCHED; PG8_LDA(At, 0, 0); PG8_STAGE(PG8_SA(1, 1), a1 + hstepA, voffA);
;             PG8_WAIT_V(8); PG8_WAIT_L(0); PG8_BAR; PG8_MMA(0, 0, At, B0); PG8_MMA(0, 1, At, B1); PG8_BAR; PG8_SCHED;
;             PG8_LDA(At, 0, 1); PG8_STAGE(PG8_SB(0, 0), b2, voffB); PG8_STAGE(PG8_SB(0, 1), b2 + hstepB, voffB); PG8_STAGE(PG8_SA(0, 0), a2, voffA);
;             PG8_WAIT_V(8); PG8_WAIT_L(0); PG8_BAR; PG8_MMA(1, 0, At, B0); PG8_MMA(1, 1, At, B1); PG8_BAR; PG8_SCHED;
	s_setprio 1
	s_waitcnt lgkmcnt(0)
	v_mfma_f32_16x16x32_bf16 v[140:143], v[40:43], v[160:163], v[140:143]
	v_mfma_f32_16x16x32_bf16 v[136:139], v[56:59], v[160:163], v[136:139]
	v_mfma_f32_16x16x32_bf16 v[124:127], v[40:43], v[186:189], v[124:127]
	v_mfma_f32_16x16x32_bf16 v[120:123], v[56:59], v[186:189], v[120:123]
	v_mfma_f32_16x16x32_bf16 v[108:111], v[40:43], v[194:197], v[108:111]
	v_mfma_f32_16x16x32_bf16 v[104:107], v[56:59], v[194:197], v[104:107]
	v_mfma_f32_16x16x32_bf16 v[92:95], v[40:43], v[202:205], v[92:95]
	v_mfma_f32_16x16x32_bf16 v[88:91], v[56:59], v[202:205], v[88:91]
	v_mfma_f32_16x16x32_bf16 v[140:143], v[44:47], v[164:167], v[140:143]
	v_mfma_f32_16x16x32_bf16 v[136:139], v[60:63], v[164:167], v[136:139]
	v_mfma_f32_16x16x32_bf16 v[124:127], v[44:47], v[190:193], v[124:127]
	v_mfma_f32_16x16x32_bf16 v[120:123], v[60:63], v[190:193], v[120:123]
	v_mfma_f32_16x16x32_bf16 v[108:111], v[44:47], v[198:201], v[108:111]
	v_mfma_f32_16x16x32_bf16 v[104:107], v[60:63], v[198:201], v[104:107]
	v_mfma_f32_16x16x32_bf16 v[92:95], v[44:47], v[214:217], v[92:95]
	v_mfma_f32_16x16x32_bf16 v[88:91], v[60:63], v[214:217], v[88:91]
	s_setprio 0
	s_setprio 1
	v_mfma_f32_16x16x32_bf16 v[132:135], v[144:147], v[160:163], v[132:135]
	v_mfma_f32_16x16x32_bf16 v[128:131], v[152:155], v[160:163], v[128:131]
	v_mfma_f32_16x16x32_bf16 v[116:119], v[144:147], v[186:189], v[116:119]
	v_mfma_f32_16x16x32_bf16 v[112:115], v[152:155], v[186:189], v[112:115]
	v_mfma_f32_16x16x32_bf16 v[100:103], v[144:147], v[194:197], v[100:103]
	v_mfma_f32_16x16x32_bf16 v[96:99], v[152:155], v[194:197], v[96:99]
	v_mfma_f32_16x16x32_bf16 v[84:87], v[144:147], v[202:205], v[84:87]
	v_mfma_f32_16x16x32_bf16 v[80:83], v[152:155], v[202:205], v[80:83]
	v_mfma_f32_16x16x32_bf16 v[132:135], v[148:151], v[164:167], v[132:135]
	v_mfma_f32_16x16x32_bf16 v[128:131], v[156:159], v[164:167], v[128:131]
	v_mfma_f32_16x16x32_bf16 v[116:119], v[148:151], v[190:193], v[116:119]
	v_mfma_f32_16x16x32_bf16 v[112:115], v[156:159], v[190:193], v[112:115]
	v_mfma_f32_16x16x32_bf16 v[100:103], v[148:151], v[198:201], v[100:103]
	v_mfma_f32_16x16x32_bf16 v[96:99], v[156:159], v[198:201], v[96:99]
	v_mfma_f32_16x16x32_bf16 v[84:87], v[148:151], v[214:217], v[84:87]
	v_mfma_f32_16x16x32_bf16 v[80:83], v[156:159], v[214:217], v[80:83]
	s_setprio 0
	s_barrier
	s_add_i32 s86, s81, s68
	v_lshl_add_u64 v[218:219], s[62:63], 0, v[170:171]
	s_mov_b32 m0, s86
	ds_read_b128 v[160:163], v210 offset:16384
	ds_read_b128 v[164:167], v210 offset:17408
	ds_read_b128 v[186:189], v210 offset:18432
	ds_read_b128 v[190:193], v210 offset:19456
	ds_read_b128 v[194:197], v210 offset:20480
	ds_read_b128 v[198:201], v210 offset:21504
	ds_read_b128 v[202:205], v210 offset:22528
	ds_read_b128 v[214:217], v210 offset:23552
	global_load_lds_dwordx4 v[218:219], off
	s_add_i32 m0, s86, 0x2000
	s_add_u32 s86, s62, 0x40000
	v_lshl_add_u64 v[220:221], s[62:63], 0, v[174:175]
	s_addc_u32 s87, s63, 0
	s_add_i32 s88, s82, s68
	global_load_lds_dwordx4 v[220:221], off
	v_lshl_add_u64 v[222:223], s[86:87], 0, v[170:171]
	s_mov_b32 m0, s88
	v_lshl_add_u64 v[226:227], s[64:65], 0, v[172:173]
	global_load_lds_dwordx4 v[222:223], off
	v_lshl_add_u64 v[222:223], s[86:87], 0, v[174:175]
	s_add_i32 m0, s88, 0x2000
	s_nop 0
	global_load_lds_dwordx4 v[222:223], off
	v_lshl_add_u64 v[222:223], s[64:65], 0, v[168:169]
	s_mov_b32 m0, s69
	s_nop 0
	global_load_lds_dwordx4 v[222:223], off
	s_mov_b32 m0, s70
	s_nop 0
	global_load_lds_dwordx4 v[226:227], off
	s_waitcnt vmcnt(8)
	s_waitcnt lgkmcnt(0)
	s_nop 0
	s_barrier
	s_setprio 1
	s_waitcnt lgkmcnt(0)
	v_mfma_f32_16x16x32_bf16 v[76:79], v[40:43], v[160:163], v[76:79]
	v_mfma_f32_16x16x32_bf16 v[72:75], v[56:59], v[160:163], v[72:75]
	v_mfma_f32_16x16x32_bf16 v[52:55], v[40:43], v[186:189], v[52:55]
	v_mfma_f32_16x16x32_bf16 v[48:51], v[56:59], v[186:189], v[48:51]
	v_mfma_f32_16x16x32_bf16 v[28:31], v[40:43], v[194:197], v[28:31]
	v_mfma_f32_16x16x32_bf16 v[24:27], v[56:59], v[194:197], v[24:27]
	v_mfma_f32_16x16x32_bf16 v[12:15], v[40:43], v[202:205], v[12:15]
	v_mfma_f32_16x16x32_bf16 v[8:11], v[56:59], v[202:205], v[8:11]
	v_mfma_f32_16x16x32_bf16 v[76:79], v[44:47], v[164:167], v[76:79]
	v_mfma_f32_16x16x32_bf16 v[72:75], v[60:63], v[164:167], v[72:75]
	v_mfma_f32_16x16x32_bf16 v[52:55], v[44:47], v[190:193], v[52:55]
	v_mfma_f32_16x16x32_bf16 v[48:51], v[60:63], v[190:193], v[48:51]
	v_mfma_f32_16x16x32_bf16 v[28:31], v[44:47], v[198:201], v[28:31]
	v_mfma_f32_16x16x32_bf16 v[24:27], v[60:63], v[198:201], v[24:27]
	v_mfma_f32_16x16x32_bf16 v[12:15], v[44:47], v[214:217], v[12:15]
	v_mfma_f32_16x16x32_bf16 v[8:11], v[60:63], v[214:217], v[8:11]
	s_setprio 0
	s_setprio 1
	v_mfma_f32_16x16x32_bf16 v[36:39], v[144:147], v[186:189], v[36:39]
	v_mfma_f32_16x16x32_bf16 v[32:35], v[152:155], v[186:189], v[32:35]
	v_mfma_f32_16x16x32_bf16 v[20:23], v[144:147], v[194:197], v[20:23]
	v_mfma_f32_16x16x32_bf16 v[16:19], v[152:155], v[194:197], v[16:19]
	v_mfma_f32_16x16x32_bf16 v[4:7], v[144:147], v[202:205], v[4:7]
	v_mfma_f32_16x16x32_bf16 v[0:3], v[152:155], v[202:205], v[0:3]
	v_mfma_f32_16x16x32_bf16 v[40:43], v[144:147], v[160:163], v[68:71]
	v_mfma_f32_16x16x32_bf16 v[44:47], v[152:155], v[160:163], v[64:67]
	v_mfma_f32_16x16x32_bf16 v[36:39], v[148:151], v[190:193], v[36:39]
	v_mfma_f32_16x16x32_bf16 v[32:35], v[156:159], v[190:193], v[32:35]
	v_mfma_f32_16x16x32_bf16 v[20:23], v[148:151], v[198:201], v[20:23]
	v_mfma_f32_16x16x32_bf16 v[16:19], v[156:159], v[198:201], v[16:19]
	v_mfma_f32_16x16x32_bf16 v[4:7], v[148:151], v[214:217], v[4:7]
	v_mfma_f32_16x16x32_bf16 v[0:3], v[156:159], v[214:217], v[0:3]
	v_mfma_f32_16x16x32_bf16 v[40:43], v[148:151], v[164:167], v[40:43]
	v_mfma_f32_16x16x32_bf16 v[44:47], v[156:159], v[164:167], v[44:47]
	s_setprio 0
	s_barrier
; #define PG8_STAGE(bufoff, gbase, voff) do { _Pragma("unroll") for (int _i = 0; _i < 2; ++_i) \
;         __builtin_amdgcn_global_load_lds((const unsigned*)((const char*)(gbase) + (voff)[_i]), (LAS unsigned*)(lds + (bufoff) + ldsw + _i * 8192), 16, 0, 0); } while (0)
; #define PG8_LDA(dst, b, h) do { _Pragma("unroll") for (int m = 0; m < 4; ++m) _Pragma("unroll") for (int k = 0; k < 2; ++k) dst[m][k] = *(const LAS bf16x8*)(lds + PG8_SA(b, h) + aoff + m * 2048 + k * 1024); } while (0)
; #define PG8_LDB(dst, b, h) do { _Pragma("unroll") for (int n = 0; n < 2; ++n) _Pragma("unroll") for (int k = 0; k < 2; ++k) dst[n][k] = *(const LAS bf16x8*)(lds + PG8_SB(b, h) + boff + n * 2048 + k * 1024); } while (0)
; #define PG8_MMA(ai, bj, At, Bt) do { __builtin_amdgcn_s_setprio(1); _Pragma("unroll") for (int m = 0; m < 4; ++m) _Pragma("unroll") for (int n = 0; n < 2; ++n) _Pragma("unroll") for (int k = 0; k < 2; ++k) \
;         acc[ai][bj][m][n] = __builtin_amdgcn_mfma_f32_16x16x32_bf16(Bt[n][k], At[m][k], acc[ai][bj][m][n], 0, 0, 0); __builtin_amdgcn_s_setprio(0); } while (0)
; #define PG8_WAIT_V(n) asm volatile("s_waitcnt vmcnt(" #n ")" ::: "memory")
; #define PG8_WAIT_L(n) asm volatile("s_waitcnt lgkmcnt(" #n ")" ::: "memory")
; #define PG8_BAR __builtin_amdgcn_s_barrier()
; #define PG8_SCHED __builtin_amdgcn_sched_barrier(0)
; template <class Epi>
; __device__ __forceinline__ void gemm_phase(LAS unsigned char* lds, const Gemm g, const StaticOrder& S, const Epi& E) {
;     ...
;             PG8_LDB(B0, 1, 0); PG8_LDB(B1, 1, 1); PG8_SCHED; PG8_LDA(At, 1, 0); PG8_STAGE(PG8_SA(0, 1), a2 + hstepA, voffA);
;             PG8_WAIT_V(8); PG8_WAIT_L(0); PG8_BAR; PG8_MMA(0, 0, At, B0); PG8_MMA(0, 1, At, B1); PG8_BAR; PG8_SCHED;
	s_add_i32 s86, 0, 0x18000
	s_add_i32 s87, 0, 0x1c000
	v_add_u32_e32 v68, s86, v207
	v_add_u32_e32 v156, s87, v207
	ds_read_b128 v[56:59], v68
	ds_read_b128 v[60:63], v68 offset:1024
	ds_read_b128 v[64:67], v68 offset:2048
	ds_read_b128 v[68:71], v68 offset:3072
	ds_read_b128 v[144:147], v156
	ds_read_b128 v[148:151], v156 offset:1024
	ds_read_b128 v[152:155], v156 offset:2048
	ds_read_b128 v[156:159], v156 offset:3072
	s_add_u32 s64, s64, 0x40000
	s_addc_u32 s65, s65, 0
	s_mov_b32 m0, s71
	v_lshl_add_u64 v[228:229], s[64:65], 0, v[168:169]
	ds_read_b128 v[160:163], v210 offset:32768
	ds_read_b128 v[164:167], v210 offset:33792
	ds_read_b128 v[186:189], v210 offset:34816
	ds_read_b128 v[190:193], v210 offset:35840
	ds_read_b128 v[194:197], v210 offset:36864
	ds_read_b128 v[198:201], v210 offset:37888
	ds_read_b128 v[202:205], v210 offset:38912
	ds_read_b128 v[214:217], v210 offset:39936
	global_load_lds_dwordx4 v[228:229], off
	v_lshl_add_u64 v[228:229], s[64:65], 0, v[172:173]
	s_mov_b32 m0, s72
	s_nop 0
	global_load_lds_dwordx4 v[228:229], off
	s_waitcnt vmcnt(8)
	s_waitcnt lgkmcnt(0)
	s_nop 0
	s_barrier
	s_setprio 1
	s_waitcnt lgkmcnt(0)
	v_mfma_f32_16x16x32_bf16 v[140:143], v[56:59], v[160:163], v[140:143]
	v_mfma_f32_16x16x32_bf16 v[136:139], v[64:67], v[160:163], v[136:139]
	v_mfma_f32_16x16x32_bf16 v[124:127], v[56:59], v[186:189], v[124:127]
	v_mfma_f32_16x16x32_bf16 v[120:123], v[64:67], v[186:189], v[120:123]
	v_mfma_f32_16x16x32_bf16 v[108:111], v[56:59], v[194:197], v[108:111]
	v_mfma_f32_16x16x32_bf16 v[104:107], v[64:67], v[194:197], v[104:107]
	v_mfma_f32_16x16x32_bf16 v[92:95], v[56:59], v[202:205], v[92:95]
	v_mfma_f32_16x16x32_bf16 v[88:91], v[64:67], v[202:205], v[88:91]
	v_mfma_f32_16x16x32_bf16 v[140:143], v[60:63], v[164:167], v[140:143]
	v_mfma_f32_16x16x32_bf16 v[136:139], v[68:71], v[164:167], v[136:139]
	v_mfma_f32_16x16x32_bf16 v[124:127], v[60:63], v[190:193], v[124:127]
	v_mfma_f32_16x16x32_bf16 v[120:123], v[68:71], v[190:193], v[120:123]
	v_mfma_f32_16x16x32_bf16 v[108:111], v[60:63], v[198:201], v[108:111]
	v_mfma_f32_16x16x32_bf16 v[104:107], v[68:71], v[198:201], v[104:107]
	v_mfma_f32_16x16x32_bf16 v[92:95], v[60:63], v[214:217], v[92:95]
	v_mfma_f32_16x16x32_bf16 v[88:91], v[68:71], v[214:217], v[88:91]
	s_setprio 0
	s_setprio 1
	v_mfma_f32_16x16x32_bf16 v[132:135], v[144:147], v[160:163], v[132:135]
	v_mfma_f32_16x16x32_bf16 v[128:131], v[152:155], v[160:163], v[128:131]
	v_mfma_f32_16x16x32_bf16 v[116:119], v[144:147], v[186:189], v[116:119]
	v_mfma_f32_16x16x32_bf16 v[112:115], v[152:155], v[186:189], v[112:115]
	v_mfma_f32_16x16x32_bf16 v[100:103], v[144:147], v[194:197], v[100:103]
	v_mfma_f32_16x16x32_bf16 v[96:99], v[152:155], v[194:197], v[96:99]
	v_mfma_f32_16x16x32_bf16 v[84:87], v[144:147], v[202:205], v[84:87]
	v_mfma_f32_16x16x32_bf16 v[80:83], v[152:155], v[202:205], v[80:83]
	v_mfma_f32_16x16x32_bf16 v[132:135], v[148:151], v[164:167], v[132:135]
	v_mfma_f32_16x16x32_bf16 v[128:131], v[156:159], v[164:167], v[128:131]
	v_mfma_f32_16x16x32_bf16 v[116:119], v[148:151], v[190:193], v[116:119]
	v_mfma_f32_16x16x32_bf16 v[112:115], v[156:159], v[190:193], v[112:115]
	v_mfma_f32_16x16x32_bf16 v[100:103], v[148:151], v[198:201], v[100:103]
	v_mfma_f32_16x16x32_bf16 v[96:99], v[156:159], v[198:201], v[96:99]
	v_mfma_f32_16x16x32_bf16 v[84:87], v[148:151], v[214:217], v[84:87]
	v_mfma_f32_16x16x32_bf16 v[80:83], v[156:159], v[214:217], v[80:83]
	s_setprio 0
	s_barrier
; #define PG8_STAGE(bufoff, gbase, voff) do { _Pragma("unroll") for (int _i = 0; _i < 2; ++_i) \
;         __builtin_amdgcn_global_load_lds((const unsigned*)((const char*)(gbase) + (voff)[_i]), (LAS unsigned*)(lds + (bufoff) + ldsw + _i * 8192), 16, 0, 0); } while (0)
; #define PG8_LDA(dst, b, h) do { _Pragma("unroll") for (int m = 0; m < 4; ++m) _Pragma("unroll") for (int k = 0; k < 2; ++k) dst[m][k] = *(const LAS bf16x8*)(lds + PG8_SA(b, h) + aoff + m * 2048 + k * 1024); } while (0)
; #define PG8_MMA(ai, bj, At, Bt) do { __builtin_amdgcn_s_setprio(1); _Pragma("unroll") for (int m = 0; m < 4; ++m) _Pragma("unroll") for (int n = 0; n < 2; ++n) _Pragma("unroll") for (int k = 0; k < 2; ++k) \
;         acc[ai][bj][m][n] = __builtin_amdgcn_mfma_f32_16x16x32_bf16(Bt[n][k], At[m][k], acc[ai][bj][m][n], 0, 0, 0); __builtin_amdgcn_s_setprio(0); } while (0)
; #define PG8_WAIT_V(n) asm volatile("s_waitcnt vmcnt(" #n ")" ::: "memory")
; #define PG8_WAIT_L(n) asm volatile("s_waitcnt lgkmcnt(" #n ")" ::: "memory")
; #define PG8_BAR __builtin_amdgcn_s_barrier()
; #define PG8_SCHED __builtin_amdgcn_sched_barrier(0)
; template <class Epi>
; __device__ __forceinline__ void gemm_phase(LAS unsigned char* lds, const Gemm g, const StaticOrder& S, const Epi& E) {
;     ...
;             PG8_LDA(At, 1, 1); PG8_STAGE(PG8_SB(1, 0), b3, voffB); PG8_STAGE(PG8_SB(1, 1), b3 + hstepB, voffB); PG8_STAGE(PG8_SA(1, 0), a3, voffA);
;             PG8_WAIT_V(8); PG8_WAIT_L(0); PG8_BAR; PG8_MMA(1, 0, At, B0); PG8_MMA(1, 1, At, B1); PG8_BAR; PG8_SCHED;
;         }
;         if (wr == 0) PG8_BAR;
	s_add_i32 s64, s86, s68
	v_lshl_add_u64 v[218:219], v[218:219], 0, s[18:19]
	s_mov_b32 m0, s64
	ds_read_b128 v[160:163], v210 offset:49152
	ds_read_b128 v[164:167], v210 offset:50176
	ds_read_b128 v[186:189], v210 offset:51200
	ds_read_b128 v[190:193], v210 offset:52224
	ds_read_b128 v[194:197], v210 offset:53248
	ds_read_b128 v[198:201], v210 offset:54272
	ds_read_b128 v[202:205], v210 offset:55296
	ds_read_b128 v[214:217], v210 offset:56320
	global_load_lds_dwordx4 v[218:219], off
	s_add_i32 m0, s64, 0x2000
	s_add_u32 s62, s62, 0x40080
	v_lshl_add_u64 v[218:219], v[220:221], 0, s[18:19]
	s_addc_u32 s63, s63, 0
	s_add_i32 s64, s87, s68
	global_load_lds_dwordx4 v[218:219], off
	v_lshl_add_u64 v[218:219], s[62:63], 0, v[170:171]
	s_mov_b32 m0, s64
	s_nop 0
	global_load_lds_dwordx4 v[218:219], off
	v_lshl_add_u64 v[218:219], s[62:63], 0, v[174:175]
	s_add_i32 m0, s64, 0x2000
	s_nop 0
	global_load_lds_dwordx4 v[218:219], off
	v_lshl_add_u64 v[218:219], v[222:223], 0, s[18:19]
	s_mov_b32 m0, s76
	s_nop 0
	global_load_lds_dwordx4 v[218:219], off
	v_lshl_add_u64 v[218:219], v[226:227], 0, s[18:19]
	s_mov_b32 m0, s77
	s_nop 0
	global_load_lds_dwordx4 v[218:219], off
	s_waitcnt vmcnt(8)
	s_waitcnt lgkmcnt(0)
	s_barrier
	s_setprio 1
	s_waitcnt lgkmcnt(0)
	v_mfma_f32_16x16x32_bf16 v[76:79], v[56:59], v[160:163], v[76:79]
	v_mfma_f32_16x16x32_bf16 v[72:75], v[64:67], v[160:163], v[72:75]
	v_mfma_f32_16x16x32_bf16 v[52:55], v[56:59], v[186:189], v[52:55]
	v_mfma_f32_16x16x32_bf16 v[48:51], v[64:67], v[186:189], v[48:51]
	v_mfma_f32_16x16x32_bf16 v[28:31], v[56:59], v[194:197], v[28:31]
	v_mfma_f32_16x16x32_bf16 v[24:27], v[64:67], v[194:197], v[24:27]
	v_mfma_f32_16x16x32_bf16 v[12:15], v[56:59], v[202:205], v[12:15]
	v_mfma_f32_16x16x32_bf16 v[8:11], v[64:67], v[202:205], v[8:11]
	v_mfma_f32_16x16x32_bf16 v[76:79], v[60:63], v[164:167], v[76:79]
	v_mfma_f32_16x16x32_bf16 v[72:75], v[68:71], v[164:167], v[72:75]
	v_mfma_f32_16x16x32_bf16 v[52:55], v[60:63], v[190:193], v[52:55]
	v_mfma_f32_16x16x32_bf16 v[48:51], v[68:71], v[190:193], v[48:51]
	v_mfma_f32_16x16x32_bf16 v[28:31], v[60:63], v[198:201], v[28:31]
	v_mfma_f32_16x16x32_bf16 v[24:27], v[68:71], v[198:201], v[24:27]
	v_mfma_f32_16x16x32_bf16 v[12:15], v[60:63], v[214:217], v[12:15]
	v_mfma_f32_16x16x32_bf16 v[8:11], v[68:71], v[214:217], v[8:11]
	s_setprio 0
	s_setprio 1
	v_mfma_f32_16x16x32_bf16 v[40:43], v[144:147], v[160:163], v[40:43]
	v_mfma_f32_16x16x32_bf16 v[68:71], v[148:151], v[164:167], v[40:43]
	v_mfma_f32_16x16x32_bf16 v[40:43], v[152:155], v[160:163], v[44:47]
	v_mfma_f32_16x16x32_bf16 v[36:39], v[144:147], v[186:189], v[36:39]
	v_mfma_f32_16x16x32_bf16 v[32:35], v[152:155], v[186:189], v[32:35]
	v_mfma_f32_16x16x32_bf16 v[20:23], v[144:147], v[194:197], v[20:23]
	v_mfma_f32_16x16x32_bf16 v[16:19], v[152:155], v[194:197], v[16:19]
	v_mfma_f32_16x16x32_bf16 v[4:7], v[144:147], v[202:205], v[4:7]
	v_mfma_f32_16x16x32_bf16 v[0:3], v[152:155], v[202:205], v[0:3]
	v_mfma_f32_16x16x32_bf16 v[64:67], v[156:159], v[164:167], v[40:43]
	v_mfma_f32_16x16x32_bf16 v[36:39], v[148:151], v[190:193], v[36:39]
	v_mfma_f32_16x16x32_bf16 v[32:35], v[156:159], v[190:193], v[32:35]
	v_mfma_f32_16x16x32_bf16 v[20:23], v[148:151], v[198:201], v[20:23]
	v_mfma_f32_16x16x32_bf16 v[16:19], v[156:159], v[198:201], v[16:19]
	v_mfma_f32_16x16x32_bf16 v[4:7], v[148:151], v[214:217], v[4:7]
	v_mfma_f32_16x16x32_bf16 v[0:3], v[156:159], v[214:217], v[0:3]
	s_setprio 0
	s_barrier
	s_add_i32 s85, s85, 2
	s_add_u32 s56, s56, 0x100
	s_addc_u32 s57, s57, 0
	s_add_u32 s83, s83, 0x100
	s_addc_u32 s84, s84, 0
	s_cmp_gt_u32 s85, 13
	s_cbranch_scc0 .LBB0_889
	s_and_b64 vcc, exec, s[22:23]
	s_cbranch_vccz .LBB0_892
	s_barrier

; #define PG8_STAGE(bufoff, gbase, voff) do { _Pragma("unroll") for (int _i = 0; _i < 2; ++_i) \
;         __builtin_amdgcn_global_load_lds((const unsigned*)((const char*)(gbase) + (voff)[_i]), (LAS unsigned*)(lds + (bufoff) + ldsw + _i * 8192), 16, 0, 0); } while (0)
; #define PG8_LDA(dst, b, h) do { _Pragma("unroll") for (int m = 0; m < 4; ++m) _Pragma("unroll") for (int k = 0; k < 2; ++k) dst[m][k] = *(const LAS bf16x8*)(lds + PG8_SA(b, h) + aoff + m * 2048 + k * 1024); } while (0)
; #define PG8_LDB(dst, b, h) do { _Pragma("unroll") for (int n = 0; n < 2; ++n) _Pragma("unroll") for (int k = 0; k < 2; ++k) dst[n][k] = *(const LAS bf16x8*)(lds + PG8_SB(b, h) + boff + n * 2048 + k * 1024); } while (0)
; #define PG8_MMA(ai, bj, At, Bt) do { __builtin_amdgcn_s_setprio(1); _Pragma("unroll") for (int m = 0; m < 4; ++m) _Pragma("unroll") for (int n = 0; n < 2; ++n) _Pragma("unroll") for (int k = 0; k < 2; ++k) \
;         acc[ai][bj][m][n] = __builtin_amdgcn_mfma_f32_16x16x32_bf16(Bt[n][k], At[m][k], acc[ai][bj][m][n], 0, 0, 0); __builtin_amdgcn_s_setprio(0); } while (0)
; #define PG8_BAR __builtin_amdgcn_s_barrier()
; template <class Epi>
; __device__ __forceinline__ void gemm_phase(LAS unsigned char* lds, const Gemm g, const StaticOrder& S, const Epi& E) {
;     ...
;         const bool has_next = S.next(ui + 1, nxt);
;         const char* nA = has_next ? (const char*)g.A + (size_t)nxt.pm * tstepA : cA; const char* nB = has_next ? (const char*)g.Bt + (size_t)nxt.pn * tstepB : cB;
; #pragma nounroll
;         for (int t = 0; t < nt; t += 2) {
;             const bool last = (t == nt - 2);
;             const char* a1 = cA + (size_t)(t + 1) * kstep;
;             const char* a2 = last ? nA : cA + (size_t)(t + 2) * kstep; const char* b2 = last ? nB : cB + (size_t)(t + 2) * kstep;
;             const char* a3 = a2 + kstep; const char* b3 = b2 + kstep;
;             PG8_LDB(B0, 0, 0); PG8_LDB(B1, 0, 1); PG8_SCHED; PG8_LDA(At, 0, 0); PG8_STAGE(PG8_SA(1, 1), a1 + hstepA, voffA);
;             PG8_WAIT_V(8); PG8_WAIT_L(0); PG8_BAR; PG8_MMA(0, 0, At, B0); PG8_MMA(0, 1, At, B1); PG8_BAR; PG8_SCHED;
;             PG8_LDA(At, 0, 1); PG8_STAGE(PG8_SB(0, 0), b2, voffB); PG8_STAGE(PG8_SB(0, 1), b2 + hstepB, voffB); PG8_STAGE(PG8_SA(0, 0), a2, voffA);
;             PG8_WAIT_V(8); PG8_WAIT_L(0); PG8_BAR; PG8_MMA(1, 0, At, B0); PG8_MMA(1, 1, At, B1); PG8_BAR; PG8_SCHED;
.LBB0_1017:
	s_ashr_i32 s35, s34, 31
	s_lshl_b64 s[38:39], s[34:35], 19
	s_add_u32 s38, s24, s38
	s_addc_u32 s39, s25, s39
	s_and_b64 s[42:43], s[4:5], exec
	s_cselect_b32 s7, s39, s55
	s_cselect_b32 s35, s38, s54
	s_ashr_i32 s23, s22, 31
	s_lshl_b64 s[42:43], s[22:23], 19
	s_add_u32 s42, s33, s42
	s_addc_u32 s43, s64, s43
	s_and_b64 s[62:63], s[4:5], exec
	s_cselect_b32 s23, s43, s57
	s_cselect_b32 s53, s42, s56
	s_add_u32 s54, s54, 0x40080
	s_addc_u32 s55, s55, 0
	s_add_u32 s83, s56, 0x100
	s_nop 0
	s_addc_u32 s84, s57, 0
	s_mov_b32 s85, -2
	v_lshl_add_u32 v248, s6, 8, v227
	v_add_u32_e32 v248, s74, v248
	v_ashrrev_i32_e32 v249, 31, v248
	v_lshl_add_u64 v[248:249], v[248:249], 2, s[10:11]
	global_load_dword v240, v[248:249], off
	global_load_dword v241, v[248:249], off offset:64
	global_load_dword v242, v[248:249], off offset:128
	global_load_dword v243, v[248:249], off offset:192
	global_load_dword v244, v[248:249], off offset:512
	global_load_dword v245, v[248:249], off offset:576
	global_load_dword v246, v[248:249], off offset:640
	global_load_dword v247, v[248:249], off offset:704
	ds_read_b128 v[0:3], v230
	ds_read_b128 v[4:7], v230 offset:1024
	ds_read_b128 v[8:11], v230 offset:2048
	ds_read_b128 v[12:15], v230 offset:3072
	ds_read_b128 v[144:147], v231
	ds_read_b128 v[148:151], v231 offset:1024
	ds_read_b128 v[152:155], v231 offset:2048
	ds_read_b128 v[156:159], v231 offset:3072
	s_add_u32 s56, s54, 0xfffc0080
	s_addc_u32 s57, s55, -1
	s_cmp_eq_u32 s85, 12
	s_cselect_b32 s63, s7, s57
	s_cselect_b32 s62, s35, s56
	s_cselect_b32 s57, s23, s84
	s_cselect_b32 s56, s53, s83
	v_lshl_add_u64 v[212:213], s[54:55], 0, v[188:189]
	s_add_i32 m0, s68, 0xc000
	ds_read_b128 v[160:163], v232
	ds_read_b128 v[164:167], v232 offset:1024
	ds_read_b128 v[168:171], v232 offset:2048
	ds_read_b128 v[172:175], v232 offset:3072
	ds_read_b128 v[196:199], v232 offset:4096
	ds_read_b128 v[200:203], v232 offset:5120
	ds_read_b128 v[204:207], v232 offset:6144
	ds_read_b128 v[208:211], v232 offset:7168
	global_load_lds_dwordx4 v[212:213], off
	v_lshl_add_u64 v[212:213], s[54:55], 0, v[190:191]
	s_add_i32 m0, s68, 0xe000
	s_nop 0
	global_load_lds_dwordx4 v[212:213], off
	s_waitcnt vmcnt(8)
	s_waitcnt lgkmcnt(0)
	s_nop 0
	s_barrier
	s_setprio 1
	s_waitcnt lgkmcnt(0)
	v_mfma_f32_16x16x32_bf16 v[140:143], v[0:3], v[160:163], 0
	v_mfma_f32_16x16x32_bf16 v[132:135], v[8:11], v[160:163], 0
	v_mfma_f32_16x16x32_bf16 v[124:127], v[0:3], v[168:171], 0
	v_mfma_f32_16x16x32_bf16 v[120:123], v[8:11], v[168:171], 0
	v_mfma_f32_16x16x32_bf16 v[108:111], v[0:3], v[196:199], 0
	v_mfma_f32_16x16x32_bf16 v[104:107], v[8:11], v[196:199], 0
	v_mfma_f32_16x16x32_bf16 v[92:95], v[0:3], v[204:207], 0
	v_mfma_f32_16x16x32_bf16 v[88:91], v[8:11], v[204:207], 0
	v_mfma_f32_16x16x32_bf16 v[140:143], v[4:7], v[164:167], v[140:143]
	v_mfma_f32_16x16x32_bf16 v[132:135], v[12:15], v[164:167], v[132:135]
	v_mfma_f32_16x16x32_bf16 v[124:127], v[4:7], v[172:175], v[124:127]
	v_mfma_f32_16x16x32_bf16 v[120:123], v[12:15], v[172:175], v[120:123]
	v_mfma_f32_16x16x32_bf16 v[108:111], v[4:7], v[200:203], v[108:111]
	v_mfma_f32_16x16x32_bf16 v[104:107], v[12:15], v[200:203], v[104:107]
	v_mfma_f32_16x16x32_bf16 v[92:95], v[4:7], v[208:211], v[92:95]
	v_mfma_f32_16x16x32_bf16 v[88:91], v[12:15], v[208:211], v[88:91]
	s_setprio 0
	s_setprio 1
	v_mfma_f32_16x16x32_bf16 v[136:139], v[144:147], v[160:163], 0
	v_mfma_f32_16x16x32_bf16 v[128:131], v[152:155], v[160:163], 0
	v_mfma_f32_16x16x32_bf16 v[116:119], v[144:147], v[168:171], 0
	v_mfma_f32_16x16x32_bf16 v[112:115], v[152:155], v[168:171], 0
	v_mfma_f32_16x16x32_bf16 v[100:103], v[144:147], v[196:199], 0
	v_mfma_f32_16x16x32_bf16 v[96:99], v[152:155], v[196:199], 0
	v_mfma_f32_16x16x32_bf16 v[84:87], v[144:147], v[204:207], 0
	v_mfma_f32_16x16x32_bf16 v[80:83], v[152:155], v[204:207], 0
	v_mfma_f32_16x16x32_bf16 v[136:139], v[148:151], v[164:167], v[136:139]
	v_mfma_f32_16x16x32_bf16 v[128:131], v[156:159], v[164:167], v[128:131]
	v_mfma_f32_16x16x32_bf16 v[116:119], v[148:151], v[172:175], v[116:119]
	v_mfma_f32_16x16x32_bf16 v[112:115], v[156:159], v[172:175], v[112:115]
	v_mfma_f32_16x16x32_bf16 v[100:103], v[148:151], v[200:203], v[100:103]
	v_mfma_f32_16x16x32_bf16 v[96:99], v[156:159], v[200:203], v[96:99]
	v_mfma_f32_16x16x32_bf16 v[84:87], v[148:151], v[208:211], v[84:87]
	v_mfma_f32_16x16x32_bf16 v[80:83], v[156:159], v[208:211], v[80:83]
	s_setprio 0
	s_barrier
	s_add_i32 s86, s81, s65
	v_lshl_add_u64 v[212:213], s[56:57], 0, v[180:181]
	s_mov_b32 m0, s86
	ds_read_b128 v[160:163], v232 offset:16384
	ds_read_b128 v[164:167], v232 offset:17408
	ds_read_b128 v[168:171], v232 offset:18432
	ds_read_b128 v[172:175], v232 offset:19456
	ds_read_b128 v[196:199], v232 offset:20480
	ds_read_b128 v[200:203], v232 offset:21504
	ds_read_b128 v[204:207], v232 offset:22528
	ds_read_b128 v[208:211], v232 offset:23552
	global_load_lds_dwordx4 v[212:213], off
	s_add_i32 m0, s86, 0x2000
	s_add_u32 s86, s56, 0x40000
	v_lshl_add_u64 v[214:215], s[56:57], 0, v[184:185]
	s_addc_u32 s87, s57, 0
	s_add_i32 s88, s82, s65
	global_load_lds_dwordx4 v[214:215], off
	v_lshl_add_u64 v[216:217], s[86:87], 0, v[180:181]
	s_mov_b32 m0, s88
	v_lshl_add_u64 v[218:219], s[62:63], 0, v[182:183]
	global_load_lds_dwordx4 v[216:217], off
	v_lshl_add_u64 v[216:217], s[86:87], 0, v[184:185]
	s_add_i32 m0, s88, 0x2000
	s_nop 0
	global_load_lds_dwordx4 v[216:217], off
	v_lshl_add_u64 v[216:217], s[62:63], 0, v[178:179]
	s_mov_b32 m0, s68
	s_nop 0
	global_load_lds_dwordx4 v[216:217], off
	s_mov_b32 m0, s69
	s_nop 0
	global_load_lds_dwordx4 v[218:219], off
	s_waitcnt vmcnt(8)
	s_waitcnt lgkmcnt(0)
	s_nop 0
	s_barrier
; #define PG8_STAGE(bufoff, gbase, voff) do { _Pragma("unroll") for (int _i = 0; _i < 2; ++_i) \
;         __builtin_amdgcn_global_load_lds((const unsigned*)((const char*)(gbase) + (voff)[_i]), (LAS unsigned*)(lds + (bufoff) + ldsw + _i * 8192), 16, 0, 0); } while (0)
; #define PG8_LDA(dst, b, h) do { _Pragma("unroll") for (int m = 0; m < 4; ++m) _Pragma("unroll") for (int k = 0; k < 2; ++k) dst[m][k] = *(const LAS bf16x8*)(lds + PG8_SA(b, h) + aoff + m * 2048 + k * 1024); } while (0)
; #define PG8_LDB(dst, b, h) do { _Pragma("unroll") for (int n = 0; n < 2; ++n) _Pragma("unroll") for (int k = 0; k < 2; ++k) dst[n][k] = *(const LAS bf16x8*)(lds + PG8_SB(b, h) + boff + n * 2048 + k * 1024); } while (0)
; #define PG8_MMA(ai, bj, At, Bt) do { __builtin_amdgcn_s_setprio(1); _Pragma("unroll") for (int m = 0; m < 4; ++m) _Pragma("unroll") for (int n = 0; n < 2; ++n) _Pragma("unroll") for (int k = 0; k < 2; ++k) \
;         acc[ai][bj][m][n] = __builtin_amdgcn_mfma_f32_16x16x32_bf16(Bt[n][k], At[m][k], acc[ai][bj][m][n], 0, 0, 0); __builtin_amdgcn_s_setprio(0); } while (0)
; #define PG8_WAIT_V(n) asm volatile("s_waitcnt vmcnt(" #n ")" ::: "memory")
; #define PG8_WAIT_L(n) asm volatile("s_waitcnt lgkmcnt(" #n ")" ::: "memory")
; #define PG8_BAR __builtin_amdgcn_s_barrier()
; #define PG8_SCHED __builtin_amdgcn_sched_barrier(0)
; template <class Epi>
; __device__ __forceinline__ void gemm_phase(LAS unsigned char* lds, const Gemm g, const StaticOrder& S, const Epi& E) {
;     ...
;             PG8_WAIT_V(8); PG8_WAIT_L(0); PG8_BAR; PG8_MMA(1, 0, At, B0); PG8_MMA(1, 1, At, B1); PG8_BAR; PG8_SCHED;
;             PG8_LDB(B0, 1, 0); PG8_LDB(B1, 1, 1); PG8_SCHED; PG8_LDA(At, 1, 0); PG8_STAGE(PG8_SA(0, 1), a2 + hstepA, voffA);
;             PG8_WAIT_V(8); PG8_WAIT_L(0); PG8_BAR; PG8_MMA(0, 0, At, B0); PG8_MMA(0, 1, At, B1); PG8_BAR; PG8_SCHED;
	s_setprio 1
	s_waitcnt lgkmcnt(0)
	v_mfma_f32_16x16x32_bf16 v[76:79], v[0:3], v[160:163], 0
	v_mfma_f32_16x16x32_bf16 v[72:75], v[8:11], v[160:163], 0
	v_mfma_f32_16x16x32_bf16 v[60:63], v[0:3], v[168:171], 0
	v_mfma_f32_16x16x32_bf16 v[56:59], v[8:11], v[168:171], 0
	v_mfma_f32_16x16x32_bf16 v[44:47], v[0:3], v[196:199], 0
	v_mfma_f32_16x16x32_bf16 v[40:43], v[8:11], v[196:199], 0
	v_mfma_f32_16x16x32_bf16 v[0:3], v[0:3], v[204:207], 0
	v_mfma_f32_16x16x32_bf16 v[76:79], v[4:7], v[164:167], v[76:79]
	v_mfma_f32_16x16x32_bf16 v[72:75], v[12:15], v[164:167], v[72:75]
	v_mfma_f32_16x16x32_bf16 v[60:63], v[4:7], v[172:175], v[60:63]
	v_mfma_f32_16x16x32_bf16 v[56:59], v[12:15], v[172:175], v[56:59]
	v_mfma_f32_16x16x32_bf16 v[44:47], v[4:7], v[200:203], v[44:47]
	v_mfma_f32_16x16x32_bf16 v[40:43], v[12:15], v[200:203], v[40:43]
	v_mfma_f32_16x16x32_bf16 v[0:3], v[4:7], v[208:211], v[0:3]
	v_mfma_f32_16x16x32_bf16 v[4:7], v[8:11], v[204:207], 0
	v_mfma_f32_16x16x32_bf16 v[4:7], v[12:15], v[208:211], v[4:7]
	s_setprio 0
	s_setprio 1
	v_mfma_f32_16x16x32_bf16 v[20:23], v[144:147], v[168:171], 0
	v_mfma_f32_16x16x32_bf16 v[52:55], v[148:151], v[172:175], v[20:23]
	v_mfma_f32_16x16x32_bf16 v[20:23], v[152:155], v[168:171], 0
	v_mfma_f32_16x16x32_bf16 v[48:51], v[156:159], v[172:175], v[20:23]
	v_mfma_f32_16x16x32_bf16 v[20:23], v[144:147], v[196:199], 0
	v_mfma_f32_16x16x32_bf16 v[36:39], v[148:151], v[200:203], v[20:23]
	v_mfma_f32_16x16x32_bf16 v[20:23], v[152:155], v[196:199], 0
	v_mfma_f32_16x16x32_bf16 v[32:35], v[156:159], v[200:203], v[20:23]
	v_mfma_f32_16x16x32_bf16 v[20:23], v[144:147], v[204:207], 0
	v_mfma_f32_16x16x32_bf16 v[16:19], v[152:155], v[204:207], 0
	v_mfma_f32_16x16x32_bf16 v[8:11], v[144:147], v[160:163], 0
	v_mfma_f32_16x16x32_bf16 v[12:15], v[152:155], v[160:163], 0
	v_mfma_f32_16x16x32_bf16 v[24:27], v[148:151], v[208:211], v[20:23]
	v_mfma_f32_16x16x32_bf16 v[16:19], v[156:159], v[208:211], v[16:19]
	v_mfma_f32_16x16x32_bf16 v[8:11], v[148:151], v[164:167], v[8:11]
	v_mfma_f32_16x16x32_bf16 v[12:15], v[156:159], v[164:167], v[12:15]
	s_setprio 0
	s_barrier
	s_add_i32 s86, 0, 0x18000
	s_add_i32 s87, 0, 0x1c000
	v_add_u32_e32 v68, s86, v229
	v_add_u32_e32 v156, s87, v229
	ds_read_b128 v[20:23], v68
	ds_read_b128 v[28:31], v68 offset:1024
	ds_read_b128 v[64:67], v68 offset:2048
	ds_read_b128 v[68:71], v68 offset:3072
	ds_read_b128 v[144:147], v156
	ds_read_b128 v[148:151], v156 offset:1024
	ds_read_b128 v[152:155], v156 offset:2048
	ds_read_b128 v[156:159], v156 offset:3072
	s_add_u32 s62, s62, 0x40000
	s_addc_u32 s63, s63, 0
	s_mov_b32 m0, s70
	v_lshl_add_u64 v[220:221], s[62:63], 0, v[178:179]
	ds_read_b128 v[160:163], v232 offset:32768
	ds_read_b128 v[164:167], v232 offset:33792
	ds_read_b128 v[168:171], v232 offset:34816
	ds_read_b128 v[172:175], v232 offset:35840
	ds_read_b128 v[196:199], v232 offset:36864
	ds_read_b128 v[200:203], v232 offset:37888
	ds_read_b128 v[204:207], v232 offset:38912
	ds_read_b128 v[208:211], v232 offset:39936
	global_load_lds_dwordx4 v[220:221], off
	v_lshl_add_u64 v[220:221], s[62:63], 0, v[182:183]
	s_mov_b32 m0, s71
	s_nop 0
	global_load_lds_dwordx4 v[220:221], off
	s_waitcnt vmcnt(8)
	s_waitcnt lgkmcnt(0)
	s_nop 0
	s_barrier
	s_setprio 1
	s_waitcnt lgkmcnt(0)
	v_mfma_f32_16x16x32_bf16 v[140:143], v[20:23], v[160:163], v[140:143]
	v_mfma_f32_16x16x32_bf16 v[132:135], v[64:67], v[160:163], v[132:135]
	v_mfma_f32_16x16x32_bf16 v[124:127], v[20:23], v[168:171], v[124:127]
	v_mfma_f32_16x16x32_bf16 v[120:123], v[64:67], v[168:171], v[120:123]
	v_mfma_f32_16x16x32_bf16 v[108:111], v[20:23], v[196:199], v[108:111]
	v_mfma_f32_16x16x32_bf16 v[104:107], v[64:67], v[196:199], v[104:107]
	v_mfma_f32_16x16x32_bf16 v[92:95], v[20:23], v[204:207], v[92:95]
	v_mfma_f32_16x16x32_bf16 v[88:91], v[64:67], v[204:207], v[88:91]
	v_mfma_f32_16x16x32_bf16 v[140:143], v[28:31], v[164:167], v[140:143]
	v_mfma_f32_16x16x32_bf16 v[132:135], v[68:71], v[164:167], v[132:135]
	v_mfma_f32_16x16x32_bf16 v[124:127], v[28:31], v[172:175], v[124:127]
	v_mfma_f32_16x16x32_bf16 v[120:123], v[68:71], v[172:175], v[120:123]
	v_mfma_f32_16x16x32_bf16 v[108:111], v[28:31], v[200:203], v[108:111]
	v_mfma_f32_16x16x32_bf16 v[104:107], v[68:71], v[200:203], v[104:107]
	v_mfma_f32_16x16x32_bf16 v[92:95], v[28:31], v[208:211], v[92:95]
	v_mfma_f32_16x16x32_bf16 v[88:91], v[68:71], v[208:211], v[88:91]
	s_setprio 0
	s_setprio 1
	v_mfma_f32_16x16x32_bf16 v[136:139], v[144:147], v[160:163], v[136:139]
	v_mfma_f32_16x16x32_bf16 v[128:131], v[152:155], v[160:163], v[128:131]
	v_mfma_f32_16x16x32_bf16 v[116:119], v[144:147], v[168:171], v[116:119]
	v_mfma_f32_16x16x32_bf16 v[112:115], v[152:155], v[168:171], v[112:115]
	v_mfma_f32_16x16x32_bf16 v[100:103], v[144:147], v[196:199], v[100:103]
	v_mfma_f32_16x16x32_bf16 v[96:99], v[152:155], v[196:199], v[96:99]
	v_mfma_f32_16x16x32_bf16 v[84:87], v[144:147], v[204:207], v[84:87]
	v_mfma_f32_16x16x32_bf16 v[80:83], v[152:155], v[204:207], v[80:83]
	v_mfma_f32_16x16x32_bf16 v[136:139], v[148:151], v[164:167], v[136:139]
	v_mfma_f32_16x16x32_bf16 v[128:131], v[156:159], v[164:167], v[128:131]
	v_mfma_f32_16x16x32_bf16 v[116:119], v[148:151], v[172:175], v[116:119]
	v_mfma_f32_16x16x32_bf16 v[112:115], v[156:159], v[172:175], v[112:115]
	v_mfma_f32_16x16x32_bf16 v[100:103], v[148:151], v[200:203], v[100:103]
	v_mfma_f32_16x16x32_bf16 v[96:99], v[156:159], v[200:203], v[96:99]
	v_mfma_f32_16x16x32_bf16 v[84:87], v[148:151], v[208:211], v[84:87]
	v_mfma_f32_16x16x32_bf16 v[80:83], v[156:159], v[208:211], v[80:83]
	s_setprio 0
	s_barrier
; #define PG8_STAGE(bufoff, gbase, voff) do { _Pragma("unroll") for (int _i = 0; _i < 2; ++_i) \
;         __builtin_amdgcn_global_load_lds((const unsigned*)((const char*)(gbase) + (voff)[_i]), (LAS unsigned*)(lds + (bufoff) + ldsw + _i * 8192), 16, 0, 0); } while (0)
; #define PG8_LDA(dst, b, h) do { _Pragma("unroll") for (int m = 0; m < 4; ++m) _Pragma("unroll") for (int k = 0; k < 2; ++k) dst[m][k] = *(const LAS bf16x8*)(lds + PG8_SA(b, h) + aoff + m * 2048 + k * 1024); } while (0)
; #define PG8_LDB(dst, b, h) do { _Pragma("unroll") for (int n = 0; n < 2; ++n) _Pragma("unroll") for (int k = 0; k < 2; ++k) dst[n][k] = *(const LAS bf16x8*)(lds + PG8_SB(b, h) + boff + n * 2048 + k * 1024); } while (0)
; #define PG8_MMA(ai, bj, At, Bt) do { __builtin_amdgcn_s_setprio(1); _Pragma("unroll") for (int m = 0; m < 4; ++m) _Pragma("unroll") for (int n = 0; n < 2; ++n) _Pragma("unroll") for (int k = 0; k < 2; ++k) \
;         acc[ai][bj][m][n] = __builtin_amdgcn_mfma_f32_16x16x32_bf16(Bt[n][k], At[m][k], acc[ai][bj][m][n], 0, 0, 0); __builtin_amdgcn_s_setprio(0); } while (0)
; #define PG8_WAIT_V(n) asm volatile("s_waitcnt vmcnt(" #n ")" ::: "memory")
; #define PG8_BAR __builtin_amdgcn_s_barrier()
; template <class Epi>
; __device__ __forceinline__ void gemm_phase(LAS unsigned char* lds, const Gemm g, const StaticOrder& S, const Epi& E) {
;     ...
;             PG8_LDB(B0, 0, 0); PG8_LDB(B1, 0, 1); PG8_SCHED; PG8_LDA(At, 0, 0); PG8_STAGE(PG8_SA(1, 1), a1 + hstepA, voffA);
;             PG8_WAIT_V(8); PG8_WAIT_L(0); PG8_BAR; PG8_MMA(0, 0, At, B0); PG8_MMA(0, 1, At, B1); PG8_BAR; PG8_SCHED;
;             PG8_LDA(At, 0, 1); PG8_STAGE(PG8_SB(0, 0), b2, voffB); PG8_STAGE(PG8_SB(0, 1), b2 + hstepB, voffB); PG8_STAGE(PG8_SA(0, 0), a2, voffA);
;             PG8_WAIT_V(8); PG8_WAIT_L(0); PG8_BAR; PG8_MMA(1, 0, At, B0); PG8_MMA(1, 1, At, B1); PG8_BAR; PG8_SCHED;
;             PG8_LDB(B0, 1, 0); PG8_LDB(B1, 1, 1); PG8_SCHED; PG8_LDA(At, 1, 0); PG8_STAGE(PG8_SA(0, 1), a2 + hstepA, voffA);
;             PG8_WAIT_V(8); PG8_WAIT_L(0); PG8_BAR; PG8_MMA(0, 0, At, B0); PG8_MMA(0, 1, At, B1); PG8_BAR; PG8_SCHED;
;             PG8_LDA(At, 1, 1); PG8_STAGE(PG8_SB(1, 0), b3, voffB); PG8_STAGE(PG8_SB(1, 1), b3 + hstepB, voffB); PG8_STAGE(PG8_SA(1, 0), a3, voffA);
;             PG8_WAIT_V(8); PG8_WAIT_L(0); PG8_BAR; PG8_MMA(1, 0, At, B0); PG8_MMA(1, 1, At, B1); PG8_BAR; PG8_SCHED;
	s_add_i32 s62, s86, s65
	v_lshl_add_u64 v[212:213], v[212:213], 0, s[16:17]
	s_mov_b32 m0, s62
	ds_read_b128 v[160:163], v232 offset:49152
	ds_read_b128 v[164:167], v232 offset:50176
	ds_read_b128 v[168:171], v232 offset:51200
	ds_read_b128 v[172:175], v232 offset:52224
	ds_read_b128 v[196:199], v232 offset:53248
	ds_read_b128 v[200:203], v232 offset:54272
	ds_read_b128 v[204:207], v232 offset:55296
	ds_read_b128 v[208:211], v232 offset:56320
	global_load_lds_dwordx4 v[212:213], off
	s_add_i32 m0, s62, 0x2000
	s_add_u32 s56, s56, 0x40080
	v_lshl_add_u64 v[212:213], v[214:215], 0, s[16:17]
	s_addc_u32 s57, s57, 0
	s_add_i32 s62, s87, s65
	global_load_lds_dwordx4 v[212:213], off
	v_lshl_add_u64 v[212:213], s[56:57], 0, v[180:181]
	s_mov_b32 m0, s62
	s_nop 0
	global_load_lds_dwordx4 v[212:213], off
	v_lshl_add_u64 v[212:213], s[56:57], 0, v[184:185]
	s_add_i32 m0, s62, 0x2000
	s_nop 0
	global_load_lds_dwordx4 v[212:213], off
	v_lshl_add_u64 v[212:213], v[216:217], 0, s[16:17]
	s_mov_b32 m0, s76
	s_nop 0
	global_load_lds_dwordx4 v[212:213], off
	v_lshl_add_u64 v[212:213], v[218:219], 0, s[16:17]
	s_mov_b32 m0, s77
	s_nop 0
	global_load_lds_dwordx4 v[212:213], off
	s_waitcnt vmcnt(8)
	s_waitcnt lgkmcnt(0)
	s_barrier
	s_setprio 1
	s_waitcnt lgkmcnt(0)
	v_mfma_f32_16x16x32_bf16 v[76:79], v[20:23], v[160:163], v[76:79]
	v_mfma_f32_16x16x32_bf16 v[60:63], v[20:23], v[168:171], v[60:63]
	v_mfma_f32_16x16x32_bf16 v[44:47], v[20:23], v[196:199], v[44:47]
	v_mfma_f32_16x16x32_bf16 v[0:3], v[20:23], v[204:207], v[0:3]
	v_mfma_f32_16x16x32_bf16 v[76:79], v[28:31], v[164:167], v[76:79]
	v_mfma_f32_16x16x32_bf16 v[72:75], v[64:67], v[160:163], v[72:75]
	v_mfma_f32_16x16x32_bf16 v[60:63], v[28:31], v[172:175], v[60:63]
	v_mfma_f32_16x16x32_bf16 v[56:59], v[64:67], v[168:171], v[56:59]
	v_mfma_f32_16x16x32_bf16 v[44:47], v[28:31], v[200:203], v[44:47]
	v_mfma_f32_16x16x32_bf16 v[40:43], v[64:67], v[196:199], v[40:43]
	v_mfma_f32_16x16x32_bf16 v[28:31], v[28:31], v[208:211], v[0:3]
	v_mfma_f32_16x16x32_bf16 v[0:3], v[64:67], v[204:207], v[4:7]
	v_mfma_f32_16x16x32_bf16 v[72:75], v[68:71], v[164:167], v[72:75]
	v_mfma_f32_16x16x32_bf16 v[56:59], v[68:71], v[172:175], v[56:59]
	v_mfma_f32_16x16x32_bf16 v[40:43], v[68:71], v[200:203], v[40:43]
	v_mfma_f32_16x16x32_bf16 v[20:23], v[68:71], v[208:211], v[0:3]
	s_setprio 0
	s_setprio 1
	v_mfma_f32_16x16x32_bf16 v[0:3], v[144:147], v[160:163], v[8:11]
	v_mfma_f32_16x16x32_bf16 v[68:71], v[148:151], v[164:167], v[0:3]
	v_mfma_f32_16x16x32_bf16 v[0:3], v[152:155], v[160:163], v[12:15]
	v_mfma_f32_16x16x32_bf16 v[64:67], v[156:159], v[164:167], v[0:3]
	v_mfma_f32_16x16x32_bf16 v[0:3], v[144:147], v[168:171], v[52:55]
	v_mfma_f32_16x16x32_bf16 v[52:55], v[148:151], v[172:175], v[0:3]
	v_mfma_f32_16x16x32_bf16 v[0:3], v[152:155], v[168:171], v[48:51]
	v_mfma_f32_16x16x32_bf16 v[48:51], v[156:159], v[172:175], v[0:3]
	v_mfma_f32_16x16x32_bf16 v[0:3], v[144:147], v[196:199], v[36:39]
	v_mfma_f32_16x16x32_bf16 v[36:39], v[148:151], v[200:203], v[0:3]
	v_mfma_f32_16x16x32_bf16 v[0:3], v[152:155], v[196:199], v[32:35]
	v_mfma_f32_16x16x32_bf16 v[32:35], v[156:159], v[200:203], v[0:3]
	v_mfma_f32_16x16x32_bf16 v[0:3], v[144:147], v[204:207], v[24:27]
	v_mfma_f32_16x16x32_bf16 v[24:27], v[148:151], v[208:211], v[0:3]
	v_mfma_f32_16x16x32_bf16 v[0:3], v[152:155], v[204:207], v[16:19]
	v_mfma_f32_16x16x32_bf16 v[16:19], v[156:159], v[208:211], v[0:3]
	s_setprio 0
	s_barrier
	s_add_i32 s85, s85, 2
	s_add_u32 s54, s54, 0x100
	s_addc_u32 s55, s55, 0
	s_add_u32 s83, s83, 0x100
	s_addc_u32 s84, s84, 0
	s_cmp_gt_u32 s85, 13
.LBB0_1018:
	ds_read_b128 v[0:3], v230
	ds_read_b128 v[4:7], v230 offset:1024
	ds_read_b128 v[8:11], v230 offset:2048
	ds_read_b128 v[12:15], v230 offset:3072
	ds_read_b128 v[144:147], v231
	ds_read_b128 v[148:151], v231 offset:1024
	ds_read_b128 v[152:155], v231 offset:2048
	ds_read_b128 v[156:159], v231 offset:3072
	s_add_u32 s56, s54, 0xfffc0080
	s_addc_u32 s57, s55, -1
	s_cmp_eq_u32 s85, 12
	s_cselect_b32 s63, s7, s57
	s_cselect_b32 s62, s35, s56
	s_cselect_b32 s57, s23, s84
	s_cselect_b32 s56, s53, s83
	v_lshl_add_u64 v[212:213], s[54:55], 0, v[188:189]
	s_add_i32 m0, s68, 0xc000
	ds_read_b128 v[160:163], v232
	ds_read_b128 v[164:167], v232 offset:1024
	ds_read_b128 v[168:171], v232 offset:2048
	ds_read_b128 v[172:175], v232 offset:3072
	ds_read_b128 v[196:199], v232 offset:4096
	ds_read_b128 v[200:203], v232 offset:5120
	ds_read_b128 v[204:207], v232 offset:6144
	ds_read_b128 v[208:211], v232 offset:7168
	global_load_lds_dwordx4 v[212:213], off
	v_lshl_add_u64 v[212:213], s[54:55], 0, v[190:191]
	s_add_i32 m0, s68, 0xe000
	s_nop 0
	global_load_lds_dwordx4 v[212:213], off
	s_waitcnt vmcnt(8)
	s_waitcnt lgkmcnt(0)
	s_barrier
; #define PG8_STAGE(bufoff, gbase, voff) do { _Pragma("unroll") for (int _i = 0; _i < 2; ++_i) \
;         __builtin_amdgcn_global_load_lds((const unsigned*)((const char*)(gbase) + (voff)[_i]), (LAS unsigned*)(lds + (bufoff) + ldsw + _i * 8192), 16, 0, 0); } while (0)
; #define PG8_LDA(dst, b, h) do { _Pragma("unroll") for (int m = 0; m < 4; ++m) _Pragma("unroll") for (int k = 0; k < 2; ++k) dst[m][k] = *(const LAS bf16x8*)(lds + PG8_SA(b, h) + aoff + m * 2048 + k * 1024); } while (0)
; #define PG8_LDB(dst, b, h) do { _Pragma("unroll") for (int n = 0; n < 2; ++n) _Pragma("unroll") for (int k = 0; k < 2; ++k) dst[n][k] = *(const LAS bf16x8*)(lds + PG8_SB(b, h) + boff + n * 2048 + k * 1024); } while (0)
; #define PG8_MMA(ai, bj, At, Bt) do { __builtin_amdgcn_s_setprio(1); _Pragma("unroll") for (int m = 0; m < 4; ++m) _Pragma("unroll") for (int n = 0; n < 2; ++n) _Pragma("unroll") for (int k = 0; k < 2; ++k) \
;         acc[ai][bj][m][n] = __builtin_amdgcn_mfma_f32_16x16x32_bf16(Bt[n][k], At[m][k], acc[ai][bj][m][n], 0, 0, 0); __builtin_amdgcn_s_setprio(0); } while (0)
; #define PG8_WAIT_V(n) asm volatile("s_waitcnt vmcnt(" #n ")" ::: "memory")
; #define PG8_WAIT_L(n) asm volatile("s_waitcnt lgkmcnt(" #n ")" ::: "memory")
; #define PG8_BAR __builtin_amdgcn_s_barrier()
; #define PG8_SCHED __builtin_amdgcn_sched_barrier(0)
; template <class Epi>
; __device__ __forceinline__ void gemm_phase(LAS unsigned char* lds, const Gemm g, const StaticOrder& S, const Epi& E) {
;     ...
;             PG8_LDB(B0, 0, 0); PG8_LDB(B1, 0, 1); PG8_SCHED; PG8_LDA(At, 0, 0); PG8_STAGE(PG8_SA(1, 1), a1 + hstepA, voffA);
;             PG8_WAIT_V(8); PG8_WAIT_L(0); PG8_BAR; PG8_MMA(0, 0, At, B0); PG8_MMA(0, 1, At, B1); PG8_BAR; PG8_SCHED;
;             PG8_LDA(At, 0, 1); PG8_STAGE(PG8_SB(0, 0), b2, voffB); PG8_STAGE(PG8_SB(0, 1), b2 + hstepB, voffB); PG8_STAGE(PG8_SA(0, 0), a2, voffA);
;             PG8_WAIT_V(8); PG8_WAIT_L(0); PG8_BAR; PG8_MMA(1, 0, At, B0); PG8_MMA(1, 1, At, B1); PG8_BAR; PG8_SCHED;
	s_setprio 1
	s_waitcnt lgkmcnt(0)
	v_mfma_f32_16x16x32_bf16 v[140:143], v[0:3], v[160:163], v[140:143]
	v_mfma_f32_16x16x32_bf16 v[132:135], v[8:11], v[160:163], v[132:135]
	v_mfma_f32_16x16x32_bf16 v[124:127], v[0:3], v[168:171], v[124:127]
	v_mfma_f32_16x16x32_bf16 v[120:123], v[8:11], v[168:171], v[120:123]
	v_mfma_f32_16x16x32_bf16 v[108:111], v[0:3], v[196:199], v[108:111]
	v_mfma_f32_16x16x32_bf16 v[104:107], v[8:11], v[196:199], v[104:107]
	v_mfma_f32_16x16x32_bf16 v[92:95], v[0:3], v[204:207], v[92:95]
	v_mfma_f32_16x16x32_bf16 v[88:91], v[8:11], v[204:207], v[88:91]
	v_mfma_f32_16x16x32_bf16 v[140:143], v[4:7], v[164:167], v[140:143]
	v_mfma_f32_16x16x32_bf16 v[132:135], v[12:15], v[164:167], v[132:135]
	v_mfma_f32_16x16x32_bf16 v[124:127], v[4:7], v[172:175], v[124:127]
	v_mfma_f32_16x16x32_bf16 v[120:123], v[12:15], v[172:175], v[120:123]
	v_mfma_f32_16x16x32_bf16 v[108:111], v[4:7], v[200:203], v[108:111]
	v_mfma_f32_16x16x32_bf16 v[104:107], v[12:15], v[200:203], v[104:107]
	v_mfma_f32_16x16x32_bf16 v[92:95], v[4:7], v[208:211], v[92:95]
	v_mfma_f32_16x16x32_bf16 v[88:91], v[12:15], v[208:211], v[88:91]
	s_setprio 0
	s_setprio 1
	v_mfma_f32_16x16x32_bf16 v[136:139], v[144:147], v[160:163], v[136:139]
	v_mfma_f32_16x16x32_bf16 v[128:131], v[152:155], v[160:163], v[128:131]
	v_mfma_f32_16x16x32_bf16 v[116:119], v[144:147], v[168:171], v[116:119]
	v_mfma_f32_16x16x32_bf16 v[112:115], v[152:155], v[168:171], v[112:115]
	v_mfma_f32_16x16x32_bf16 v[100:103], v[144:147], v[196:199], v[100:103]
	v_mfma_f32_16x16x32_bf16 v[96:99], v[152:155], v[196:199], v[96:99]
	v_mfma_f32_16x16x32_bf16 v[84:87], v[144:147], v[204:207], v[84:87]
	v_mfma_f32_16x16x32_bf16 v[80:83], v[152:155], v[204:207], v[80:83]
	v_mfma_f32_16x16x32_bf16 v[136:139], v[148:151], v[164:167], v[136:139]
	v_mfma_f32_16x16x32_bf16 v[128:131], v[156:159], v[164:167], v[128:131]
	v_mfma_f32_16x16x32_bf16 v[116:119], v[148:151], v[172:175], v[116:119]
	v_mfma_f32_16x16x32_bf16 v[112:115], v[156:159], v[172:175], v[112:115]
	v_mfma_f32_16x16x32_bf16 v[100:103], v[148:151], v[200:203], v[100:103]
	v_mfma_f32_16x16x32_bf16 v[96:99], v[156:159], v[200:203], v[96:99]
	v_mfma_f32_16x16x32_bf16 v[84:87], v[148:151], v[208:211], v[84:87]
	v_mfma_f32_16x16x32_bf16 v[80:83], v[156:159], v[208:211], v[80:83]
	s_setprio 0
	s_barrier
	s_add_i32 s86, s81, s65
	v_lshl_add_u64 v[212:213], s[56:57], 0, v[180:181]
	s_mov_b32 m0, s86
	ds_read_b128 v[160:163], v232 offset:16384
	ds_read_b128 v[164:167], v232 offset:17408
	ds_read_b128 v[168:171], v232 offset:18432
	ds_read_b128 v[172:175], v232 offset:19456
	ds_read_b128 v[196:199], v232 offset:20480
	ds_read_b128 v[200:203], v232 offset:21504
	ds_read_b128 v[204:207], v232 offset:22528
	ds_read_b128 v[208:211], v232 offset:23552
	global_load_lds_dwordx4 v[212:213], off
	s_add_i32 m0, s86, 0x2000
	s_add_u32 s86, s56, 0x40000
	v_lshl_add_u64 v[214:215], s[56:57], 0, v[184:185]
	s_addc_u32 s87, s57, 0
	s_add_i32 s88, s82, s65
	global_load_lds_dwordx4 v[214:215], off
	v_lshl_add_u64 v[216:217], s[86:87], 0, v[180:181]
	s_mov_b32 m0, s88
	v_lshl_add_u64 v[218:219], s[62:63], 0, v[182:183]
	global_load_lds_dwordx4 v[216:217], off
	v_lshl_add_u64 v[216:217], s[86:87], 0, v[184:185]
	s_add_i32 m0, s88, 0x2000
	s_nop 0
	global_load_lds_dwordx4 v[216:217], off
	v_lshl_add_u64 v[216:217], s[62:63], 0, v[178:179]
	s_mov_b32 m0, s68
	s_nop 0
	global_load_lds_dwordx4 v[216:217], off
	s_mov_b32 m0, s69
	s_nop 0
	global_load_lds_dwordx4 v[218:219], off
	s_waitcnt vmcnt(8)
	s_waitcnt lgkmcnt(0)
	s_nop 0
	s_barrier
	s_setprio 1
	s_waitcnt lgkmcnt(0)
	v_mfma_f32_16x16x32_bf16 v[76:79], v[0:3], v[160:163], v[76:79]
	v_mfma_f32_16x16x32_bf16 v[72:75], v[8:11], v[160:163], v[72:75]
	v_mfma_f32_16x16x32_bf16 v[60:63], v[0:3], v[168:171], v[60:63]
	v_mfma_f32_16x16x32_bf16 v[56:59], v[8:11], v[168:171], v[56:59]
	v_mfma_f32_16x16x32_bf16 v[44:47], v[0:3], v[196:199], v[44:47]
	v_mfma_f32_16x16x32_bf16 v[40:43], v[8:11], v[196:199], v[40:43]
	v_mfma_f32_16x16x32_bf16 v[0:3], v[0:3], v[204:207], v[28:31]
	v_mfma_f32_16x16x32_bf16 v[76:79], v[4:7], v[164:167], v[76:79]
	v_mfma_f32_16x16x32_bf16 v[72:75], v[12:15], v[164:167], v[72:75]
	v_mfma_f32_16x16x32_bf16 v[60:63], v[4:7], v[172:175], v[60:63]
	v_mfma_f32_16x16x32_bf16 v[56:59], v[12:15], v[172:175], v[56:59]
	v_mfma_f32_16x16x32_bf16 v[44:47], v[4:7], v[200:203], v[44:47]
	v_mfma_f32_16x16x32_bf16 v[40:43], v[12:15], v[200:203], v[40:43]
	v_mfma_f32_16x16x32_bf16 v[0:3], v[4:7], v[208:211], v[0:3]
	v_mfma_f32_16x16x32_bf16 v[4:7], v[8:11], v[204:207], v[20:23]
	v_mfma_f32_16x16x32_bf16 v[4:7], v[12:15], v[208:211], v[4:7]
	s_setprio 0
	s_setprio 1
	v_mfma_f32_16x16x32_bf16 v[20:23], v[144:147], v[168:171], v[52:55]
	v_mfma_f32_16x16x32_bf16 v[52:55], v[148:151], v[172:175], v[20:23]
	v_mfma_f32_16x16x32_bf16 v[20:23], v[152:155], v[168:171], v[48:51]
	v_mfma_f32_16x16x32_bf16 v[48:51], v[156:159], v[172:175], v[20:23]
	v_mfma_f32_16x16x32_bf16 v[20:23], v[144:147], v[196:199], v[36:39]
	v_mfma_f32_16x16x32_bf16 v[36:39], v[148:151], v[200:203], v[20:23]
	v_mfma_f32_16x16x32_bf16 v[20:23], v[152:155], v[196:199], v[32:35]
	v_mfma_f32_16x16x32_bf16 v[32:35], v[156:159], v[200:203], v[20:23]
	v_mfma_f32_16x16x32_bf16 v[20:23], v[144:147], v[204:207], v[24:27]
	v_mfma_f32_16x16x32_bf16 v[16:19], v[152:155], v[204:207], v[16:19]
	v_mfma_f32_16x16x32_bf16 v[8:11], v[144:147], v[160:163], v[68:71]
	v_mfma_f32_16x16x32_bf16 v[12:15], v[152:155], v[160:163], v[64:67]
	v_mfma_f32_16x16x32_bf16 v[24:27], v[148:151], v[208:211], v[20:23]
	v_mfma_f32_16x16x32_bf16 v[16:19], v[156:159], v[208:211], v[16:19]
	v_mfma_f32_16x16x32_bf16 v[8:11], v[148:151], v[164:167], v[8:11]
	v_mfma_f32_16x16x32_bf16 v[12:15], v[156:159], v[164:167], v[12:15]
	s_setprio 0
	s_barrier
; #define PG8_STAGE(bufoff, gbase, voff) do { _Pragma("unroll") for (int _i = 0; _i < 2; ++_i) \
;         __builtin_amdgcn_global_load_lds((const unsigned*)((const char*)(gbase) + (voff)[_i]), (LAS unsigned*)(lds + (bufoff) + ldsw + _i * 8192), 16, 0, 0); } while (0)
; #define PG8_LDA(dst, b, h) do { _Pragma("unroll") for (int m = 0; m < 4; ++m) _Pragma("unroll") for (int k = 0; k < 2; ++k) dst[m][k] = *(const LAS bf16x8*)(lds + PG8_SA(b, h) + aoff + m * 2048 + k * 1024); } while (0)
; #define PG8_LDB(dst, b, h) do { _Pragma("unroll") for (int n = 0; n < 2; ++n) _Pragma("unroll") for (int k = 0; k < 2; ++k) dst[n][k] = *(const LAS bf16x8*)(lds + PG8_SB(b, h) + boff + n * 2048 + k * 1024); } while (0)
; #define PG8_MMA(ai, bj, At, Bt) do { __builtin_amdgcn_s_setprio(1); _Pragma("unroll") for (int m = 0; m < 4; ++m) _Pragma("unroll") for (int n = 0; n < 2; ++n) _Pragma("unroll") for (int k = 0; k < 2; ++k) \
;         acc[ai][bj][m][n] = __builtin_amdgcn_mfma_f32_16x16x32_bf16(Bt[n][k], At[m][k], acc[ai][bj][m][n], 0, 0, 0); __builtin_amdgcn_s_setprio(0); } while (0)
; #define PG8_WAIT_V(n) asm volatile("s_waitcnt vmcnt(" #n ")" ::: "memory")
; #define PG8_WAIT_L(n) asm volatile("s_waitcnt lgkmcnt(" #n ")" ::: "memory")
; #define PG8_BAR __builtin_amdgcn_s_barrier()
; #define PG8_SCHED __builtin_amdgcn_sched_barrier(0)
; template <class Epi>
; __device__ __forceinline__ void gemm_phase(LAS unsigned char* lds, const Gemm g, const StaticOrder& S, const Epi& E) {
;     ...
;             PG8_LDB(B0, 1, 0); PG8_LDB(B1, 1, 1); PG8_SCHED; PG8_LDA(At, 1, 0); PG8_STAGE(PG8_SA(0, 1), a2 + hstepA, voffA);
;             PG8_WAIT_V(8); PG8_WAIT_L(0); PG8_BAR; PG8_MMA(0, 0, At, B0); PG8_MMA(0, 1, At, B1); PG8_BAR; PG8_SCHED;
	s_add_i32 s86, 0, 0x18000
	s_add_i32 s87, 0, 0x1c000
	v_add_u32_e32 v68, s86, v229
	v_add_u32_e32 v156, s87, v229
	ds_read_b128 v[20:23], v68
	ds_read_b128 v[28:31], v68 offset:1024
	ds_read_b128 v[64:67], v68 offset:2048
	ds_read_b128 v[68:71], v68 offset:3072
	ds_read_b128 v[144:147], v156
	ds_read_b128 v[148:151], v156 offset:1024
	ds_read_b128 v[152:155], v156 offset:2048
	ds_read_b128 v[156:159], v156 offset:3072
	s_add_u32 s62, s62, 0x40000
	s_addc_u32 s63, s63, 0
	s_mov_b32 m0, s70
	v_lshl_add_u64 v[220:221], s[62:63], 0, v[178:179]
	ds_read_b128 v[160:163], v232 offset:32768
	ds_read_b128 v[164:167], v232 offset:33792
	ds_read_b128 v[168:171], v232 offset:34816
	ds_read_b128 v[172:175], v232 offset:35840
	ds_read_b128 v[196:199], v232 offset:36864
	ds_read_b128 v[200:203], v232 offset:37888
	ds_read_b128 v[204:207], v232 offset:38912
	ds_read_b128 v[208:211], v232 offset:39936
	global_load_lds_dwordx4 v[220:221], off
	v_lshl_add_u64 v[220:221], s[62:63], 0, v[182:183]
	s_mov_b32 m0, s71
	s_nop 0
	global_load_lds_dwordx4 v[220:221], off
	s_waitcnt vmcnt(8)
	s_waitcnt lgkmcnt(0)
	s_nop 0
	s_barrier
	s_setprio 1
	s_waitcnt lgkmcnt(0)
	v_mfma_f32_16x16x32_bf16 v[140:143], v[20:23], v[160:163], v[140:143]
	v_mfma_f32_16x16x32_bf16 v[132:135], v[64:67], v[160:163], v[132:135]
	v_mfma_f32_16x16x32_bf16 v[124:127], v[20:23], v[168:171], v[124:127]
	v_mfma_f32_16x16x32_bf16 v[120:123], v[64:67], v[168:171], v[120:123]
	v_mfma_f32_16x16x32_bf16 v[108:111], v[20:23], v[196:199], v[108:111]
	v_mfma_f32_16x16x32_bf16 v[104:107], v[64:67], v[196:199], v[104:107]
	v_mfma_f32_16x16x32_bf16 v[92:95], v[20:23], v[204:207], v[92:95]
	v_mfma_f32_16x16x32_bf16 v[88:91], v[64:67], v[204:207], v[88:91]
	v_mfma_f32_16x16x32_bf16 v[140:143], v[28:31], v[164:167], v[140:143]
	v_mfma_f32_16x16x32_bf16 v[132:135], v[68:71], v[164:167], v[132:135]
	v_mfma_f32_16x16x32_bf16 v[124:127], v[28:31], v[172:175], v[124:127]
	v_mfma_f32_16x16x32_bf16 v[120:123], v[68:71], v[172:175], v[120:123]
	v_mfma_f32_16x16x32_bf16 v[108:111], v[28:31], v[200:203], v[108:111]
	v_mfma_f32_16x16x32_bf16 v[104:107], v[68:71], v[200:203], v[104:107]
	v_mfma_f32_16x16x32_bf16 v[92:95], v[28:31], v[208:211], v[92:95]
	v_mfma_f32_16x16x32_bf16 v[88:91], v[68:71], v[208:211], v[88:91]
	s_setprio 0
	s_setprio 1
	v_mfma_f32_16x16x32_bf16 v[136:139], v[144:147], v[160:163], v[136:139]
	v_mfma_f32_16x16x32_bf16 v[128:131], v[152:155], v[160:163], v[128:131]
	v_mfma_f32_16x16x32_bf16 v[116:119], v[144:147], v[168:171], v[116:119]
	v_mfma_f32_16x16x32_bf16 v[112:115], v[152:155], v[168:171], v[112:115]
	v_mfma_f32_16x16x32_bf16 v[100:103], v[144:147], v[196:199], v[100:103]
	v_mfma_f32_16x16x32_bf16 v[96:99], v[152:155], v[196:199], v[96:99]
	v_mfma_f32_16x16x32_bf16 v[84:87], v[144:147], v[204:207], v[84:87]
	v_mfma_f32_16x16x32_bf16 v[80:83], v[152:155], v[204:207], v[80:83]
	v_mfma_f32_16x16x32_bf16 v[136:139], v[148:151], v[164:167], v[136:139]
	v_mfma_f32_16x16x32_bf16 v[128:131], v[156:159], v[164:167], v[128:131]
	v_mfma_f32_16x16x32_bf16 v[116:119], v[148:151], v[172:175], v[116:119]
	v_mfma_f32_16x16x32_bf16 v[112:115], v[156:159], v[172:175], v[112:115]
	v_mfma_f32_16x16x32_bf16 v[100:103], v[148:151], v[200:203], v[100:103]
	v_mfma_f32_16x16x32_bf16 v[96:99], v[156:159], v[200:203], v[96:99]
	v_mfma_f32_16x16x32_bf16 v[84:87], v[148:151], v[208:211], v[84:87]
	v_mfma_f32_16x16x32_bf16 v[80:83], v[156:159], v[208:211], v[80:83]
	s_setprio 0
	s_barrier
; #define PG8_STAGE(bufoff, gbase, voff) do { _Pragma("unroll") for (int _i = 0; _i < 2; ++_i) \
;         __builtin_amdgcn_global_load_lds((const unsigned*)((const char*)(gbase) + (voff)[_i]), (LAS unsigned*)(lds + (bufoff) + ldsw + _i * 8192), 16, 0, 0); } while (0)
; #define PG8_LDA(dst, b, h) do { _Pragma("unroll") for (int m = 0; m < 4; ++m) _Pragma("unroll") for (int k = 0; k < 2; ++k) dst[m][k] = *(const LAS bf16x8*)(lds + PG8_SA(b, h) + aoff + m * 2048 + k * 1024); } while (0)
; #define PG8_MMA(ai, bj, At, Bt) do { __builtin_amdgcn_s_setprio(1); _Pragma("unroll") for (int m = 0; m < 4; ++m) _Pragma("unroll") for (int n = 0; n < 2; ++n) _Pragma("unroll") for (int k = 0; k < 2; ++k) \
;         acc[ai][bj][m][n] = __builtin_amdgcn_mfma_f32_16x16x32_bf16(Bt[n][k], At[m][k], acc[ai][bj][m][n], 0, 0, 0); __builtin_amdgcn_s_setprio(0); } while (0)
; #define PG8_WAIT_V(n) asm volatile("s_waitcnt vmcnt(" #n ")" ::: "memory")
; #define PG8_WAIT_L(n) asm volatile("s_waitcnt lgkmcnt(" #n ")" ::: "memory")
; #define PG8_BAR __builtin_amdgcn_s_barrier()
; #define PG8_SCHED __builtin_amdgcn_sched_barrier(0)
; template <class Epi>
; __device__ __forceinline__ void gemm_phase(LAS unsigned char* lds, const Gemm g, const StaticOrder& S, const Epi& E) {
;     ...
;             PG8_LDA(At, 1, 1); PG8_STAGE(PG8_SB(1, 0), b3, voffB); PG8_STAGE(PG8_SB(1, 1), b3 + hstepB, voffB); PG8_STAGE(PG8_SA(1, 0), a3, voffA);
;             PG8_WAIT_V(8); PG8_WAIT_L(0); PG8_BAR; PG8_MMA(1, 0, At, B0); PG8_MMA(1, 1, At, B1); PG8_BAR; PG8_SCHED;
;         }
;         if (wr == 0) PG8_BAR;
	s_add_i32 s62, s86, s65
	v_lshl_add_u64 v[212:213], v[212:213], 0, s[16:17]
	s_mov_b32 m0, s62
	ds_read_b128 v[160:163], v232 offset:49152
	ds_read_b128 v[164:167], v232 offset:50176
	ds_read_b128 v[168:171], v232 offset:51200
	ds_read_b128 v[172:175], v232 offset:52224
	ds_read_b128 v[196:199], v232 offset:53248
	ds_read_b128 v[200:203], v232 offset:54272
	ds_read_b128 v[204:207], v232 offset:55296
	ds_read_b128 v[208:211], v232 offset:56320
	global_load_lds_dwordx4 v[212:213], off
	s_add_i32 m0, s62, 0x2000
	s_add_u32 s56, s56, 0x40080
	v_lshl_add_u64 v[212:213], v[214:215], 0, s[16:17]
	s_addc_u32 s57, s57, 0
	s_add_i32 s62, s87, s65
	global_load_lds_dwordx4 v[212:213], off
	v_lshl_add_u64 v[212:213], s[56:57], 0, v[180:181]
	s_mov_b32 m0, s62
	s_nop 0
	global_load_lds_dwordx4 v[212:213], off
	v_lshl_add_u64 v[212:213], s[56:57], 0, v[184:185]
	s_add_i32 m0, s62, 0x2000
	s_nop 0
	global_load_lds_dwordx4 v[212:213], off
	v_lshl_add_u64 v[212:213], v[216:217], 0, s[16:17]
	s_mov_b32 m0, s76
	s_nop 0
	global_load_lds_dwordx4 v[212:213], off
	v_lshl_add_u64 v[212:213], v[218:219], 0, s[16:17]
	s_mov_b32 m0, s77
	s_nop 0
	global_load_lds_dwordx4 v[212:213], off
	s_waitcnt vmcnt(8)
	s_waitcnt lgkmcnt(0)
	s_barrier
	s_setprio 1
	s_waitcnt lgkmcnt(0)
	v_mfma_f32_16x16x32_bf16 v[76:79], v[20:23], v[160:163], v[76:79]
	v_mfma_f32_16x16x32_bf16 v[60:63], v[20:23], v[168:171], v[60:63]
	v_mfma_f32_16x16x32_bf16 v[44:47], v[20:23], v[196:199], v[44:47]
	v_mfma_f32_16x16x32_bf16 v[0:3], v[20:23], v[204:207], v[0:3]
	v_mfma_f32_16x16x32_bf16 v[76:79], v[28:31], v[164:167], v[76:79]
	v_mfma_f32_16x16x32_bf16 v[72:75], v[64:67], v[160:163], v[72:75]
	v_mfma_f32_16x16x32_bf16 v[60:63], v[28:31], v[172:175], v[60:63]
	v_mfma_f32_16x16x32_bf16 v[56:59], v[64:67], v[168:171], v[56:59]
	v_mfma_f32_16x16x32_bf16 v[44:47], v[28:31], v[200:203], v[44:47]
	v_mfma_f32_16x16x32_bf16 v[40:43], v[64:67], v[196:199], v[40:43]
	v_mfma_f32_16x16x32_bf16 v[28:31], v[28:31], v[208:211], v[0:3]
	v_mfma_f32_16x16x32_bf16 v[0:3], v[64:67], v[204:207], v[4:7]
	v_mfma_f32_16x16x32_bf16 v[72:75], v[68:71], v[164:167], v[72:75]
	v_mfma_f32_16x16x32_bf16 v[56:59], v[68:71], v[172:175], v[56:59]
	v_mfma_f32_16x16x32_bf16 v[40:43], v[68:71], v[200:203], v[40:43]
	v_mfma_f32_16x16x32_bf16 v[20:23], v[68:71], v[208:211], v[0:3]
	s_setprio 0
	s_setprio 1
	v_mfma_f32_16x16x32_bf16 v[0:3], v[144:147], v[160:163], v[8:11]
	v_mfma_f32_16x16x32_bf16 v[68:71], v[148:151], v[164:167], v[0:3]
	v_mfma_f32_16x16x32_bf16 v[0:3], v[152:155], v[160:163], v[12:15]
	v_mfma_f32_16x16x32_bf16 v[64:67], v[156:159], v[164:167], v[0:3]
	v_mfma_f32_16x16x32_bf16 v[0:3], v[144:147], v[168:171], v[52:55]
	v_mfma_f32_16x16x32_bf16 v[52:55], v[148:151], v[172:175], v[0:3]
	v_mfma_f32_16x16x32_bf16 v[0:3], v[152:155], v[168:171], v[48:51]
	v_mfma_f32_16x16x32_bf16 v[48:51], v[156:159], v[172:175], v[0:3]
	v_mfma_f32_16x16x32_bf16 v[0:3], v[144:147], v[196:199], v[36:39]
	v_mfma_f32_16x16x32_bf16 v[36:39], v[148:151], v[200:203], v[0:3]
	v_mfma_f32_16x16x32_bf16 v[0:3], v[152:155], v[196:199], v[32:35]
	v_mfma_f32_16x16x32_bf16 v[32:35], v[156:159], v[200:203], v[0:3]
	v_mfma_f32_16x16x32_bf16 v[0:3], v[144:147], v[204:207], v[24:27]
	v_mfma_f32_16x16x32_bf16 v[24:27], v[148:151], v[208:211], v[0:3]
	v_mfma_f32_16x16x32_bf16 v[0:3], v[152:155], v[204:207], v[16:19]
	v_mfma_f32_16x16x32_bf16 v[16:19], v[156:159], v[208:211], v[0:3]
	s_setprio 0
	s_barrier
	s_add_i32 s85, s85, 2
	s_add_u32 s54, s54, 0x100
	s_addc_u32 s55, s55, 0
	s_add_u32 s83, s83, 0x100
	s_addc_u32 s84, s84, 0
	s_cmp_gt_u32 s85, 13
	s_cbranch_scc0 .LBB0_1018
	s_and_b64 vcc, exec, s[18:19]
	s_cbranch_vccz .LBB0_1021
	s_barrier

; #define PG8_STAGE(bufoff, gbase, voff) do { _Pragma("unroll") for (int _i = 0; _i < 2; ++_i) \
;         __builtin_amdgcn_global_load_lds((const unsigned*)((const char*)(gbase) + (voff)[_i]), (LAS unsigned*)(lds + (bufoff) + ldsw + _i * 8192), 16, 0, 0); } while (0)
; #define PG8_LDA(dst, b, h) do { _Pragma("unroll") for (int m = 0; m < 4; ++m) _Pragma("unroll") for (int k = 0; k < 2; ++k) dst[m][k] = *(const LAS bf16x8*)(lds + PG8_SA(b, h) + aoff + m * 2048 + k * 1024); } while (0)
; #define PG8_LDB(dst, b, h) do { _Pragma("unroll") for (int n = 0; n < 2; ++n) _Pragma("unroll") for (int k = 0; k < 2; ++k) dst[n][k] = *(const LAS bf16x8*)(lds + PG8_SB(b, h) + boff + n * 2048 + k * 1024); } while (0)
; #define PG8_MMA(ai, bj, At, Bt) do { __builtin_amdgcn_s_setprio(1); _Pragma("unroll") for (int m = 0; m < 4; ++m) _Pragma("unroll") for (int n = 0; n < 2; ++n) _Pragma("unroll") for (int k = 0; k < 2; ++k) \
;         acc[ai][bj][m][n] = __builtin_amdgcn_mfma_f32_16x16x32_bf16(Bt[n][k], At[m][k], acc[ai][bj][m][n], 0, 0, 0); __builtin_amdgcn_s_setprio(0); } while (0)
; #define PG8_BAR __builtin_amdgcn_s_barrier()
; template <class Epi>
; __device__ __forceinline__ void gemm_phase(LAS unsigned char* lds, const Gemm g, const StaticOrder& S, const Epi& E) {
;     ...
;         const bool has_next = S.next(ui + 1, nxt);
;         const char* nA = has_next ? (const char*)g.A + (size_t)nxt.pm * tstepA : cA; const char* nB = has_next ? (const char*)g.Bt + (size_t)nxt.pn * tstepB : cB;
; #pragma nounroll
;         for (int t = 0; t < nt; t += 2) {
;             const bool last = (t == nt - 2);
;             const char* a1 = cA + (size_t)(t + 1) * kstep;
;             const char* a2 = last ? nA : cA + (size_t)(t + 2) * kstep; const char* b2 = last ? nB : cB + (size_t)(t + 2) * kstep;
;             const char* a3 = a2 + kstep; const char* b3 = b2 + kstep;
;             PG8_LDB(B0, 0, 0); PG8_LDB(B1, 0, 1); PG8_SCHED; PG8_LDA(At, 0, 0); PG8_STAGE(PG8_SA(1, 1), a1 + hstepA, voffA);
;             PG8_WAIT_V(8); PG8_WAIT_L(0); PG8_BAR; PG8_MMA(0, 0, At, B0); PG8_MMA(0, 1, At, B1); PG8_BAR; PG8_SCHED;
;             PG8_LDA(At, 0, 1); PG8_STAGE(PG8_SB(0, 0), b2, voffB); PG8_STAGE(PG8_SB(0, 1), b2 + hstepB, voffB); PG8_STAGE(PG8_SA(0, 0), a2, voffA);
;             PG8_WAIT_V(8); PG8_WAIT_L(0); PG8_BAR; PG8_MMA(1, 0, At, B0); PG8_MMA(1, 1, At, B1); PG8_BAR; PG8_SCHED;
.LBB0_1232:
	s_ashr_i32 s23, s22, 31
	s_lshl_b64 s[34:35], s[22:23], 19
	s_add_u32 s34, s24, s34
	s_addc_u32 s35, s25, s35
	s_and_b64 s[38:39], s[4:5], exec
	s_cselect_b32 s23, s35, s53
	s_cselect_b32 s76, s34, s52
	s_ashr_i32 s21, s20, 31
	s_lshl_b64 s[38:39], s[20:21], 19
	s_add_u32 s38, s19, s38
	s_addc_u32 s39, s33, s39
	s_and_b64 s[56:57], s[4:5], exec
	s_cselect_b32 s21, s39, s55
	s_cselect_b32 s77, s38, s54
	s_add_u32 s52, s52, 0x40080
	s_addc_u32 s53, s53, 0
	s_add_u32 s78, s54, 0x100
	s_addc_u32 s79, s55, 0
	s_mov_b32 s80, -2
	ds_read_b128 v[56:59], v189
	ds_read_b128 v[60:63], v189 offset:1024
	ds_read_b128 v[72:75], v189 offset:2048
	ds_read_b128 v[76:79], v189 offset:3072
	ds_read_b128 v[144:147], v195
	ds_read_b128 v[148:151], v195 offset:1024
	ds_read_b128 v[168:171], v195 offset:2048
	ds_read_b128 v[178:181], v195 offset:3072
	s_add_u32 s54, s52, 0xfffc0080
	s_addc_u32 s55, s53, -1
	s_cmp_eq_u32 s80, 12
	s_cselect_b32 s57, s23, s55
	s_cselect_b32 s56, s76, s54
	s_cselect_b32 s55, s21, s79
	s_cselect_b32 s54, s77, s78
	v_lshl_add_u64 v[174:175], s[52:53], 0, v[160:161]
	s_add_i32 m0, s43, 0xc000
	ds_read_b128 v[184:187], v201
	ds_read_b128 v[190:193], v201 offset:1024
	ds_read_b128 v[196:199], v201 offset:2048
	ds_read_b128 v[202:205], v201 offset:3072
	ds_read_b128 v[208:211], v201 offset:4096
	ds_read_b128 v[212:215], v201 offset:5120
	ds_read_b128 v[216:219], v201 offset:6144
	ds_read_b128 v[220:223], v201 offset:7168
	global_load_lds_dwordx4 v[174:175], off
	v_lshl_add_u64 v[174:175], s[52:53], 0, v[162:163]
	s_add_i32 m0, s43, 0xe000
	s_nop 0
	global_load_lds_dwordx4 v[174:175], off
	s_waitcnt vmcnt(8)
	s_waitcnt lgkmcnt(0)
	s_nop 0
	s_barrier
	s_setprio 1
	s_waitcnt lgkmcnt(0)
	v_mfma_f32_16x16x32_bf16 v[140:143], v[56:59], v[184:187], 0
	v_mfma_f32_16x16x32_bf16 v[136:139], v[72:75], v[184:187], 0
	v_mfma_f32_16x16x32_bf16 v[124:127], v[56:59], v[196:199], 0
	v_mfma_f32_16x16x32_bf16 v[120:123], v[72:75], v[196:199], 0
	v_mfma_f32_16x16x32_bf16 v[108:111], v[56:59], v[208:211], 0
	v_mfma_f32_16x16x32_bf16 v[104:107], v[72:75], v[208:211], 0
	v_mfma_f32_16x16x32_bf16 v[92:95], v[56:59], v[216:219], 0
	v_mfma_f32_16x16x32_bf16 v[88:91], v[72:75], v[216:219], 0
	v_mfma_f32_16x16x32_bf16 v[140:143], v[60:63], v[190:193], v[140:143]
	v_mfma_f32_16x16x32_bf16 v[136:139], v[76:79], v[190:193], v[136:139]
	v_mfma_f32_16x16x32_bf16 v[124:127], v[60:63], v[202:205], v[124:127]
	v_mfma_f32_16x16x32_bf16 v[120:123], v[76:79], v[202:205], v[120:123]
	v_mfma_f32_16x16x32_bf16 v[108:111], v[60:63], v[212:215], v[108:111]
	v_mfma_f32_16x16x32_bf16 v[104:107], v[76:79], v[212:215], v[104:107]
	v_mfma_f32_16x16x32_bf16 v[92:95], v[60:63], v[220:223], v[92:95]
	v_mfma_f32_16x16x32_bf16 v[88:91], v[76:79], v[220:223], v[88:91]
	s_setprio 0
	s_setprio 1
	v_mfma_f32_16x16x32_bf16 v[132:135], v[144:147], v[184:187], 0
	v_mfma_f32_16x16x32_bf16 v[128:131], v[168:171], v[184:187], 0
	v_mfma_f32_16x16x32_bf16 v[116:119], v[144:147], v[196:199], 0
	v_mfma_f32_16x16x32_bf16 v[112:115], v[168:171], v[196:199], 0
	v_mfma_f32_16x16x32_bf16 v[100:103], v[144:147], v[208:211], 0
	v_mfma_f32_16x16x32_bf16 v[96:99], v[168:171], v[208:211], 0
	v_mfma_f32_16x16x32_bf16 v[84:87], v[144:147], v[216:219], 0
	v_mfma_f32_16x16x32_bf16 v[80:83], v[168:171], v[216:219], 0
	v_mfma_f32_16x16x32_bf16 v[132:135], v[148:151], v[190:193], v[132:135]
	v_mfma_f32_16x16x32_bf16 v[128:131], v[178:181], v[190:193], v[128:131]
	v_mfma_f32_16x16x32_bf16 v[116:119], v[148:151], v[202:205], v[116:119]
	v_mfma_f32_16x16x32_bf16 v[112:115], v[178:181], v[202:205], v[112:115]
	v_mfma_f32_16x16x32_bf16 v[100:103], v[148:151], v[212:215], v[100:103]
	v_mfma_f32_16x16x32_bf16 v[96:99], v[178:181], v[212:215], v[96:99]
	v_mfma_f32_16x16x32_bf16 v[84:87], v[148:151], v[220:223], v[84:87]
	v_mfma_f32_16x16x32_bf16 v[80:83], v[178:181], v[220:223], v[80:83]
	s_setprio 0
	s_barrier
	s_add_i32 s81, s73, s58
	v_lshl_add_u64 v[174:175], s[54:55], 0, v[154:155]
	s_mov_b32 m0, s81
	ds_read_b128 v[184:187], v201 offset:16384
	ds_read_b128 v[190:193], v201 offset:17408
	ds_read_b128 v[196:199], v201 offset:18432
	ds_read_b128 v[202:205], v201 offset:19456
	ds_read_b128 v[208:211], v201 offset:20480
	ds_read_b128 v[212:215], v201 offset:21504
	ds_read_b128 v[216:219], v201 offset:22528
	ds_read_b128 v[220:223], v201 offset:23552
	global_load_lds_dwordx4 v[174:175], off
	s_add_i32 m0, s81, 0x2000
	s_add_u32 s82, s54, 0x40000
	v_lshl_add_u64 v[224:225], s[54:55], 0, v[158:159]
	s_addc_u32 s83, s55, 0
	s_add_i32 s81, s74, s58
	global_load_lds_dwordx4 v[224:225], off
	v_lshl_add_u64 v[226:227], s[82:83], 0, v[154:155]
	s_mov_b32 m0, s81
	v_lshl_add_u64 v[228:229], s[56:57], 0, v[156:157]
	global_load_lds_dwordx4 v[226:227], off
	v_lshl_add_u64 v[226:227], s[82:83], 0, v[158:159]
	s_add_i32 m0, s81, 0x2000
	s_nop 0
	global_load_lds_dwordx4 v[226:227], off
	v_lshl_add_u64 v[226:227], s[56:57], 0, v[152:153]
	s_mov_b32 m0, s43
	s_nop 0
	global_load_lds_dwordx4 v[226:227], off
	s_mov_b32 m0, s59
	s_nop 0
	global_load_lds_dwordx4 v[228:229], off
	s_waitcnt vmcnt(8)
	s_waitcnt lgkmcnt(0)
	s_nop 0
	s_barrier
; #define PG8_STAGE(bufoff, gbase, voff) do { _Pragma("unroll") for (int _i = 0; _i < 2; ++_i) \
;         __builtin_amdgcn_global_load_lds((const unsigned*)((const char*)(gbase) + (voff)[_i]), (LAS unsigned*)(lds + (bufoff) + ldsw + _i * 8192), 16, 0, 0); } while (0)
; #define PG8_LDA(dst, b, h) do { _Pragma("unroll") for (int m = 0; m < 4; ++m) _Pragma("unroll") for (int k = 0; k < 2; ++k) dst[m][k] = *(const LAS bf16x8*)(lds + PG8_SA(b, h) + aoff + m * 2048 + k * 1024); } while (0)
; #define PG8_LDB(dst, b, h) do { _Pragma("unroll") for (int n = 0; n < 2; ++n) _Pragma("unroll") for (int k = 0; k < 2; ++k) dst[n][k] = *(const LAS bf16x8*)(lds + PG8_SB(b, h) + boff + n * 2048 + k * 1024); } while (0)
; #define PG8_MMA(ai, bj, At, Bt) do { __builtin_amdgcn_s_setprio(1); _Pragma("unroll") for (int m = 0; m < 4; ++m) _Pragma("unroll") for (int n = 0; n < 2; ++n) _Pragma("unroll") for (int k = 0; k < 2; ++k) \
;         acc[ai][bj][m][n] = __builtin_amdgcn_mfma_f32_16x16x32_bf16(Bt[n][k], At[m][k], acc[ai][bj][m][n], 0, 0, 0); __builtin_amdgcn_s_setprio(0); } while (0)
; #define PG8_WAIT_V(n) asm volatile("s_waitcnt vmcnt(" #n ")" ::: "memory")
; #define PG8_WAIT_L(n) asm volatile("s_waitcnt lgkmcnt(" #n ")" ::: "memory")
; #define PG8_BAR __builtin_amdgcn_s_barrier()
; #define PG8_SCHED __builtin_amdgcn_sched_barrier(0)
; template <class Epi>
; __device__ __forceinline__ void gemm_phase(LAS unsigned char* lds, const Gemm g, const StaticOrder& S, const Epi& E) {
;     ...
;             PG8_WAIT_V(8); PG8_WAIT_L(0); PG8_BAR; PG8_MMA(1, 0, At, B0); PG8_MMA(1, 1, At, B1); PG8_BAR; PG8_SCHED;
;             PG8_LDB(B0, 1, 0); PG8_LDB(B1, 1, 1); PG8_SCHED; PG8_LDA(At, 1, 0); PG8_STAGE(PG8_SA(0, 1), a2 + hstepA, voffA);
;             PG8_WAIT_V(8); PG8_WAIT_L(0); PG8_BAR; PG8_MMA(0, 0, At, B0); PG8_MMA(0, 1, At, B1); PG8_BAR; PG8_SCHED;
	s_setprio 1
	s_waitcnt lgkmcnt(0)
	v_mfma_f32_16x16x32_bf16 v[68:71], v[56:59], v[184:187], 0
	v_mfma_f32_16x16x32_bf16 v[64:67], v[72:75], v[184:187], 0
	v_mfma_f32_16x16x32_bf16 v[44:47], v[56:59], v[196:199], 0
	v_mfma_f32_16x16x32_bf16 v[40:43], v[72:75], v[196:199], 0
	v_mfma_f32_16x16x32_bf16 v[28:31], v[56:59], v[208:211], 0
	v_mfma_f32_16x16x32_bf16 v[24:27], v[72:75], v[208:211], 0
	v_mfma_f32_16x16x32_bf16 v[12:15], v[56:59], v[216:219], 0
	v_mfma_f32_16x16x32_bf16 v[8:11], v[72:75], v[216:219], 0
	v_mfma_f32_16x16x32_bf16 v[68:71], v[60:63], v[190:193], v[68:71]
	v_mfma_f32_16x16x32_bf16 v[64:67], v[76:79], v[190:193], v[64:67]
	v_mfma_f32_16x16x32_bf16 v[44:47], v[60:63], v[202:205], v[44:47]
	v_mfma_f32_16x16x32_bf16 v[40:43], v[76:79], v[202:205], v[40:43]
	v_mfma_f32_16x16x32_bf16 v[28:31], v[60:63], v[212:215], v[28:31]
	v_mfma_f32_16x16x32_bf16 v[24:27], v[76:79], v[212:215], v[24:27]
	v_mfma_f32_16x16x32_bf16 v[12:15], v[60:63], v[220:223], v[12:15]
	v_mfma_f32_16x16x32_bf16 v[8:11], v[76:79], v[220:223], v[8:11]
	s_setprio 0
	s_setprio 1
	v_mfma_f32_16x16x32_bf16 v[52:55], v[144:147], v[184:187], 0
	v_mfma_f32_16x16x32_bf16 v[48:51], v[168:171], v[184:187], 0
	v_mfma_f32_16x16x32_bf16 v[36:39], v[144:147], v[196:199], 0
	v_mfma_f32_16x16x32_bf16 v[32:35], v[168:171], v[196:199], 0
	v_mfma_f32_16x16x32_bf16 v[20:23], v[144:147], v[208:211], 0
	v_mfma_f32_16x16x32_bf16 v[16:19], v[168:171], v[208:211], 0
	v_mfma_f32_16x16x32_bf16 v[4:7], v[144:147], v[216:219], 0
	v_mfma_f32_16x16x32_bf16 v[0:3], v[168:171], v[216:219], 0
	v_mfma_f32_16x16x32_bf16 v[52:55], v[148:151], v[190:193], v[52:55]
	v_mfma_f32_16x16x32_bf16 v[48:51], v[178:181], v[190:193], v[48:51]
	v_mfma_f32_16x16x32_bf16 v[36:39], v[148:151], v[202:205], v[36:39]
	v_mfma_f32_16x16x32_bf16 v[32:35], v[178:181], v[202:205], v[32:35]
	v_mfma_f32_16x16x32_bf16 v[20:23], v[148:151], v[212:215], v[20:23]
	v_mfma_f32_16x16x32_bf16 v[16:19], v[178:181], v[212:215], v[16:19]
	v_mfma_f32_16x16x32_bf16 v[4:7], v[148:151], v[220:223], v[4:7]
	v_mfma_f32_16x16x32_bf16 v[0:3], v[178:181], v[220:223], v[0:3]
	s_setprio 0
	s_barrier
	s_add_i32 s81, 0, 0x18000
	s_add_i32 s82, 0, 0x1c000
	v_add_u32_e32 v76, s81, v183
	v_add_u32_e32 v172, s82, v183
	ds_read_b128 v[56:59], v76
	ds_read_b128 v[60:63], v76 offset:1024
	ds_read_b128 v[72:75], v76 offset:2048
	ds_read_b128 v[76:79], v76 offset:3072
	ds_read_b128 v[144:147], v172
	ds_read_b128 v[148:151], v172 offset:1024
	ds_read_b128 v[168:171], v172 offset:2048
	ds_read_b128 v[178:181], v172 offset:3072
	s_add_u32 s56, s56, 0x40000
	s_addc_u32 s57, s57, 0
	s_mov_b32 m0, s62
	v_lshl_add_u64 v[230:231], s[56:57], 0, v[152:153]
	ds_read_b128 v[184:187], v201 offset:32768
	ds_read_b128 v[190:193], v201 offset:33792
	ds_read_b128 v[196:199], v201 offset:34816
	ds_read_b128 v[202:205], v201 offset:35840
	ds_read_b128 v[208:211], v201 offset:36864
	ds_read_b128 v[212:215], v201 offset:37888
	ds_read_b128 v[216:219], v201 offset:38912
	ds_read_b128 v[220:223], v201 offset:39936
	global_load_lds_dwordx4 v[230:231], off
	v_lshl_add_u64 v[230:231], s[56:57], 0, v[156:157]
	s_mov_b32 m0, s63
	s_nop 0
	global_load_lds_dwordx4 v[230:231], off
	s_waitcnt vmcnt(8)
	s_waitcnt lgkmcnt(0)
	s_nop 0
	s_barrier
	s_setprio 1
	s_waitcnt lgkmcnt(0)
	v_mfma_f32_16x16x32_bf16 v[140:143], v[56:59], v[184:187], v[140:143]
	v_mfma_f32_16x16x32_bf16 v[136:139], v[72:75], v[184:187], v[136:139]
	v_mfma_f32_16x16x32_bf16 v[124:127], v[56:59], v[196:199], v[124:127]
	v_mfma_f32_16x16x32_bf16 v[120:123], v[72:75], v[196:199], v[120:123]
	v_mfma_f32_16x16x32_bf16 v[108:111], v[56:59], v[208:211], v[108:111]
	v_mfma_f32_16x16x32_bf16 v[104:107], v[72:75], v[208:211], v[104:107]
	v_mfma_f32_16x16x32_bf16 v[92:95], v[56:59], v[216:219], v[92:95]
	v_mfma_f32_16x16x32_bf16 v[88:91], v[72:75], v[216:219], v[88:91]
	v_mfma_f32_16x16x32_bf16 v[140:143], v[60:63], v[190:193], v[140:143]
	v_mfma_f32_16x16x32_bf16 v[136:139], v[76:79], v[190:193], v[136:139]
	v_mfma_f32_16x16x32_bf16 v[124:127], v[60:63], v[202:205], v[124:127]
	v_mfma_f32_16x16x32_bf16 v[120:123], v[76:79], v[202:205], v[120:123]
	v_mfma_f32_16x16x32_bf16 v[108:111], v[60:63], v[212:215], v[108:111]
	v_mfma_f32_16x16x32_bf16 v[104:107], v[76:79], v[212:215], v[104:107]
	v_mfma_f32_16x16x32_bf16 v[92:95], v[60:63], v[220:223], v[92:95]
	v_mfma_f32_16x16x32_bf16 v[88:91], v[76:79], v[220:223], v[88:91]
	s_setprio 0
	s_setprio 1
	v_mfma_f32_16x16x32_bf16 v[132:135], v[144:147], v[184:187], v[132:135]
	v_mfma_f32_16x16x32_bf16 v[128:131], v[168:171], v[184:187], v[128:131]
	v_mfma_f32_16x16x32_bf16 v[116:119], v[144:147], v[196:199], v[116:119]
	v_mfma_f32_16x16x32_bf16 v[112:115], v[168:171], v[196:199], v[112:115]
	v_mfma_f32_16x16x32_bf16 v[100:103], v[144:147], v[208:211], v[100:103]
	v_mfma_f32_16x16x32_bf16 v[96:99], v[168:171], v[208:211], v[96:99]
	v_mfma_f32_16x16x32_bf16 v[84:87], v[144:147], v[216:219], v[84:87]
	v_mfma_f32_16x16x32_bf16 v[80:83], v[168:171], v[216:219], v[80:83]
	v_mfma_f32_16x16x32_bf16 v[132:135], v[148:151], v[190:193], v[132:135]
	v_mfma_f32_16x16x32_bf16 v[128:131], v[178:181], v[190:193], v[128:131]
	v_mfma_f32_16x16x32_bf16 v[116:119], v[148:151], v[202:205], v[116:119]
	v_mfma_f32_16x16x32_bf16 v[112:115], v[178:181], v[202:205], v[112:115]
	v_mfma_f32_16x16x32_bf16 v[100:103], v[148:151], v[212:215], v[100:103]
	v_mfma_f32_16x16x32_bf16 v[96:99], v[178:181], v[212:215], v[96:99]
	v_mfma_f32_16x16x32_bf16 v[84:87], v[148:151], v[220:223], v[84:87]
	v_mfma_f32_16x16x32_bf16 v[80:83], v[178:181], v[220:223], v[80:83]
	s_setprio 0
	s_barrier
; #define PG8_STAGE(bufoff, gbase, voff) do { _Pragma("unroll") for (int _i = 0; _i < 2; ++_i) \
;         __builtin_amdgcn_global_load_lds((const unsigned*)((const char*)(gbase) + (voff)[_i]), (LAS unsigned*)(lds + (bufoff) + ldsw + _i * 8192), 16, 0, 0); } while (0)
; #define PG8_LDA(dst, b, h) do { _Pragma("unroll") for (int m = 0; m < 4; ++m) _Pragma("unroll") for (int k = 0; k < 2; ++k) dst[m][k] = *(const LAS bf16x8*)(lds + PG8_SA(b, h) + aoff + m * 2048 + k * 1024); } while (0)
; #define PG8_LDB(dst, b, h) do { _Pragma("unroll") for (int n = 0; n < 2; ++n) _Pragma("unroll") for (int k = 0; k < 2; ++k) dst[n][k] = *(const LAS bf16x8*)(lds + PG8_SB(b, h) + boff + n * 2048 + k * 1024); } while (0)
; #define PG8_MMA(ai, bj, At, Bt) do { __builtin_amdgcn_s_setprio(1); _Pragma("unroll") for (int m = 0; m < 4; ++m) _Pragma("unroll") for (int n = 0; n < 2; ++n) _Pragma("unroll") for (int k = 0; k < 2; ++k) \
;         acc[ai][bj][m][n] = __builtin_amdgcn_mfma_f32_16x16x32_bf16(Bt[n][k], At[m][k], acc[ai][bj][m][n], 0, 0, 0); __builtin_amdgcn_s_setprio(0); } while (0)
; #define PG8_WAIT_V(n) asm volatile("s_waitcnt vmcnt(" #n ")" ::: "memory")
; #define PG8_BAR __builtin_amdgcn_s_barrier()
; template <class Epi>
; __device__ __forceinline__ void gemm_phase(LAS unsigned char* lds, const Gemm g, const StaticOrder& S, const Epi& E) {
;     ...
;             PG8_LDB(B0, 0, 0); PG8_LDB(B1, 0, 1); PG8_SCHED; PG8_LDA(At, 0, 0); PG8_STAGE(PG8_SA(1, 1), a1 + hstepA, voffA);
;             PG8_WAIT_V(8); PG8_WAIT_L(0); PG8_BAR; PG8_MMA(0, 0, At, B0); PG8_MMA(0, 1, At, B1); PG8_BAR; PG8_SCHED;
;             PG8_LDA(At, 0, 1); PG8_STAGE(PG8_SB(0, 0), b2, voffB); PG8_STAGE(PG8_SB(0, 1), b2 + hstepB, voffB); PG8_STAGE(PG8_SA(0, 0), a2, voffA);
;             PG8_WAIT_V(8); PG8_WAIT_L(0); PG8_BAR; PG8_MMA(1, 0, At, B0); PG8_MMA(1, 1, At, B1); PG8_BAR; PG8_SCHED;
;             PG8_LDB(B0, 1, 0); PG8_LDB(B1, 1, 1); PG8_SCHED; PG8_LDA(At, 1, 0); PG8_STAGE(PG8_SA(0, 1), a2 + hstepA, voffA);
;             PG8_WAIT_V(8); PG8_WAIT_L(0); PG8_BAR; PG8_MMA(0, 0, At, B0); PG8_MMA(0, 1, At, B1); PG8_BAR; PG8_SCHED;
;             PG8_LDA(At, 1, 1); PG8_STAGE(PG8_SB(1, 0), b3, voffB); PG8_STAGE(PG8_SB(1, 1), b3 + hstepB, voffB); PG8_STAGE(PG8_SA(1, 0), a3, voffA);
;             PG8_WAIT_V(8); PG8_WAIT_L(0); PG8_BAR; PG8_MMA(1, 0, At, B0); PG8_MMA(1, 1, At, B1); PG8_BAR; PG8_SCHED;
	s_add_i32 s56, s81, s58
	v_lshl_add_u64 v[174:175], v[174:175], 0, s[12:13]
	s_mov_b32 m0, s56
	ds_read_b128 v[184:187], v201 offset:49152
	ds_read_b128 v[190:193], v201 offset:50176
	ds_read_b128 v[196:199], v201 offset:51200
	ds_read_b128 v[202:205], v201 offset:52224
	ds_read_b128 v[208:211], v201 offset:53248
	ds_read_b128 v[212:215], v201 offset:54272
	ds_read_b128 v[216:219], v201 offset:55296
	ds_read_b128 v[220:223], v201 offset:56320
	global_load_lds_dwordx4 v[174:175], off
	s_add_i32 m0, s56, 0x2000
	s_add_u32 s54, s54, 0x40080
	v_lshl_add_u64 v[174:175], v[224:225], 0, s[12:13]
	s_addc_u32 s55, s55, 0
	s_add_i32 s56, s82, s58
	global_load_lds_dwordx4 v[174:175], off
	v_lshl_add_u64 v[174:175], s[54:55], 0, v[154:155]
	s_mov_b32 m0, s56
	s_nop 0
	global_load_lds_dwordx4 v[174:175], off
	v_lshl_add_u64 v[174:175], s[54:55], 0, v[158:159]
	s_add_i32 m0, s56, 0x2000
	s_nop 0
	global_load_lds_dwordx4 v[174:175], off
	v_lshl_add_u64 v[174:175], v[226:227], 0, s[12:13]
	s_mov_b32 m0, s69
	s_nop 0
	global_load_lds_dwordx4 v[174:175], off
	v_lshl_add_u64 v[174:175], v[228:229], 0, s[12:13]
	s_mov_b32 m0, s70
	s_nop 0
	global_load_lds_dwordx4 v[174:175], off
	s_waitcnt vmcnt(8)
	s_waitcnt lgkmcnt(0)
	s_barrier
	s_setprio 1
	s_waitcnt lgkmcnt(0)
	v_mfma_f32_16x16x32_bf16 v[68:71], v[56:59], v[184:187], v[68:71]
	v_mfma_f32_16x16x32_bf16 v[64:67], v[72:75], v[184:187], v[64:67]
	v_mfma_f32_16x16x32_bf16 v[44:47], v[56:59], v[196:199], v[44:47]
	v_mfma_f32_16x16x32_bf16 v[40:43], v[72:75], v[196:199], v[40:43]
	v_mfma_f32_16x16x32_bf16 v[28:31], v[56:59], v[208:211], v[28:31]
	v_mfma_f32_16x16x32_bf16 v[24:27], v[72:75], v[208:211], v[24:27]
	v_mfma_f32_16x16x32_bf16 v[12:15], v[56:59], v[216:219], v[12:15]
	v_mfma_f32_16x16x32_bf16 v[8:11], v[72:75], v[216:219], v[8:11]
	v_mfma_f32_16x16x32_bf16 v[68:71], v[60:63], v[190:193], v[68:71]
	v_mfma_f32_16x16x32_bf16 v[64:67], v[76:79], v[190:193], v[64:67]
	v_mfma_f32_16x16x32_bf16 v[44:47], v[60:63], v[202:205], v[44:47]
	v_mfma_f32_16x16x32_bf16 v[40:43], v[76:79], v[202:205], v[40:43]
	v_mfma_f32_16x16x32_bf16 v[28:31], v[60:63], v[212:215], v[28:31]
	v_mfma_f32_16x16x32_bf16 v[24:27], v[76:79], v[212:215], v[24:27]
	v_mfma_f32_16x16x32_bf16 v[12:15], v[60:63], v[220:223], v[12:15]
	v_mfma_f32_16x16x32_bf16 v[8:11], v[76:79], v[220:223], v[8:11]
	s_setprio 0
	s_setprio 1
	v_mfma_f32_16x16x32_bf16 v[52:55], v[144:147], v[184:187], v[52:55]
	v_mfma_f32_16x16x32_bf16 v[48:51], v[168:171], v[184:187], v[48:51]
	v_mfma_f32_16x16x32_bf16 v[36:39], v[144:147], v[196:199], v[36:39]
	v_mfma_f32_16x16x32_bf16 v[32:35], v[168:171], v[196:199], v[32:35]
	v_mfma_f32_16x16x32_bf16 v[20:23], v[144:147], v[208:211], v[20:23]
	v_mfma_f32_16x16x32_bf16 v[16:19], v[168:171], v[208:211], v[16:19]
	v_mfma_f32_16x16x32_bf16 v[4:7], v[144:147], v[216:219], v[4:7]
	v_mfma_f32_16x16x32_bf16 v[0:3], v[168:171], v[216:219], v[0:3]
	v_mfma_f32_16x16x32_bf16 v[52:55], v[148:151], v[190:193], v[52:55]
	v_mfma_f32_16x16x32_bf16 v[48:51], v[178:181], v[190:193], v[48:51]
	v_mfma_f32_16x16x32_bf16 v[36:39], v[148:151], v[202:205], v[36:39]
	v_mfma_f32_16x16x32_bf16 v[32:35], v[178:181], v[202:205], v[32:35]
	v_mfma_f32_16x16x32_bf16 v[20:23], v[148:151], v[212:215], v[20:23]
	v_mfma_f32_16x16x32_bf16 v[16:19], v[178:181], v[212:215], v[16:19]
	v_mfma_f32_16x16x32_bf16 v[4:7], v[148:151], v[220:223], v[4:7]
	v_mfma_f32_16x16x32_bf16 v[0:3], v[178:181], v[220:223], v[0:3]
	s_setprio 0
	s_barrier
	s_add_i32 s80, s80, 2
	s_add_u32 s52, s52, 0x100
	s_addc_u32 s53, s53, 0
	s_add_u32 s78, s78, 0x100
	s_addc_u32 s79, s79, 0
	s_cmp_gt_u32 s80, 13
.LBB0_1233:
	ds_read_b128 v[56:59], v189
	ds_read_b128 v[60:63], v189 offset:1024
	ds_read_b128 v[72:75], v189 offset:2048
	ds_read_b128 v[76:79], v189 offset:3072
	ds_read_b128 v[144:147], v195
	ds_read_b128 v[148:151], v195 offset:1024
	ds_read_b128 v[168:171], v195 offset:2048
	ds_read_b128 v[178:181], v195 offset:3072
	s_add_u32 s54, s52, 0xfffc0080
	s_addc_u32 s55, s53, -1
	s_cmp_eq_u32 s80, 12
	s_cselect_b32 s57, s23, s55
	s_cselect_b32 s56, s76, s54
	s_cselect_b32 s55, s21, s79
	s_cselect_b32 s54, s77, s78
	v_lshl_add_u64 v[174:175], s[52:53], 0, v[160:161]
	s_add_i32 m0, s43, 0xc000
	ds_read_b128 v[184:187], v201
	ds_read_b128 v[190:193], v201 offset:1024
	ds_read_b128 v[196:199], v201 offset:2048
	ds_read_b128 v[202:205], v201 offset:3072
	ds_read_b128 v[208:211], v201 offset:4096
	ds_read_b128 v[212:215], v201 offset:5120
	ds_read_b128 v[216:219], v201 offset:6144
	ds_read_b128 v[220:223], v201 offset:7168
	global_load_lds_dwordx4 v[174:175], off
	v_lshl_add_u64 v[174:175], s[52:53], 0, v[162:163]
	s_add_i32 m0, s43, 0xe000
	s_nop 0
	global_load_lds_dwordx4 v[174:175], off
	s_waitcnt vmcnt(8)
	s_waitcnt lgkmcnt(0)
	s_barrier
; #define PG8_STAGE(bufoff, gbase, voff) do { _Pragma("unroll") for (int _i = 0; _i < 2; ++_i) \
;         __builtin_amdgcn_global_load_lds((const unsigned*)((const char*)(gbase) + (voff)[_i]), (LAS unsigned*)(lds + (bufoff) + ldsw + _i * 8192), 16, 0, 0); } while (0)
; #define PG8_LDA(dst, b, h) do { _Pragma("unroll") for (int m = 0; m < 4; ++m) _Pragma("unroll") for (int k = 0; k < 2; ++k) dst[m][k] = *(const LAS bf16x8*)(lds + PG8_SA(b, h) + aoff + m * 2048 + k * 1024); } while (0)
; #define PG8_MMA(ai, bj, At, Bt) do { __builtin_amdgcn_s_setprio(1); _Pragma("unroll") for (int m = 0; m < 4; ++m) _Pragma("unroll") for (int n = 0; n < 2; ++n) _Pragma("unroll") for (int k = 0; k < 2; ++k) \
;         acc[ai][bj][m][n] = __builtin_amdgcn_mfma_f32_16x16x32_bf16(Bt[n][k], At[m][k], acc[ai][bj][m][n], 0, 0, 0); __builtin_amdgcn_s_setprio(0); } while (0)
; #define PG8_WAIT_V(n) asm volatile("s_waitcnt vmcnt(" #n ")" ::: "memory")
; #define PG8_WAIT_L(n) asm volatile("s_waitcnt lgkmcnt(" #n ")" ::: "memory")
; #define PG8_BAR __builtin_amdgcn_s_barrier()
; #define PG8_SCHED __builtin_amdgcn_sched_barrier(0)
; template <class Epi>
; __device__ __forceinline__ void gemm_phase(LAS unsigned char* lds, const Gemm g, const StaticOrder& S, const Epi& E) {
;     ...
;             PG8_WAIT_V(8); PG8_WAIT_L(0); PG8_BAR; PG8_MMA(0, 0, At, B0); PG8_MMA(0, 1, At, B1); PG8_BAR; PG8_SCHED;
;             PG8_LDA(At, 0, 1); PG8_STAGE(PG8_SB(0, 0), b2, voffB); PG8_STAGE(PG8_SB(0, 1), b2 + hstepB, voffB); PG8_STAGE(PG8_SA(0, 0), a2, voffA);
;             PG8_WAIT_V(8); PG8_WAIT_L(0); PG8_BAR; PG8_MMA(1, 0, At, B0); PG8_MMA(1, 1, At, B1); PG8_BAR; PG8_SCHED;
	s_setprio 1
	s_waitcnt lgkmcnt(0)
	v_mfma_f32_16x16x32_bf16 v[140:143], v[56:59], v[184:187], v[140:143]
	v_mfma_f32_16x16x32_bf16 v[136:139], v[72:75], v[184:187], v[136:139]
	v_mfma_f32_16x16x32_bf16 v[124:127], v[56:59], v[196:199], v[124:127]
	v_mfma_f32_16x16x32_bf16 v[120:123], v[72:75], v[196:199], v[120:123]
	v_mfma_f32_16x16x32_bf16 v[108:111], v[56:59], v[208:211], v[108:111]
	v_mfma_f32_16x16x32_bf16 v[104:107], v[72:75], v[208:211], v[104:107]
	v_mfma_f32_16x16x32_bf16 v[92:95], v[56:59], v[216:219], v[92:95]
	v_mfma_f32_16x16x32_bf16 v[88:91], v[72:75], v[216:219], v[88:91]
	v_mfma_f32_16x16x32_bf16 v[140:143], v[60:63], v[190:193], v[140:143]
	v_mfma_f32_16x16x32_bf16 v[136:139], v[76:79], v[190:193], v[136:139]
	v_mfma_f32_16x16x32_bf16 v[124:127], v[60:63], v[202:205], v[124:127]
	v_mfma_f32_16x16x32_bf16 v[120:123], v[76:79], v[202:205], v[120:123]
	v_mfma_f32_16x16x32_bf16 v[108:111], v[60:63], v[212:215], v[108:111]
	v_mfma_f32_16x16x32_bf16 v[104:107], v[76:79], v[212:215], v[104:107]
	v_mfma_f32_16x16x32_bf16 v[92:95], v[60:63], v[220:223], v[92:95]
	v_mfma_f32_16x16x32_bf16 v[88:91], v[76:79], v[220:223], v[88:91]
	s_setprio 0
	s_setprio 1
	v_mfma_f32_16x16x32_bf16 v[132:135], v[144:147], v[184:187], v[132:135]
	v_mfma_f32_16x16x32_bf16 v[128:131], v[168:171], v[184:187], v[128:131]
	v_mfma_f32_16x16x32_bf16 v[116:119], v[144:147], v[196:199], v[116:119]
	v_mfma_f32_16x16x32_bf16 v[112:115], v[168:171], v[196:199], v[112:115]
	v_mfma_f32_16x16x32_bf16 v[100:103], v[144:147], v[208:211], v[100:103]
	v_mfma_f32_16x16x32_bf16 v[96:99], v[168:171], v[208:211], v[96:99]
	v_mfma_f32_16x16x32_bf16 v[84:87], v[144:147], v[216:219], v[84:87]
	v_mfma_f32_16x16x32_bf16 v[80:83], v[168:171], v[216:219], v[80:83]
	v_mfma_f32_16x16x32_bf16 v[132:135], v[148:151], v[190:193], v[132:135]
	v_mfma_f32_16x16x32_bf16 v[128:131], v[178:181], v[190:193], v[128:131]
	v_mfma_f32_16x16x32_bf16 v[116:119], v[148:151], v[202:205], v[116:119]
	v_mfma_f32_16x16x32_bf16 v[112:115], v[178:181], v[202:205], v[112:115]
	v_mfma_f32_16x16x32_bf16 v[100:103], v[148:151], v[212:215], v[100:103]
	v_mfma_f32_16x16x32_bf16 v[96:99], v[178:181], v[212:215], v[96:99]
	v_mfma_f32_16x16x32_bf16 v[84:87], v[148:151], v[220:223], v[84:87]
	v_mfma_f32_16x16x32_bf16 v[80:83], v[178:181], v[220:223], v[80:83]
	s_setprio 0
	s_barrier
	s_add_i32 s81, s73, s58
	v_lshl_add_u64 v[174:175], s[54:55], 0, v[154:155]
	s_mov_b32 m0, s81
	ds_read_b128 v[184:187], v201 offset:16384
	ds_read_b128 v[190:193], v201 offset:17408
	ds_read_b128 v[196:199], v201 offset:18432
	ds_read_b128 v[202:205], v201 offset:19456
	ds_read_b128 v[208:211], v201 offset:20480
	ds_read_b128 v[212:215], v201 offset:21504
	ds_read_b128 v[216:219], v201 offset:22528
	ds_read_b128 v[220:223], v201 offset:23552
	global_load_lds_dwordx4 v[174:175], off
	s_add_i32 m0, s81, 0x2000
	s_add_u32 s82, s54, 0x40000
	v_lshl_add_u64 v[224:225], s[54:55], 0, v[158:159]
	s_addc_u32 s83, s55, 0
	s_add_i32 s81, s74, s58
	global_load_lds_dwordx4 v[224:225], off
	v_lshl_add_u64 v[226:227], s[82:83], 0, v[154:155]
	s_mov_b32 m0, s81
	v_lshl_add_u64 v[228:229], s[56:57], 0, v[156:157]
	global_load_lds_dwordx4 v[226:227], off
	v_lshl_add_u64 v[226:227], s[82:83], 0, v[158:159]
	s_add_i32 m0, s81, 0x2000
	s_nop 0
	global_load_lds_dwordx4 v[226:227], off
	v_lshl_add_u64 v[226:227], s[56:57], 0, v[152:153]
	s_mov_b32 m0, s43
	s_nop 0
	global_load_lds_dwordx4 v[226:227], off
	s_mov_b32 m0, s59
	s_nop 0
	global_load_lds_dwordx4 v[228:229], off
	s_waitcnt vmcnt(8)
	s_waitcnt lgkmcnt(0)
	s_nop 0
	s_barrier
	s_setprio 1
	s_waitcnt lgkmcnt(0)
	v_mfma_f32_16x16x32_bf16 v[68:71], v[56:59], v[184:187], v[68:71]
	v_mfma_f32_16x16x32_bf16 v[64:67], v[72:75], v[184:187], v[64:67]
	v_mfma_f32_16x16x32_bf16 v[44:47], v[56:59], v[196:199], v[44:47]
	v_mfma_f32_16x16x32_bf16 v[40:43], v[72:75], v[196:199], v[40:43]
	v_mfma_f32_16x16x32_bf16 v[28:31], v[56:59], v[208:211], v[28:31]
	v_mfma_f32_16x16x32_bf16 v[24:27], v[72:75], v[208:211], v[24:27]
	v_mfma_f32_16x16x32_bf16 v[12:15], v[56:59], v[216:219], v[12:15]
	v_mfma_f32_16x16x32_bf16 v[8:11], v[72:75], v[216:219], v[8:11]
	v_mfma_f32_16x16x32_bf16 v[68:71], v[60:63], v[190:193], v[68:71]
	v_mfma_f32_16x16x32_bf16 v[64:67], v[76:79], v[190:193], v[64:67]
	v_mfma_f32_16x16x32_bf16 v[44:47], v[60:63], v[202:205], v[44:47]
	v_mfma_f32_16x16x32_bf16 v[40:43], v[76:79], v[202:205], v[40:43]
	v_mfma_f32_16x16x32_bf16 v[28:31], v[60:63], v[212:215], v[28:31]
	v_mfma_f32_16x16x32_bf16 v[24:27], v[76:79], v[212:215], v[24:27]
	v_mfma_f32_16x16x32_bf16 v[12:15], v[60:63], v[220:223], v[12:15]
	v_mfma_f32_16x16x32_bf16 v[8:11], v[76:79], v[220:223], v[8:11]
	s_setprio 0
	s_setprio 1
	v_mfma_f32_16x16x32_bf16 v[52:55], v[144:147], v[184:187], v[52:55]
	v_mfma_f32_16x16x32_bf16 v[48:51], v[168:171], v[184:187], v[48:51]
	v_mfma_f32_16x16x32_bf16 v[36:39], v[144:147], v[196:199], v[36:39]
	v_mfma_f32_16x16x32_bf16 v[32:35], v[168:171], v[196:199], v[32:35]
	v_mfma_f32_16x16x32_bf16 v[20:23], v[144:147], v[208:211], v[20:23]
	v_mfma_f32_16x16x32_bf16 v[16:19], v[168:171], v[208:211], v[16:19]
	v_mfma_f32_16x16x32_bf16 v[4:7], v[144:147], v[216:219], v[4:7]
	v_mfma_f32_16x16x32_bf16 v[0:3], v[168:171], v[216:219], v[0:3]
	v_mfma_f32_16x16x32_bf16 v[52:55], v[148:151], v[190:193], v[52:55]
	v_mfma_f32_16x16x32_bf16 v[48:51], v[178:181], v[190:193], v[48:51]
	v_mfma_f32_16x16x32_bf16 v[36:39], v[148:151], v[202:205], v[36:39]
	v_mfma_f32_16x16x32_bf16 v[32:35], v[178:181], v[202:205], v[32:35]
	v_mfma_f32_16x16x32_bf16 v[20:23], v[148:151], v[212:215], v[20:23]
	v_mfma_f32_16x16x32_bf16 v[16:19], v[178:181], v[212:215], v[16:19]
	v_mfma_f32_16x16x32_bf16 v[4:7], v[148:151], v[220:223], v[4:7]
	v_mfma_f32_16x16x32_bf16 v[0:3], v[178:181], v[220:223], v[0:3]
	s_setprio 0
	s_barrier
; #define PG8_STAGE(bufoff, gbase, voff) do { _Pragma("unroll") for (int _i = 0; _i < 2; ++_i) \
;         __builtin_amdgcn_global_load_lds((const unsigned*)((const char*)(gbase) + (voff)[_i]), (LAS unsigned*)(lds + (bufoff) + ldsw + _i * 8192), 16, 0, 0); } while (0)
; #define PG8_LDA(dst, b, h) do { _Pragma("unroll") for (int m = 0; m < 4; ++m) _Pragma("unroll") for (int k = 0; k < 2; ++k) dst[m][k] = *(const LAS bf16x8*)(lds + PG8_SA(b, h) + aoff + m * 2048 + k * 1024); } while (0)
; #define PG8_LDB(dst, b, h) do { _Pragma("unroll") for (int n = 0; n < 2; ++n) _Pragma("unroll") for (int k = 0; k < 2; ++k) dst[n][k] = *(const LAS bf16x8*)(lds + PG8_SB(b, h) + boff + n * 2048 + k * 1024); } while (0)
; #define PG8_MMA(ai, bj, At, Bt) do { __builtin_amdgcn_s_setprio(1); _Pragma("unroll") for (int m = 0; m < 4; ++m) _Pragma("unroll") for (int n = 0; n < 2; ++n) _Pragma("unroll") for (int k = 0; k < 2; ++k) \
;         acc[ai][bj][m][n] = __builtin_amdgcn_mfma_f32_16x16x32_bf16(Bt[n][k], At[m][k], acc[ai][bj][m][n], 0, 0, 0); __builtin_amdgcn_s_setprio(0); } while (0)
; #define PG8_WAIT_V(n) asm volatile("s_waitcnt vmcnt(" #n ")" ::: "memory")
; #define PG8_WAIT_L(n) asm volatile("s_waitcnt lgkmcnt(" #n ")" ::: "memory")
; #define PG8_BAR __builtin_amdgcn_s_barrier()
; #define PG8_SCHED __builtin_amdgcn_sched_barrier(0)
; template <class Epi>
; __device__ __forceinline__ void gemm_phase(LAS unsigned char* lds, const Gemm g, const StaticOrder& S, const Epi& E) {
;     ...
;             PG8_LDB(B0, 1, 0); PG8_LDB(B1, 1, 1); PG8_SCHED; PG8_LDA(At, 1, 0); PG8_STAGE(PG8_SA(0, 1), a2 + hstepA, voffA);
;             PG8_WAIT_V(8); PG8_WAIT_L(0); PG8_BAR; PG8_MMA(0, 0, At, B0); PG8_MMA(0, 1, At, B1); PG8_BAR; PG8_SCHED;
	s_add_i32 s81, 0, 0x18000
	s_add_i32 s82, 0, 0x1c000
	v_add_u32_e32 v76, s81, v183
	v_add_u32_e32 v172, s82, v183
	ds_read_b128 v[56:59], v76
	ds_read_b128 v[60:63], v76 offset:1024
	ds_read_b128 v[72:75], v76 offset:2048
	ds_read_b128 v[76:79], v76 offset:3072
	ds_read_b128 v[144:147], v172
	ds_read_b128 v[148:151], v172 offset:1024
	ds_read_b128 v[168:171], v172 offset:2048
	ds_read_b128 v[178:181], v172 offset:3072
	s_add_u32 s56, s56, 0x40000
	s_addc_u32 s57, s57, 0
	s_mov_b32 m0, s62
	v_lshl_add_u64 v[230:231], s[56:57], 0, v[152:153]
	ds_read_b128 v[184:187], v201 offset:32768
	ds_read_b128 v[190:193], v201 offset:33792
	ds_read_b128 v[196:199], v201 offset:34816
	ds_read_b128 v[202:205], v201 offset:35840
	ds_read_b128 v[208:211], v201 offset:36864
	ds_read_b128 v[212:215], v201 offset:37888
	ds_read_b128 v[216:219], v201 offset:38912
	ds_read_b128 v[220:223], v201 offset:39936
	global_load_lds_dwordx4 v[230:231], off
	v_lshl_add_u64 v[230:231], s[56:57], 0, v[156:157]
	s_mov_b32 m0, s63
	s_nop 0
	global_load_lds_dwordx4 v[230:231], off
	s_waitcnt vmcnt(8)
	s_waitcnt lgkmcnt(0)
	s_nop 0
	s_barrier
	s_setprio 1
	s_waitcnt lgkmcnt(0)
	v_mfma_f32_16x16x32_bf16 v[140:143], v[56:59], v[184:187], v[140:143]
	v_mfma_f32_16x16x32_bf16 v[136:139], v[72:75], v[184:187], v[136:139]
	v_mfma_f32_16x16x32_bf16 v[124:127], v[56:59], v[196:199], v[124:127]
	v_mfma_f32_16x16x32_bf16 v[120:123], v[72:75], v[196:199], v[120:123]
	v_mfma_f32_16x16x32_bf16 v[108:111], v[56:59], v[208:211], v[108:111]
	v_mfma_f32_16x16x32_bf16 v[104:107], v[72:75], v[208:211], v[104:107]
	v_mfma_f32_16x16x32_bf16 v[92:95], v[56:59], v[216:219], v[92:95]
	v_mfma_f32_16x16x32_bf16 v[88:91], v[72:75], v[216:219], v[88:91]
	v_mfma_f32_16x16x32_bf16 v[140:143], v[60:63], v[190:193], v[140:143]
	v_mfma_f32_16x16x32_bf16 v[136:139], v[76:79], v[190:193], v[136:139]
	v_mfma_f32_16x16x32_bf16 v[124:127], v[60:63], v[202:205], v[124:127]
	v_mfma_f32_16x16x32_bf16 v[120:123], v[76:79], v[202:205], v[120:123]
	v_mfma_f32_16x16x32_bf16 v[108:111], v[60:63], v[212:215], v[108:111]
	v_mfma_f32_16x16x32_bf16 v[104:107], v[76:79], v[212:215], v[104:107]
	v_mfma_f32_16x16x32_bf16 v[92:95], v[60:63], v[220:223], v[92:95]
	v_mfma_f32_16x16x32_bf16 v[88:91], v[76:79], v[220:223], v[88:91]
	s_setprio 0
	s_setprio 1
	v_mfma_f32_16x16x32_bf16 v[132:135], v[144:147], v[184:187], v[132:135]
	v_mfma_f32_16x16x32_bf16 v[128:131], v[168:171], v[184:187], v[128:131]
	v_mfma_f32_16x16x32_bf16 v[116:119], v[144:147], v[196:199], v[116:119]
	v_mfma_f32_16x16x32_bf16 v[112:115], v[168:171], v[196:199], v[112:115]
	v_mfma_f32_16x16x32_bf16 v[100:103], v[144:147], v[208:211], v[100:103]
	v_mfma_f32_16x16x32_bf16 v[96:99], v[168:171], v[208:211], v[96:99]
	v_mfma_f32_16x16x32_bf16 v[84:87], v[144:147], v[216:219], v[84:87]
	v_mfma_f32_16x16x32_bf16 v[80:83], v[168:171], v[216:219], v[80:83]
	v_mfma_f32_16x16x32_bf16 v[132:135], v[148:151], v[190:193], v[132:135]
	v_mfma_f32_16x16x32_bf16 v[128:131], v[178:181], v[190:193], v[128:131]
	v_mfma_f32_16x16x32_bf16 v[116:119], v[148:151], v[202:205], v[116:119]
	v_mfma_f32_16x16x32_bf16 v[112:115], v[178:181], v[202:205], v[112:115]
	v_mfma_f32_16x16x32_bf16 v[100:103], v[148:151], v[212:215], v[100:103]
	v_mfma_f32_16x16x32_bf16 v[96:99], v[178:181], v[212:215], v[96:99]
	v_mfma_f32_16x16x32_bf16 v[84:87], v[148:151], v[220:223], v[84:87]
	v_mfma_f32_16x16x32_bf16 v[80:83], v[178:181], v[220:223], v[80:83]
	s_setprio 0
	s_barrier
; #define PG8_STAGE(bufoff, gbase, voff) do { _Pragma("unroll") for (int _i = 0; _i < 2; ++_i) \
;         __builtin_amdgcn_global_load_lds((const unsigned*)((const char*)(gbase) + (voff)[_i]), (LAS unsigned*)(lds + (bufoff) + ldsw + _i * 8192), 16, 0, 0); } while (0)
; #define PG8_LDA(dst, b, h) do { _Pragma("unroll") for (int m = 0; m < 4; ++m) _Pragma("unroll") for (int k = 0; k < 2; ++k) dst[m][k] = *(const LAS bf16x8*)(lds + PG8_SA(b, h) + aoff + m * 2048 + k * 1024); } while (0)
; #define PG8_MMA(ai, bj, At, Bt) do { __builtin_amdgcn_s_setprio(1); _Pragma("unroll") for (int m = 0; m < 4; ++m) _Pragma("unroll") for (int n = 0; n < 2; ++n) _Pragma("unroll") for (int k = 0; k < 2; ++k) \
;         acc[ai][bj][m][n] = __builtin_amdgcn_mfma_f32_16x16x32_bf16(Bt[n][k], At[m][k], acc[ai][bj][m][n], 0, 0, 0); __builtin_amdgcn_s_setprio(0); } while (0)
; #define PG8_WAIT_V(n) asm volatile("s_waitcnt vmcnt(" #n ")" ::: "memory")
; #define PG8_WAIT_L(n) asm volatile("s_waitcnt lgkmcnt(" #n ")" ::: "memory")
; #define PG8_BAR __builtin_amdgcn_s_barrier()
; #define PG8_SCHED __builtin_amdgcn_sched_barrier(0)
; template <class Epi>
; __device__ __forceinline__ void gemm_phase(LAS unsigned char* lds, const Gemm g, const StaticOrder& S, const Epi& E) {
;     ...
;             PG8_LDA(At, 1, 1); PG8_STAGE(PG8_SB(1, 0), b3, voffB); PG8_STAGE(PG8_SB(1, 1), b3 + hstepB, voffB); PG8_STAGE(PG8_SA(1, 0), a3, voffA);
;             PG8_WAIT_V(8); PG8_WAIT_L(0); PG8_BAR; PG8_MMA(1, 0, At, B0); PG8_MMA(1, 1, At, B1); PG8_BAR; PG8_SCHED;
;         }
;         if (wr == 0) PG8_BAR;
	s_add_i32 s56, s81, s58
	v_lshl_add_u64 v[174:175], v[174:175], 0, s[12:13]
	s_mov_b32 m0, s56
	ds_read_b128 v[184:187], v201 offset:49152
	ds_read_b128 v[190:193], v201 offset:50176
	ds_read_b128 v[196:199], v201 offset:51200
	ds_read_b128 v[202:205], v201 offset:52224
	ds_read_b128 v[208:211], v201 offset:53248
	ds_read_b128 v[212:215], v201 offset:54272
	ds_read_b128 v[216:219], v201 offset:55296
	ds_read_b128 v[220:223], v201 offset:56320
	global_load_lds_dwordx4 v[174:175], off
	s_add_i32 m0, s56, 0x2000
	s_add_u32 s54, s54, 0x40080
	v_lshl_add_u64 v[174:175], v[224:225], 0, s[12:13]
	s_addc_u32 s55, s55, 0
	s_add_i32 s56, s82, s58
	global_load_lds_dwordx4 v[174:175], off
	v_lshl_add_u64 v[174:175], s[54:55], 0, v[154:155]
	s_mov_b32 m0, s56
	s_nop 0
	global_load_lds_dwordx4 v[174:175], off
	v_lshl_add_u64 v[174:175], s[54:55], 0, v[158:159]
	s_add_i32 m0, s56, 0x2000
	s_nop 0
	global_load_lds_dwordx4 v[174:175], off
	v_lshl_add_u64 v[174:175], v[226:227], 0, s[12:13]
	s_mov_b32 m0, s69
	s_nop 0
	global_load_lds_dwordx4 v[174:175], off
	v_lshl_add_u64 v[174:175], v[228:229], 0, s[12:13]
	s_mov_b32 m0, s70
	s_nop 0
	global_load_lds_dwordx4 v[174:175], off
	s_waitcnt vmcnt(8)
	s_waitcnt lgkmcnt(0)
	s_barrier
	s_setprio 1
	s_waitcnt lgkmcnt(0)
	v_mfma_f32_16x16x32_bf16 v[68:71], v[56:59], v[184:187], v[68:71]
	v_mfma_f32_16x16x32_bf16 v[64:67], v[72:75], v[184:187], v[64:67]
	v_mfma_f32_16x16x32_bf16 v[44:47], v[56:59], v[196:199], v[44:47]
	v_mfma_f32_16x16x32_bf16 v[40:43], v[72:75], v[196:199], v[40:43]
	v_mfma_f32_16x16x32_bf16 v[28:31], v[56:59], v[208:211], v[28:31]
	v_mfma_f32_16x16x32_bf16 v[24:27], v[72:75], v[208:211], v[24:27]
	v_mfma_f32_16x16x32_bf16 v[12:15], v[56:59], v[216:219], v[12:15]
	v_mfma_f32_16x16x32_bf16 v[8:11], v[72:75], v[216:219], v[8:11]
	v_mfma_f32_16x16x32_bf16 v[68:71], v[60:63], v[190:193], v[68:71]
	v_mfma_f32_16x16x32_bf16 v[64:67], v[76:79], v[190:193], v[64:67]
	v_mfma_f32_16x16x32_bf16 v[44:47], v[60:63], v[202:205], v[44:47]
	v_mfma_f32_16x16x32_bf16 v[40:43], v[76:79], v[202:205], v[40:43]
	v_mfma_f32_16x16x32_bf16 v[28:31], v[60:63], v[212:215], v[28:31]
	v_mfma_f32_16x16x32_bf16 v[24:27], v[76:79], v[212:215], v[24:27]
	v_mfma_f32_16x16x32_bf16 v[12:15], v[60:63], v[220:223], v[12:15]
	v_mfma_f32_16x16x32_bf16 v[8:11], v[76:79], v[220:223], v[8:11]
	s_setprio 0
	s_setprio 1
	v_mfma_f32_16x16x32_bf16 v[52:55], v[144:147], v[184:187], v[52:55]
	v_mfma_f32_16x16x32_bf16 v[48:51], v[168:171], v[184:187], v[48:51]
	v_mfma_f32_16x16x32_bf16 v[36:39], v[144:147], v[196:199], v[36:39]
	v_mfma_f32_16x16x32_bf16 v[32:35], v[168:171], v[196:199], v[32:35]
	v_mfma_f32_16x16x32_bf16 v[20:23], v[144:147], v[208:211], v[20:23]
	v_mfma_f32_16x16x32_bf16 v[16:19], v[168:171], v[208:211], v[16:19]
	v_mfma_f32_16x16x32_bf16 v[4:7], v[144:147], v[216:219], v[4:7]
	v_mfma_f32_16x16x32_bf16 v[0:3], v[168:171], v[216:219], v[0:3]
	v_mfma_f32_16x16x32_bf16 v[52:55], v[148:151], v[190:193], v[52:55]
	v_mfma_f32_16x16x32_bf16 v[48:51], v[178:181], v[190:193], v[48:51]
	v_mfma_f32_16x16x32_bf16 v[36:39], v[148:151], v[202:205], v[36:39]
	v_mfma_f32_16x16x32_bf16 v[32:35], v[178:181], v[202:205], v[32:35]
	v_mfma_f32_16x16x32_bf16 v[20:23], v[148:151], v[212:215], v[20:23]
	v_mfma_f32_16x16x32_bf16 v[16:19], v[178:181], v[212:215], v[16:19]
	v_mfma_f32_16x16x32_bf16 v[4:7], v[148:151], v[220:223], v[4:7]
	v_mfma_f32_16x16x32_bf16 v[0:3], v[178:181], v[220:223], v[0:3]
	s_setprio 0
	s_barrier
	s_add_i32 s80, s80, 2
	s_add_u32 s52, s52, 0x100
	s_addc_u32 s53, s53, 0
	s_add_u32 s78, s78, 0x100
	s_addc_u32 s79, s79, 0
	s_cmp_gt_u32 s80, 13
	s_cbranch_scc0 .LBB0_1233
	s_and_b64 vcc, exec, s[14:15]
	s_cbranch_vccz .LBB0_1236
	s_barrier

; #define PG8_STAGE(bufoff, gbase, voff) do { _Pragma("unroll") for (int _i = 0; _i < 2; ++_i) \
;         __builtin_amdgcn_global_load_lds((const unsigned*)((const char*)(gbase) + (voff)[_i]), (LAS unsigned*)(lds + (bufoff) + ldsw + _i * 8192), 16, 0, 0); } while (0)
; #define PG8_LDA(dst, b, h) do { _Pragma("unroll") for (int m = 0; m < 4; ++m) _Pragma("unroll") for (int k = 0; k < 2; ++k) dst[m][k] = *(const LAS bf16x8*)(lds + PG8_SA(b, h) + aoff + m * 2048 + k * 1024); } while (0)
; #define PG8_LDB(dst, b, h) do { _Pragma("unroll") for (int n = 0; n < 2; ++n) _Pragma("unroll") for (int k = 0; k < 2; ++k) dst[n][k] = *(const LAS bf16x8*)(lds + PG8_SB(b, h) + boff + n * 2048 + k * 1024); } while (0)
; #define PG8_MMA(ai, bj, At, Bt) do { __builtin_amdgcn_s_setprio(1); _Pragma("unroll") for (int m = 0; m < 4; ++m) _Pragma("unroll") for (int n = 0; n < 2; ++n) _Pragma("unroll") for (int k = 0; k < 2; ++k) \
;         acc[ai][bj][m][n] = __builtin_amdgcn_mfma_f32_16x16x32_bf16(Bt[n][k], At[m][k], acc[ai][bj][m][n], 0, 0, 0); __builtin_amdgcn_s_setprio(0); } while (0)
; #define PG8_BAR __builtin_amdgcn_s_barrier()
; template <class Epi>
; __device__ __forceinline__ void gemm_phase(LAS unsigned char* lds, const Gemm g, const StaticOrder& S, const Epi& E) {
;     ...
;         const bool has_next = S.next(ui + 1, nxt);
;         const char* nA = has_next ? (const char*)g.A + (size_t)nxt.pm * tstepA : cA; const char* nB = has_next ? (const char*)g.Bt + (size_t)nxt.pn * tstepB : cB;
; #pragma nounroll
;         for (int t = 0; t < nt; t += 2) {
;             const bool last = (t == nt - 2);
;             const char* a1 = cA + (size_t)(t + 1) * kstep;
;             const char* a2 = last ? nA : cA + (size_t)(t + 2) * kstep; const char* b2 = last ? nB : cB + (size_t)(t + 2) * kstep;
;             const char* a3 = a2 + kstep; const char* b3 = b2 + kstep;
;             PG8_LDB(B0, 0, 0); PG8_LDB(B1, 0, 1); PG8_SCHED; PG8_LDA(At, 0, 0); PG8_STAGE(PG8_SA(1, 1), a1 + hstepA, voffA);
;             PG8_WAIT_V(8); PG8_WAIT_L(0); PG8_BAR; PG8_MMA(0, 0, At, B0); PG8_MMA(0, 1, At, B1); PG8_BAR; PG8_SCHED;
;             PG8_LDA(At, 0, 1); PG8_STAGE(PG8_SB(0, 0), b2, voffB); PG8_STAGE(PG8_SB(0, 1), b2 + hstepB, voffB); PG8_STAGE(PG8_SA(0, 0), a2, voffA);
;             PG8_WAIT_V(8); PG8_WAIT_L(0); PG8_BAR; PG8_MMA(1, 0, At, B0); PG8_MMA(1, 1, At, B1); PG8_BAR; PG8_SCHED;
.LBB0_1313:
	s_ashr_i32 s19, s18, 31
	s_lshl_b64 s[20:21], s[18:19], 21
	s_add_u32 s20, s26, s20
	s_addc_u32 s21, s27, s21
	s_and_b64 s[22:23], s[4:5], exec
	s_cselect_b32 s1, s21, s39
	s_cselect_b32 s19, s20, s38
	s_ashr_i32 s17, s16, 31
	s_lshl_b64 s[22:23], s[16:17], 20
	s_add_u32 s22, s3, s22
	s_addc_u32 s23, s33, s23
	s_and_b64 s[52:53], s[4:5], exec
	s_cselect_b32 s17, s23, s43
	s_cselect_b32 s70, s22, s42
	s_add_u32 s38, s38, 0x100080
	s_addc_u32 s39, s39, 0
	s_add_u32 s71, s42, 0x100
	s_addc_u32 s72, s43, 0
	s_mov_b32 s73, -2
	s_waitcnt lgkmcnt(0)
	ds_read_b128 v[128:131], v182
	ds_read_b128 v[132:135], v182 offset:1024
	ds_read_b128 v[136:139], v182 offset:2048
	ds_read_b128 v[140:143], v182 offset:3072
	ds_read_b128 v[160:163], v183
	ds_read_b128 v[164:167], v183 offset:1024
	ds_read_b128 v[168:171], v183 offset:2048
	ds_read_b128 v[172:175], v183 offset:3072
	s_add_u32 s42, s38, 0xfff00080
	s_addc_u32 s43, s39, -1
	s_cmp_eq_u32 s73, 28
	s_cselect_b32 s53, s1, s43
	s_cselect_b32 s52, s19, s42
	s_cselect_b32 s43, s17, s72
	s_cselect_b32 s42, s70, s71
	v_lshl_add_u64 v[178:179], s[38:39], 0, v[152:153]
	s_add_i32 m0, s35, 0xc000
	ds_read_b128 v[186:189], v184
	ds_read_b128 v[190:193], v184 offset:1024
	ds_read_b128 v[194:197], v184 offset:2048
	ds_read_b128 v[198:201], v184 offset:3072
	ds_read_b128 v[202:205], v184 offset:4096
	ds_read_b128 v[206:209], v184 offset:5120
	ds_read_b128 v[210:213], v184 offset:6144
	ds_read_b128 v[214:217], v184 offset:7168
	global_load_lds_dwordx4 v[178:179], off
	v_lshl_add_u64 v[178:179], s[38:39], 0, v[154:155]
	s_add_i32 m0, s35, 0xe000
	s_nop 0
	global_load_lds_dwordx4 v[178:179], off
	s_waitcnt vmcnt(8)
	s_waitcnt lgkmcnt(0)
	s_barrier
	s_setprio 1
	s_waitcnt lgkmcnt(0)
	v_mfma_f32_16x16x32_bf16 v[124:127], v[128:131], v[186:189], 0
	v_mfma_f32_16x16x32_bf16 v[120:123], v[136:139], v[186:189], 0
	v_mfma_f32_16x16x32_bf16 v[108:111], v[128:131], v[194:197], 0
	v_mfma_f32_16x16x32_bf16 v[104:107], v[136:139], v[194:197], 0
	v_mfma_f32_16x16x32_bf16 v[92:95], v[128:131], v[202:205], 0
	v_mfma_f32_16x16x32_bf16 v[88:91], v[136:139], v[202:205], 0
	v_mfma_f32_16x16x32_bf16 v[76:79], v[128:131], v[210:213], 0
	v_mfma_f32_16x16x32_bf16 v[72:75], v[136:139], v[210:213], 0
	v_mfma_f32_16x16x32_bf16 v[124:127], v[132:135], v[190:193], v[124:127]
	v_mfma_f32_16x16x32_bf16 v[120:123], v[140:143], v[190:193], v[120:123]
	v_mfma_f32_16x16x32_bf16 v[108:111], v[132:135], v[198:201], v[108:111]
	v_mfma_f32_16x16x32_bf16 v[104:107], v[140:143], v[198:201], v[104:107]
	v_mfma_f32_16x16x32_bf16 v[92:95], v[132:135], v[206:209], v[92:95]
	v_mfma_f32_16x16x32_bf16 v[88:91], v[140:143], v[206:209], v[88:91]
	v_mfma_f32_16x16x32_bf16 v[76:79], v[132:135], v[214:217], v[76:79]
	v_mfma_f32_16x16x32_bf16 v[72:75], v[140:143], v[214:217], v[72:75]
	s_setprio 0
	s_setprio 1
	v_mfma_f32_16x16x32_bf16 v[116:119], v[160:163], v[186:189], 0
	v_mfma_f32_16x16x32_bf16 v[112:115], v[168:171], v[186:189], 0
	v_mfma_f32_16x16x32_bf16 v[100:103], v[160:163], v[194:197], 0
	v_mfma_f32_16x16x32_bf16 v[96:99], v[168:171], v[194:197], 0
	v_mfma_f32_16x16x32_bf16 v[84:87], v[160:163], v[202:205], 0
	v_mfma_f32_16x16x32_bf16 v[80:83], v[168:171], v[202:205], 0
	v_mfma_f32_16x16x32_bf16 v[68:71], v[160:163], v[210:213], 0
	v_mfma_f32_16x16x32_bf16 v[64:67], v[168:171], v[210:213], 0
	v_mfma_f32_16x16x32_bf16 v[116:119], v[164:167], v[190:193], v[116:119]
	v_mfma_f32_16x16x32_bf16 v[112:115], v[172:175], v[190:193], v[112:115]
	v_mfma_f32_16x16x32_bf16 v[100:103], v[164:167], v[198:201], v[100:103]
	v_mfma_f32_16x16x32_bf16 v[96:99], v[172:175], v[198:201], v[96:99]
	v_mfma_f32_16x16x32_bf16 v[84:87], v[164:167], v[206:209], v[84:87]
	v_mfma_f32_16x16x32_bf16 v[80:83], v[172:175], v[206:209], v[80:83]
	v_mfma_f32_16x16x32_bf16 v[68:71], v[164:167], v[214:217], v[68:71]
	v_mfma_f32_16x16x32_bf16 v[64:67], v[172:175], v[214:217], v[64:67]
	s_setprio 0
	s_barrier
	s_add_i32 s74, s68, s54
	v_lshl_add_u64 v[178:179], s[42:43], 0, v[146:147]
	s_mov_b32 m0, s74
	ds_read_b128 v[186:189], v184 offset:16384
	ds_read_b128 v[190:193], v184 offset:17408
	ds_read_b128 v[194:197], v184 offset:18432
	ds_read_b128 v[198:201], v184 offset:19456
	ds_read_b128 v[202:205], v184 offset:20480
	ds_read_b128 v[206:209], v184 offset:21504
	ds_read_b128 v[210:213], v184 offset:22528
	ds_read_b128 v[214:217], v184 offset:23552
	global_load_lds_dwordx4 v[178:179], off
	s_add_i32 m0, s74, 0x2000
	s_add_u32 s74, s42, 0x80000
	v_lshl_add_u64 v[218:219], s[42:43], 0, v[150:151]
	s_addc_u32 s75, s43, 0
	s_add_i32 s76, s69, s54
	global_load_lds_dwordx4 v[218:219], off
	v_lshl_add_u64 v[220:221], s[74:75], 0, v[146:147]
	s_mov_b32 m0, s76
	v_lshl_add_u64 v[222:223], s[52:53], 0, v[148:149]
	global_load_lds_dwordx4 v[220:221], off
	v_lshl_add_u64 v[220:221], s[74:75], 0, v[150:151]
	s_add_i32 m0, s76, 0x2000
	s_nop 0
	global_load_lds_dwordx4 v[220:221], off
	v_lshl_add_u64 v[220:221], s[52:53], 0, v[144:145]
	s_mov_b32 m0, s35
	s_nop 0
	global_load_lds_dwordx4 v[220:221], off
	s_mov_b32 m0, s55
	s_nop 0
	global_load_lds_dwordx4 v[222:223], off
	s_waitcnt vmcnt(8)
	s_waitcnt lgkmcnt(0)
	s_nop 0
	s_barrier
; #define PG8_STAGE(bufoff, gbase, voff) do { _Pragma("unroll") for (int _i = 0; _i < 2; ++_i) \
;         __builtin_amdgcn_global_load_lds((const unsigned*)((const char*)(gbase) + (voff)[_i]), (LAS unsigned*)(lds + (bufoff) + ldsw + _i * 8192), 16, 0, 0); } while (0)
; #define PG8_LDA(dst, b, h) do { _Pragma("unroll") for (int m = 0; m < 4; ++m) _Pragma("unroll") for (int k = 0; k < 2; ++k) dst[m][k] = *(const LAS bf16x8*)(lds + PG8_SA(b, h) + aoff + m * 2048 + k * 1024); } while (0)
; #define PG8_LDB(dst, b, h) do { _Pragma("unroll") for (int n = 0; n < 2; ++n) _Pragma("unroll") for (int k = 0; k < 2; ++k) dst[n][k] = *(const LAS bf16x8*)(lds + PG8_SB(b, h) + boff + n * 2048 + k * 1024); } while (0)
; #define PG8_MMA(ai, bj, At, Bt) do { __builtin_amdgcn_s_setprio(1); _Pragma("unroll") for (int m = 0; m < 4; ++m) _Pragma("unroll") for (int n = 0; n < 2; ++n) _Pragma("unroll") for (int k = 0; k < 2; ++k) \
;         acc[ai][bj][m][n] = __builtin_amdgcn_mfma_f32_16x16x32_bf16(Bt[n][k], At[m][k], acc[ai][bj][m][n], 0, 0, 0); __builtin_amdgcn_s_setprio(0); } while (0)
; #define PG8_WAIT_V(n) asm volatile("s_waitcnt vmcnt(" #n ")" ::: "memory")
; #define PG8_WAIT_L(n) asm volatile("s_waitcnt lgkmcnt(" #n ")" ::: "memory")
; #define PG8_BAR __builtin_amdgcn_s_barrier()
; #define PG8_SCHED __builtin_amdgcn_sched_barrier(0)
; template <class Epi>
; __device__ __forceinline__ void gemm_phase(LAS unsigned char* lds, const Gemm g, const StaticOrder& S, const Epi& E) {
;     ...
;             PG8_WAIT_V(8); PG8_WAIT_L(0); PG8_BAR; PG8_MMA(1, 0, At, B0); PG8_MMA(1, 1, At, B1); PG8_BAR; PG8_SCHED;
;             PG8_LDB(B0, 1, 0); PG8_LDB(B1, 1, 1); PG8_SCHED; PG8_LDA(At, 1, 0); PG8_STAGE(PG8_SA(0, 1), a2 + hstepA, voffA);
;             PG8_WAIT_V(8); PG8_WAIT_L(0); PG8_BAR; PG8_MMA(0, 0, At, B0); PG8_MMA(0, 1, At, B1); PG8_BAR; PG8_SCHED;
	s_setprio 1
	s_waitcnt lgkmcnt(0)
	v_mfma_f32_16x16x32_bf16 v[60:63], v[128:131], v[186:189], 0
	v_mfma_f32_16x16x32_bf16 v[56:59], v[136:139], v[186:189], 0
	v_mfma_f32_16x16x32_bf16 v[44:47], v[128:131], v[194:197], 0
	v_mfma_f32_16x16x32_bf16 v[40:43], v[136:139], v[194:197], 0
	v_mfma_f32_16x16x32_bf16 v[28:31], v[128:131], v[202:205], 0
	v_mfma_f32_16x16x32_bf16 v[24:27], v[136:139], v[202:205], 0
	v_mfma_f32_16x16x32_bf16 v[12:15], v[128:131], v[210:213], 0
	v_mfma_f32_16x16x32_bf16 v[8:11], v[136:139], v[210:213], 0
	v_mfma_f32_16x16x32_bf16 v[60:63], v[132:135], v[190:193], v[60:63]
	v_mfma_f32_16x16x32_bf16 v[56:59], v[140:143], v[190:193], v[56:59]
	v_mfma_f32_16x16x32_bf16 v[44:47], v[132:135], v[198:201], v[44:47]
	v_mfma_f32_16x16x32_bf16 v[40:43], v[140:143], v[198:201], v[40:43]
	v_mfma_f32_16x16x32_bf16 v[28:31], v[132:135], v[206:209], v[28:31]
	v_mfma_f32_16x16x32_bf16 v[24:27], v[140:143], v[206:209], v[24:27]
	v_mfma_f32_16x16x32_bf16 v[12:15], v[132:135], v[214:217], v[12:15]
	v_mfma_f32_16x16x32_bf16 v[8:11], v[140:143], v[214:217], v[8:11]
	s_setprio 0
	s_setprio 1
	v_mfma_f32_16x16x32_bf16 v[52:55], v[160:163], v[186:189], 0
	v_mfma_f32_16x16x32_bf16 v[48:51], v[168:171], v[186:189], 0
	v_mfma_f32_16x16x32_bf16 v[36:39], v[160:163], v[194:197], 0
	v_mfma_f32_16x16x32_bf16 v[32:35], v[168:171], v[194:197], 0
	v_mfma_f32_16x16x32_bf16 v[20:23], v[160:163], v[202:205], 0
	v_mfma_f32_16x16x32_bf16 v[16:19], v[168:171], v[202:205], 0
	v_mfma_f32_16x16x32_bf16 v[4:7], v[160:163], v[210:213], 0
	v_mfma_f32_16x16x32_bf16 v[0:3], v[168:171], v[210:213], 0
	v_mfma_f32_16x16x32_bf16 v[52:55], v[164:167], v[190:193], v[52:55]
	v_mfma_f32_16x16x32_bf16 v[48:51], v[172:175], v[190:193], v[48:51]
	v_mfma_f32_16x16x32_bf16 v[36:39], v[164:167], v[198:201], v[36:39]
	v_mfma_f32_16x16x32_bf16 v[32:35], v[172:175], v[198:201], v[32:35]
	v_mfma_f32_16x16x32_bf16 v[20:23], v[164:167], v[206:209], v[20:23]
	v_mfma_f32_16x16x32_bf16 v[16:19], v[172:175], v[206:209], v[16:19]
	v_mfma_f32_16x16x32_bf16 v[4:7], v[164:167], v[214:217], v[4:7]
	v_mfma_f32_16x16x32_bf16 v[0:3], v[172:175], v[214:217], v[0:3]
	s_setprio 0
	s_barrier
	s_add_i32 s74, 0, 0x18000
	s_add_i32 s75, 0, 0x1c000
	v_add_u32_e32 v140, s74, v181
	v_add_u32_e32 v172, s75, v181
	ds_read_b128 v[128:131], v140
	ds_read_b128 v[132:135], v140 offset:1024
	ds_read_b128 v[136:139], v140 offset:2048
	ds_read_b128 v[140:143], v140 offset:3072
	ds_read_b128 v[160:163], v172
	ds_read_b128 v[164:167], v172 offset:1024
	ds_read_b128 v[168:171], v172 offset:2048
	ds_read_b128 v[172:175], v172 offset:3072
	s_add_u32 s52, s52, 0x100000
	s_addc_u32 s53, s53, 0
	s_mov_b32 m0, s56
	v_lshl_add_u64 v[224:225], s[52:53], 0, v[144:145]
	ds_read_b128 v[186:189], v184 offset:32768
	ds_read_b128 v[190:193], v184 offset:33792
	ds_read_b128 v[194:197], v184 offset:34816
	ds_read_b128 v[198:201], v184 offset:35840
	ds_read_b128 v[202:205], v184 offset:36864
	ds_read_b128 v[206:209], v184 offset:37888
	ds_read_b128 v[210:213], v184 offset:38912
	ds_read_b128 v[214:217], v184 offset:39936
	global_load_lds_dwordx4 v[224:225], off
	v_lshl_add_u64 v[224:225], s[52:53], 0, v[148:149]
	s_mov_b32 m0, s57
	s_nop 0
	global_load_lds_dwordx4 v[224:225], off
	s_waitcnt vmcnt(8)
	s_waitcnt lgkmcnt(0)
	s_nop 0
	s_barrier
	s_setprio 1
	s_waitcnt lgkmcnt(0)
	v_mfma_f32_16x16x32_bf16 v[124:127], v[128:131], v[186:189], v[124:127]
	v_mfma_f32_16x16x32_bf16 v[120:123], v[136:139], v[186:189], v[120:123]
	v_mfma_f32_16x16x32_bf16 v[108:111], v[128:131], v[194:197], v[108:111]
	v_mfma_f32_16x16x32_bf16 v[104:107], v[136:139], v[194:197], v[104:107]
	v_mfma_f32_16x16x32_bf16 v[92:95], v[128:131], v[202:205], v[92:95]
	v_mfma_f32_16x16x32_bf16 v[88:91], v[136:139], v[202:205], v[88:91]
	v_mfma_f32_16x16x32_bf16 v[76:79], v[128:131], v[210:213], v[76:79]
	v_mfma_f32_16x16x32_bf16 v[72:75], v[136:139], v[210:213], v[72:75]
	v_mfma_f32_16x16x32_bf16 v[124:127], v[132:135], v[190:193], v[124:127]
	v_mfma_f32_16x16x32_bf16 v[120:123], v[140:143], v[190:193], v[120:123]
	v_mfma_f32_16x16x32_bf16 v[108:111], v[132:135], v[198:201], v[108:111]
	v_mfma_f32_16x16x32_bf16 v[104:107], v[140:143], v[198:201], v[104:107]
	v_mfma_f32_16x16x32_bf16 v[92:95], v[132:135], v[206:209], v[92:95]
	v_mfma_f32_16x16x32_bf16 v[88:91], v[140:143], v[206:209], v[88:91]
	v_mfma_f32_16x16x32_bf16 v[76:79], v[132:135], v[214:217], v[76:79]
	v_mfma_f32_16x16x32_bf16 v[72:75], v[140:143], v[214:217], v[72:75]
	s_setprio 0
	s_setprio 1
	v_mfma_f32_16x16x32_bf16 v[116:119], v[160:163], v[186:189], v[116:119]
	v_mfma_f32_16x16x32_bf16 v[112:115], v[168:171], v[186:189], v[112:115]
	v_mfma_f32_16x16x32_bf16 v[100:103], v[160:163], v[194:197], v[100:103]
	v_mfma_f32_16x16x32_bf16 v[96:99], v[168:171], v[194:197], v[96:99]
	v_mfma_f32_16x16x32_bf16 v[84:87], v[160:163], v[202:205], v[84:87]
	v_mfma_f32_16x16x32_bf16 v[80:83], v[168:171], v[202:205], v[80:83]
	v_mfma_f32_16x16x32_bf16 v[68:71], v[160:163], v[210:213], v[68:71]
	v_mfma_f32_16x16x32_bf16 v[64:67], v[168:171], v[210:213], v[64:67]
	v_mfma_f32_16x16x32_bf16 v[116:119], v[164:167], v[190:193], v[116:119]
	v_mfma_f32_16x16x32_bf16 v[112:115], v[172:175], v[190:193], v[112:115]
	v_mfma_f32_16x16x32_bf16 v[100:103], v[164:167], v[198:201], v[100:103]
	v_mfma_f32_16x16x32_bf16 v[96:99], v[172:175], v[198:201], v[96:99]
	v_mfma_f32_16x16x32_bf16 v[84:87], v[164:167], v[206:209], v[84:87]
	v_mfma_f32_16x16x32_bf16 v[80:83], v[172:175], v[206:209], v[80:83]
	v_mfma_f32_16x16x32_bf16 v[68:71], v[164:167], v[214:217], v[68:71]
	v_mfma_f32_16x16x32_bf16 v[64:67], v[172:175], v[214:217], v[64:67]
	s_setprio 0
	s_barrier
; #define PG8_STAGE(bufoff, gbase, voff) do { _Pragma("unroll") for (int _i = 0; _i < 2; ++_i) \
;         __builtin_amdgcn_global_load_lds((const unsigned*)((const char*)(gbase) + (voff)[_i]), (LAS unsigned*)(lds + (bufoff) + ldsw + _i * 8192), 16, 0, 0); } while (0)
; #define PG8_LDA(dst, b, h) do { _Pragma("unroll") for (int m = 0; m < 4; ++m) _Pragma("unroll") for (int k = 0; k < 2; ++k) dst[m][k] = *(const LAS bf16x8*)(lds + PG8_SA(b, h) + aoff + m * 2048 + k * 1024); } while (0)
; #define PG8_LDB(dst, b, h) do { _Pragma("unroll") for (int n = 0; n < 2; ++n) _Pragma("unroll") for (int k = 0; k < 2; ++k) dst[n][k] = *(const LAS bf16x8*)(lds + PG8_SB(b, h) + boff + n * 2048 + k * 1024); } while (0)
; #define PG8_MMA(ai, bj, At, Bt) do { __builtin_amdgcn_s_setprio(1); _Pragma("unroll") for (int m = 0; m < 4; ++m) _Pragma("unroll") for (int n = 0; n < 2; ++n) _Pragma("unroll") for (int k = 0; k < 2; ++k) \
;         acc[ai][bj][m][n] = __builtin_amdgcn_mfma_f32_16x16x32_bf16(Bt[n][k], At[m][k], acc[ai][bj][m][n], 0, 0, 0); __builtin_amdgcn_s_setprio(0); } while (0)
; #define PG8_WAIT_V(n) asm volatile("s_waitcnt vmcnt(" #n ")" ::: "memory")
; #define PG8_BAR __builtin_amdgcn_s_barrier()
; template <class Epi>
; __device__ __forceinline__ void gemm_phase(LAS unsigned char* lds, const Gemm g, const StaticOrder& S, const Epi& E) {
;     ...
;             PG8_LDB(B0, 0, 0); PG8_LDB(B1, 0, 1); PG8_SCHED; PG8_LDA(At, 0, 0); PG8_STAGE(PG8_SA(1, 1), a1 + hstepA, voffA);
;             PG8_WAIT_V(8); PG8_WAIT_L(0); PG8_BAR; PG8_MMA(0, 0, At, B0); PG8_MMA(0, 1, At, B1); PG8_BAR; PG8_SCHED;
;             PG8_LDA(At, 0, 1); PG8_STAGE(PG8_SB(0, 0), b2, voffB); PG8_STAGE(PG8_SB(0, 1), b2 + hstepB, voffB); PG8_STAGE(PG8_SA(0, 0), a2, voffA);
;             PG8_WAIT_V(8); PG8_WAIT_L(0); PG8_BAR; PG8_MMA(1, 0, At, B0); PG8_MMA(1, 1, At, B1); PG8_BAR; PG8_SCHED;
;             PG8_LDB(B0, 1, 0); PG8_LDB(B1, 1, 1); PG8_SCHED; PG8_LDA(At, 1, 0); PG8_STAGE(PG8_SA(0, 1), a2 + hstepA, voffA);
;             PG8_WAIT_V(8); PG8_WAIT_L(0); PG8_BAR; PG8_MMA(0, 0, At, B0); PG8_MMA(0, 1, At, B1); PG8_BAR; PG8_SCHED;
;             PG8_LDA(At, 1, 1); PG8_STAGE(PG8_SB(1, 0), b3, voffB); PG8_STAGE(PG8_SB(1, 1), b3 + hstepB, voffB); PG8_STAGE(PG8_SA(1, 0), a3, voffA);
;             PG8_WAIT_V(8); PG8_WAIT_L(0); PG8_BAR; PG8_MMA(1, 0, At, B0); PG8_MMA(1, 1, At, B1); PG8_BAR; PG8_SCHED;
	s_add_i32 s52, s74, s54
	v_lshl_add_u64 v[178:179], v[178:179], 0, s[12:13]
	s_mov_b32 m0, s52
	ds_read_b128 v[186:189], v184 offset:49152
	ds_read_b128 v[190:193], v184 offset:50176
	ds_read_b128 v[194:197], v184 offset:51200
	ds_read_b128 v[198:201], v184 offset:52224
	ds_read_b128 v[202:205], v184 offset:53248
	ds_read_b128 v[206:209], v184 offset:54272
	ds_read_b128 v[210:213], v184 offset:55296
	ds_read_b128 v[214:217], v184 offset:56320
	global_load_lds_dwordx4 v[178:179], off
	s_add_i32 m0, s52, 0x2000
	s_add_u32 s42, s42, 0x80080
	v_lshl_add_u64 v[178:179], v[218:219], 0, s[12:13]
	s_addc_u32 s43, s43, 0
	s_add_i32 s52, s75, s54
	global_load_lds_dwordx4 v[178:179], off
	v_lshl_add_u64 v[178:179], s[42:43], 0, v[146:147]
	s_mov_b32 m0, s52
	s_nop 0
	global_load_lds_dwordx4 v[178:179], off
	v_lshl_add_u64 v[178:179], s[42:43], 0, v[150:151]
	s_add_i32 m0, s52, 0x2000
	s_nop 0
	global_load_lds_dwordx4 v[178:179], off
	v_lshl_add_u64 v[178:179], v[220:221], 0, s[12:13]
	s_mov_b32 m0, s61
	s_nop 0
	global_load_lds_dwordx4 v[178:179], off
	v_lshl_add_u64 v[178:179], v[222:223], 0, s[12:13]
	s_mov_b32 m0, s62
	s_nop 0
	global_load_lds_dwordx4 v[178:179], off
	s_waitcnt vmcnt(8)
	s_waitcnt lgkmcnt(0)
	s_barrier
	s_setprio 1
	s_waitcnt lgkmcnt(0)
	v_mfma_f32_16x16x32_bf16 v[60:63], v[128:131], v[186:189], v[60:63]
	v_mfma_f32_16x16x32_bf16 v[56:59], v[136:139], v[186:189], v[56:59]
	v_mfma_f32_16x16x32_bf16 v[44:47], v[128:131], v[194:197], v[44:47]
	v_mfma_f32_16x16x32_bf16 v[40:43], v[136:139], v[194:197], v[40:43]
	v_mfma_f32_16x16x32_bf16 v[28:31], v[128:131], v[202:205], v[28:31]
	v_mfma_f32_16x16x32_bf16 v[24:27], v[136:139], v[202:205], v[24:27]
	v_mfma_f32_16x16x32_bf16 v[12:15], v[128:131], v[210:213], v[12:15]
	v_mfma_f32_16x16x32_bf16 v[8:11], v[136:139], v[210:213], v[8:11]
	v_mfma_f32_16x16x32_bf16 v[60:63], v[132:135], v[190:193], v[60:63]
	v_mfma_f32_16x16x32_bf16 v[56:59], v[140:143], v[190:193], v[56:59]
	v_mfma_f32_16x16x32_bf16 v[44:47], v[132:135], v[198:201], v[44:47]
	v_mfma_f32_16x16x32_bf16 v[40:43], v[140:143], v[198:201], v[40:43]
	v_mfma_f32_16x16x32_bf16 v[28:31], v[132:135], v[206:209], v[28:31]
	v_mfma_f32_16x16x32_bf16 v[24:27], v[140:143], v[206:209], v[24:27]
	v_mfma_f32_16x16x32_bf16 v[12:15], v[132:135], v[214:217], v[12:15]
	v_mfma_f32_16x16x32_bf16 v[8:11], v[140:143], v[214:217], v[8:11]
	s_setprio 0
	s_setprio 1
	v_mfma_f32_16x16x32_bf16 v[52:55], v[160:163], v[186:189], v[52:55]
	v_mfma_f32_16x16x32_bf16 v[48:51], v[168:171], v[186:189], v[48:51]
	v_mfma_f32_16x16x32_bf16 v[36:39], v[160:163], v[194:197], v[36:39]
	v_mfma_f32_16x16x32_bf16 v[32:35], v[168:171], v[194:197], v[32:35]
	v_mfma_f32_16x16x32_bf16 v[20:23], v[160:163], v[202:205], v[20:23]
	v_mfma_f32_16x16x32_bf16 v[16:19], v[168:171], v[202:205], v[16:19]
	v_mfma_f32_16x16x32_bf16 v[4:7], v[160:163], v[210:213], v[4:7]
	v_mfma_f32_16x16x32_bf16 v[0:3], v[168:171], v[210:213], v[0:3]
	v_mfma_f32_16x16x32_bf16 v[52:55], v[164:167], v[190:193], v[52:55]
	v_mfma_f32_16x16x32_bf16 v[48:51], v[172:175], v[190:193], v[48:51]
	v_mfma_f32_16x16x32_bf16 v[36:39], v[164:167], v[198:201], v[36:39]
	v_mfma_f32_16x16x32_bf16 v[32:35], v[172:175], v[198:201], v[32:35]
	v_mfma_f32_16x16x32_bf16 v[20:23], v[164:167], v[206:209], v[20:23]
	v_mfma_f32_16x16x32_bf16 v[16:19], v[172:175], v[206:209], v[16:19]
	v_mfma_f32_16x16x32_bf16 v[4:7], v[164:167], v[214:217], v[4:7]
	v_mfma_f32_16x16x32_bf16 v[0:3], v[172:175], v[214:217], v[0:3]
	s_setprio 0
	s_barrier
	s_add_i32 s73, s73, 2
	s_add_u32 s38, s38, 0x100
	s_addc_u32 s39, s39, 0
	s_add_u32 s71, s71, 0x100
	s_addc_u32 s72, s72, 0
	s_cmp_gt_u32 s73, 29
.LBB0_1314:
	ds_read_b128 v[128:131], v182
	ds_read_b128 v[132:135], v182 offset:1024
	ds_read_b128 v[136:139], v182 offset:2048
	ds_read_b128 v[140:143], v182 offset:3072
	ds_read_b128 v[160:163], v183
	ds_read_b128 v[164:167], v183 offset:1024
	ds_read_b128 v[168:171], v183 offset:2048
	ds_read_b128 v[172:175], v183 offset:3072
	s_add_u32 s42, s38, 0xfff00080
	s_addc_u32 s43, s39, -1
	s_cmp_eq_u32 s73, 28
	s_cselect_b32 s53, s1, s43
	s_cselect_b32 s52, s19, s42
	s_cselect_b32 s43, s17, s72
	s_cselect_b32 s42, s70, s71
	v_lshl_add_u64 v[178:179], s[38:39], 0, v[152:153]
	s_add_i32 m0, s35, 0xc000
	ds_read_b128 v[186:189], v184
	ds_read_b128 v[190:193], v184 offset:1024
	ds_read_b128 v[194:197], v184 offset:2048
	ds_read_b128 v[198:201], v184 offset:3072
	ds_read_b128 v[202:205], v184 offset:4096
	ds_read_b128 v[206:209], v184 offset:5120
	ds_read_b128 v[210:213], v184 offset:6144
	ds_read_b128 v[214:217], v184 offset:7168
	global_load_lds_dwordx4 v[178:179], off
	v_lshl_add_u64 v[178:179], s[38:39], 0, v[154:155]
	s_add_i32 m0, s35, 0xe000
	s_nop 0
	global_load_lds_dwordx4 v[178:179], off
	s_waitcnt vmcnt(8)
	s_waitcnt lgkmcnt(0)
	s_barrier
; #define PG8_STAGE(bufoff, gbase, voff) do { _Pragma("unroll") for (int _i = 0; _i < 2; ++_i) \
;         __builtin_amdgcn_global_load_lds((const unsigned*)((const char*)(gbase) + (voff)[_i]), (LAS unsigned*)(lds + (bufoff) + ldsw + _i * 8192), 16, 0, 0); } while (0)
; #define PG8_LDA(dst, b, h) do { _Pragma("unroll") for (int m = 0; m < 4; ++m) _Pragma("unroll") for (int k = 0; k < 2; ++k) dst[m][k] = *(const LAS bf16x8*)(lds + PG8_SA(b, h) + aoff + m * 2048 + k * 1024); } while (0)
; #define PG8_MMA(ai, bj, At, Bt) do { __builtin_amdgcn_s_setprio(1); _Pragma("unroll") for (int m = 0; m < 4; ++m) _Pragma("unroll") for (int n = 0; n < 2; ++n) _Pragma("unroll") for (int k = 0; k < 2; ++k) \
;         acc[ai][bj][m][n] = __builtin_amdgcn_mfma_f32_16x16x32_bf16(Bt[n][k], At[m][k], acc[ai][bj][m][n], 0, 0, 0); __builtin_amdgcn_s_setprio(0); } while (0)
; #define PG8_WAIT_V(n) asm volatile("s_waitcnt vmcnt(" #n ")" ::: "memory")
; #define PG8_WAIT_L(n) asm volatile("s_waitcnt lgkmcnt(" #n ")" ::: "memory")
; #define PG8_BAR __builtin_amdgcn_s_barrier()
; #define PG8_SCHED __builtin_amdgcn_sched_barrier(0)
; template <class Epi>
; __device__ __forceinline__ void gemm_phase(LAS unsigned char* lds, const Gemm g, const StaticOrder& S, const Epi& E) {
;     ...
;             PG8_WAIT_V(8); PG8_WAIT_L(0); PG8_BAR; PG8_MMA(0, 0, At, B0); PG8_MMA(0, 1, At, B1); PG8_BAR; PG8_SCHED;
;             PG8_LDA(At, 0, 1); PG8_STAGE(PG8_SB(0, 0), b2, voffB); PG8_STAGE(PG8_SB(0, 1), b2 + hstepB, voffB); PG8_STAGE(PG8_SA(0, 0), a2, voffA);
;             PG8_WAIT_V(8); PG8_WAIT_L(0); PG8_BAR; PG8_MMA(1, 0, At, B0); PG8_MMA(1, 1, At, B1); PG8_BAR; PG8_SCHED;
	s_setprio 1
	s_waitcnt lgkmcnt(0)
	v_mfma_f32_16x16x32_bf16 v[124:127], v[128:131], v[186:189], v[124:127]
	v_mfma_f32_16x16x32_bf16 v[120:123], v[136:139], v[186:189], v[120:123]
	v_mfma_f32_16x16x32_bf16 v[108:111], v[128:131], v[194:197], v[108:111]
	v_mfma_f32_16x16x32_bf16 v[104:107], v[136:139], v[194:197], v[104:107]
	v_mfma_f32_16x16x32_bf16 v[92:95], v[128:131], v[202:205], v[92:95]
	v_mfma_f32_16x16x32_bf16 v[88:91], v[136:139], v[202:205], v[88:91]
	v_mfma_f32_16x16x32_bf16 v[76:79], v[128:131], v[210:213], v[76:79]
	v_mfma_f32_16x16x32_bf16 v[72:75], v[136:139], v[210:213], v[72:75]
	v_mfma_f32_16x16x32_bf16 v[124:127], v[132:135], v[190:193], v[124:127]
	v_mfma_f32_16x16x32_bf16 v[120:123], v[140:143], v[190:193], v[120:123]
	v_mfma_f32_16x16x32_bf16 v[108:111], v[132:135], v[198:201], v[108:111]
	v_mfma_f32_16x16x32_bf16 v[104:107], v[140:143], v[198:201], v[104:107]
	v_mfma_f32_16x16x32_bf16 v[92:95], v[132:135], v[206:209], v[92:95]
	v_mfma_f32_16x16x32_bf16 v[88:91], v[140:143], v[206:209], v[88:91]
	v_mfma_f32_16x16x32_bf16 v[76:79], v[132:135], v[214:217], v[76:79]
	v_mfma_f32_16x16x32_bf16 v[72:75], v[140:143], v[214:217], v[72:75]
	s_setprio 0
	s_setprio 1
	v_mfma_f32_16x16x32_bf16 v[116:119], v[160:163], v[186:189], v[116:119]
	v_mfma_f32_16x16x32_bf16 v[112:115], v[168:171], v[186:189], v[112:115]
	v_mfma_f32_16x16x32_bf16 v[100:103], v[160:163], v[194:197], v[100:103]
	v_mfma_f32_16x16x32_bf16 v[96:99], v[168:171], v[194:197], v[96:99]
	v_mfma_f32_16x16x32_bf16 v[84:87], v[160:163], v[202:205], v[84:87]
	v_mfma_f32_16x16x32_bf16 v[80:83], v[168:171], v[202:205], v[80:83]
	v_mfma_f32_16x16x32_bf16 v[68:71], v[160:163], v[210:213], v[68:71]
	v_mfma_f32_16x16x32_bf16 v[64:67], v[168:171], v[210:213], v[64:67]
	v_mfma_f32_16x16x32_bf16 v[116:119], v[164:167], v[190:193], v[116:119]
	v_mfma_f32_16x16x32_bf16 v[112:115], v[172:175], v[190:193], v[112:115]
	v_mfma_f32_16x16x32_bf16 v[100:103], v[164:167], v[198:201], v[100:103]
	v_mfma_f32_16x16x32_bf16 v[96:99], v[172:175], v[198:201], v[96:99]
	v_mfma_f32_16x16x32_bf16 v[84:87], v[164:167], v[206:209], v[84:87]
	v_mfma_f32_16x16x32_bf16 v[80:83], v[172:175], v[206:209], v[80:83]
	v_mfma_f32_16x16x32_bf16 v[68:71], v[164:167], v[214:217], v[68:71]
	v_mfma_f32_16x16x32_bf16 v[64:67], v[172:175], v[214:217], v[64:67]
	s_setprio 0
	s_barrier
	s_add_i32 s74, s68, s54
	v_lshl_add_u64 v[178:179], s[42:43], 0, v[146:147]
	s_mov_b32 m0, s74
	ds_read_b128 v[186:189], v184 offset:16384
	ds_read_b128 v[190:193], v184 offset:17408
	ds_read_b128 v[194:197], v184 offset:18432
	ds_read_b128 v[198:201], v184 offset:19456
	ds_read_b128 v[202:205], v184 offset:20480
	ds_read_b128 v[206:209], v184 offset:21504
	ds_read_b128 v[210:213], v184 offset:22528
	ds_read_b128 v[214:217], v184 offset:23552
	global_load_lds_dwordx4 v[178:179], off
	s_add_i32 m0, s74, 0x2000
	s_add_u32 s74, s42, 0x80000
	v_lshl_add_u64 v[218:219], s[42:43], 0, v[150:151]
	s_addc_u32 s75, s43, 0
	s_add_i32 s76, s69, s54
	global_load_lds_dwordx4 v[218:219], off
	v_lshl_add_u64 v[220:221], s[74:75], 0, v[146:147]
	s_mov_b32 m0, s76
	v_lshl_add_u64 v[222:223], s[52:53], 0, v[148:149]
	global_load_lds_dwordx4 v[220:221], off
	v_lshl_add_u64 v[220:221], s[74:75], 0, v[150:151]
	s_add_i32 m0, s76, 0x2000
	s_nop 0
	global_load_lds_dwordx4 v[220:221], off
	v_lshl_add_u64 v[220:221], s[52:53], 0, v[144:145]
	s_mov_b32 m0, s35
	s_nop 0
	global_load_lds_dwordx4 v[220:221], off
	s_mov_b32 m0, s55
	s_nop 0
	global_load_lds_dwordx4 v[222:223], off
	s_waitcnt vmcnt(8)
	s_waitcnt lgkmcnt(0)
	s_nop 0
	s_barrier
	s_setprio 1
	s_waitcnt lgkmcnt(0)
	v_mfma_f32_16x16x32_bf16 v[60:63], v[128:131], v[186:189], v[60:63]
	v_mfma_f32_16x16x32_bf16 v[56:59], v[136:139], v[186:189], v[56:59]
	v_mfma_f32_16x16x32_bf16 v[44:47], v[128:131], v[194:197], v[44:47]
	v_mfma_f32_16x16x32_bf16 v[40:43], v[136:139], v[194:197], v[40:43]
	v_mfma_f32_16x16x32_bf16 v[28:31], v[128:131], v[202:205], v[28:31]
	v_mfma_f32_16x16x32_bf16 v[24:27], v[136:139], v[202:205], v[24:27]
	v_mfma_f32_16x16x32_bf16 v[12:15], v[128:131], v[210:213], v[12:15]
	v_mfma_f32_16x16x32_bf16 v[8:11], v[136:139], v[210:213], v[8:11]
	v_mfma_f32_16x16x32_bf16 v[60:63], v[132:135], v[190:193], v[60:63]
	v_mfma_f32_16x16x32_bf16 v[56:59], v[140:143], v[190:193], v[56:59]
	v_mfma_f32_16x16x32_bf16 v[44:47], v[132:135], v[198:201], v[44:47]
	v_mfma_f32_16x16x32_bf16 v[40:43], v[140:143], v[198:201], v[40:43]
	v_mfma_f32_16x16x32_bf16 v[28:31], v[132:135], v[206:209], v[28:31]
	v_mfma_f32_16x16x32_bf16 v[24:27], v[140:143], v[206:209], v[24:27]
	v_mfma_f32_16x16x32_bf16 v[12:15], v[132:135], v[214:217], v[12:15]
	v_mfma_f32_16x16x32_bf16 v[8:11], v[140:143], v[214:217], v[8:11]
	s_setprio 0
	s_setprio 1
	v_mfma_f32_16x16x32_bf16 v[52:55], v[160:163], v[186:189], v[52:55]
	v_mfma_f32_16x16x32_bf16 v[48:51], v[168:171], v[186:189], v[48:51]
	v_mfma_f32_16x16x32_bf16 v[36:39], v[160:163], v[194:197], v[36:39]
	v_mfma_f32_16x16x32_bf16 v[32:35], v[168:171], v[194:197], v[32:35]
	v_mfma_f32_16x16x32_bf16 v[20:23], v[160:163], v[202:205], v[20:23]
	v_mfma_f32_16x16x32_bf16 v[16:19], v[168:171], v[202:205], v[16:19]
	v_mfma_f32_16x16x32_bf16 v[4:7], v[160:163], v[210:213], v[4:7]
	v_mfma_f32_16x16x32_bf16 v[0:3], v[168:171], v[210:213], v[0:3]
	v_mfma_f32_16x16x32_bf16 v[52:55], v[164:167], v[190:193], v[52:55]
	v_mfma_f32_16x16x32_bf16 v[48:51], v[172:175], v[190:193], v[48:51]
	v_mfma_f32_16x16x32_bf16 v[36:39], v[164:167], v[198:201], v[36:39]
	v_mfma_f32_16x16x32_bf16 v[32:35], v[172:175], v[198:201], v[32:35]
	v_mfma_f32_16x16x32_bf16 v[20:23], v[164:167], v[206:209], v[20:23]
	v_mfma_f32_16x16x32_bf16 v[16:19], v[172:175], v[206:209], v[16:19]
	v_mfma_f32_16x16x32_bf16 v[4:7], v[164:167], v[214:217], v[4:7]
	v_mfma_f32_16x16x32_bf16 v[0:3], v[172:175], v[214:217], v[0:3]
	s_setprio 0
	s_barrier
; #define PG8_STAGE(bufoff, gbase, voff) do { _Pragma("unroll") for (int _i = 0; _i < 2; ++_i) \
;         __builtin_amdgcn_global_load_lds((const unsigned*)((const char*)(gbase) + (voff)[_i]), (LAS unsigned*)(lds + (bufoff) + ldsw + _i * 8192), 16, 0, 0); } while (0)
; #define PG8_LDA(dst, b, h) do { _Pragma("unroll") for (int m = 0; m < 4; ++m) _Pragma("unroll") for (int k = 0; k < 2; ++k) dst[m][k] = *(const LAS bf16x8*)(lds + PG8_SA(b, h) + aoff + m * 2048 + k * 1024); } while (0)
; #define PG8_LDB(dst, b, h) do { _Pragma("unroll") for (int n = 0; n < 2; ++n) _Pragma("unroll") for (int k = 0; k < 2; ++k) dst[n][k] = *(const LAS bf16x8*)(lds + PG8_SB(b, h) + boff + n * 2048 + k * 1024); } while (0)
; #define PG8_MMA(ai, bj, At, Bt) do { __builtin_amdgcn_s_setprio(1); _Pragma("unroll") for (int m = 0; m < 4; ++m) _Pragma("unroll") for (int n = 0; n < 2; ++n) _Pragma("unroll") for (int k = 0; k < 2; ++k) \
;         acc[ai][bj][m][n] = __builtin_amdgcn_mfma_f32_16x16x32_bf16(Bt[n][k], At[m][k], acc[ai][bj][m][n], 0, 0, 0); __builtin_amdgcn_s_setprio(0); } while (0)
; #define PG8_WAIT_V(n) asm volatile("s_waitcnt vmcnt(" #n ")" ::: "memory")
; #define PG8_WAIT_L(n) asm volatile("s_waitcnt lgkmcnt(" #n ")" ::: "memory")
; #define PG8_BAR __builtin_amdgcn_s_barrier()
; #define PG8_SCHED __builtin_amdgcn_sched_barrier(0)
; template <class Epi>
; __device__ __forceinline__ void gemm_phase(LAS unsigned char* lds, const Gemm g, const StaticOrder& S, const Epi& E) {
;     ...
;             PG8_LDB(B0, 1, 0); PG8_LDB(B1, 1, 1); PG8_SCHED; PG8_LDA(At, 1, 0); PG8_STAGE(PG8_SA(0, 1), a2 + hstepA, voffA);
;             PG8_WAIT_V(8); PG8_WAIT_L(0); PG8_BAR; PG8_MMA(0, 0, At, B0); PG8_MMA(0, 1, At, B1); PG8_BAR; PG8_SCHED;
	s_add_i32 s74, 0, 0x18000
	s_add_i32 s75, 0, 0x1c000
	v_add_u32_e32 v140, s74, v181
	v_add_u32_e32 v172, s75, v181
	ds_read_b128 v[128:131], v140
	ds_read_b128 v[132:135], v140 offset:1024
	ds_read_b128 v[136:139], v140 offset:2048
	ds_read_b128 v[140:143], v140 offset:3072
	ds_read_b128 v[160:163], v172
	ds_read_b128 v[164:167], v172 offset:1024
	ds_read_b128 v[168:171], v172 offset:2048
	ds_read_b128 v[172:175], v172 offset:3072
	s_add_u32 s52, s52, 0x100000
	s_addc_u32 s53, s53, 0
	s_mov_b32 m0, s56
	v_lshl_add_u64 v[224:225], s[52:53], 0, v[144:145]
	ds_read_b128 v[186:189], v184 offset:32768
	ds_read_b128 v[190:193], v184 offset:33792
	ds_read_b128 v[194:197], v184 offset:34816
	ds_read_b128 v[198:201], v184 offset:35840
	ds_read_b128 v[202:205], v184 offset:36864
	ds_read_b128 v[206:209], v184 offset:37888
	ds_read_b128 v[210:213], v184 offset:38912
	ds_read_b128 v[214:217], v184 offset:39936
	global_load_lds_dwordx4 v[224:225], off
	v_lshl_add_u64 v[224:225], s[52:53], 0, v[148:149]
	s_mov_b32 m0, s57
	s_nop 0
	global_load_lds_dwordx4 v[224:225], off
	s_waitcnt vmcnt(8)
	s_waitcnt lgkmcnt(0)
	s_nop 0
	s_barrier
	s_setprio 1
	s_waitcnt lgkmcnt(0)
	v_mfma_f32_16x16x32_bf16 v[124:127], v[128:131], v[186:189], v[124:127]
	v_mfma_f32_16x16x32_bf16 v[120:123], v[136:139], v[186:189], v[120:123]
	v_mfma_f32_16x16x32_bf16 v[108:111], v[128:131], v[194:197], v[108:111]
	v_mfma_f32_16x16x32_bf16 v[104:107], v[136:139], v[194:197], v[104:107]
	v_mfma_f32_16x16x32_bf16 v[92:95], v[128:131], v[202:205], v[92:95]
	v_mfma_f32_16x16x32_bf16 v[88:91], v[136:139], v[202:205], v[88:91]
	v_mfma_f32_16x16x32_bf16 v[76:79], v[128:131], v[210:213], v[76:79]
	v_mfma_f32_16x16x32_bf16 v[72:75], v[136:139], v[210:213], v[72:75]
	v_mfma_f32_16x16x32_bf16 v[124:127], v[132:135], v[190:193], v[124:127]
	v_mfma_f32_16x16x32_bf16 v[120:123], v[140:143], v[190:193], v[120:123]
	v_mfma_f32_16x16x32_bf16 v[108:111], v[132:135], v[198:201], v[108:111]
	v_mfma_f32_16x16x32_bf16 v[104:107], v[140:143], v[198:201], v[104:107]
	v_mfma_f32_16x16x32_bf16 v[92:95], v[132:135], v[206:209], v[92:95]
	v_mfma_f32_16x16x32_bf16 v[88:91], v[140:143], v[206:209], v[88:91]
	v_mfma_f32_16x16x32_bf16 v[76:79], v[132:135], v[214:217], v[76:79]
	v_mfma_f32_16x16x32_bf16 v[72:75], v[140:143], v[214:217], v[72:75]
	s_setprio 0
	s_setprio 1
	v_mfma_f32_16x16x32_bf16 v[116:119], v[160:163], v[186:189], v[116:119]
	v_mfma_f32_16x16x32_bf16 v[112:115], v[168:171], v[186:189], v[112:115]
	v_mfma_f32_16x16x32_bf16 v[100:103], v[160:163], v[194:197], v[100:103]
	v_mfma_f32_16x16x32_bf16 v[96:99], v[168:171], v[194:197], v[96:99]
	v_mfma_f32_16x16x32_bf16 v[84:87], v[160:163], v[202:205], v[84:87]
	v_mfma_f32_16x16x32_bf16 v[80:83], v[168:171], v[202:205], v[80:83]
	v_mfma_f32_16x16x32_bf16 v[68:71], v[160:163], v[210:213], v[68:71]
	v_mfma_f32_16x16x32_bf16 v[64:67], v[168:171], v[210:213], v[64:67]
	v_mfma_f32_16x16x32_bf16 v[116:119], v[164:167], v[190:193], v[116:119]
	v_mfma_f32_16x16x32_bf16 v[112:115], v[172:175], v[190:193], v[112:115]
	v_mfma_f32_16x16x32_bf16 v[100:103], v[164:167], v[198:201], v[100:103]
	v_mfma_f32_16x16x32_bf16 v[96:99], v[172:175], v[198:201], v[96:99]
	v_mfma_f32_16x16x32_bf16 v[84:87], v[164:167], v[206:209], v[84:87]
	v_mfma_f32_16x16x32_bf16 v[80:83], v[172:175], v[206:209], v[80:83]
	v_mfma_f32_16x16x32_bf16 v[68:71], v[164:167], v[214:217], v[68:71]
	v_mfma_f32_16x16x32_bf16 v[64:67], v[172:175], v[214:217], v[64:67]
	s_setprio 0
	s_barrier
; #define PG8_STAGE(bufoff, gbase, voff) do { _Pragma("unroll") for (int _i = 0; _i < 2; ++_i) \
;         __builtin_amdgcn_global_load_lds((const unsigned*)((const char*)(gbase) + (voff)[_i]), (LAS unsigned*)(lds + (bufoff) + ldsw + _i * 8192), 16, 0, 0); } while (0)
; #define PG8_LDA(dst, b, h) do { _Pragma("unroll") for (int m = 0; m < 4; ++m) _Pragma("unroll") for (int k = 0; k < 2; ++k) dst[m][k] = *(const LAS bf16x8*)(lds + PG8_SA(b, h) + aoff + m * 2048 + k * 1024); } while (0)
; #define PG8_MMA(ai, bj, At, Bt) do { __builtin_amdgcn_s_setprio(1); _Pragma("unroll") for (int m = 0; m < 4; ++m) _Pragma("unroll") for (int n = 0; n < 2; ++n) _Pragma("unroll") for (int k = 0; k < 2; ++k) \
;         acc[ai][bj][m][n] = __builtin_amdgcn_mfma_f32_16x16x32_bf16(Bt[n][k], At[m][k], acc[ai][bj][m][n], 0, 0, 0); __builtin_amdgcn_s_setprio(0); } while (0)
; #define PG8_WAIT_V(n) asm volatile("s_waitcnt vmcnt(" #n ")" ::: "memory")
; #define PG8_WAIT_L(n) asm volatile("s_waitcnt lgkmcnt(" #n ")" ::: "memory")
; #define PG8_BAR __builtin_amdgcn_s_barrier()
; #define PG8_SCHED __builtin_amdgcn_sched_barrier(0)
; template <class Epi>
; __device__ __forceinline__ void gemm_phase(LAS unsigned char* lds, const Gemm g, const StaticOrder& S, const Epi& E) {
;     ...
;             PG8_LDA(At, 1, 1); PG8_STAGE(PG8_SB(1, 0), b3, voffB); PG8_STAGE(PG8_SB(1, 1), b3 + hstepB, voffB); PG8_STAGE(PG8_SA(1, 0), a3, voffA);
;             PG8_WAIT_V(8); PG8_WAIT_L(0); PG8_BAR; PG8_MMA(1, 0, At, B0); PG8_MMA(1, 1, At, B1); PG8_BAR; PG8_SCHED;
;         }
;         if (wr == 0) PG8_BAR;
	s_add_i32 s52, s74, s54
	v_lshl_add_u64 v[178:179], v[178:179], 0, s[12:13]
	s_mov_b32 m0, s52
	ds_read_b128 v[186:189], v184 offset:49152
	ds_read_b128 v[190:193], v184 offset:50176
	ds_read_b128 v[194:197], v184 offset:51200
	ds_read_b128 v[198:201], v184 offset:52224
	ds_read_b128 v[202:205], v184 offset:53248
	ds_read_b128 v[206:209], v184 offset:54272
	ds_read_b128 v[210:213], v184 offset:55296
	ds_read_b128 v[214:217], v184 offset:56320
	global_load_lds_dwordx4 v[178:179], off
	s_add_i32 m0, s52, 0x2000
	s_add_u32 s42, s42, 0x80080
	v_lshl_add_u64 v[178:179], v[218:219], 0, s[12:13]
	s_addc_u32 s43, s43, 0
	s_add_i32 s52, s75, s54
	global_load_lds_dwordx4 v[178:179], off
	v_lshl_add_u64 v[178:179], s[42:43], 0, v[146:147]
	s_mov_b32 m0, s52
	s_nop 0
	global_load_lds_dwordx4 v[178:179], off
	v_lshl_add_u64 v[178:179], s[42:43], 0, v[150:151]
	s_add_i32 m0, s52, 0x2000
	s_nop 0
	global_load_lds_dwordx4 v[178:179], off
	v_lshl_add_u64 v[178:179], v[220:221], 0, s[12:13]
	s_mov_b32 m0, s61
	s_nop 0
	global_load_lds_dwordx4 v[178:179], off
	v_lshl_add_u64 v[178:179], v[222:223], 0, s[12:13]
	s_mov_b32 m0, s62
	s_nop 0
	global_load_lds_dwordx4 v[178:179], off
	s_waitcnt vmcnt(8)
	s_waitcnt lgkmcnt(0)
	s_barrier
	s_setprio 1
	s_waitcnt lgkmcnt(0)
	v_mfma_f32_16x16x32_bf16 v[60:63], v[128:131], v[186:189], v[60:63]
	v_mfma_f32_16x16x32_bf16 v[56:59], v[136:139], v[186:189], v[56:59]
	v_mfma_f32_16x16x32_bf16 v[44:47], v[128:131], v[194:197], v[44:47]
	v_mfma_f32_16x16x32_bf16 v[40:43], v[136:139], v[194:197], v[40:43]
	v_mfma_f32_16x16x32_bf16 v[28:31], v[128:131], v[202:205], v[28:31]
	v_mfma_f32_16x16x32_bf16 v[24:27], v[136:139], v[202:205], v[24:27]
	v_mfma_f32_16x16x32_bf16 v[12:15], v[128:131], v[210:213], v[12:15]
	v_mfma_f32_16x16x32_bf16 v[8:11], v[136:139], v[210:213], v[8:11]
	v_mfma_f32_16x16x32_bf16 v[60:63], v[132:135], v[190:193], v[60:63]
	v_mfma_f32_16x16x32_bf16 v[56:59], v[140:143], v[190:193], v[56:59]
	v_mfma_f32_16x16x32_bf16 v[44:47], v[132:135], v[198:201], v[44:47]
	v_mfma_f32_16x16x32_bf16 v[40:43], v[140:143], v[198:201], v[40:43]
	v_mfma_f32_16x16x32_bf16 v[28:31], v[132:135], v[206:209], v[28:31]
	v_mfma_f32_16x16x32_bf16 v[24:27], v[140:143], v[206:209], v[24:27]
	v_mfma_f32_16x16x32_bf16 v[12:15], v[132:135], v[214:217], v[12:15]
	v_mfma_f32_16x16x32_bf16 v[8:11], v[140:143], v[214:217], v[8:11]
	s_setprio 0
	s_setprio 1
	v_mfma_f32_16x16x32_bf16 v[52:55], v[160:163], v[186:189], v[52:55]
	v_mfma_f32_16x16x32_bf16 v[48:51], v[168:171], v[186:189], v[48:51]
	v_mfma_f32_16x16x32_bf16 v[36:39], v[160:163], v[194:197], v[36:39]
	v_mfma_f32_16x16x32_bf16 v[32:35], v[168:171], v[194:197], v[32:35]
	v_mfma_f32_16x16x32_bf16 v[20:23], v[160:163], v[202:205], v[20:23]
	v_mfma_f32_16x16x32_bf16 v[16:19], v[168:171], v[202:205], v[16:19]
	v_mfma_f32_16x16x32_bf16 v[4:7], v[160:163], v[210:213], v[4:7]
	v_mfma_f32_16x16x32_bf16 v[0:3], v[168:171], v[210:213], v[0:3]
	v_mfma_f32_16x16x32_bf16 v[52:55], v[164:167], v[190:193], v[52:55]
	v_mfma_f32_16x16x32_bf16 v[48:51], v[172:175], v[190:193], v[48:51]
	v_mfma_f32_16x16x32_bf16 v[36:39], v[164:167], v[198:201], v[36:39]
	v_mfma_f32_16x16x32_bf16 v[32:35], v[172:175], v[198:201], v[32:35]
	v_mfma_f32_16x16x32_bf16 v[20:23], v[164:167], v[206:209], v[20:23]
	v_mfma_f32_16x16x32_bf16 v[16:19], v[172:175], v[206:209], v[16:19]
	v_mfma_f32_16x16x32_bf16 v[4:7], v[164:167], v[214:217], v[4:7]
	v_mfma_f32_16x16x32_bf16 v[0:3], v[172:175], v[214:217], v[0:3]
	s_setprio 0
	s_barrier
	s_add_i32 s73, s73, 2
	s_add_u32 s38, s38, 0x100
	s_addc_u32 s39, s39, 0
	s_add_u32 s71, s71, 0x100
	s_addc_u32 s72, s72, 0
	s_cmp_gt_u32 s73, 29
	s_cbranch_scc0 .LBB0_1314
	s_and_b64 vcc, exec, s[14:15]
	s_cbranch_vccz .LBB0_1317
	s_barrier

; #define PG8_STAGE(bufoff, gbase, voff) do { _Pragma("unroll") for (int _i = 0; _i < 2; ++_i) \
;         __builtin_amdgcn_global_load_lds((const unsigned*)((const char*)(gbase) + (voff)[_i]), (LAS unsigned*)(lds + (bufoff) + ldsw + _i * 8192), 16, 0, 0); } while (0)
; #define PG8_LDA(dst, b, h) do { _Pragma("unroll") for (int m = 0; m < 4; ++m) _Pragma("unroll") for (int k = 0; k < 2; ++k) dst[m][k] = *(const LAS bf16x8*)(lds + PG8_SA(b, h) + aoff + m * 2048 + k * 1024); } while (0)
; #define PG8_LDB(dst, b, h) do { _Pragma("unroll") for (int n = 0; n < 2; ++n) _Pragma("unroll") for (int k = 0; k < 2; ++k) dst[n][k] = *(const LAS bf16x8*)(lds + PG8_SB(b, h) + boff + n * 2048 + k * 1024); } while (0)
; #define PG8_MMA(ai, bj, At, Bt) do { __builtin_amdgcn_s_setprio(1); _Pragma("unroll") for (int m = 0; m < 4; ++m) _Pragma("unroll") for (int n = 0; n < 2; ++n) _Pragma("unroll") for (int k = 0; k < 2; ++k) \
;         acc[ai][bj][m][n] = __builtin_amdgcn_mfma_f32_16x16x32_bf16(Bt[n][k], At[m][k], acc[ai][bj][m][n], 0, 0, 0); __builtin_amdgcn_s_setprio(0); } while (0)
; #define PG8_BAR __builtin_amdgcn_s_barrier()
; template <class Epi>
; __device__ __forceinline__ void gemm_phase(LAS unsigned char* lds, const Gemm g, const StaticOrder& S, const Epi& E) {
;     ...
;         const bool has_next = S.next(ui + 1, nxt);
;         const char* nA = has_next ? (const char*)g.A + (size_t)nxt.pm * tstepA : cA; const char* nB = has_next ? (const char*)g.Bt + (size_t)nxt.pn * tstepB : cB;
; #pragma nounroll
;         for (int t = 0; t < nt; t += 2) {
;             const bool last = (t == nt - 2);
;             const char* a1 = cA + (size_t)(t + 1) * kstep;
;             const char* a2 = last ? nA : cA + (size_t)(t + 2) * kstep; const char* b2 = last ? nB : cB + (size_t)(t + 2) * kstep;
;             const char* a3 = a2 + kstep; const char* b3 = b2 + kstep;
;             PG8_LDB(B0, 0, 0); PG8_LDB(B1, 0, 1); PG8_SCHED; PG8_LDA(At, 0, 0); PG8_STAGE(PG8_SA(1, 1), a1 + hstepA, voffA);
;             PG8_WAIT_V(8); PG8_WAIT_L(0); PG8_BAR; PG8_MMA(0, 0, At, B0); PG8_MMA(0, 1, At, B1); PG8_BAR; PG8_SCHED;
;             PG8_LDA(At, 0, 1); PG8_STAGE(PG8_SB(0, 0), b2, voffB); PG8_STAGE(PG8_SB(0, 1), b2 + hstepB, voffB); PG8_STAGE(PG8_SA(0, 0), a2, voffA);
;             PG8_WAIT_V(8); PG8_WAIT_L(0); PG8_BAR; PG8_MMA(1, 0, At, B0); PG8_MMA(1, 1, At, B1); PG8_BAR; PG8_SCHED;
.LBB0_1402:
	s_ashr_i32 s69, s68, 31
	s_lshl_b64 s[12:13], s[68:69], 19
	s_add_u32 s70, s24, s12
	s_addc_u32 s71, s25, s13
	s_and_b64 s[12:13], s[4:5], exec
	s_cselect_b32 s1, s71, s9
	s_cselect_b32 s7, s70, s8
	s_ashr_i32 s65, s64, 31
	s_lshl_b64 s[12:13], s[64:65], 19
	s_add_u32 s72, s3, s12
	s_addc_u32 s73, s33, s13
	s_and_b64 s[12:13], s[4:5], exec
	s_cselect_b32 s65, s73, s11
	s_cselect_b32 s69, s72, s10
	s_add_u32 s8, s8, 0x40080
	s_addc_u32 s9, s9, 0
	s_add_u32 s74, s10, 0x100
	s_addc_u32 s75, s11, 0
	s_mov_b32 s87, -2
	v_lshl_add_u32 v248, s6, 8, v151
	v_add_u32_e32 v248, s63, v248
	v_ashrrev_i32_e32 v249, 31, v248
	v_lshl_add_u64 v[248:249], v[248:249], 2, s[18:19]
	global_load_dword v240, v[248:249], off
	global_load_dword v241, v[248:249], off offset:64
	global_load_dword v242, v[248:249], off offset:128
	global_load_dword v243, v[248:249], off offset:192
	global_load_dword v244, v[248:249], off offset:512
	global_load_dword v245, v[248:249], off offset:576
	global_load_dword v246, v[248:249], off offset:640
	global_load_dword v247, v[248:249], off offset:704
	ds_read_b128 v[146:149], v162
	ds_read_b128 v[166:169], v162 offset:1024
	ds_read_b128 v[170:173], v162 offset:2048
	ds_read_b128 v[178:181], v162 offset:3072
	ds_read_b128 v[182:185], v163
	ds_read_b128 v[186:189], v163 offset:1024
	ds_read_b128 v[190:193], v163 offset:2048
	ds_read_b128 v[194:197], v163 offset:3072
	s_add_u32 s10, s8, 0xfffc0080
	s_addc_u32 s11, s9, -1
	s_cmp_eq_u32 s87, 12
	s_cselect_b32 s13, s1, s11
	s_cselect_b32 s12, s7, s10
	s_cselect_b32 s11, s65, s75
	s_cselect_b32 s10, s69, s74
	v_lshl_add_u64 v[174:175], s[8:9], 0, v[138:139]
	s_add_i32 m0, s53, 0xc000
	ds_read_b128 v[198:201], v164
	ds_read_b128 v[202:205], v164 offset:1024
	ds_read_b128 v[206:209], v164 offset:2048
	ds_read_b128 v[210:213], v164 offset:3072
	ds_read_b128 v[214:217], v164 offset:4096
	ds_read_b128 v[218:221], v164 offset:5120
	ds_read_b128 v[222:225], v164 offset:6144
	ds_read_b128 v[226:229], v164 offset:7168
	global_load_lds_dwordx4 v[174:175], off
	v_lshl_add_u64 v[174:175], s[8:9], 0, v[140:141]
	s_add_i32 m0, s53, 0xe000
	s_nop 0
	global_load_lds_dwordx4 v[174:175], off
	s_waitcnt vmcnt(8)
	s_waitcnt lgkmcnt(0)
	s_nop 0
	s_barrier
	s_setprio 1
	s_waitcnt lgkmcnt(0)
	v_mfma_f32_16x16x32_bf16 v[124:127], v[146:149], v[198:201], 0
	v_mfma_f32_16x16x32_bf16 v[120:123], v[170:173], v[198:201], 0
	v_mfma_f32_16x16x32_bf16 v[112:115], v[146:149], v[206:209], 0
	v_mfma_f32_16x16x32_bf16 v[104:107], v[170:173], v[206:209], 0
	v_mfma_f32_16x16x32_bf16 v[100:103], v[146:149], v[214:217], 0
	v_mfma_f32_16x16x32_bf16 v[92:95], v[170:173], v[214:217], 0
	v_mfma_f32_16x16x32_bf16 v[84:87], v[146:149], v[222:225], 0
	v_mfma_f32_16x16x32_bf16 v[76:79], v[170:173], v[222:225], 0
	v_mfma_f32_16x16x32_bf16 v[124:127], v[166:169], v[202:205], v[124:127]
	v_mfma_f32_16x16x32_bf16 v[120:123], v[178:181], v[202:205], v[120:123]
	v_mfma_f32_16x16x32_bf16 v[112:115], v[166:169], v[210:213], v[112:115]
	v_mfma_f32_16x16x32_bf16 v[104:107], v[178:181], v[210:213], v[104:107]
	v_mfma_f32_16x16x32_bf16 v[100:103], v[166:169], v[218:221], v[100:103]
	v_mfma_f32_16x16x32_bf16 v[92:95], v[178:181], v[218:221], v[92:95]
	v_mfma_f32_16x16x32_bf16 v[84:87], v[166:169], v[226:229], v[84:87]
	v_mfma_f32_16x16x32_bf16 v[76:79], v[178:181], v[226:229], v[76:79]
	s_setprio 0
	s_setprio 1
	v_mfma_f32_16x16x32_bf16 v[116:119], v[182:185], v[198:201], 0
	v_mfma_f32_16x16x32_bf16 v[108:111], v[190:193], v[198:201], 0
	v_mfma_f32_16x16x32_bf16 v[96:99], v[182:185], v[206:209], 0
	v_mfma_f32_16x16x32_bf16 v[88:91], v[190:193], v[206:209], 0
	v_mfma_f32_16x16x32_bf16 v[80:83], v[182:185], v[214:217], 0
	v_mfma_f32_16x16x32_bf16 v[72:75], v[190:193], v[214:217], 0
	v_mfma_f32_16x16x32_bf16 v[68:71], v[182:185], v[222:225], 0
	v_mfma_f32_16x16x32_bf16 v[64:67], v[190:193], v[222:225], 0
	v_mfma_f32_16x16x32_bf16 v[116:119], v[186:189], v[202:205], v[116:119]
	v_mfma_f32_16x16x32_bf16 v[108:111], v[194:197], v[202:205], v[108:111]
	v_mfma_f32_16x16x32_bf16 v[96:99], v[186:189], v[210:213], v[96:99]
	v_mfma_f32_16x16x32_bf16 v[88:91], v[194:197], v[210:213], v[88:91]
	v_mfma_f32_16x16x32_bf16 v[80:83], v[186:189], v[218:221], v[80:83]
	v_mfma_f32_16x16x32_bf16 v[72:75], v[194:197], v[218:221], v[72:75]
	v_mfma_f32_16x16x32_bf16 v[68:71], v[186:189], v[226:229], v[68:71]
	v_mfma_f32_16x16x32_bf16 v[64:67], v[194:197], v[226:229], v[64:67]
	s_setprio 0
	s_barrier
	s_add_i32 s88, s83, s43
	v_lshl_add_u64 v[174:175], s[10:11], 0, v[130:131]
	s_mov_b32 m0, s88
	ds_read_b128 v[198:201], v164 offset:16384
	ds_read_b128 v[202:205], v164 offset:17408
	ds_read_b128 v[206:209], v164 offset:18432
	ds_read_b128 v[210:213], v164 offset:19456
	ds_read_b128 v[214:217], v164 offset:20480
	ds_read_b128 v[218:221], v164 offset:21504
	ds_read_b128 v[222:225], v164 offset:22528
	ds_read_b128 v[226:229], v164 offset:23552
	global_load_lds_dwordx4 v[174:175], off
	s_add_i32 m0, s88, 0x2000
	s_add_u32 s88, s10, 0x40000
	v_lshl_add_u64 v[230:231], s[10:11], 0, v[134:135]
	s_addc_u32 s89, s11, 0
	s_add_i32 s90, s84, s43
	global_load_lds_dwordx4 v[230:231], off
	v_lshl_add_u64 v[232:233], s[88:89], 0, v[130:131]
	s_mov_b32 m0, s90
	v_lshl_add_u64 v[234:235], s[12:13], 0, v[132:133]
	global_load_lds_dwordx4 v[232:233], off
	v_lshl_add_u64 v[232:233], s[88:89], 0, v[134:135]
	s_add_i32 m0, s90, 0x2000
	s_nop 0
	global_load_lds_dwordx4 v[232:233], off
	v_lshl_add_u64 v[232:233], s[12:13], 0, v[128:129]
	s_mov_b32 m0, s53
	s_nop 0
	global_load_lds_dwordx4 v[232:233], off
	s_mov_b32 m0, s55
	s_nop 0
	global_load_lds_dwordx4 v[234:235], off
	s_waitcnt vmcnt(8)
	s_waitcnt lgkmcnt(0)
	s_nop 0
	s_barrier
; #define PG8_STAGE(bufoff, gbase, voff) do { _Pragma("unroll") for (int _i = 0; _i < 2; ++_i) \
;         __builtin_amdgcn_global_load_lds((const unsigned*)((const char*)(gbase) + (voff)[_i]), (LAS unsigned*)(lds + (bufoff) + ldsw + _i * 8192), 16, 0, 0); } while (0)
; #define PG8_LDA(dst, b, h) do { _Pragma("unroll") for (int m = 0; m < 4; ++m) _Pragma("unroll") for (int k = 0; k < 2; ++k) dst[m][k] = *(const LAS bf16x8*)(lds + PG8_SA(b, h) + aoff + m * 2048 + k * 1024); } while (0)
; #define PG8_LDB(dst, b, h) do { _Pragma("unroll") for (int n = 0; n < 2; ++n) _Pragma("unroll") for (int k = 0; k < 2; ++k) dst[n][k] = *(const LAS bf16x8*)(lds + PG8_SB(b, h) + boff + n * 2048 + k * 1024); } while (0)
; #define PG8_MMA(ai, bj, At, Bt) do { __builtin_amdgcn_s_setprio(1); _Pragma("unroll") for (int m = 0; m < 4; ++m) _Pragma("unroll") for (int n = 0; n < 2; ++n) _Pragma("unroll") for (int k = 0; k < 2; ++k) \
;         acc[ai][bj][m][n] = __builtin_amdgcn_mfma_f32_16x16x32_bf16(Bt[n][k], At[m][k], acc[ai][bj][m][n], 0, 0, 0); __builtin_amdgcn_s_setprio(0); } while (0)
; #define PG8_WAIT_V(n) asm volatile("s_waitcnt vmcnt(" #n ")" ::: "memory")
; #define PG8_WAIT_L(n) asm volatile("s_waitcnt lgkmcnt(" #n ")" ::: "memory")
; #define PG8_BAR __builtin_amdgcn_s_barrier()
; #define PG8_SCHED __builtin_amdgcn_sched_barrier(0)
; template <class Epi>
; __device__ __forceinline__ void gemm_phase(LAS unsigned char* lds, const Gemm g, const StaticOrder& S, const Epi& E) {
;     ...
;             PG8_WAIT_V(8); PG8_WAIT_L(0); PG8_BAR; PG8_MMA(1, 0, At, B0); PG8_MMA(1, 1, At, B1); PG8_BAR; PG8_SCHED;
;             PG8_LDB(B0, 1, 0); PG8_LDB(B1, 1, 1); PG8_SCHED; PG8_LDA(At, 1, 0); PG8_STAGE(PG8_SA(0, 1), a2 + hstepA, voffA);
;             PG8_WAIT_V(8); PG8_WAIT_L(0); PG8_BAR; PG8_MMA(0, 0, At, B0); PG8_MMA(0, 1, At, B1); PG8_BAR; PG8_SCHED;
	s_setprio 1
	s_waitcnt lgkmcnt(0)
	v_mfma_f32_16x16x32_bf16 v[60:63], v[146:149], v[198:201], 0
	v_mfma_f32_16x16x32_bf16 v[56:59], v[170:173], v[198:201], 0
	v_mfma_f32_16x16x32_bf16 v[52:55], v[146:149], v[206:209], 0
	v_mfma_f32_16x16x32_bf16 v[44:47], v[170:173], v[206:209], 0
	v_mfma_f32_16x16x32_bf16 v[36:39], v[146:149], v[214:217], 0
	v_mfma_f32_16x16x32_bf16 v[28:31], v[170:173], v[214:217], 0
	v_mfma_f32_16x16x32_bf16 v[20:23], v[146:149], v[222:225], 0
	v_mfma_f32_16x16x32_bf16 v[12:15], v[170:173], v[222:225], 0
	v_mfma_f32_16x16x32_bf16 v[60:63], v[166:169], v[202:205], v[60:63]
	v_mfma_f32_16x16x32_bf16 v[56:59], v[178:181], v[202:205], v[56:59]
	v_mfma_f32_16x16x32_bf16 v[52:55], v[166:169], v[210:213], v[52:55]
	v_mfma_f32_16x16x32_bf16 v[44:47], v[178:181], v[210:213], v[44:47]
	v_mfma_f32_16x16x32_bf16 v[36:39], v[166:169], v[218:221], v[36:39]
	v_mfma_f32_16x16x32_bf16 v[28:31], v[178:181], v[218:221], v[28:31]
	v_mfma_f32_16x16x32_bf16 v[20:23], v[166:169], v[226:229], v[20:23]
	v_mfma_f32_16x16x32_bf16 v[12:15], v[178:181], v[226:229], v[12:15]
	s_setprio 0
	s_setprio 1
	v_mfma_f32_16x16x32_bf16 v[48:51], v[182:185], v[198:201], 0
	v_mfma_f32_16x16x32_bf16 v[40:43], v[190:193], v[198:201], 0
	v_mfma_f32_16x16x32_bf16 v[32:35], v[182:185], v[206:209], 0
	v_mfma_f32_16x16x32_bf16 v[24:27], v[190:193], v[206:209], 0
	v_mfma_f32_16x16x32_bf16 v[16:19], v[182:185], v[214:217], 0
	v_mfma_f32_16x16x32_bf16 v[8:11], v[190:193], v[214:217], 0
	v_mfma_f32_16x16x32_bf16 v[4:7], v[182:185], v[222:225], 0
	v_mfma_f32_16x16x32_bf16 v[0:3], v[190:193], v[222:225], 0
	v_mfma_f32_16x16x32_bf16 v[48:51], v[186:189], v[202:205], v[48:51]
	v_mfma_f32_16x16x32_bf16 v[40:43], v[194:197], v[202:205], v[40:43]
	v_mfma_f32_16x16x32_bf16 v[32:35], v[186:189], v[210:213], v[32:35]
	v_mfma_f32_16x16x32_bf16 v[24:27], v[194:197], v[210:213], v[24:27]
	v_mfma_f32_16x16x32_bf16 v[16:19], v[186:189], v[218:221], v[16:19]
	v_mfma_f32_16x16x32_bf16 v[8:11], v[194:197], v[218:221], v[8:11]
	v_mfma_f32_16x16x32_bf16 v[4:7], v[186:189], v[226:229], v[4:7]
	v_mfma_f32_16x16x32_bf16 v[0:3], v[194:197], v[226:229], v[0:3]
	s_setprio 0
	s_barrier
	s_add_i32 s88, 0, 0x18000
	v_add_u32_e32 v136, s88, v161
	s_add_i32 s89, 0, 0x1c000
	ds_read_b128 v[146:149], v136
	ds_read_b128 v[166:169], v136 offset:1024
	ds_read_b128 v[170:173], v136 offset:2048
	ds_read_b128 v[178:181], v136 offset:3072
	v_add_u32_e32 v136, s89, v161
	ds_read_b128 v[182:185], v136
	ds_read_b128 v[186:189], v136 offset:1024
	ds_read_b128 v[190:193], v136 offset:2048
	ds_read_b128 v[194:197], v136 offset:3072
	s_add_u32 s12, s12, 0x40000
	s_addc_u32 s13, s13, 0
	s_mov_b32 m0, s57
	v_lshl_add_u64 v[236:237], s[12:13], 0, v[128:129]
	ds_read_b128 v[198:201], v164 offset:32768
	ds_read_b128 v[202:205], v164 offset:33792
	ds_read_b128 v[206:209], v164 offset:34816
	ds_read_b128 v[210:213], v164 offset:35840
	ds_read_b128 v[214:217], v164 offset:36864
	ds_read_b128 v[218:221], v164 offset:37888
	ds_read_b128 v[222:225], v164 offset:38912
	ds_read_b128 v[226:229], v164 offset:39936
	global_load_lds_dwordx4 v[236:237], off
	v_lshl_add_u64 v[236:237], s[12:13], 0, v[132:133]
	s_mov_b32 m0, s59
	s_nop 0
	global_load_lds_dwordx4 v[236:237], off
	s_waitcnt vmcnt(8)
	s_waitcnt lgkmcnt(0)
	s_nop 0
	s_barrier
	s_setprio 1
	s_waitcnt lgkmcnt(0)
	v_mfma_f32_16x16x32_bf16 v[124:127], v[146:149], v[198:201], v[124:127]
	v_mfma_f32_16x16x32_bf16 v[120:123], v[170:173], v[198:201], v[120:123]
	v_mfma_f32_16x16x32_bf16 v[112:115], v[146:149], v[206:209], v[112:115]
	v_mfma_f32_16x16x32_bf16 v[104:107], v[170:173], v[206:209], v[104:107]
	v_mfma_f32_16x16x32_bf16 v[100:103], v[146:149], v[214:217], v[100:103]
	v_mfma_f32_16x16x32_bf16 v[92:95], v[170:173], v[214:217], v[92:95]
	v_mfma_f32_16x16x32_bf16 v[84:87], v[146:149], v[222:225], v[84:87]
	v_mfma_f32_16x16x32_bf16 v[76:79], v[170:173], v[222:225], v[76:79]
	v_mfma_f32_16x16x32_bf16 v[124:127], v[166:169], v[202:205], v[124:127]
	v_mfma_f32_16x16x32_bf16 v[120:123], v[178:181], v[202:205], v[120:123]
	v_mfma_f32_16x16x32_bf16 v[112:115], v[166:169], v[210:213], v[112:115]
	v_mfma_f32_16x16x32_bf16 v[104:107], v[178:181], v[210:213], v[104:107]
	v_mfma_f32_16x16x32_bf16 v[100:103], v[166:169], v[218:221], v[100:103]
	v_mfma_f32_16x16x32_bf16 v[92:95], v[178:181], v[218:221], v[92:95]
	v_mfma_f32_16x16x32_bf16 v[84:87], v[166:169], v[226:229], v[84:87]
	v_mfma_f32_16x16x32_bf16 v[76:79], v[178:181], v[226:229], v[76:79]
	s_setprio 0
	s_setprio 1
	v_mfma_f32_16x16x32_bf16 v[116:119], v[182:185], v[198:201], v[116:119]
	v_mfma_f32_16x16x32_bf16 v[108:111], v[190:193], v[198:201], v[108:111]
	v_mfma_f32_16x16x32_bf16 v[96:99], v[182:185], v[206:209], v[96:99]
	v_mfma_f32_16x16x32_bf16 v[88:91], v[190:193], v[206:209], v[88:91]
	v_mfma_f32_16x16x32_bf16 v[80:83], v[182:185], v[214:217], v[80:83]
	v_mfma_f32_16x16x32_bf16 v[72:75], v[190:193], v[214:217], v[72:75]
	v_mfma_f32_16x16x32_bf16 v[68:71], v[182:185], v[222:225], v[68:71]
	v_mfma_f32_16x16x32_bf16 v[64:67], v[190:193], v[222:225], v[64:67]
	v_mfma_f32_16x16x32_bf16 v[116:119], v[186:189], v[202:205], v[116:119]
	v_mfma_f32_16x16x32_bf16 v[108:111], v[194:197], v[202:205], v[108:111]
	v_mfma_f32_16x16x32_bf16 v[96:99], v[186:189], v[210:213], v[96:99]
	v_mfma_f32_16x16x32_bf16 v[88:91], v[194:197], v[210:213], v[88:91]
	v_mfma_f32_16x16x32_bf16 v[80:83], v[186:189], v[218:221], v[80:83]
	v_mfma_f32_16x16x32_bf16 v[72:75], v[194:197], v[218:221], v[72:75]
	v_mfma_f32_16x16x32_bf16 v[68:71], v[186:189], v[226:229], v[68:71]
	v_mfma_f32_16x16x32_bf16 v[64:67], v[194:197], v[226:229], v[64:67]
	s_setprio 0
	s_barrier
; #define PG8_STAGE(bufoff, gbase, voff) do { _Pragma("unroll") for (int _i = 0; _i < 2; ++_i) \
;         __builtin_amdgcn_global_load_lds((const unsigned*)((const char*)(gbase) + (voff)[_i]), (LAS unsigned*)(lds + (bufoff) + ldsw + _i * 8192), 16, 0, 0); } while (0)
; #define PG8_LDA(dst, b, h) do { _Pragma("unroll") for (int m = 0; m < 4; ++m) _Pragma("unroll") for (int k = 0; k < 2; ++k) dst[m][k] = *(const LAS bf16x8*)(lds + PG8_SA(b, h) + aoff + m * 2048 + k * 1024); } while (0)
; #define PG8_LDB(dst, b, h) do { _Pragma("unroll") for (int n = 0; n < 2; ++n) _Pragma("unroll") for (int k = 0; k < 2; ++k) dst[n][k] = *(const LAS bf16x8*)(lds + PG8_SB(b, h) + boff + n * 2048 + k * 1024); } while (0)
; #define PG8_MMA(ai, bj, At, Bt) do { __builtin_amdgcn_s_setprio(1); _Pragma("unroll") for (int m = 0; m < 4; ++m) _Pragma("unroll") for (int n = 0; n < 2; ++n) _Pragma("unroll") for (int k = 0; k < 2; ++k) \
;         acc[ai][bj][m][n] = __builtin_amdgcn_mfma_f32_16x16x32_bf16(Bt[n][k], At[m][k], acc[ai][bj][m][n], 0, 0, 0); __builtin_amdgcn_s_setprio(0); } while (0)
; #define PG8_WAIT_V(n) asm volatile("s_waitcnt vmcnt(" #n ")" ::: "memory")
; #define PG8_BAR __builtin_amdgcn_s_barrier()
; template <class Epi>
; __device__ __forceinline__ void gemm_phase(LAS unsigned char* lds, const Gemm g, const StaticOrder& S, const Epi& E) {
;     ...
;             PG8_LDB(B0, 0, 0); PG8_LDB(B1, 0, 1); PG8_SCHED; PG8_LDA(At, 0, 0); PG8_STAGE(PG8_SA(1, 1), a1 + hstepA, voffA);
;             PG8_WAIT_V(8); PG8_WAIT_L(0); PG8_BAR; PG8_MMA(0, 0, At, B0); PG8_MMA(0, 1, At, B1); PG8_BAR; PG8_SCHED;
;             PG8_LDA(At, 0, 1); PG8_STAGE(PG8_SB(0, 0), b2, voffB); PG8_STAGE(PG8_SB(0, 1), b2 + hstepB, voffB); PG8_STAGE(PG8_SA(0, 0), a2, voffA);
;             PG8_WAIT_V(8); PG8_WAIT_L(0); PG8_BAR; PG8_MMA(1, 0, At, B0); PG8_MMA(1, 1, At, B1); PG8_BAR; PG8_SCHED;
;             PG8_LDB(B0, 1, 0); PG8_LDB(B1, 1, 1); PG8_SCHED; PG8_LDA(At, 1, 0); PG8_STAGE(PG8_SA(0, 1), a2 + hstepA, voffA);
;             PG8_WAIT_V(8); PG8_WAIT_L(0); PG8_BAR; PG8_MMA(0, 0, At, B0); PG8_MMA(0, 1, At, B1); PG8_BAR; PG8_SCHED;
;             PG8_LDA(At, 1, 1); PG8_STAGE(PG8_SB(1, 0), b3, voffB); PG8_STAGE(PG8_SB(1, 1), b3 + hstepB, voffB); PG8_STAGE(PG8_SA(1, 0), a3, voffA);
;             PG8_WAIT_V(8); PG8_WAIT_L(0); PG8_BAR; PG8_MMA(1, 0, At, B0); PG8_MMA(1, 1, At, B1); PG8_BAR; PG8_SCHED;
	s_add_i32 s12, s88, s43
	v_lshl_add_u64 v[174:175], v[174:175], 0, s[34:35]
	s_mov_b32 m0, s12
	ds_read_b128 v[198:201], v164 offset:49152
	ds_read_b128 v[202:205], v164 offset:50176
	ds_read_b128 v[206:209], v164 offset:51200
	ds_read_b128 v[210:213], v164 offset:52224
	ds_read_b128 v[214:217], v164 offset:53248
	ds_read_b128 v[218:221], v164 offset:54272
	ds_read_b128 v[222:225], v164 offset:55296
	ds_read_b128 v[226:229], v164 offset:56320
	global_load_lds_dwordx4 v[174:175], off
	s_add_i32 m0, s12, 0x2000
	s_add_u32 s10, s10, 0x40080
	v_lshl_add_u64 v[174:175], v[230:231], 0, s[34:35]
	s_addc_u32 s11, s11, 0
	s_add_i32 s12, s89, s43
	global_load_lds_dwordx4 v[174:175], off
	v_lshl_add_u64 v[174:175], s[10:11], 0, v[130:131]
	s_mov_b32 m0, s12
	s_nop 0
	global_load_lds_dwordx4 v[174:175], off
	v_lshl_add_u64 v[174:175], s[10:11], 0, v[134:135]
	s_add_i32 m0, s12, 0x2000
	s_nop 0
	global_load_lds_dwordx4 v[174:175], off
	v_lshl_add_u64 v[174:175], v[232:233], 0, s[34:35]
	s_mov_b32 m0, s77
	s_nop 0
	global_load_lds_dwordx4 v[174:175], off
	v_lshl_add_u64 v[174:175], v[234:235], 0, s[34:35]
	s_mov_b32 m0, s78
	s_nop 0
	global_load_lds_dwordx4 v[174:175], off
	s_waitcnt vmcnt(8)
	s_waitcnt lgkmcnt(0)
	s_barrier
	s_setprio 1
	s_waitcnt lgkmcnt(0)
	v_mfma_f32_16x16x32_bf16 v[60:63], v[146:149], v[198:201], v[60:63]
	v_mfma_f32_16x16x32_bf16 v[56:59], v[170:173], v[198:201], v[56:59]
	v_mfma_f32_16x16x32_bf16 v[52:55], v[146:149], v[206:209], v[52:55]
	v_mfma_f32_16x16x32_bf16 v[44:47], v[170:173], v[206:209], v[44:47]
	v_mfma_f32_16x16x32_bf16 v[36:39], v[146:149], v[214:217], v[36:39]
	v_mfma_f32_16x16x32_bf16 v[28:31], v[170:173], v[214:217], v[28:31]
	v_mfma_f32_16x16x32_bf16 v[20:23], v[146:149], v[222:225], v[20:23]
	v_mfma_f32_16x16x32_bf16 v[12:15], v[170:173], v[222:225], v[12:15]
	v_mfma_f32_16x16x32_bf16 v[60:63], v[166:169], v[202:205], v[60:63]
	v_mfma_f32_16x16x32_bf16 v[56:59], v[178:181], v[202:205], v[56:59]
	v_mfma_f32_16x16x32_bf16 v[52:55], v[166:169], v[210:213], v[52:55]
	v_mfma_f32_16x16x32_bf16 v[44:47], v[178:181], v[210:213], v[44:47]
	v_mfma_f32_16x16x32_bf16 v[36:39], v[166:169], v[218:221], v[36:39]
	v_mfma_f32_16x16x32_bf16 v[28:31], v[178:181], v[218:221], v[28:31]
	v_mfma_f32_16x16x32_bf16 v[20:23], v[166:169], v[226:229], v[20:23]
	v_mfma_f32_16x16x32_bf16 v[12:15], v[178:181], v[226:229], v[12:15]
	s_setprio 0
	s_setprio 1
	v_mfma_f32_16x16x32_bf16 v[48:51], v[182:185], v[198:201], v[48:51]
	v_mfma_f32_16x16x32_bf16 v[40:43], v[190:193], v[198:201], v[40:43]
	v_mfma_f32_16x16x32_bf16 v[32:35], v[182:185], v[206:209], v[32:35]
	v_mfma_f32_16x16x32_bf16 v[24:27], v[190:193], v[206:209], v[24:27]
	v_mfma_f32_16x16x32_bf16 v[16:19], v[182:185], v[214:217], v[16:19]
	v_mfma_f32_16x16x32_bf16 v[8:11], v[190:193], v[214:217], v[8:11]
	v_mfma_f32_16x16x32_bf16 v[4:7], v[182:185], v[222:225], v[4:7]
	v_mfma_f32_16x16x32_bf16 v[0:3], v[190:193], v[222:225], v[0:3]
	v_mfma_f32_16x16x32_bf16 v[48:51], v[186:189], v[202:205], v[48:51]
	v_mfma_f32_16x16x32_bf16 v[40:43], v[194:197], v[202:205], v[40:43]
	v_mfma_f32_16x16x32_bf16 v[32:35], v[186:189], v[210:213], v[32:35]
	v_mfma_f32_16x16x32_bf16 v[24:27], v[194:197], v[210:213], v[24:27]
	v_mfma_f32_16x16x32_bf16 v[16:19], v[186:189], v[218:221], v[16:19]
	v_mfma_f32_16x16x32_bf16 v[8:11], v[194:197], v[218:221], v[8:11]
	v_mfma_f32_16x16x32_bf16 v[4:7], v[186:189], v[226:229], v[4:7]
	v_mfma_f32_16x16x32_bf16 v[0:3], v[194:197], v[226:229], v[0:3]
	s_setprio 0
	s_barrier
	s_add_i32 s87, s87, 2
	s_add_u32 s8, s8, 0x100
	s_addc_u32 s9, s9, 0
	s_add_u32 s74, s74, 0x100
	s_addc_u32 s75, s75, 0
	s_cmp_gt_u32 s87, 13
.LBB0_1403:
	ds_read_b128 v[146:149], v162
	ds_read_b128 v[166:169], v162 offset:1024
	ds_read_b128 v[170:173], v162 offset:2048
	ds_read_b128 v[178:181], v162 offset:3072
	ds_read_b128 v[182:185], v163
	ds_read_b128 v[186:189], v163 offset:1024
	ds_read_b128 v[190:193], v163 offset:2048
	ds_read_b128 v[194:197], v163 offset:3072
	s_add_u32 s10, s8, 0xfffc0080
	s_addc_u32 s11, s9, -1
	s_cmp_eq_u32 s87, 12
	s_cselect_b32 s13, s1, s11
	s_cselect_b32 s12, s7, s10
	s_cselect_b32 s11, s65, s75
	s_cselect_b32 s10, s69, s74
	v_lshl_add_u64 v[174:175], s[8:9], 0, v[138:139]
	s_add_i32 m0, s53, 0xc000
	ds_read_b128 v[198:201], v164
	ds_read_b128 v[202:205], v164 offset:1024
	ds_read_b128 v[206:209], v164 offset:2048
	ds_read_b128 v[210:213], v164 offset:3072
	ds_read_b128 v[214:217], v164 offset:4096
	ds_read_b128 v[218:221], v164 offset:5120
	ds_read_b128 v[222:225], v164 offset:6144
	ds_read_b128 v[226:229], v164 offset:7168
	global_load_lds_dwordx4 v[174:175], off
	v_lshl_add_u64 v[174:175], s[8:9], 0, v[140:141]
	s_add_i32 m0, s53, 0xe000
	s_nop 0
	global_load_lds_dwordx4 v[174:175], off
	s_waitcnt vmcnt(8)
	s_waitcnt lgkmcnt(0)
	s_barrier
; #define PG8_STAGE(bufoff, gbase, voff) do { _Pragma("unroll") for (int _i = 0; _i < 2; ++_i) \
;         __builtin_amdgcn_global_load_lds((const unsigned*)((const char*)(gbase) + (voff)[_i]), (LAS unsigned*)(lds + (bufoff) + ldsw + _i * 8192), 16, 0, 0); } while (0)
; #define PG8_LDA(dst, b, h) do { _Pragma("unroll") for (int m = 0; m < 4; ++m) _Pragma("unroll") for (int k = 0; k < 2; ++k) dst[m][k] = *(const LAS bf16x8*)(lds + PG8_SA(b, h) + aoff + m * 2048 + k * 1024); } while (0)
; #define PG8_MMA(ai, bj, At, Bt) do { __builtin_amdgcn_s_setprio(1); _Pragma("unroll") for (int m = 0; m < 4; ++m) _Pragma("unroll") for (int n = 0; n < 2; ++n) _Pragma("unroll") for (int k = 0; k < 2; ++k) \
;         acc[ai][bj][m][n] = __builtin_amdgcn_mfma_f32_16x16x32_bf16(Bt[n][k], At[m][k], acc[ai][bj][m][n], 0, 0, 0); __builtin_amdgcn_s_setprio(0); } while (0)
; #define PG8_WAIT_V(n) asm volatile("s_waitcnt vmcnt(" #n ")" ::: "memory")
; #define PG8_WAIT_L(n) asm volatile("s_waitcnt lgkmcnt(" #n ")" ::: "memory")
; #define PG8_BAR __builtin_amdgcn_s_barrier()
; #define PG8_SCHED __builtin_amdgcn_sched_barrier(0)
; template <class Epi>
; __device__ __forceinline__ void gemm_phase(LAS unsigned char* lds, const Gemm g, const StaticOrder& S, const Epi& E) {
;     ...
;             PG8_WAIT_V(8); PG8_WAIT_L(0); PG8_BAR; PG8_MMA(0, 0, At, B0); PG8_MMA(0, 1, At, B1); PG8_BAR; PG8_SCHED;
;             PG8_LDA(At, 0, 1); PG8_STAGE(PG8_SB(0, 0), b2, voffB); PG8_STAGE(PG8_SB(0, 1), b2 + hstepB, voffB); PG8_STAGE(PG8_SA(0, 0), a2, voffA);
;             PG8_WAIT_V(8); PG8_WAIT_L(0); PG8_BAR; PG8_MMA(1, 0, At, B0); PG8_MMA(1, 1, At, B1); PG8_BAR; PG8_SCHED;
	s_setprio 1
	s_waitcnt lgkmcnt(0)
	v_mfma_f32_16x16x32_bf16 v[124:127], v[146:149], v[198:201], v[124:127]
	v_mfma_f32_16x16x32_bf16 v[120:123], v[170:173], v[198:201], v[120:123]
	v_mfma_f32_16x16x32_bf16 v[112:115], v[146:149], v[206:209], v[112:115]
	v_mfma_f32_16x16x32_bf16 v[104:107], v[170:173], v[206:209], v[104:107]
	v_mfma_f32_16x16x32_bf16 v[100:103], v[146:149], v[214:217], v[100:103]
	v_mfma_f32_16x16x32_bf16 v[92:95], v[170:173], v[214:217], v[92:95]
	v_mfma_f32_16x16x32_bf16 v[84:87], v[146:149], v[222:225], v[84:87]
	v_mfma_f32_16x16x32_bf16 v[76:79], v[170:173], v[222:225], v[76:79]
	v_mfma_f32_16x16x32_bf16 v[124:127], v[166:169], v[202:205], v[124:127]
	v_mfma_f32_16x16x32_bf16 v[120:123], v[178:181], v[202:205], v[120:123]
	v_mfma_f32_16x16x32_bf16 v[112:115], v[166:169], v[210:213], v[112:115]
	v_mfma_f32_16x16x32_bf16 v[104:107], v[178:181], v[210:213], v[104:107]
	v_mfma_f32_16x16x32_bf16 v[100:103], v[166:169], v[218:221], v[100:103]
	v_mfma_f32_16x16x32_bf16 v[92:95], v[178:181], v[218:221], v[92:95]
	v_mfma_f32_16x16x32_bf16 v[84:87], v[166:169], v[226:229], v[84:87]
	v_mfma_f32_16x16x32_bf16 v[76:79], v[178:181], v[226:229], v[76:79]
	s_setprio 0
	s_setprio 1
	v_mfma_f32_16x16x32_bf16 v[116:119], v[182:185], v[198:201], v[116:119]
	v_mfma_f32_16x16x32_bf16 v[108:111], v[190:193], v[198:201], v[108:111]
	v_mfma_f32_16x16x32_bf16 v[96:99], v[182:185], v[206:209], v[96:99]
	v_mfma_f32_16x16x32_bf16 v[88:91], v[190:193], v[206:209], v[88:91]
	v_mfma_f32_16x16x32_bf16 v[80:83], v[182:185], v[214:217], v[80:83]
	v_mfma_f32_16x16x32_bf16 v[72:75], v[190:193], v[214:217], v[72:75]
	v_mfma_f32_16x16x32_bf16 v[68:71], v[182:185], v[222:225], v[68:71]
	v_mfma_f32_16x16x32_bf16 v[64:67], v[190:193], v[222:225], v[64:67]
	v_mfma_f32_16x16x32_bf16 v[116:119], v[186:189], v[202:205], v[116:119]
	v_mfma_f32_16x16x32_bf16 v[108:111], v[194:197], v[202:205], v[108:111]
	v_mfma_f32_16x16x32_bf16 v[96:99], v[186:189], v[210:213], v[96:99]
	v_mfma_f32_16x16x32_bf16 v[88:91], v[194:197], v[210:213], v[88:91]
	v_mfma_f32_16x16x32_bf16 v[80:83], v[186:189], v[218:221], v[80:83]
	v_mfma_f32_16x16x32_bf16 v[72:75], v[194:197], v[218:221], v[72:75]
	v_mfma_f32_16x16x32_bf16 v[68:71], v[186:189], v[226:229], v[68:71]
	v_mfma_f32_16x16x32_bf16 v[64:67], v[194:197], v[226:229], v[64:67]
	s_setprio 0
	s_barrier
	s_add_i32 s88, s83, s43
	v_lshl_add_u64 v[174:175], s[10:11], 0, v[130:131]
	s_mov_b32 m0, s88
	ds_read_b128 v[198:201], v164 offset:16384
	ds_read_b128 v[202:205], v164 offset:17408
	ds_read_b128 v[206:209], v164 offset:18432
	ds_read_b128 v[210:213], v164 offset:19456
	ds_read_b128 v[214:217], v164 offset:20480
	ds_read_b128 v[218:221], v164 offset:21504
	ds_read_b128 v[222:225], v164 offset:22528
	ds_read_b128 v[226:229], v164 offset:23552
	global_load_lds_dwordx4 v[174:175], off
	s_add_i32 m0, s88, 0x2000
	s_add_u32 s88, s10, 0x40000
	v_lshl_add_u64 v[230:231], s[10:11], 0, v[134:135]
	s_addc_u32 s89, s11, 0
	s_add_i32 s90, s84, s43
	global_load_lds_dwordx4 v[230:231], off
	v_lshl_add_u64 v[232:233], s[88:89], 0, v[130:131]
	s_mov_b32 m0, s90
	v_lshl_add_u64 v[234:235], s[12:13], 0, v[132:133]
	global_load_lds_dwordx4 v[232:233], off
	v_lshl_add_u64 v[232:233], s[88:89], 0, v[134:135]
	s_add_i32 m0, s90, 0x2000
	s_nop 0
	global_load_lds_dwordx4 v[232:233], off
	v_lshl_add_u64 v[232:233], s[12:13], 0, v[128:129]
	s_mov_b32 m0, s53
	s_nop 0
	global_load_lds_dwordx4 v[232:233], off
	s_mov_b32 m0, s55
	s_nop 0
	global_load_lds_dwordx4 v[234:235], off
	s_waitcnt vmcnt(8)
	s_waitcnt lgkmcnt(0)
	s_nop 0
	s_barrier
	s_setprio 1
	s_waitcnt lgkmcnt(0)
	v_mfma_f32_16x16x32_bf16 v[60:63], v[146:149], v[198:201], v[60:63]
	v_mfma_f32_16x16x32_bf16 v[56:59], v[170:173], v[198:201], v[56:59]
	v_mfma_f32_16x16x32_bf16 v[52:55], v[146:149], v[206:209], v[52:55]
	v_mfma_f32_16x16x32_bf16 v[44:47], v[170:173], v[206:209], v[44:47]
	v_mfma_f32_16x16x32_bf16 v[36:39], v[146:149], v[214:217], v[36:39]
	v_mfma_f32_16x16x32_bf16 v[28:31], v[170:173], v[214:217], v[28:31]
	v_mfma_f32_16x16x32_bf16 v[20:23], v[146:149], v[222:225], v[20:23]
	v_mfma_f32_16x16x32_bf16 v[12:15], v[170:173], v[222:225], v[12:15]
	v_mfma_f32_16x16x32_bf16 v[60:63], v[166:169], v[202:205], v[60:63]
	v_mfma_f32_16x16x32_bf16 v[56:59], v[178:181], v[202:205], v[56:59]
	v_mfma_f32_16x16x32_bf16 v[52:55], v[166:169], v[210:213], v[52:55]
	v_mfma_f32_16x16x32_bf16 v[44:47], v[178:181], v[210:213], v[44:47]
	v_mfma_f32_16x16x32_bf16 v[36:39], v[166:169], v[218:221], v[36:39]
	v_mfma_f32_16x16x32_bf16 v[28:31], v[178:181], v[218:221], v[28:31]
	v_mfma_f32_16x16x32_bf16 v[20:23], v[166:169], v[226:229], v[20:23]
	v_mfma_f32_16x16x32_bf16 v[12:15], v[178:181], v[226:229], v[12:15]
	s_setprio 0
	s_setprio 1
	v_mfma_f32_16x16x32_bf16 v[48:51], v[182:185], v[198:201], v[48:51]
	v_mfma_f32_16x16x32_bf16 v[40:43], v[190:193], v[198:201], v[40:43]
	v_mfma_f32_16x16x32_bf16 v[32:35], v[182:185], v[206:209], v[32:35]
	v_mfma_f32_16x16x32_bf16 v[24:27], v[190:193], v[206:209], v[24:27]
	v_mfma_f32_16x16x32_bf16 v[16:19], v[182:185], v[214:217], v[16:19]
	v_mfma_f32_16x16x32_bf16 v[8:11], v[190:193], v[214:217], v[8:11]
	v_mfma_f32_16x16x32_bf16 v[4:7], v[182:185], v[222:225], v[4:7]
	v_mfma_f32_16x16x32_bf16 v[0:3], v[190:193], v[222:225], v[0:3]
	v_mfma_f32_16x16x32_bf16 v[48:51], v[186:189], v[202:205], v[48:51]
	v_mfma_f32_16x16x32_bf16 v[40:43], v[194:197], v[202:205], v[40:43]
	v_mfma_f32_16x16x32_bf16 v[32:35], v[186:189], v[210:213], v[32:35]
	v_mfma_f32_16x16x32_bf16 v[24:27], v[194:197], v[210:213], v[24:27]
	v_mfma_f32_16x16x32_bf16 v[16:19], v[186:189], v[218:221], v[16:19]
	v_mfma_f32_16x16x32_bf16 v[8:11], v[194:197], v[218:221], v[8:11]
	v_mfma_f32_16x16x32_bf16 v[4:7], v[186:189], v[226:229], v[4:7]
	v_mfma_f32_16x16x32_bf16 v[0:3], v[194:197], v[226:229], v[0:3]
	s_setprio 0
	s_barrier
; #define PG8_STAGE(bufoff, gbase, voff) do { _Pragma("unroll") for (int _i = 0; _i < 2; ++_i) \
;         __builtin_amdgcn_global_load_lds((const unsigned*)((const char*)(gbase) + (voff)[_i]), (LAS unsigned*)(lds + (bufoff) + ldsw + _i * 8192), 16, 0, 0); } while (0)
; #define PG8_LDA(dst, b, h) do { _Pragma("unroll") for (int m = 0; m < 4; ++m) _Pragma("unroll") for (int k = 0; k < 2; ++k) dst[m][k] = *(const LAS bf16x8*)(lds + PG8_SA(b, h) + aoff + m * 2048 + k * 1024); } while (0)
; #define PG8_LDB(dst, b, h) do { _Pragma("unroll") for (int n = 0; n < 2; ++n) _Pragma("unroll") for (int k = 0; k < 2; ++k) dst[n][k] = *(const LAS bf16x8*)(lds + PG8_SB(b, h) + boff + n * 2048 + k * 1024); } while (0)
; #define PG8_MMA(ai, bj, At, Bt) do { __builtin_amdgcn_s_setprio(1); _Pragma("unroll") for (int m = 0; m < 4; ++m) _Pragma("unroll") for (int n = 0; n < 2; ++n) _Pragma("unroll") for (int k = 0; k < 2; ++k) \
;         acc[ai][bj][m][n] = __builtin_amdgcn_mfma_f32_16x16x32_bf16(Bt[n][k], At[m][k], acc[ai][bj][m][n], 0, 0, 0); __builtin_amdgcn_s_setprio(0); } while (0)
; #define PG8_WAIT_V(n) asm volatile("s_waitcnt vmcnt(" #n ")" ::: "memory")
; #define PG8_WAIT_L(n) asm volatile("s_waitcnt lgkmcnt(" #n ")" ::: "memory")
; #define PG8_BAR __builtin_amdgcn_s_barrier()
; #define PG8_SCHED __builtin_amdgcn_sched_barrier(0)
; template <class Epi>
; __device__ __forceinline__ void gemm_phase(LAS unsigned char* lds, const Gemm g, const StaticOrder& S, const Epi& E) {
;     ...
;             PG8_LDB(B0, 1, 0); PG8_LDB(B1, 1, 1); PG8_SCHED; PG8_LDA(At, 1, 0); PG8_STAGE(PG8_SA(0, 1), a2 + hstepA, voffA);
;             PG8_WAIT_V(8); PG8_WAIT_L(0); PG8_BAR; PG8_MMA(0, 0, At, B0); PG8_MMA(0, 1, At, B1); PG8_BAR; PG8_SCHED;
	s_add_i32 s88, 0, 0x18000
	v_add_u32_e32 v136, s88, v161
	s_add_i32 s89, 0, 0x1c000
	ds_read_b128 v[146:149], v136
	ds_read_b128 v[166:169], v136 offset:1024
	ds_read_b128 v[170:173], v136 offset:2048
	ds_read_b128 v[178:181], v136 offset:3072
	v_add_u32_e32 v136, s89, v161
	ds_read_b128 v[182:185], v136
	ds_read_b128 v[186:189], v136 offset:1024
	ds_read_b128 v[190:193], v136 offset:2048
	ds_read_b128 v[194:197], v136 offset:3072
	s_add_u32 s12, s12, 0x40000
	s_addc_u32 s13, s13, 0
	s_mov_b32 m0, s57
	v_lshl_add_u64 v[236:237], s[12:13], 0, v[128:129]
	ds_read_b128 v[198:201], v164 offset:32768
	ds_read_b128 v[202:205], v164 offset:33792
	ds_read_b128 v[206:209], v164 offset:34816
	ds_read_b128 v[210:213], v164 offset:35840
	ds_read_b128 v[214:217], v164 offset:36864
	ds_read_b128 v[218:221], v164 offset:37888
	ds_read_b128 v[222:225], v164 offset:38912
	ds_read_b128 v[226:229], v164 offset:39936
	global_load_lds_dwordx4 v[236:237], off
	v_lshl_add_u64 v[236:237], s[12:13], 0, v[132:133]
	s_mov_b32 m0, s59
	s_nop 0
	global_load_lds_dwordx4 v[236:237], off
	s_waitcnt vmcnt(8)
	s_waitcnt lgkmcnt(0)
	s_nop 0
	s_barrier
	s_setprio 1
	s_waitcnt lgkmcnt(0)
	v_mfma_f32_16x16x32_bf16 v[124:127], v[146:149], v[198:201], v[124:127]
	v_mfma_f32_16x16x32_bf16 v[120:123], v[170:173], v[198:201], v[120:123]
	v_mfma_f32_16x16x32_bf16 v[112:115], v[146:149], v[206:209], v[112:115]
	v_mfma_f32_16x16x32_bf16 v[104:107], v[170:173], v[206:209], v[104:107]
	v_mfma_f32_16x16x32_bf16 v[100:103], v[146:149], v[214:217], v[100:103]
	v_mfma_f32_16x16x32_bf16 v[92:95], v[170:173], v[214:217], v[92:95]
	v_mfma_f32_16x16x32_bf16 v[84:87], v[146:149], v[222:225], v[84:87]
	v_mfma_f32_16x16x32_bf16 v[76:79], v[170:173], v[222:225], v[76:79]
	v_mfma_f32_16x16x32_bf16 v[124:127], v[166:169], v[202:205], v[124:127]
	v_mfma_f32_16x16x32_bf16 v[120:123], v[178:181], v[202:205], v[120:123]
	v_mfma_f32_16x16x32_bf16 v[112:115], v[166:169], v[210:213], v[112:115]
	v_mfma_f32_16x16x32_bf16 v[104:107], v[178:181], v[210:213], v[104:107]
	v_mfma_f32_16x16x32_bf16 v[100:103], v[166:169], v[218:221], v[100:103]
	v_mfma_f32_16x16x32_bf16 v[92:95], v[178:181], v[218:221], v[92:95]
	v_mfma_f32_16x16x32_bf16 v[84:87], v[166:169], v[226:229], v[84:87]
	v_mfma_f32_16x16x32_bf16 v[76:79], v[178:181], v[226:229], v[76:79]
	s_setprio 0
	s_setprio 1
	v_mfma_f32_16x16x32_bf16 v[116:119], v[182:185], v[198:201], v[116:119]
	v_mfma_f32_16x16x32_bf16 v[108:111], v[190:193], v[198:201], v[108:111]
	v_mfma_f32_16x16x32_bf16 v[96:99], v[182:185], v[206:209], v[96:99]
	v_mfma_f32_16x16x32_bf16 v[88:91], v[190:193], v[206:209], v[88:91]
	v_mfma_f32_16x16x32_bf16 v[80:83], v[182:185], v[214:217], v[80:83]
	v_mfma_f32_16x16x32_bf16 v[72:75], v[190:193], v[214:217], v[72:75]
	v_mfma_f32_16x16x32_bf16 v[68:71], v[182:185], v[222:225], v[68:71]
	v_mfma_f32_16x16x32_bf16 v[64:67], v[190:193], v[222:225], v[64:67]
	v_mfma_f32_16x16x32_bf16 v[116:119], v[186:189], v[202:205], v[116:119]
	v_mfma_f32_16x16x32_bf16 v[108:111], v[194:197], v[202:205], v[108:111]
	v_mfma_f32_16x16x32_bf16 v[96:99], v[186:189], v[210:213], v[96:99]
	v_mfma_f32_16x16x32_bf16 v[88:91], v[194:197], v[210:213], v[88:91]
	v_mfma_f32_16x16x32_bf16 v[80:83], v[186:189], v[218:221], v[80:83]
	v_mfma_f32_16x16x32_bf16 v[72:75], v[194:197], v[218:221], v[72:75]
	v_mfma_f32_16x16x32_bf16 v[68:71], v[186:189], v[226:229], v[68:71]
	v_mfma_f32_16x16x32_bf16 v[64:67], v[194:197], v[226:229], v[64:67]
	s_setprio 0
	s_barrier
; #define PG8_STAGE(bufoff, gbase, voff) do { _Pragma("unroll") for (int _i = 0; _i < 2; ++_i) \
;         __builtin_amdgcn_global_load_lds((const unsigned*)((const char*)(gbase) + (voff)[_i]), (LAS unsigned*)(lds + (bufoff) + ldsw + _i * 8192), 16, 0, 0); } while (0)
; #define PG8_LDA(dst, b, h) do { _Pragma("unroll") for (int m = 0; m < 4; ++m) _Pragma("unroll") for (int k = 0; k < 2; ++k) dst[m][k] = *(const LAS bf16x8*)(lds + PG8_SA(b, h) + aoff + m * 2048 + k * 1024); } while (0)
; #define PG8_MMA(ai, bj, At, Bt) do { __builtin_amdgcn_s_setprio(1); _Pragma("unroll") for (int m = 0; m < 4; ++m) _Pragma("unroll") for (int n = 0; n < 2; ++n) _Pragma("unroll") for (int k = 0; k < 2; ++k) \
;         acc[ai][bj][m][n] = __builtin_amdgcn_mfma_f32_16x16x32_bf16(Bt[n][k], At[m][k], acc[ai][bj][m][n], 0, 0, 0); __builtin_amdgcn_s_setprio(0); } while (0)
; #define PG8_WAIT_V(n) asm volatile("s_waitcnt vmcnt(" #n ")" ::: "memory")
; #define PG8_WAIT_L(n) asm volatile("s_waitcnt lgkmcnt(" #n ")" ::: "memory")
; #define PG8_BAR __builtin_amdgcn_s_barrier()
; #define PG8_SCHED __builtin_amdgcn_sched_barrier(0)
; template <class Epi>
; __device__ __forceinline__ void gemm_phase(LAS unsigned char* lds, const Gemm g, const StaticOrder& S, const Epi& E) {
;     ...
;             PG8_LDA(At, 1, 1); PG8_STAGE(PG8_SB(1, 0), b3, voffB); PG8_STAGE(PG8_SB(1, 1), b3 + hstepB, voffB); PG8_STAGE(PG8_SA(1, 0), a3, voffA);
;             PG8_WAIT_V(8); PG8_WAIT_L(0); PG8_BAR; PG8_MMA(1, 0, At, B0); PG8_MMA(1, 1, At, B1); PG8_BAR; PG8_SCHED;
;         }
;         if (wr == 0) PG8_BAR;
	s_add_i32 s12, s88, s43
	v_lshl_add_u64 v[174:175], v[174:175], 0, s[34:35]
	s_mov_b32 m0, s12
	ds_read_b128 v[198:201], v164 offset:49152
	ds_read_b128 v[202:205], v164 offset:50176
	ds_read_b128 v[206:209], v164 offset:51200
	ds_read_b128 v[210:213], v164 offset:52224
	ds_read_b128 v[214:217], v164 offset:53248
	ds_read_b128 v[218:221], v164 offset:54272
	ds_read_b128 v[222:225], v164 offset:55296
	ds_read_b128 v[226:229], v164 offset:56320
	global_load_lds_dwordx4 v[174:175], off
	s_add_i32 m0, s12, 0x2000
	s_add_u32 s10, s10, 0x40080
	v_lshl_add_u64 v[174:175], v[230:231], 0, s[34:35]
	s_addc_u32 s11, s11, 0
	s_add_i32 s12, s89, s43
	global_load_lds_dwordx4 v[174:175], off
	v_lshl_add_u64 v[174:175], s[10:11], 0, v[130:131]
	s_mov_b32 m0, s12
	s_nop 0
	global_load_lds_dwordx4 v[174:175], off
	v_lshl_add_u64 v[174:175], s[10:11], 0, v[134:135]
	s_add_i32 m0, s12, 0x2000
	s_nop 0
	global_load_lds_dwordx4 v[174:175], off
	v_lshl_add_u64 v[174:175], v[232:233], 0, s[34:35]
	s_mov_b32 m0, s77
	s_nop 0
	global_load_lds_dwordx4 v[174:175], off
	v_lshl_add_u64 v[174:175], v[234:235], 0, s[34:35]
	s_mov_b32 m0, s78
	s_nop 0
	global_load_lds_dwordx4 v[174:175], off
	s_waitcnt vmcnt(8)
	s_waitcnt lgkmcnt(0)
	s_barrier
	s_setprio 1
	s_waitcnt lgkmcnt(0)
	v_mfma_f32_16x16x32_bf16 v[60:63], v[146:149], v[198:201], v[60:63]
	v_mfma_f32_16x16x32_bf16 v[56:59], v[170:173], v[198:201], v[56:59]
	v_mfma_f32_16x16x32_bf16 v[52:55], v[146:149], v[206:209], v[52:55]
	v_mfma_f32_16x16x32_bf16 v[44:47], v[170:173], v[206:209], v[44:47]
	v_mfma_f32_16x16x32_bf16 v[36:39], v[146:149], v[214:217], v[36:39]
	v_mfma_f32_16x16x32_bf16 v[28:31], v[170:173], v[214:217], v[28:31]
	v_mfma_f32_16x16x32_bf16 v[20:23], v[146:149], v[222:225], v[20:23]
	v_mfma_f32_16x16x32_bf16 v[12:15], v[170:173], v[222:225], v[12:15]
	v_mfma_f32_16x16x32_bf16 v[60:63], v[166:169], v[202:205], v[60:63]
	v_mfma_f32_16x16x32_bf16 v[56:59], v[178:181], v[202:205], v[56:59]
	v_mfma_f32_16x16x32_bf16 v[52:55], v[166:169], v[210:213], v[52:55]
	v_mfma_f32_16x16x32_bf16 v[44:47], v[178:181], v[210:213], v[44:47]
	v_mfma_f32_16x16x32_bf16 v[36:39], v[166:169], v[218:221], v[36:39]
	v_mfma_f32_16x16x32_bf16 v[28:31], v[178:181], v[218:221], v[28:31]
	v_mfma_f32_16x16x32_bf16 v[20:23], v[166:169], v[226:229], v[20:23]
	v_mfma_f32_16x16x32_bf16 v[12:15], v[178:181], v[226:229], v[12:15]
	s_setprio 0
	s_setprio 1
	v_mfma_f32_16x16x32_bf16 v[48:51], v[182:185], v[198:201], v[48:51]
	v_mfma_f32_16x16x32_bf16 v[40:43], v[190:193], v[198:201], v[40:43]
	v_mfma_f32_16x16x32_bf16 v[32:35], v[182:185], v[206:209], v[32:35]
	v_mfma_f32_16x16x32_bf16 v[24:27], v[190:193], v[206:209], v[24:27]
	v_mfma_f32_16x16x32_bf16 v[16:19], v[182:185], v[214:217], v[16:19]
	v_mfma_f32_16x16x32_bf16 v[8:11], v[190:193], v[214:217], v[8:11]
	v_mfma_f32_16x16x32_bf16 v[4:7], v[182:185], v[222:225], v[4:7]
	v_mfma_f32_16x16x32_bf16 v[0:3], v[190:193], v[222:225], v[0:3]
	v_mfma_f32_16x16x32_bf16 v[48:51], v[186:189], v[202:205], v[48:51]
	v_mfma_f32_16x16x32_bf16 v[40:43], v[194:197], v[202:205], v[40:43]
	v_mfma_f32_16x16x32_bf16 v[32:35], v[186:189], v[210:213], v[32:35]
	v_mfma_f32_16x16x32_bf16 v[24:27], v[194:197], v[210:213], v[24:27]
	v_mfma_f32_16x16x32_bf16 v[16:19], v[186:189], v[218:221], v[16:19]
	v_mfma_f32_16x16x32_bf16 v[8:11], v[194:197], v[218:221], v[8:11]
	v_mfma_f32_16x16x32_bf16 v[4:7], v[186:189], v[226:229], v[4:7]
	v_mfma_f32_16x16x32_bf16 v[0:3], v[194:197], v[226:229], v[0:3]
	s_setprio 0
	s_barrier
	s_add_i32 s87, s87, 2
	s_add_u32 s8, s8, 0x100
	s_addc_u32 s9, s9, 0
	s_add_u32 s74, s74, 0x100
	s_addc_u32 s75, s75, 0
	s_cmp_gt_u32 s87, 13
	s_cbranch_scc0 .LBB0_1403
	s_and_b64 vcc, exec, s[38:39]
	s_cbranch_vccz .LBB0_1406
	s_barrier

; #define PG8_STAGE(bufoff, gbase, voff) do { _Pragma("unroll") for (int _i = 0; _i < 2; ++_i) \
;         __builtin_amdgcn_global_load_lds((const unsigned*)((const char*)(gbase) + (voff)[_i]), (LAS unsigned*)(lds + (bufoff) + ldsw + _i * 8192), 16, 0, 0); } while (0)
; #define PG8_LDA(dst, b, h) do { _Pragma("unroll") for (int m = 0; m < 4; ++m) _Pragma("unroll") for (int k = 0; k < 2; ++k) dst[m][k] = *(const LAS bf16x8*)(lds + PG8_SA(b, h) + aoff + m * 2048 + k * 1024); } while (0)
; #define PG8_LDB(dst, b, h) do { _Pragma("unroll") for (int n = 0; n < 2; ++n) _Pragma("unroll") for (int k = 0; k < 2; ++k) dst[n][k] = *(const LAS bf16x8*)(lds + PG8_SB(b, h) + boff + n * 2048 + k * 1024); } while (0)
; #define PG8_MMA(ai, bj, At, Bt) do { __builtin_amdgcn_s_setprio(1); _Pragma("unroll") for (int m = 0; m < 4; ++m) _Pragma("unroll") for (int n = 0; n < 2; ++n) _Pragma("unroll") for (int k = 0; k < 2; ++k) \
;         acc[ai][bj][m][n] = __builtin_amdgcn_mfma_f32_16x16x32_bf16(Bt[n][k], At[m][k], acc[ai][bj][m][n], 0, 0, 0); __builtin_amdgcn_s_setprio(0); } while (0)
; #define PG8_WAIT_V(n) asm volatile("s_waitcnt vmcnt(" #n ")" ::: "memory")
; template <class Epi>
; __device__ __forceinline__ void gemm_phase(LAS unsigned char* lds, const Gemm g, const StaticOrder& S, const Epi& E) {
;     ...
;         const char* nA = has_next ? (const char*)g.A + (size_t)nxt.pm * tstepA : cA; const char* nB = has_next ? (const char*)g.Bt + (size_t)nxt.pn * tstepB : cB;
; #pragma nounroll
;         for (int t = 0; t < nt; t += 2) {
;             const bool last = (t == nt - 2);
;             const char* a1 = cA + (size_t)(t + 1) * kstep;
;             const char* a2 = last ? nA : cA + (size_t)(t + 2) * kstep; const char* b2 = last ? nB : cB + (size_t)(t + 2) * kstep;
;             const char* a3 = a2 + kstep; const char* b3 = b2 + kstep;
;             PG8_LDB(B0, 0, 0); PG8_LDB(B1, 0, 1); PG8_SCHED; PG8_LDA(At, 0, 0); PG8_STAGE(PG8_SA(1, 1), a1 + hstepA, voffA);
;             PG8_WAIT_V(8); PG8_WAIT_L(0); PG8_BAR; PG8_MMA(0, 0, At, B0); PG8_MMA(0, 1, At, B1); PG8_BAR; PG8_SCHED;
;             PG8_LDA(At, 0, 1); PG8_STAGE(PG8_SB(0, 0), b2, voffB); PG8_STAGE(PG8_SB(0, 1), b2 + hstepB, voffB); PG8_STAGE(PG8_SA(0, 0), a2, voffA);
;             PG8_WAIT_V(8); PG8_WAIT_L(0); PG8_BAR; PG8_MMA(1, 0, At, B0); PG8_MMA(1, 1, At, B1); PG8_BAR; PG8_SCHED;
.LBB0_1469:
	s_add_u32 s62, s42, s56
	s_addc_u32 s63, s43, s57
	s_add_u32 s60, s62, 0x100
	s_addc_u32 s61, s63, 0
	s_and_b64 s[58:59], s[54:55], exec
	s_cselect_b32 s59, s1, s61
	s_cselect_b32 s58, s19, s60
	s_add_u32 s56, s38, s56
	s_addc_u32 s57, s39, s57
	s_add_u32 s56, s56, 0x100
	s_addc_u32 s57, s57, 0
	s_and_b64 s[54:55], s[54:55], exec
	s_cselect_b32 s61, s17, s57
	s_cselect_b32 s60, s84, s56
	s_add_u32 s64, s62, 0x10080
	ds_read_b128 v[140:143], v145
	ds_read_b128 v[154:157], v145 offset:1024
	ds_read_b128 v[158:161], v145 offset:2048
	ds_read_b128 v[162:165], v145 offset:3072
	ds_read_b128 v[166:169], v146
	ds_read_b128 v[170:173], v146 offset:1024
	ds_read_b128 v[178:181], v146 offset:2048
	ds_read_b128 v[182:185], v146 offset:3072
	s_addc_u32 s65, s63, 0
	s_add_i32 s94, s82, s70
	s_add_i32 m0, s35, 0xc000
	s_add_i32 s95, s35, 0xe000
	s_add_i32 s91, s94, 0x2000
	s_add_u32 s62, s60, 0x10000
	s_addc_u32 s63, s61, 0
	s_add_i32 s93, s83, s70
	s_add_i32 s92, s93, 0x2000
	s_add_i32 s90, 0, 0x18000
	s_add_i32 s89, 0, 0x1c000
	s_add_u32 s56, s58, 0x10000
	s_addc_u32 s57, s59, 0
	s_add_i32 s88, s90, s70
	s_add_i32 s86, s88, 0x2000
	s_add_u32 s54, s60, 0x10080
	s_addc_u32 s55, s61, 0
	s_add_i32 s87, s89, s70
	s_add_i32 s85, s87, 0x2000
	v_lshl_add_u64 v[174:175], s[64:65], 0, v[128:129]
	ds_read_b128 v[186:189], v147
	ds_read_b128 v[190:193], v147 offset:1024
	ds_read_b128 v[194:197], v147 offset:2048
	ds_read_b128 v[198:201], v147 offset:3072
	ds_read_b128 v[202:205], v147 offset:4096
	ds_read_b128 v[206:209], v147 offset:5120
	ds_read_b128 v[210:213], v147 offset:6144
	ds_read_b128 v[214:217], v147 offset:7168
	global_load_lds_dwordx4 v[174:175], off
	v_lshl_add_u64 v[174:175], s[64:65], 0, v[132:133]
	s_mov_b32 m0, s95
	s_nop 0
	global_load_lds_dwordx4 v[174:175], off
	s_waitcnt vmcnt(8)
	s_waitcnt lgkmcnt(0)
	s_nop 0
	s_barrier
	s_setprio 1
	s_waitcnt lgkmcnt(0)
	v_mfma_f32_16x16x32_bf16 v[124:127], v[140:143], v[186:189], v[124:127]
	v_mfma_f32_16x16x32_bf16 v[120:123], v[158:161], v[186:189], v[120:123]
	v_mfma_f32_16x16x32_bf16 v[108:111], v[140:143], v[194:197], v[108:111]
	v_mfma_f32_16x16x32_bf16 v[104:107], v[158:161], v[194:197], v[104:107]
	v_mfma_f32_16x16x32_bf16 v[92:95], v[140:143], v[202:205], v[92:95]
	v_mfma_f32_16x16x32_bf16 v[88:91], v[158:161], v[202:205], v[88:91]
	v_mfma_f32_16x16x32_bf16 v[76:79], v[140:143], v[210:213], v[76:79]
	v_mfma_f32_16x16x32_bf16 v[72:75], v[158:161], v[210:213], v[72:75]
	v_mfma_f32_16x16x32_bf16 v[124:127], v[154:157], v[190:193], v[124:127]
	v_mfma_f32_16x16x32_bf16 v[120:123], v[162:165], v[190:193], v[120:123]
	v_mfma_f32_16x16x32_bf16 v[108:111], v[154:157], v[198:201], v[108:111]
	v_mfma_f32_16x16x32_bf16 v[104:107], v[162:165], v[198:201], v[104:107]
	v_mfma_f32_16x16x32_bf16 v[92:95], v[154:157], v[206:209], v[92:95]
	v_mfma_f32_16x16x32_bf16 v[88:91], v[162:165], v[206:209], v[88:91]
	v_mfma_f32_16x16x32_bf16 v[76:79], v[154:157], v[214:217], v[76:79]
	v_mfma_f32_16x16x32_bf16 v[72:75], v[162:165], v[214:217], v[72:75]
	s_setprio 0
	s_setprio 1
	v_mfma_f32_16x16x32_bf16 v[116:119], v[166:169], v[186:189], v[116:119]
	v_mfma_f32_16x16x32_bf16 v[112:115], v[178:181], v[186:189], v[112:115]
	v_mfma_f32_16x16x32_bf16 v[100:103], v[166:169], v[194:197], v[100:103]
	v_mfma_f32_16x16x32_bf16 v[96:99], v[178:181], v[194:197], v[96:99]
	v_mfma_f32_16x16x32_bf16 v[84:87], v[166:169], v[202:205], v[84:87]
	v_mfma_f32_16x16x32_bf16 v[80:83], v[178:181], v[202:205], v[80:83]
	v_mfma_f32_16x16x32_bf16 v[68:71], v[166:169], v[210:213], v[68:71]
	v_mfma_f32_16x16x32_bf16 v[64:67], v[178:181], v[210:213], v[64:67]
	v_mfma_f32_16x16x32_bf16 v[116:119], v[170:173], v[190:193], v[116:119]
	v_mfma_f32_16x16x32_bf16 v[112:115], v[182:185], v[190:193], v[112:115]
	v_mfma_f32_16x16x32_bf16 v[100:103], v[170:173], v[198:201], v[100:103]
	v_mfma_f32_16x16x32_bf16 v[96:99], v[182:185], v[198:201], v[96:99]
	v_mfma_f32_16x16x32_bf16 v[84:87], v[170:173], v[206:209], v[84:87]
	v_mfma_f32_16x16x32_bf16 v[80:83], v[182:185], v[206:209], v[80:83]
	v_mfma_f32_16x16x32_bf16 v[68:71], v[170:173], v[214:217], v[68:71]
	v_mfma_f32_16x16x32_bf16 v[64:67], v[182:185], v[214:217], v[64:67]
	s_setprio 0
	s_barrier
	s_mov_b32 m0, s94
	v_lshl_add_u64 v[174:175], s[60:61], 0, v[130:131]
	ds_read_b128 v[186:189], v147 offset:16384
	ds_read_b128 v[190:193], v147 offset:17408
	ds_read_b128 v[194:197], v147 offset:18432
	ds_read_b128 v[198:201], v147 offset:19456
	ds_read_b128 v[202:205], v147 offset:20480
	ds_read_b128 v[206:209], v147 offset:21504
	ds_read_b128 v[210:213], v147 offset:22528
	ds_read_b128 v[214:217], v147 offset:23552
	global_load_lds_dwordx4 v[174:175], off
	v_lshl_add_u64 v[218:219], s[60:61], 0, v[134:135]
	s_mov_b32 m0, s91
	v_lshl_add_u64 v[220:221], s[62:63], 0, v[130:131]
	global_load_lds_dwordx4 v[218:219], off
	s_mov_b32 m0, s93
	v_lshl_add_u64 v[222:223], s[58:59], 0, v[132:133]
	global_load_lds_dwordx4 v[220:221], off
	v_lshl_add_u64 v[220:221], s[62:63], 0, v[134:135]
	s_mov_b32 m0, s92
	s_nop 0
	global_load_lds_dwordx4 v[220:221], off
	v_lshl_add_u64 v[220:221], s[58:59], 0, v[128:129]
	s_mov_b32 m0, s35
	s_nop 0
	global_load_lds_dwordx4 v[220:221], off
	s_mov_b32 m0, s71
	s_nop 0
	global_load_lds_dwordx4 v[222:223], off
	s_waitcnt vmcnt(8)
	s_waitcnt lgkmcnt(0)
	s_barrier
; #define PG8_STAGE(bufoff, gbase, voff) do { _Pragma("unroll") for (int _i = 0; _i < 2; ++_i) \
;         __builtin_amdgcn_global_load_lds((const unsigned*)((const char*)(gbase) + (voff)[_i]), (LAS unsigned*)(lds + (bufoff) + ldsw + _i * 8192), 16, 0, 0); } while (0)
; #define PG8_LDA(dst, b, h) do { _Pragma("unroll") for (int m = 0; m < 4; ++m) _Pragma("unroll") for (int k = 0; k < 2; ++k) dst[m][k] = *(const LAS bf16x8*)(lds + PG8_SA(b, h) + aoff + m * 2048 + k * 1024); } while (0)
; #define PG8_LDB(dst, b, h) do { _Pragma("unroll") for (int n = 0; n < 2; ++n) _Pragma("unroll") for (int k = 0; k < 2; ++k) dst[n][k] = *(const LAS bf16x8*)(lds + PG8_SB(b, h) + boff + n * 2048 + k * 1024); } while (0)
; #define PG8_MMA(ai, bj, At, Bt) do { __builtin_amdgcn_s_setprio(1); _Pragma("unroll") for (int m = 0; m < 4; ++m) _Pragma("unroll") for (int n = 0; n < 2; ++n) _Pragma("unroll") for (int k = 0; k < 2; ++k) \
;         acc[ai][bj][m][n] = __builtin_amdgcn_mfma_f32_16x16x32_bf16(Bt[n][k], At[m][k], acc[ai][bj][m][n], 0, 0, 0); __builtin_amdgcn_s_setprio(0); } while (0)
; #define PG8_WAIT_V(n) asm volatile("s_waitcnt vmcnt(" #n ")" ::: "memory")
; #define PG8_WAIT_L(n) asm volatile("s_waitcnt lgkmcnt(" #n ")" ::: "memory")
; #define PG8_BAR __builtin_amdgcn_s_barrier()
; #define PG8_SCHED __builtin_amdgcn_sched_barrier(0)
; template <class Epi>
; __device__ __forceinline__ void gemm_phase(LAS unsigned char* lds, const Gemm g, const StaticOrder& S, const Epi& E) {
;     ...
;             PG8_WAIT_V(8); PG8_WAIT_L(0); PG8_BAR; PG8_MMA(1, 0, At, B0); PG8_MMA(1, 1, At, B1); PG8_BAR; PG8_SCHED;
;             PG8_LDB(B0, 1, 0); PG8_LDB(B1, 1, 1); PG8_SCHED; PG8_LDA(At, 1, 0); PG8_STAGE(PG8_SA(0, 1), a2 + hstepA, voffA);
;             PG8_WAIT_V(8); PG8_WAIT_L(0); PG8_BAR; PG8_MMA(0, 0, At, B0); PG8_MMA(0, 1, At, B1); PG8_BAR; PG8_SCHED;
	s_setprio 1
	s_waitcnt lgkmcnt(0)
	v_mfma_f32_16x16x32_bf16 v[60:63], v[140:143], v[186:189], v[60:63]
	v_mfma_f32_16x16x32_bf16 v[56:59], v[158:161], v[186:189], v[56:59]
	v_mfma_f32_16x16x32_bf16 v[44:47], v[140:143], v[194:197], v[44:47]
	v_mfma_f32_16x16x32_bf16 v[40:43], v[158:161], v[194:197], v[40:43]
	v_mfma_f32_16x16x32_bf16 v[28:31], v[140:143], v[202:205], v[28:31]
	v_mfma_f32_16x16x32_bf16 v[24:27], v[158:161], v[202:205], v[24:27]
	v_mfma_f32_16x16x32_bf16 v[12:15], v[140:143], v[210:213], v[12:15]
	v_mfma_f32_16x16x32_bf16 v[8:11], v[158:161], v[210:213], v[8:11]
	v_mfma_f32_16x16x32_bf16 v[60:63], v[154:157], v[190:193], v[60:63]
	v_mfma_f32_16x16x32_bf16 v[56:59], v[162:165], v[190:193], v[56:59]
	v_mfma_f32_16x16x32_bf16 v[44:47], v[154:157], v[198:201], v[44:47]
	v_mfma_f32_16x16x32_bf16 v[40:43], v[162:165], v[198:201], v[40:43]
	v_mfma_f32_16x16x32_bf16 v[28:31], v[154:157], v[206:209], v[28:31]
	v_mfma_f32_16x16x32_bf16 v[24:27], v[162:165], v[206:209], v[24:27]
	v_mfma_f32_16x16x32_bf16 v[12:15], v[154:157], v[214:217], v[12:15]
	v_mfma_f32_16x16x32_bf16 v[8:11], v[162:165], v[214:217], v[8:11]
	s_setprio 0
	s_setprio 1
	v_mfma_f32_16x16x32_bf16 v[52:55], v[166:169], v[186:189], v[52:55]
	v_mfma_f32_16x16x32_bf16 v[48:51], v[178:181], v[186:189], v[48:51]
	v_mfma_f32_16x16x32_bf16 v[36:39], v[166:169], v[194:197], v[36:39]
	v_mfma_f32_16x16x32_bf16 v[32:35], v[178:181], v[194:197], v[32:35]
	v_mfma_f32_16x16x32_bf16 v[20:23], v[166:169], v[202:205], v[20:23]
	v_mfma_f32_16x16x32_bf16 v[16:19], v[178:181], v[202:205], v[16:19]
	v_mfma_f32_16x16x32_bf16 v[4:7], v[166:169], v[210:213], v[4:7]
	v_mfma_f32_16x16x32_bf16 v[0:3], v[178:181], v[210:213], v[0:3]
	v_mfma_f32_16x16x32_bf16 v[52:55], v[170:173], v[190:193], v[52:55]
	v_mfma_f32_16x16x32_bf16 v[48:51], v[182:185], v[190:193], v[48:51]
	v_mfma_f32_16x16x32_bf16 v[36:39], v[170:173], v[198:201], v[36:39]
	v_mfma_f32_16x16x32_bf16 v[32:35], v[182:185], v[198:201], v[32:35]
	v_mfma_f32_16x16x32_bf16 v[20:23], v[170:173], v[206:209], v[20:23]
	v_mfma_f32_16x16x32_bf16 v[16:19], v[182:185], v[206:209], v[16:19]
	v_mfma_f32_16x16x32_bf16 v[4:7], v[170:173], v[214:217], v[4:7]
	v_mfma_f32_16x16x32_bf16 v[0:3], v[182:185], v[214:217], v[0:3]
	s_setprio 0
	s_barrier
	v_add_u32_e32 v149, s90, v144
	ds_read_b128 v[140:143], v149
	ds_read_b128 v[154:157], v149 offset:1024
	ds_read_b128 v[158:161], v149 offset:2048
	ds_read_b128 v[162:165], v149 offset:3072
	v_add_u32_e32 v149, s89, v144
	ds_read_b128 v[166:169], v149
	ds_read_b128 v[170:173], v149 offset:1024
	ds_read_b128 v[178:181], v149 offset:2048
	ds_read_b128 v[182:185], v149 offset:3072
	s_mov_b32 m0, s72
	v_lshl_add_u64 v[224:225], s[56:57], 0, v[128:129]
	ds_read_b128 v[186:189], v147 offset:32768
	ds_read_b128 v[190:193], v147 offset:33792
	ds_read_b128 v[194:197], v147 offset:34816
	ds_read_b128 v[198:201], v147 offset:35840
	ds_read_b128 v[202:205], v147 offset:36864
	ds_read_b128 v[206:209], v147 offset:37888
	ds_read_b128 v[210:213], v147 offset:38912
	ds_read_b128 v[214:217], v147 offset:39936
	global_load_lds_dwordx4 v[224:225], off
	v_lshl_add_u64 v[224:225], s[56:57], 0, v[132:133]
	s_mov_b32 m0, s73
	s_nop 0
	global_load_lds_dwordx4 v[224:225], off
	s_waitcnt vmcnt(8)
	s_waitcnt lgkmcnt(0)
	s_barrier
	s_setprio 1
	s_waitcnt lgkmcnt(0)
	v_mfma_f32_16x16x32_bf16 v[124:127], v[140:143], v[186:189], v[124:127]
	v_mfma_f32_16x16x32_bf16 v[120:123], v[158:161], v[186:189], v[120:123]
	v_mfma_f32_16x16x32_bf16 v[108:111], v[140:143], v[194:197], v[108:111]
	v_mfma_f32_16x16x32_bf16 v[104:107], v[158:161], v[194:197], v[104:107]
	v_mfma_f32_16x16x32_bf16 v[92:95], v[140:143], v[202:205], v[92:95]
	v_mfma_f32_16x16x32_bf16 v[88:91], v[158:161], v[202:205], v[88:91]
	v_mfma_f32_16x16x32_bf16 v[76:79], v[140:143], v[210:213], v[76:79]
	v_mfma_f32_16x16x32_bf16 v[72:75], v[158:161], v[210:213], v[72:75]
	v_mfma_f32_16x16x32_bf16 v[124:127], v[154:157], v[190:193], v[124:127]
	v_mfma_f32_16x16x32_bf16 v[120:123], v[162:165], v[190:193], v[120:123]
	v_mfma_f32_16x16x32_bf16 v[108:111], v[154:157], v[198:201], v[108:111]
	v_mfma_f32_16x16x32_bf16 v[104:107], v[162:165], v[198:201], v[104:107]
	v_mfma_f32_16x16x32_bf16 v[92:95], v[154:157], v[206:209], v[92:95]
	v_mfma_f32_16x16x32_bf16 v[88:91], v[162:165], v[206:209], v[88:91]
	v_mfma_f32_16x16x32_bf16 v[76:79], v[154:157], v[214:217], v[76:79]
	v_mfma_f32_16x16x32_bf16 v[72:75], v[162:165], v[214:217], v[72:75]
	s_setprio 0
	s_setprio 1
	v_mfma_f32_16x16x32_bf16 v[116:119], v[166:169], v[186:189], v[116:119]
	v_mfma_f32_16x16x32_bf16 v[112:115], v[178:181], v[186:189], v[112:115]
	v_mfma_f32_16x16x32_bf16 v[100:103], v[166:169], v[194:197], v[100:103]
	v_mfma_f32_16x16x32_bf16 v[96:99], v[178:181], v[194:197], v[96:99]
	v_mfma_f32_16x16x32_bf16 v[84:87], v[166:169], v[202:205], v[84:87]
	v_mfma_f32_16x16x32_bf16 v[80:83], v[178:181], v[202:205], v[80:83]
	v_mfma_f32_16x16x32_bf16 v[68:71], v[166:169], v[210:213], v[68:71]
	v_mfma_f32_16x16x32_bf16 v[64:67], v[178:181], v[210:213], v[64:67]
	v_mfma_f32_16x16x32_bf16 v[116:119], v[170:173], v[190:193], v[116:119]
	v_mfma_f32_16x16x32_bf16 v[112:115], v[182:185], v[190:193], v[112:115]
	v_mfma_f32_16x16x32_bf16 v[100:103], v[170:173], v[198:201], v[100:103]
	v_mfma_f32_16x16x32_bf16 v[96:99], v[182:185], v[198:201], v[96:99]
	v_mfma_f32_16x16x32_bf16 v[84:87], v[170:173], v[206:209], v[84:87]
	v_mfma_f32_16x16x32_bf16 v[80:83], v[182:185], v[206:209], v[80:83]
	v_mfma_f32_16x16x32_bf16 v[68:71], v[170:173], v[214:217], v[68:71]
	v_mfma_f32_16x16x32_bf16 v[64:67], v[182:185], v[214:217], v[64:67]
	s_setprio 0
	s_barrier
; #define PG8_STAGE(bufoff, gbase, voff) do { _Pragma("unroll") for (int _i = 0; _i < 2; ++_i) \
;         __builtin_amdgcn_global_load_lds((const unsigned*)((const char*)(gbase) + (voff)[_i]), (LAS unsigned*)(lds + (bufoff) + ldsw + _i * 8192), 16, 0, 0); } while (0)
; #define PG8_LDA(dst, b, h) do { _Pragma("unroll") for (int m = 0; m < 4; ++m) _Pragma("unroll") for (int k = 0; k < 2; ++k) dst[m][k] = *(const LAS bf16x8*)(lds + PG8_SA(b, h) + aoff + m * 2048 + k * 1024); } while (0)
; #define PG8_MMA(ai, bj, At, Bt) do { __builtin_amdgcn_s_setprio(1); _Pragma("unroll") for (int m = 0; m < 4; ++m) _Pragma("unroll") for (int n = 0; n < 2; ++n) _Pragma("unroll") for (int k = 0; k < 2; ++k) \
;         acc[ai][bj][m][n] = __builtin_amdgcn_mfma_f32_16x16x32_bf16(Bt[n][k], At[m][k], acc[ai][bj][m][n], 0, 0, 0); __builtin_amdgcn_s_setprio(0); } while (0)
; #define PG8_WAIT_V(n) asm volatile("s_waitcnt vmcnt(" #n ")" ::: "memory")
; #define PG8_WAIT_L(n) asm volatile("s_waitcnt lgkmcnt(" #n ")" ::: "memory")
; #define PG8_BAR __builtin_amdgcn_s_barrier()
; #define PG8_SCHED __builtin_amdgcn_sched_barrier(0)
; template <class Epi>
; __device__ __forceinline__ void gemm_phase(LAS unsigned char* lds, const Gemm g, const StaticOrder& S, const Epi& E) {
;     ...
;             PG8_LDA(At, 1, 1); PG8_STAGE(PG8_SB(1, 0), b3, voffB); PG8_STAGE(PG8_SB(1, 1), b3 + hstepB, voffB); PG8_STAGE(PG8_SA(1, 0), a3, voffA);
;             PG8_WAIT_V(8); PG8_WAIT_L(0); PG8_BAR; PG8_MMA(1, 0, At, B0); PG8_MMA(1, 1, At, B1); PG8_BAR; PG8_SCHED;
;         }
;         if (wr == 0) PG8_BAR;
	s_mov_b32 m0, s88
	v_lshl_add_u64 v[174:175], v[174:175], 0, s[10:11]
	ds_read_b128 v[186:189], v147 offset:49152
	ds_read_b128 v[190:193], v147 offset:50176
	ds_read_b128 v[194:197], v147 offset:51200
	ds_read_b128 v[198:201], v147 offset:52224
	ds_read_b128 v[202:205], v147 offset:53248
	ds_read_b128 v[206:209], v147 offset:54272
	ds_read_b128 v[210:213], v147 offset:55296
	ds_read_b128 v[214:217], v147 offset:56320
	global_load_lds_dwordx4 v[174:175], off
	v_lshl_add_u64 v[174:175], v[218:219], 0, s[10:11]
	s_mov_b32 m0, s86
	s_nop 0
	global_load_lds_dwordx4 v[174:175], off
	v_lshl_add_u64 v[174:175], s[54:55], 0, v[130:131]
	s_mov_b32 m0, s87
	s_nop 0
	global_load_lds_dwordx4 v[174:175], off
	v_lshl_add_u64 v[174:175], s[54:55], 0, v[134:135]
	s_mov_b32 m0, s85
	s_nop 0
	global_load_lds_dwordx4 v[174:175], off
	v_lshl_add_u64 v[174:175], v[220:221], 0, s[10:11]
	s_mov_b32 m0, s77
	s_nop 0
	global_load_lds_dwordx4 v[174:175], off
	v_lshl_add_u64 v[174:175], v[222:223], 0, s[10:11]
	s_mov_b32 m0, s78
	s_nop 0
	global_load_lds_dwordx4 v[174:175], off
	s_waitcnt vmcnt(8)
	s_waitcnt lgkmcnt(0)
	s_barrier
	s_setprio 1
	s_waitcnt lgkmcnt(0)
	v_mfma_f32_16x16x32_bf16 v[60:63], v[140:143], v[186:189], v[60:63]
	v_mfma_f32_16x16x32_bf16 v[56:59], v[158:161], v[186:189], v[56:59]
	v_mfma_f32_16x16x32_bf16 v[44:47], v[140:143], v[194:197], v[44:47]
	v_mfma_f32_16x16x32_bf16 v[40:43], v[158:161], v[194:197], v[40:43]
	v_mfma_f32_16x16x32_bf16 v[28:31], v[140:143], v[202:205], v[28:31]
	v_mfma_f32_16x16x32_bf16 v[24:27], v[158:161], v[202:205], v[24:27]
	v_mfma_f32_16x16x32_bf16 v[12:15], v[140:143], v[210:213], v[12:15]
	v_mfma_f32_16x16x32_bf16 v[8:11], v[158:161], v[210:213], v[8:11]
	v_mfma_f32_16x16x32_bf16 v[60:63], v[154:157], v[190:193], v[60:63]
	v_mfma_f32_16x16x32_bf16 v[56:59], v[162:165], v[190:193], v[56:59]
	v_mfma_f32_16x16x32_bf16 v[44:47], v[154:157], v[198:201], v[44:47]
	v_mfma_f32_16x16x32_bf16 v[40:43], v[162:165], v[198:201], v[40:43]
	v_mfma_f32_16x16x32_bf16 v[28:31], v[154:157], v[206:209], v[28:31]
	v_mfma_f32_16x16x32_bf16 v[24:27], v[162:165], v[206:209], v[24:27]
	v_mfma_f32_16x16x32_bf16 v[12:15], v[154:157], v[214:217], v[12:15]
	v_mfma_f32_16x16x32_bf16 v[8:11], v[162:165], v[214:217], v[8:11]
	s_setprio 0
	s_setprio 1
	v_mfma_f32_16x16x32_bf16 v[52:55], v[166:169], v[186:189], v[52:55]
	v_mfma_f32_16x16x32_bf16 v[48:51], v[178:181], v[186:189], v[48:51]
	v_mfma_f32_16x16x32_bf16 v[36:39], v[166:169], v[194:197], v[36:39]
	v_mfma_f32_16x16x32_bf16 v[32:35], v[178:181], v[194:197], v[32:35]
	v_mfma_f32_16x16x32_bf16 v[20:23], v[166:169], v[202:205], v[20:23]
	v_mfma_f32_16x16x32_bf16 v[16:19], v[178:181], v[202:205], v[16:19]
	v_mfma_f32_16x16x32_bf16 v[4:7], v[166:169], v[210:213], v[4:7]
	v_mfma_f32_16x16x32_bf16 v[0:3], v[178:181], v[210:213], v[0:3]
	v_mfma_f32_16x16x32_bf16 v[52:55], v[170:173], v[190:193], v[52:55]
	v_mfma_f32_16x16x32_bf16 v[48:51], v[182:185], v[190:193], v[48:51]
	v_mfma_f32_16x16x32_bf16 v[36:39], v[170:173], v[198:201], v[36:39]
	v_mfma_f32_16x16x32_bf16 v[32:35], v[182:185], v[198:201], v[32:35]
	v_mfma_f32_16x16x32_bf16 v[20:23], v[170:173], v[206:209], v[20:23]
	v_mfma_f32_16x16x32_bf16 v[16:19], v[182:185], v[206:209], v[16:19]
	v_mfma_f32_16x16x32_bf16 v[4:7], v[170:173], v[214:217], v[4:7]
	v_mfma_f32_16x16x32_bf16 v[0:3], v[182:185], v[214:217], v[0:3]
	s_setprio 0
	s_barrier
	s_andn2_b64 vcc, exec, s[52:53]
	s_mov_b64 s[54:55], -1
	s_mov_b64 s[52:53], 0
	s_mov_b64 s[56:57], 0x100
	s_cbranch_vccz .LBB0_1469
	s_and_b64 vcc, exec, s[12:13]
	s_cbranch_vccz .LBB0_1472
	s_barrier

; #define PG8_STAGE(bufoff, gbase, voff) do { _Pragma("unroll") for (int _i = 0; _i < 2; ++_i) \
;         __builtin_amdgcn_global_load_lds((const unsigned*)((const char*)(gbase) + (voff)[_i]), (LAS unsigned*)(lds + (bufoff) + ldsw + _i * 8192), 16, 0, 0); } while (0)
; #define PG8_LDA(dst, b, h) do { _Pragma("unroll") for (int m = 0; m < 4; ++m) _Pragma("unroll") for (int k = 0; k < 2; ++k) dst[m][k] = *(const LAS bf16x8*)(lds + PG8_SA(b, h) + aoff + m * 2048 + k * 1024); } while (0)
; #define PG8_LDB(dst, b, h) do { _Pragma("unroll") for (int n = 0; n < 2; ++n) _Pragma("unroll") for (int k = 0; k < 2; ++k) dst[n][k] = *(const LAS bf16x8*)(lds + PG8_SB(b, h) + boff + n * 2048 + k * 1024); } while (0)
; #define PG8_MMA(ai, bj, At, Bt) do { __builtin_amdgcn_s_setprio(1); _Pragma("unroll") for (int m = 0; m < 4; ++m) _Pragma("unroll") for (int n = 0; n < 2; ++n) _Pragma("unroll") for (int k = 0; k < 2; ++k) \
;         acc[ai][bj][m][n] = __builtin_amdgcn_mfma_f32_16x16x32_bf16(Bt[n][k], At[m][k], acc[ai][bj][m][n], 0, 0, 0); __builtin_amdgcn_s_setprio(0); } while (0)
; #define PG8_WAIT_V(n) asm volatile("s_waitcnt vmcnt(" #n ")" ::: "memory")
; #define PG8_WAIT_L(n) asm volatile("s_waitcnt lgkmcnt(" #n ")" ::: "memory")
; #define PG8_BAR __builtin_amdgcn_s_barrier()
; #define PG8_SCHED __builtin_amdgcn_sched_barrier(0)
; template <class Epi>
; __device__ __forceinline__ void gemm_phase(LAS unsigned char* lds, const Gemm g, const StaticOrder& S, const Epi& E) {
;     ...
;             const bool last = (t == nt - 2);
;             const char* a1 = cA + (size_t)(t + 1) * kstep;
;             const char* a2 = last ? nA : cA + (size_t)(t + 2) * kstep; const char* b2 = last ? nB : cB + (size_t)(t + 2) * kstep;
;             const char* a3 = a2 + kstep; const char* b3 = b2 + kstep;
;             PG8_LDB(B0, 0, 0); PG8_LDB(B1, 0, 1); PG8_SCHED; PG8_LDA(At, 0, 0); PG8_STAGE(PG8_SA(1, 1), a1 + hstepA, voffA);
;             PG8_WAIT_V(8); PG8_WAIT_L(0); PG8_BAR; PG8_MMA(0, 0, At, B0); PG8_MMA(0, 1, At, B1); PG8_BAR; PG8_SCHED;
;             PG8_LDA(At, 0, 1); PG8_STAGE(PG8_SB(0, 0), b2, voffB); PG8_STAGE(PG8_SB(0, 1), b2 + hstepB, voffB); PG8_STAGE(PG8_SA(0, 0), a2, voffA);
;             PG8_WAIT_V(8); PG8_WAIT_L(0); PG8_BAR; PG8_MMA(1, 0, At, B0); PG8_MMA(1, 1, At, B1); PG8_BAR; PG8_SCHED;
.LBB0_1648:
	s_add_u32 s0, s0, 0xb0080
	s_addc_u32 s1, s1, 0
	s_add_u32 s61, s20, 0x100
	s_addc_u32 s62, s21, 0
	s_mov_b32 s63, -2
	s_waitcnt lgkmcnt(0)
	ds_read_b128 v[128:131], v182
	ds_read_b128 v[132:135], v182 offset:1024
	ds_read_b128 v[136:139], v182 offset:2048
	ds_read_b128 v[140:143], v182 offset:3072
	ds_read_b128 v[160:163], v183
	ds_read_b128 v[164:167], v183 offset:1024
	ds_read_b128 v[168:171], v183 offset:2048
	ds_read_b128 v[172:175], v183 offset:3072
	s_add_u32 s20, s0, 0xfff50080
	s_addc_u32 s21, s1, -1
	s_cmp_eq_u32 s63, 40
	s_cselect_b32 s23, s7, s21
	s_cselect_b32 s22, s6, s20
	s_cselect_b32 s21, s19, s62
	s_cselect_b32 s20, s18, s61
	v_lshl_add_u64 v[178:179], s[0:1], 0, v[152:153]
	s_add_i32 m0, s33, 0xc000
	ds_read_b128 v[186:189], v184
	ds_read_b128 v[190:193], v184 offset:1024
	ds_read_b128 v[194:197], v184 offset:2048
	ds_read_b128 v[198:201], v184 offset:3072
	ds_read_b128 v[202:205], v184 offset:4096
	ds_read_b128 v[206:209], v184 offset:5120
	ds_read_b128 v[210:213], v184 offset:6144
	ds_read_b128 v[214:217], v184 offset:7168
	global_load_lds_dwordx4 v[178:179], off
	v_lshl_add_u64 v[178:179], s[0:1], 0, v[154:155]
	s_add_i32 m0, s33, 0xe000
	s_nop 0
	global_load_lds_dwordx4 v[178:179], off
	s_waitcnt vmcnt(8)
	s_waitcnt lgkmcnt(0)
	s_barrier
	s_setprio 1
	s_waitcnt lgkmcnt(0)
	v_mfma_f32_16x16x32_bf16 v[124:127], v[128:131], v[186:189], 0
	v_mfma_f32_16x16x32_bf16 v[120:123], v[136:139], v[186:189], 0
	v_mfma_f32_16x16x32_bf16 v[108:111], v[128:131], v[194:197], 0
	v_mfma_f32_16x16x32_bf16 v[104:107], v[136:139], v[194:197], 0
	v_mfma_f32_16x16x32_bf16 v[92:95], v[128:131], v[202:205], 0
	v_mfma_f32_16x16x32_bf16 v[88:91], v[136:139], v[202:205], 0
	v_mfma_f32_16x16x32_bf16 v[76:79], v[128:131], v[210:213], 0
	v_mfma_f32_16x16x32_bf16 v[72:75], v[136:139], v[210:213], 0
	v_mfma_f32_16x16x32_bf16 v[124:127], v[132:135], v[190:193], v[124:127]
	v_mfma_f32_16x16x32_bf16 v[120:123], v[140:143], v[190:193], v[120:123]
	v_mfma_f32_16x16x32_bf16 v[108:111], v[132:135], v[198:201], v[108:111]
	v_mfma_f32_16x16x32_bf16 v[104:107], v[140:143], v[198:201], v[104:107]
	v_mfma_f32_16x16x32_bf16 v[92:95], v[132:135], v[206:209], v[92:95]
	v_mfma_f32_16x16x32_bf16 v[88:91], v[140:143], v[206:209], v[88:91]
	v_mfma_f32_16x16x32_bf16 v[76:79], v[132:135], v[214:217], v[76:79]
	v_mfma_f32_16x16x32_bf16 v[72:75], v[140:143], v[214:217], v[72:75]
	s_setprio 0
	s_setprio 1
	v_mfma_f32_16x16x32_bf16 v[116:119], v[160:163], v[186:189], 0
	v_mfma_f32_16x16x32_bf16 v[112:115], v[168:171], v[186:189], 0
	v_mfma_f32_16x16x32_bf16 v[100:103], v[160:163], v[194:197], 0
	v_mfma_f32_16x16x32_bf16 v[96:99], v[168:171], v[194:197], 0
	v_mfma_f32_16x16x32_bf16 v[84:87], v[160:163], v[202:205], 0
	v_mfma_f32_16x16x32_bf16 v[80:83], v[168:171], v[202:205], 0
	v_mfma_f32_16x16x32_bf16 v[68:71], v[160:163], v[210:213], 0
	v_mfma_f32_16x16x32_bf16 v[64:67], v[168:171], v[210:213], 0
	v_mfma_f32_16x16x32_bf16 v[116:119], v[164:167], v[190:193], v[116:119]
	v_mfma_f32_16x16x32_bf16 v[112:115], v[172:175], v[190:193], v[112:115]
	v_mfma_f32_16x16x32_bf16 v[100:103], v[164:167], v[198:201], v[100:103]
	v_mfma_f32_16x16x32_bf16 v[96:99], v[172:175], v[198:201], v[96:99]
	v_mfma_f32_16x16x32_bf16 v[84:87], v[164:167], v[206:209], v[84:87]
	v_mfma_f32_16x16x32_bf16 v[80:83], v[172:175], v[206:209], v[80:83]
	v_mfma_f32_16x16x32_bf16 v[68:71], v[164:167], v[214:217], v[68:71]
	v_mfma_f32_16x16x32_bf16 v[64:67], v[172:175], v[214:217], v[64:67]
	s_setprio 0
	s_barrier
	s_add_i32 s64, s55, s29
	v_lshl_add_u64 v[178:179], s[20:21], 0, v[146:147]
	s_mov_b32 m0, s64
	ds_read_b128 v[186:189], v184 offset:16384
	ds_read_b128 v[190:193], v184 offset:17408
	ds_read_b128 v[194:197], v184 offset:18432
	ds_read_b128 v[198:201], v184 offset:19456
	ds_read_b128 v[202:205], v184 offset:20480
	ds_read_b128 v[206:209], v184 offset:21504
	ds_read_b128 v[210:213], v184 offset:22528
	ds_read_b128 v[214:217], v184 offset:23552
	global_load_lds_dwordx4 v[178:179], off
	s_add_i32 m0, s64, 0x2000
	s_add_u32 s64, s20, 0xb0000
	v_lshl_add_u64 v[218:219], s[20:21], 0, v[150:151]
	s_addc_u32 s65, s21, 0
	s_add_i32 s66, s56, s29
	global_load_lds_dwordx4 v[218:219], off
	v_lshl_add_u64 v[220:221], s[64:65], 0, v[146:147]
	s_mov_b32 m0, s66
	v_lshl_add_u64 v[222:223], s[22:23], 0, v[148:149]
	global_load_lds_dwordx4 v[220:221], off
	v_lshl_add_u64 v[220:221], s[64:65], 0, v[150:151]
	s_add_i32 m0, s66, 0x2000
	s_nop 0
	global_load_lds_dwordx4 v[220:221], off
	v_lshl_add_u64 v[220:221], s[22:23], 0, v[144:145]
	s_mov_b32 m0, s33
	s_nop 0
	global_load_lds_dwordx4 v[220:221], off
	s_mov_b32 m0, s34
	s_nop 0
	global_load_lds_dwordx4 v[222:223], off
	s_waitcnt vmcnt(8)
	s_waitcnt lgkmcnt(0)
	s_nop 0
	s_barrier
; #define PG8_STAGE(bufoff, gbase, voff) do { _Pragma("unroll") for (int _i = 0; _i < 2; ++_i) \
;         __builtin_amdgcn_global_load_lds((const unsigned*)((const char*)(gbase) + (voff)[_i]), (LAS unsigned*)(lds + (bufoff) + ldsw + _i * 8192), 16, 0, 0); } while (0)
; #define PG8_LDA(dst, b, h) do { _Pragma("unroll") for (int m = 0; m < 4; ++m) _Pragma("unroll") for (int k = 0; k < 2; ++k) dst[m][k] = *(const LAS bf16x8*)(lds + PG8_SA(b, h) + aoff + m * 2048 + k * 1024); } while (0)
; #define PG8_LDB(dst, b, h) do { _Pragma("unroll") for (int n = 0; n < 2; ++n) _Pragma("unroll") for (int k = 0; k < 2; ++k) dst[n][k] = *(const LAS bf16x8*)(lds + PG8_SB(b, h) + boff + n * 2048 + k * 1024); } while (0)
; #define PG8_MMA(ai, bj, At, Bt) do { __builtin_amdgcn_s_setprio(1); _Pragma("unroll") for (int m = 0; m < 4; ++m) _Pragma("unroll") for (int n = 0; n < 2; ++n) _Pragma("unroll") for (int k = 0; k < 2; ++k) \
;         acc[ai][bj][m][n] = __builtin_amdgcn_mfma_f32_16x16x32_bf16(Bt[n][k], At[m][k], acc[ai][bj][m][n], 0, 0, 0); __builtin_amdgcn_s_setprio(0); } while (0)
; #define PG8_WAIT_V(n) asm volatile("s_waitcnt vmcnt(" #n ")" ::: "memory")
; #define PG8_WAIT_L(n) asm volatile("s_waitcnt lgkmcnt(" #n ")" ::: "memory")
; #define PG8_BAR __builtin_amdgcn_s_barrier()
; #define PG8_SCHED __builtin_amdgcn_sched_barrier(0)
; template <class Epi>
; __device__ __forceinline__ void gemm_phase(LAS unsigned char* lds, const Gemm g, const StaticOrder& S, const Epi& E) {
;     ...
;             PG8_WAIT_V(8); PG8_WAIT_L(0); PG8_BAR; PG8_MMA(1, 0, At, B0); PG8_MMA(1, 1, At, B1); PG8_BAR; PG8_SCHED;
;             PG8_LDB(B0, 1, 0); PG8_LDB(B1, 1, 1); PG8_SCHED; PG8_LDA(At, 1, 0); PG8_STAGE(PG8_SA(0, 1), a2 + hstepA, voffA);
;             PG8_WAIT_V(8); PG8_WAIT_L(0); PG8_BAR; PG8_MMA(0, 0, At, B0); PG8_MMA(0, 1, At, B1); PG8_BAR; PG8_SCHED;
	s_setprio 1
	s_waitcnt lgkmcnt(0)
	v_mfma_f32_16x16x32_bf16 v[60:63], v[128:131], v[186:189], 0
	v_mfma_f32_16x16x32_bf16 v[56:59], v[136:139], v[186:189], 0
	v_mfma_f32_16x16x32_bf16 v[44:47], v[128:131], v[194:197], 0
	v_mfma_f32_16x16x32_bf16 v[40:43], v[136:139], v[194:197], 0
	v_mfma_f32_16x16x32_bf16 v[28:31], v[128:131], v[202:205], 0
	v_mfma_f32_16x16x32_bf16 v[24:27], v[136:139], v[202:205], 0
	v_mfma_f32_16x16x32_bf16 v[12:15], v[128:131], v[210:213], 0
	v_mfma_f32_16x16x32_bf16 v[8:11], v[136:139], v[210:213], 0
	v_mfma_f32_16x16x32_bf16 v[60:63], v[132:135], v[190:193], v[60:63]
	v_mfma_f32_16x16x32_bf16 v[56:59], v[140:143], v[190:193], v[56:59]
	v_mfma_f32_16x16x32_bf16 v[44:47], v[132:135], v[198:201], v[44:47]
	v_mfma_f32_16x16x32_bf16 v[40:43], v[140:143], v[198:201], v[40:43]
	v_mfma_f32_16x16x32_bf16 v[28:31], v[132:135], v[206:209], v[28:31]
	v_mfma_f32_16x16x32_bf16 v[24:27], v[140:143], v[206:209], v[24:27]
	v_mfma_f32_16x16x32_bf16 v[12:15], v[132:135], v[214:217], v[12:15]
	v_mfma_f32_16x16x32_bf16 v[8:11], v[140:143], v[214:217], v[8:11]
	s_setprio 0
	s_setprio 1
	v_mfma_f32_16x16x32_bf16 v[52:55], v[160:163], v[186:189], 0
	v_mfma_f32_16x16x32_bf16 v[48:51], v[168:171], v[186:189], 0
	v_mfma_f32_16x16x32_bf16 v[36:39], v[160:163], v[194:197], 0
	v_mfma_f32_16x16x32_bf16 v[32:35], v[168:171], v[194:197], 0
	v_mfma_f32_16x16x32_bf16 v[20:23], v[160:163], v[202:205], 0
	v_mfma_f32_16x16x32_bf16 v[16:19], v[168:171], v[202:205], 0
	v_mfma_f32_16x16x32_bf16 v[4:7], v[160:163], v[210:213], 0
	v_mfma_f32_16x16x32_bf16 v[0:3], v[168:171], v[210:213], 0
	v_mfma_f32_16x16x32_bf16 v[52:55], v[164:167], v[190:193], v[52:55]
	v_mfma_f32_16x16x32_bf16 v[48:51], v[172:175], v[190:193], v[48:51]
	v_mfma_f32_16x16x32_bf16 v[36:39], v[164:167], v[198:201], v[36:39]
	v_mfma_f32_16x16x32_bf16 v[32:35], v[172:175], v[198:201], v[32:35]
	v_mfma_f32_16x16x32_bf16 v[20:23], v[164:167], v[206:209], v[20:23]
	v_mfma_f32_16x16x32_bf16 v[16:19], v[172:175], v[206:209], v[16:19]
	v_mfma_f32_16x16x32_bf16 v[4:7], v[164:167], v[214:217], v[4:7]
	v_mfma_f32_16x16x32_bf16 v[0:3], v[172:175], v[214:217], v[0:3]
	s_setprio 0
	s_barrier
	s_add_i32 s64, 0, 0x18000
	s_add_i32 s65, 0, 0x1c000
	v_add_u32_e32 v140, s64, v181
	v_add_u32_e32 v172, s65, v181
	ds_read_b128 v[128:131], v140
	ds_read_b128 v[132:135], v140 offset:1024
	ds_read_b128 v[136:139], v140 offset:2048
	ds_read_b128 v[140:143], v140 offset:3072
	ds_read_b128 v[160:163], v172
	ds_read_b128 v[164:167], v172 offset:1024
	ds_read_b128 v[168:171], v172 offset:2048
	ds_read_b128 v[172:175], v172 offset:3072
	s_add_u32 s22, s22, 0xb0000
	s_addc_u32 s23, s23, 0
	s_mov_b32 m0, s35
	v_lshl_add_u64 v[224:225], s[22:23], 0, v[144:145]
	ds_read_b128 v[186:189], v184 offset:32768
	ds_read_b128 v[190:193], v184 offset:33792
	ds_read_b128 v[194:197], v184 offset:34816
	ds_read_b128 v[198:201], v184 offset:35840
	ds_read_b128 v[202:205], v184 offset:36864
	ds_read_b128 v[206:209], v184 offset:37888
	ds_read_b128 v[210:213], v184 offset:38912
	ds_read_b128 v[214:217], v184 offset:39936
	global_load_lds_dwordx4 v[224:225], off
	v_lshl_add_u64 v[224:225], s[22:23], 0, v[148:149]
	s_mov_b32 m0, s36
	s_nop 0
	global_load_lds_dwordx4 v[224:225], off
	s_waitcnt vmcnt(8)
	s_waitcnt lgkmcnt(0)
	s_nop 0
	s_barrier
	s_setprio 1
	s_waitcnt lgkmcnt(0)
	v_mfma_f32_16x16x32_bf16 v[124:127], v[128:131], v[186:189], v[124:127]
	v_mfma_f32_16x16x32_bf16 v[120:123], v[136:139], v[186:189], v[120:123]
	v_mfma_f32_16x16x32_bf16 v[108:111], v[128:131], v[194:197], v[108:111]
	v_mfma_f32_16x16x32_bf16 v[104:107], v[136:139], v[194:197], v[104:107]
	v_mfma_f32_16x16x32_bf16 v[92:95], v[128:131], v[202:205], v[92:95]
	v_mfma_f32_16x16x32_bf16 v[88:91], v[136:139], v[202:205], v[88:91]
	v_mfma_f32_16x16x32_bf16 v[76:79], v[128:131], v[210:213], v[76:79]
	v_mfma_f32_16x16x32_bf16 v[72:75], v[136:139], v[210:213], v[72:75]
	v_mfma_f32_16x16x32_bf16 v[124:127], v[132:135], v[190:193], v[124:127]
	v_mfma_f32_16x16x32_bf16 v[120:123], v[140:143], v[190:193], v[120:123]
	v_mfma_f32_16x16x32_bf16 v[108:111], v[132:135], v[198:201], v[108:111]
	v_mfma_f32_16x16x32_bf16 v[104:107], v[140:143], v[198:201], v[104:107]
	v_mfma_f32_16x16x32_bf16 v[92:95], v[132:135], v[206:209], v[92:95]
	v_mfma_f32_16x16x32_bf16 v[88:91], v[140:143], v[206:209], v[88:91]
	v_mfma_f32_16x16x32_bf16 v[76:79], v[132:135], v[214:217], v[76:79]
	v_mfma_f32_16x16x32_bf16 v[72:75], v[140:143], v[214:217], v[72:75]
	s_setprio 0
	s_setprio 1
	v_mfma_f32_16x16x32_bf16 v[116:119], v[160:163], v[186:189], v[116:119]
	v_mfma_f32_16x16x32_bf16 v[112:115], v[168:171], v[186:189], v[112:115]
	v_mfma_f32_16x16x32_bf16 v[100:103], v[160:163], v[194:197], v[100:103]
	v_mfma_f32_16x16x32_bf16 v[96:99], v[168:171], v[194:197], v[96:99]
	v_mfma_f32_16x16x32_bf16 v[84:87], v[160:163], v[202:205], v[84:87]
	v_mfma_f32_16x16x32_bf16 v[80:83], v[168:171], v[202:205], v[80:83]
	v_mfma_f32_16x16x32_bf16 v[68:71], v[160:163], v[210:213], v[68:71]
	v_mfma_f32_16x16x32_bf16 v[64:67], v[168:171], v[210:213], v[64:67]
	v_mfma_f32_16x16x32_bf16 v[116:119], v[164:167], v[190:193], v[116:119]
	v_mfma_f32_16x16x32_bf16 v[112:115], v[172:175], v[190:193], v[112:115]
	v_mfma_f32_16x16x32_bf16 v[100:103], v[164:167], v[198:201], v[100:103]
	v_mfma_f32_16x16x32_bf16 v[96:99], v[172:175], v[198:201], v[96:99]
	v_mfma_f32_16x16x32_bf16 v[84:87], v[164:167], v[206:209], v[84:87]
	v_mfma_f32_16x16x32_bf16 v[80:83], v[172:175], v[206:209], v[80:83]
	v_mfma_f32_16x16x32_bf16 v[68:71], v[164:167], v[214:217], v[68:71]
	v_mfma_f32_16x16x32_bf16 v[64:67], v[172:175], v[214:217], v[64:67]
	s_setprio 0
	s_barrier
; #define PG8_STAGE(bufoff, gbase, voff) do { _Pragma("unroll") for (int _i = 0; _i < 2; ++_i) \
;         __builtin_amdgcn_global_load_lds((const unsigned*)((const char*)(gbase) + (voff)[_i]), (LAS unsigned*)(lds + (bufoff) + ldsw + _i * 8192), 16, 0, 0); } while (0)
; #define PG8_LDA(dst, b, h) do { _Pragma("unroll") for (int m = 0; m < 4; ++m) _Pragma("unroll") for (int k = 0; k < 2; ++k) dst[m][k] = *(const LAS bf16x8*)(lds + PG8_SA(b, h) + aoff + m * 2048 + k * 1024); } while (0)
; #define PG8_LDB(dst, b, h) do { _Pragma("unroll") for (int n = 0; n < 2; ++n) _Pragma("unroll") for (int k = 0; k < 2; ++k) dst[n][k] = *(const LAS bf16x8*)(lds + PG8_SB(b, h) + boff + n * 2048 + k * 1024); } while (0)
; #define PG8_MMA(ai, bj, At, Bt) do { __builtin_amdgcn_s_setprio(1); _Pragma("unroll") for (int m = 0; m < 4; ++m) _Pragma("unroll") for (int n = 0; n < 2; ++n) _Pragma("unroll") for (int k = 0; k < 2; ++k) \
;         acc[ai][bj][m][n] = __builtin_amdgcn_mfma_f32_16x16x32_bf16(Bt[n][k], At[m][k], acc[ai][bj][m][n], 0, 0, 0); __builtin_amdgcn_s_setprio(0); } while (0)
; #define PG8_WAIT_V(n) asm volatile("s_waitcnt vmcnt(" #n ")" ::: "memory")
; #define PG8_WAIT_L(n) asm volatile("s_waitcnt lgkmcnt(" #n ")" ::: "memory")
; #define PG8_BAR __builtin_amdgcn_s_barrier()
; #define PG8_SCHED __builtin_amdgcn_sched_barrier(0)
; template <class Epi>
; __device__ __forceinline__ void gemm_phase(LAS unsigned char* lds, const Gemm g, const StaticOrder& S, const Epi& E) {
;     ...
;             const char* a1 = cA + (size_t)(t + 1) * kstep;
;             const char* a2 = last ? nA : cA + (size_t)(t + 2) * kstep; const char* b2 = last ? nB : cB + (size_t)(t + 2) * kstep;
;             const char* a3 = a2 + kstep; const char* b3 = b2 + kstep;
;             PG8_LDB(B0, 0, 0); PG8_LDB(B1, 0, 1); PG8_SCHED; PG8_LDA(At, 0, 0); PG8_STAGE(PG8_SA(1, 1), a1 + hstepA, voffA);
;             PG8_WAIT_V(8); PG8_WAIT_L(0); PG8_BAR; PG8_MMA(0, 0, At, B0); PG8_MMA(0, 1, At, B1); PG8_BAR; PG8_SCHED;
;     ...
;             PG8_LDA(At, 1, 1); PG8_STAGE(PG8_SB(1, 0), b3, voffB); PG8_STAGE(PG8_SB(1, 1), b3 + hstepB, voffB); PG8_STAGE(PG8_SA(1, 0), a3, voffA);
;             PG8_WAIT_V(8); PG8_WAIT_L(0); PG8_BAR; PG8_MMA(1, 0, At, B0); PG8_MMA(1, 1, At, B1); PG8_BAR; PG8_SCHED;
	s_add_i32 s22, s64, s29
	v_lshl_add_u64 v[178:179], v[178:179], 0, s[14:15]
	s_mov_b32 m0, s22
	ds_read_b128 v[186:189], v184 offset:49152
	ds_read_b128 v[190:193], v184 offset:50176
	ds_read_b128 v[194:197], v184 offset:51200
	ds_read_b128 v[198:201], v184 offset:52224
	ds_read_b128 v[202:205], v184 offset:53248
	ds_read_b128 v[206:209], v184 offset:54272
	ds_read_b128 v[210:213], v184 offset:55296
	ds_read_b128 v[214:217], v184 offset:56320
	global_load_lds_dwordx4 v[178:179], off
	s_add_i32 m0, s22, 0x2000
	s_add_u32 s20, s20, 0xb0080
	v_lshl_add_u64 v[178:179], v[218:219], 0, s[14:15]
	s_addc_u32 s21, s21, 0
	s_add_i32 s22, s65, s29
	global_load_lds_dwordx4 v[178:179], off
	v_lshl_add_u64 v[178:179], s[20:21], 0, v[146:147]
	s_mov_b32 m0, s22
	s_nop 0
	global_load_lds_dwordx4 v[178:179], off
	v_lshl_add_u64 v[178:179], s[20:21], 0, v[150:151]
	s_add_i32 m0, s22, 0x2000
	s_nop 0
	global_load_lds_dwordx4 v[178:179], off
	v_lshl_add_u64 v[178:179], v[220:221], 0, s[14:15]
	s_mov_b32 m0, s42
	s_nop 0
	global_load_lds_dwordx4 v[178:179], off
	v_lshl_add_u64 v[178:179], v[222:223], 0, s[14:15]
	s_mov_b32 m0, s43
	s_nop 0
	global_load_lds_dwordx4 v[178:179], off
	s_waitcnt vmcnt(8)
	s_waitcnt lgkmcnt(0)
	s_barrier
	s_setprio 1
	s_waitcnt lgkmcnt(0)
	v_mfma_f32_16x16x32_bf16 v[60:63], v[128:131], v[186:189], v[60:63]
	v_mfma_f32_16x16x32_bf16 v[56:59], v[136:139], v[186:189], v[56:59]
	v_mfma_f32_16x16x32_bf16 v[44:47], v[128:131], v[194:197], v[44:47]
	v_mfma_f32_16x16x32_bf16 v[40:43], v[136:139], v[194:197], v[40:43]
	v_mfma_f32_16x16x32_bf16 v[28:31], v[128:131], v[202:205], v[28:31]
	v_mfma_f32_16x16x32_bf16 v[24:27], v[136:139], v[202:205], v[24:27]
	v_mfma_f32_16x16x32_bf16 v[12:15], v[128:131], v[210:213], v[12:15]
	v_mfma_f32_16x16x32_bf16 v[8:11], v[136:139], v[210:213], v[8:11]
	v_mfma_f32_16x16x32_bf16 v[60:63], v[132:135], v[190:193], v[60:63]
	v_mfma_f32_16x16x32_bf16 v[56:59], v[140:143], v[190:193], v[56:59]
	v_mfma_f32_16x16x32_bf16 v[44:47], v[132:135], v[198:201], v[44:47]
	v_mfma_f32_16x16x32_bf16 v[40:43], v[140:143], v[198:201], v[40:43]
	v_mfma_f32_16x16x32_bf16 v[28:31], v[132:135], v[206:209], v[28:31]
	v_mfma_f32_16x16x32_bf16 v[24:27], v[140:143], v[206:209], v[24:27]
	v_mfma_f32_16x16x32_bf16 v[12:15], v[132:135], v[214:217], v[12:15]
	v_mfma_f32_16x16x32_bf16 v[8:11], v[140:143], v[214:217], v[8:11]
	s_setprio 0
	s_setprio 1
	v_mfma_f32_16x16x32_bf16 v[52:55], v[160:163], v[186:189], v[52:55]
	v_mfma_f32_16x16x32_bf16 v[48:51], v[168:171], v[186:189], v[48:51]
	v_mfma_f32_16x16x32_bf16 v[36:39], v[160:163], v[194:197], v[36:39]
	v_mfma_f32_16x16x32_bf16 v[32:35], v[168:171], v[194:197], v[32:35]
	v_mfma_f32_16x16x32_bf16 v[20:23], v[160:163], v[202:205], v[20:23]
	v_mfma_f32_16x16x32_bf16 v[16:19], v[168:171], v[202:205], v[16:19]
	v_mfma_f32_16x16x32_bf16 v[4:7], v[160:163], v[210:213], v[4:7]
	v_mfma_f32_16x16x32_bf16 v[0:3], v[168:171], v[210:213], v[0:3]
	v_mfma_f32_16x16x32_bf16 v[52:55], v[164:167], v[190:193], v[52:55]
	v_mfma_f32_16x16x32_bf16 v[48:51], v[172:175], v[190:193], v[48:51]
	v_mfma_f32_16x16x32_bf16 v[36:39], v[164:167], v[198:201], v[36:39]
	v_mfma_f32_16x16x32_bf16 v[32:35], v[172:175], v[198:201], v[32:35]
	v_mfma_f32_16x16x32_bf16 v[20:23], v[164:167], v[206:209], v[20:23]
	v_mfma_f32_16x16x32_bf16 v[16:19], v[172:175], v[206:209], v[16:19]
	v_mfma_f32_16x16x32_bf16 v[4:7], v[164:167], v[214:217], v[4:7]
	v_mfma_f32_16x16x32_bf16 v[0:3], v[172:175], v[214:217], v[0:3]
	s_setprio 0
	s_barrier
	s_add_i32 s63, s63, 2
	s_add_u32 s0, s0, 0x100
	s_addc_u32 s1, s1, 0
	s_add_u32 s61, s61, 0x100
	s_addc_u32 s62, s62, 0
	s_cmp_gt_u32 s63, 41
.LBB0_1649:
	ds_read_b128 v[128:131], v182
	ds_read_b128 v[132:135], v182 offset:1024
	ds_read_b128 v[136:139], v182 offset:2048
	ds_read_b128 v[140:143], v182 offset:3072
	ds_read_b128 v[160:163], v183
	ds_read_b128 v[164:167], v183 offset:1024
	ds_read_b128 v[168:171], v183 offset:2048
	ds_read_b128 v[172:175], v183 offset:3072
	s_add_u32 s20, s0, 0xfff50080
	s_addc_u32 s21, s1, -1
	s_cmp_eq_u32 s63, 40
	s_cselect_b32 s23, s7, s21
	s_cselect_b32 s22, s6, s20
	s_cselect_b32 s21, s19, s62
	s_cselect_b32 s20, s18, s61
	v_lshl_add_u64 v[178:179], s[0:1], 0, v[152:153]
	s_add_i32 m0, s33, 0xc000
	ds_read_b128 v[186:189], v184
	ds_read_b128 v[190:193], v184 offset:1024
	ds_read_b128 v[194:197], v184 offset:2048
	ds_read_b128 v[198:201], v184 offset:3072
	ds_read_b128 v[202:205], v184 offset:4096
	ds_read_b128 v[206:209], v184 offset:5120
	ds_read_b128 v[210:213], v184 offset:6144
	ds_read_b128 v[214:217], v184 offset:7168
	global_load_lds_dwordx4 v[178:179], off
	v_lshl_add_u64 v[178:179], s[0:1], 0, v[154:155]
	s_add_i32 m0, s33, 0xe000
	s_nop 0
	global_load_lds_dwordx4 v[178:179], off
	s_waitcnt vmcnt(8)
	s_waitcnt lgkmcnt(0)
	s_barrier
; #define PG8_STAGE(bufoff, gbase, voff) do { _Pragma("unroll") for (int _i = 0; _i < 2; ++_i) \
;         __builtin_amdgcn_global_load_lds((const unsigned*)((const char*)(gbase) + (voff)[_i]), (LAS unsigned*)(lds + (bufoff) + ldsw + _i * 8192), 16, 0, 0); } while (0)
; #define PG8_LDA(dst, b, h) do { _Pragma("unroll") for (int m = 0; m < 4; ++m) _Pragma("unroll") for (int k = 0; k < 2; ++k) dst[m][k] = *(const LAS bf16x8*)(lds + PG8_SA(b, h) + aoff + m * 2048 + k * 1024); } while (0)
; #define PG8_MMA(ai, bj, At, Bt) do { __builtin_amdgcn_s_setprio(1); _Pragma("unroll") for (int m = 0; m < 4; ++m) _Pragma("unroll") for (int n = 0; n < 2; ++n) _Pragma("unroll") for (int k = 0; k < 2; ++k) \
;         acc[ai][bj][m][n] = __builtin_amdgcn_mfma_f32_16x16x32_bf16(Bt[n][k], At[m][k], acc[ai][bj][m][n], 0, 0, 0); __builtin_amdgcn_s_setprio(0); } while (0)
; #define PG8_WAIT_V(n) asm volatile("s_waitcnt vmcnt(" #n ")" ::: "memory")
; #define PG8_WAIT_L(n) asm volatile("s_waitcnt lgkmcnt(" #n ")" ::: "memory")
; #define PG8_BAR __builtin_amdgcn_s_barrier()
; #define PG8_SCHED __builtin_amdgcn_sched_barrier(0)
; template <class Epi>
; __device__ __forceinline__ void gemm_phase(LAS unsigned char* lds, const Gemm g, const StaticOrder& S, const Epi& E) {
;     ...
;             PG8_WAIT_V(8); PG8_WAIT_L(0); PG8_BAR; PG8_MMA(0, 0, At, B0); PG8_MMA(0, 1, At, B1); PG8_BAR; PG8_SCHED;
;             PG8_LDA(At, 0, 1); PG8_STAGE(PG8_SB(0, 0), b2, voffB); PG8_STAGE(PG8_SB(0, 1), b2 + hstepB, voffB); PG8_STAGE(PG8_SA(0, 0), a2, voffA);
;             PG8_WAIT_V(8); PG8_WAIT_L(0); PG8_BAR; PG8_MMA(1, 0, At, B0); PG8_MMA(1, 1, At, B1); PG8_BAR; PG8_SCHED;
	s_setprio 1
	s_waitcnt lgkmcnt(0)
	v_mfma_f32_16x16x32_bf16 v[124:127], v[128:131], v[186:189], v[124:127]
	v_mfma_f32_16x16x32_bf16 v[120:123], v[136:139], v[186:189], v[120:123]
	v_mfma_f32_16x16x32_bf16 v[108:111], v[128:131], v[194:197], v[108:111]
	v_mfma_f32_16x16x32_bf16 v[104:107], v[136:139], v[194:197], v[104:107]
	v_mfma_f32_16x16x32_bf16 v[92:95], v[128:131], v[202:205], v[92:95]
	v_mfma_f32_16x16x32_bf16 v[88:91], v[136:139], v[202:205], v[88:91]
	v_mfma_f32_16x16x32_bf16 v[76:79], v[128:131], v[210:213], v[76:79]
	v_mfma_f32_16x16x32_bf16 v[72:75], v[136:139], v[210:213], v[72:75]
	v_mfma_f32_16x16x32_bf16 v[124:127], v[132:135], v[190:193], v[124:127]
	v_mfma_f32_16x16x32_bf16 v[120:123], v[140:143], v[190:193], v[120:123]
	v_mfma_f32_16x16x32_bf16 v[108:111], v[132:135], v[198:201], v[108:111]
	v_mfma_f32_16x16x32_bf16 v[104:107], v[140:143], v[198:201], v[104:107]
	v_mfma_f32_16x16x32_bf16 v[92:95], v[132:135], v[206:209], v[92:95]
	v_mfma_f32_16x16x32_bf16 v[88:91], v[140:143], v[206:209], v[88:91]
	v_mfma_f32_16x16x32_bf16 v[76:79], v[132:135], v[214:217], v[76:79]
	v_mfma_f32_16x16x32_bf16 v[72:75], v[140:143], v[214:217], v[72:75]
	s_setprio 0
	s_setprio 1
	v_mfma_f32_16x16x32_bf16 v[116:119], v[160:163], v[186:189], v[116:119]
	v_mfma_f32_16x16x32_bf16 v[112:115], v[168:171], v[186:189], v[112:115]
	v_mfma_f32_16x16x32_bf16 v[100:103], v[160:163], v[194:197], v[100:103]
	v_mfma_f32_16x16x32_bf16 v[96:99], v[168:171], v[194:197], v[96:99]
	v_mfma_f32_16x16x32_bf16 v[84:87], v[160:163], v[202:205], v[84:87]
	v_mfma_f32_16x16x32_bf16 v[80:83], v[168:171], v[202:205], v[80:83]
	v_mfma_f32_16x16x32_bf16 v[68:71], v[160:163], v[210:213], v[68:71]
	v_mfma_f32_16x16x32_bf16 v[64:67], v[168:171], v[210:213], v[64:67]
	v_mfma_f32_16x16x32_bf16 v[116:119], v[164:167], v[190:193], v[116:119]
	v_mfma_f32_16x16x32_bf16 v[112:115], v[172:175], v[190:193], v[112:115]
	v_mfma_f32_16x16x32_bf16 v[100:103], v[164:167], v[198:201], v[100:103]
	v_mfma_f32_16x16x32_bf16 v[96:99], v[172:175], v[198:201], v[96:99]
	v_mfma_f32_16x16x32_bf16 v[84:87], v[164:167], v[206:209], v[84:87]
	v_mfma_f32_16x16x32_bf16 v[80:83], v[172:175], v[206:209], v[80:83]
	v_mfma_f32_16x16x32_bf16 v[68:71], v[164:167], v[214:217], v[68:71]
	v_mfma_f32_16x16x32_bf16 v[64:67], v[172:175], v[214:217], v[64:67]
	s_setprio 0
	s_barrier
	s_add_i32 s64, s55, s29
	v_lshl_add_u64 v[178:179], s[20:21], 0, v[146:147]
	s_mov_b32 m0, s64
	ds_read_b128 v[186:189], v184 offset:16384
	ds_read_b128 v[190:193], v184 offset:17408
	ds_read_b128 v[194:197], v184 offset:18432
	ds_read_b128 v[198:201], v184 offset:19456
	ds_read_b128 v[202:205], v184 offset:20480
	ds_read_b128 v[206:209], v184 offset:21504
	ds_read_b128 v[210:213], v184 offset:22528
	ds_read_b128 v[214:217], v184 offset:23552
	global_load_lds_dwordx4 v[178:179], off
	s_add_i32 m0, s64, 0x2000
	s_add_u32 s64, s20, 0xb0000
	v_lshl_add_u64 v[218:219], s[20:21], 0, v[150:151]
	s_addc_u32 s65, s21, 0
	s_add_i32 s66, s56, s29
	global_load_lds_dwordx4 v[218:219], off
	v_lshl_add_u64 v[220:221], s[64:65], 0, v[146:147]
	s_mov_b32 m0, s66
	v_lshl_add_u64 v[222:223], s[22:23], 0, v[148:149]
	global_load_lds_dwordx4 v[220:221], off
	v_lshl_add_u64 v[220:221], s[64:65], 0, v[150:151]
	s_add_i32 m0, s66, 0x2000
	s_nop 0
	global_load_lds_dwordx4 v[220:221], off
	v_lshl_add_u64 v[220:221], s[22:23], 0, v[144:145]
	s_mov_b32 m0, s33
	s_nop 0
	global_load_lds_dwordx4 v[220:221], off
	s_mov_b32 m0, s34
	s_nop 0
	global_load_lds_dwordx4 v[222:223], off
	s_waitcnt vmcnt(8)
	s_waitcnt lgkmcnt(0)
	s_nop 0
	s_barrier
	s_setprio 1
	s_waitcnt lgkmcnt(0)
	v_mfma_f32_16x16x32_bf16 v[60:63], v[128:131], v[186:189], v[60:63]
	v_mfma_f32_16x16x32_bf16 v[56:59], v[136:139], v[186:189], v[56:59]
	v_mfma_f32_16x16x32_bf16 v[44:47], v[128:131], v[194:197], v[44:47]
	v_mfma_f32_16x16x32_bf16 v[40:43], v[136:139], v[194:197], v[40:43]
	v_mfma_f32_16x16x32_bf16 v[28:31], v[128:131], v[202:205], v[28:31]
	v_mfma_f32_16x16x32_bf16 v[24:27], v[136:139], v[202:205], v[24:27]
	v_mfma_f32_16x16x32_bf16 v[12:15], v[128:131], v[210:213], v[12:15]
	v_mfma_f32_16x16x32_bf16 v[8:11], v[136:139], v[210:213], v[8:11]
	v_mfma_f32_16x16x32_bf16 v[60:63], v[132:135], v[190:193], v[60:63]
	v_mfma_f32_16x16x32_bf16 v[56:59], v[140:143], v[190:193], v[56:59]
	v_mfma_f32_16x16x32_bf16 v[44:47], v[132:135], v[198:201], v[44:47]
	v_mfma_f32_16x16x32_bf16 v[40:43], v[140:143], v[198:201], v[40:43]
	v_mfma_f32_16x16x32_bf16 v[28:31], v[132:135], v[206:209], v[28:31]
	v_mfma_f32_16x16x32_bf16 v[24:27], v[140:143], v[206:209], v[24:27]
	v_mfma_f32_16x16x32_bf16 v[12:15], v[132:135], v[214:217], v[12:15]
	v_mfma_f32_16x16x32_bf16 v[8:11], v[140:143], v[214:217], v[8:11]
	s_setprio 0
	s_setprio 1
	v_mfma_f32_16x16x32_bf16 v[52:55], v[160:163], v[186:189], v[52:55]
	v_mfma_f32_16x16x32_bf16 v[48:51], v[168:171], v[186:189], v[48:51]
	v_mfma_f32_16x16x32_bf16 v[36:39], v[160:163], v[194:197], v[36:39]
	v_mfma_f32_16x16x32_bf16 v[32:35], v[168:171], v[194:197], v[32:35]
	v_mfma_f32_16x16x32_bf16 v[20:23], v[160:163], v[202:205], v[20:23]
	v_mfma_f32_16x16x32_bf16 v[16:19], v[168:171], v[202:205], v[16:19]
	v_mfma_f32_16x16x32_bf16 v[4:7], v[160:163], v[210:213], v[4:7]
	v_mfma_f32_16x16x32_bf16 v[0:3], v[168:171], v[210:213], v[0:3]
	v_mfma_f32_16x16x32_bf16 v[52:55], v[164:167], v[190:193], v[52:55]
	v_mfma_f32_16x16x32_bf16 v[48:51], v[172:175], v[190:193], v[48:51]
	v_mfma_f32_16x16x32_bf16 v[36:39], v[164:167], v[198:201], v[36:39]
	v_mfma_f32_16x16x32_bf16 v[32:35], v[172:175], v[198:201], v[32:35]
	v_mfma_f32_16x16x32_bf16 v[20:23], v[164:167], v[206:209], v[20:23]
	v_mfma_f32_16x16x32_bf16 v[16:19], v[172:175], v[206:209], v[16:19]
	v_mfma_f32_16x16x32_bf16 v[4:7], v[164:167], v[214:217], v[4:7]
	v_mfma_f32_16x16x32_bf16 v[0:3], v[172:175], v[214:217], v[0:3]
	s_setprio 0
	s_barrier
; #define PG8_STAGE(bufoff, gbase, voff) do { _Pragma("unroll") for (int _i = 0; _i < 2; ++_i) \
;         __builtin_amdgcn_global_load_lds((const unsigned*)((const char*)(gbase) + (voff)[_i]), (LAS unsigned*)(lds + (bufoff) + ldsw + _i * 8192), 16, 0, 0); } while (0)
; #define PG8_LDA(dst, b, h) do { _Pragma("unroll") for (int m = 0; m < 4; ++m) _Pragma("unroll") for (int k = 0; k < 2; ++k) dst[m][k] = *(const LAS bf16x8*)(lds + PG8_SA(b, h) + aoff + m * 2048 + k * 1024); } while (0)
; #define PG8_LDB(dst, b, h) do { _Pragma("unroll") for (int n = 0; n < 2; ++n) _Pragma("unroll") for (int k = 0; k < 2; ++k) dst[n][k] = *(const LAS bf16x8*)(lds + PG8_SB(b, h) + boff + n * 2048 + k * 1024); } while (0)
; #define PG8_MMA(ai, bj, At, Bt) do { __builtin_amdgcn_s_setprio(1); _Pragma("unroll") for (int m = 0; m < 4; ++m) _Pragma("unroll") for (int n = 0; n < 2; ++n) _Pragma("unroll") for (int k = 0; k < 2; ++k) \
;         acc[ai][bj][m][n] = __builtin_amdgcn_mfma_f32_16x16x32_bf16(Bt[n][k], At[m][k], acc[ai][bj][m][n], 0, 0, 0); __builtin_amdgcn_s_setprio(0); } while (0)
; #define PG8_WAIT_V(n) asm volatile("s_waitcnt vmcnt(" #n ")" ::: "memory")
; #define PG8_WAIT_L(n) asm volatile("s_waitcnt lgkmcnt(" #n ")" ::: "memory")
; #define PG8_BAR __builtin_amdgcn_s_barrier()
; #define PG8_SCHED __builtin_amdgcn_sched_barrier(0)
; template <class Epi>
; __device__ __forceinline__ void gemm_phase(LAS unsigned char* lds, const Gemm g, const StaticOrder& S, const Epi& E) {
;     ...
;             PG8_LDB(B0, 1, 0); PG8_LDB(B1, 1, 1); PG8_SCHED; PG8_LDA(At, 1, 0); PG8_STAGE(PG8_SA(0, 1), a2 + hstepA, voffA);
;             PG8_WAIT_V(8); PG8_WAIT_L(0); PG8_BAR; PG8_MMA(0, 0, At, B0); PG8_MMA(0, 1, At, B1); PG8_BAR; PG8_SCHED;
	s_add_i32 s64, 0, 0x18000
	s_add_i32 s65, 0, 0x1c000
	v_add_u32_e32 v140, s64, v181
	v_add_u32_e32 v172, s65, v181
	ds_read_b128 v[128:131], v140
	ds_read_b128 v[132:135], v140 offset:1024
	ds_read_b128 v[136:139], v140 offset:2048
	ds_read_b128 v[140:143], v140 offset:3072
	ds_read_b128 v[160:163], v172
	ds_read_b128 v[164:167], v172 offset:1024
	ds_read_b128 v[168:171], v172 offset:2048
	ds_read_b128 v[172:175], v172 offset:3072
	s_add_u32 s22, s22, 0xb0000
	s_addc_u32 s23, s23, 0
	s_mov_b32 m0, s35
	v_lshl_add_u64 v[224:225], s[22:23], 0, v[144:145]
	ds_read_b128 v[186:189], v184 offset:32768
	ds_read_b128 v[190:193], v184 offset:33792
	ds_read_b128 v[194:197], v184 offset:34816
	ds_read_b128 v[198:201], v184 offset:35840
	ds_read_b128 v[202:205], v184 offset:36864
	ds_read_b128 v[206:209], v184 offset:37888
	ds_read_b128 v[210:213], v184 offset:38912
	ds_read_b128 v[214:217], v184 offset:39936
	global_load_lds_dwordx4 v[224:225], off
	v_lshl_add_u64 v[224:225], s[22:23], 0, v[148:149]
	s_mov_b32 m0, s36
	s_nop 0
	global_load_lds_dwordx4 v[224:225], off
	s_waitcnt vmcnt(8)
	s_waitcnt lgkmcnt(0)
	s_nop 0
	s_barrier
	s_setprio 1
	s_waitcnt lgkmcnt(0)
	v_mfma_f32_16x16x32_bf16 v[124:127], v[128:131], v[186:189], v[124:127]
	v_mfma_f32_16x16x32_bf16 v[120:123], v[136:139], v[186:189], v[120:123]
	v_mfma_f32_16x16x32_bf16 v[108:111], v[128:131], v[194:197], v[108:111]
	v_mfma_f32_16x16x32_bf16 v[104:107], v[136:139], v[194:197], v[104:107]
	v_mfma_f32_16x16x32_bf16 v[92:95], v[128:131], v[202:205], v[92:95]
	v_mfma_f32_16x16x32_bf16 v[88:91], v[136:139], v[202:205], v[88:91]
	v_mfma_f32_16x16x32_bf16 v[76:79], v[128:131], v[210:213], v[76:79]
	v_mfma_f32_16x16x32_bf16 v[72:75], v[136:139], v[210:213], v[72:75]
	v_mfma_f32_16x16x32_bf16 v[124:127], v[132:135], v[190:193], v[124:127]
	v_mfma_f32_16x16x32_bf16 v[120:123], v[140:143], v[190:193], v[120:123]
	v_mfma_f32_16x16x32_bf16 v[108:111], v[132:135], v[198:201], v[108:111]
	v_mfma_f32_16x16x32_bf16 v[104:107], v[140:143], v[198:201], v[104:107]
	v_mfma_f32_16x16x32_bf16 v[92:95], v[132:135], v[206:209], v[92:95]
	v_mfma_f32_16x16x32_bf16 v[88:91], v[140:143], v[206:209], v[88:91]
	v_mfma_f32_16x16x32_bf16 v[76:79], v[132:135], v[214:217], v[76:79]
	v_mfma_f32_16x16x32_bf16 v[72:75], v[140:143], v[214:217], v[72:75]
	s_setprio 0
	s_setprio 1
	v_mfma_f32_16x16x32_bf16 v[116:119], v[160:163], v[186:189], v[116:119]
	v_mfma_f32_16x16x32_bf16 v[112:115], v[168:171], v[186:189], v[112:115]
	v_mfma_f32_16x16x32_bf16 v[100:103], v[160:163], v[194:197], v[100:103]
	v_mfma_f32_16x16x32_bf16 v[96:99], v[168:171], v[194:197], v[96:99]
	v_mfma_f32_16x16x32_bf16 v[84:87], v[160:163], v[202:205], v[84:87]
	v_mfma_f32_16x16x32_bf16 v[80:83], v[168:171], v[202:205], v[80:83]
	v_mfma_f32_16x16x32_bf16 v[68:71], v[160:163], v[210:213], v[68:71]
	v_mfma_f32_16x16x32_bf16 v[64:67], v[168:171], v[210:213], v[64:67]
	v_mfma_f32_16x16x32_bf16 v[116:119], v[164:167], v[190:193], v[116:119]
	v_mfma_f32_16x16x32_bf16 v[112:115], v[172:175], v[190:193], v[112:115]
	v_mfma_f32_16x16x32_bf16 v[100:103], v[164:167], v[198:201], v[100:103]
	v_mfma_f32_16x16x32_bf16 v[96:99], v[172:175], v[198:201], v[96:99]
	v_mfma_f32_16x16x32_bf16 v[84:87], v[164:167], v[206:209], v[84:87]
	v_mfma_f32_16x16x32_bf16 v[80:83], v[172:175], v[206:209], v[80:83]
	v_mfma_f32_16x16x32_bf16 v[68:71], v[164:167], v[214:217], v[68:71]
	v_mfma_f32_16x16x32_bf16 v[64:67], v[172:175], v[214:217], v[64:67]
	s_setprio 0
	s_barrier
; #define PG8_STAGE(bufoff, gbase, voff) do { _Pragma("unroll") for (int _i = 0; _i < 2; ++_i) \
;         __builtin_amdgcn_global_load_lds((const unsigned*)((const char*)(gbase) + (voff)[_i]), (LAS unsigned*)(lds + (bufoff) + ldsw + _i * 8192), 16, 0, 0); } while (0)
; #define PG8_LDA(dst, b, h) do { _Pragma("unroll") for (int m = 0; m < 4; ++m) _Pragma("unroll") for (int k = 0; k < 2; ++k) dst[m][k] = *(const LAS bf16x8*)(lds + PG8_SA(b, h) + aoff + m * 2048 + k * 1024); } while (0)
; #define PG8_MMA(ai, bj, At, Bt) do { __builtin_amdgcn_s_setprio(1); _Pragma("unroll") for (int m = 0; m < 4; ++m) _Pragma("unroll") for (int n = 0; n < 2; ++n) _Pragma("unroll") for (int k = 0; k < 2; ++k) \
;         acc[ai][bj][m][n] = __builtin_amdgcn_mfma_f32_16x16x32_bf16(Bt[n][k], At[m][k], acc[ai][bj][m][n], 0, 0, 0); __builtin_amdgcn_s_setprio(0); } while (0)
; #define PG8_WAIT_V(n) asm volatile("s_waitcnt vmcnt(" #n ")" ::: "memory")
; #define PG8_WAIT_L(n) asm volatile("s_waitcnt lgkmcnt(" #n ")" ::: "memory")
; #define PG8_BAR __builtin_amdgcn_s_barrier()
; #define PG8_SCHED __builtin_amdgcn_sched_barrier(0)
; template <class Epi>
; __device__ __forceinline__ void gemm_phase(LAS unsigned char* lds, const Gemm g, const StaticOrder& S, const Epi& E) {
;     ...
;             PG8_LDA(At, 1, 1); PG8_STAGE(PG8_SB(1, 0), b3, voffB); PG8_STAGE(PG8_SB(1, 1), b3 + hstepB, voffB); PG8_STAGE(PG8_SA(1, 0), a3, voffA);
;             PG8_WAIT_V(8); PG8_WAIT_L(0); PG8_BAR; PG8_MMA(1, 0, At, B0); PG8_MMA(1, 1, At, B1); PG8_BAR; PG8_SCHED;
;         }
;         if (wr == 0) PG8_BAR;
	s_add_i32 s22, s64, s29
	v_lshl_add_u64 v[178:179], v[178:179], 0, s[14:15]
	s_mov_b32 m0, s22
	ds_read_b128 v[186:189], v184 offset:49152
	ds_read_b128 v[190:193], v184 offset:50176
	ds_read_b128 v[194:197], v184 offset:51200
	ds_read_b128 v[198:201], v184 offset:52224
	ds_read_b128 v[202:205], v184 offset:53248
	ds_read_b128 v[206:209], v184 offset:54272
	ds_read_b128 v[210:213], v184 offset:55296
	ds_read_b128 v[214:217], v184 offset:56320
	global_load_lds_dwordx4 v[178:179], off
	s_add_i32 m0, s22, 0x2000
	s_add_u32 s20, s20, 0xb0080
	v_lshl_add_u64 v[178:179], v[218:219], 0, s[14:15]
	s_addc_u32 s21, s21, 0
	s_add_i32 s22, s65, s29
	global_load_lds_dwordx4 v[178:179], off
	v_lshl_add_u64 v[178:179], s[20:21], 0, v[146:147]
	s_mov_b32 m0, s22
	s_nop 0
	global_load_lds_dwordx4 v[178:179], off
	v_lshl_add_u64 v[178:179], s[20:21], 0, v[150:151]
	s_add_i32 m0, s22, 0x2000
	s_nop 0
	global_load_lds_dwordx4 v[178:179], off
	v_lshl_add_u64 v[178:179], v[220:221], 0, s[14:15]
	s_mov_b32 m0, s42
	s_nop 0
	global_load_lds_dwordx4 v[178:179], off
	v_lshl_add_u64 v[178:179], v[222:223], 0, s[14:15]
	s_mov_b32 m0, s43
	s_nop 0
	global_load_lds_dwordx4 v[178:179], off
	s_waitcnt vmcnt(8)
	s_waitcnt lgkmcnt(0)
	s_barrier
	s_setprio 1
	s_waitcnt lgkmcnt(0)
	v_mfma_f32_16x16x32_bf16 v[60:63], v[128:131], v[186:189], v[60:63]
	v_mfma_f32_16x16x32_bf16 v[56:59], v[136:139], v[186:189], v[56:59]
	v_mfma_f32_16x16x32_bf16 v[44:47], v[128:131], v[194:197], v[44:47]
	v_mfma_f32_16x16x32_bf16 v[40:43], v[136:139], v[194:197], v[40:43]
	v_mfma_f32_16x16x32_bf16 v[28:31], v[128:131], v[202:205], v[28:31]
	v_mfma_f32_16x16x32_bf16 v[24:27], v[136:139], v[202:205], v[24:27]
	v_mfma_f32_16x16x32_bf16 v[12:15], v[128:131], v[210:213], v[12:15]
	v_mfma_f32_16x16x32_bf16 v[8:11], v[136:139], v[210:213], v[8:11]
	v_mfma_f32_16x16x32_bf16 v[60:63], v[132:135], v[190:193], v[60:63]
	v_mfma_f32_16x16x32_bf16 v[56:59], v[140:143], v[190:193], v[56:59]
	v_mfma_f32_16x16x32_bf16 v[44:47], v[132:135], v[198:201], v[44:47]
	v_mfma_f32_16x16x32_bf16 v[40:43], v[140:143], v[198:201], v[40:43]
	v_mfma_f32_16x16x32_bf16 v[28:31], v[132:135], v[206:209], v[28:31]
	v_mfma_f32_16x16x32_bf16 v[24:27], v[140:143], v[206:209], v[24:27]
	v_mfma_f32_16x16x32_bf16 v[12:15], v[132:135], v[214:217], v[12:15]
	v_mfma_f32_16x16x32_bf16 v[8:11], v[140:143], v[214:217], v[8:11]
	s_setprio 0
	s_setprio 1
	v_mfma_f32_16x16x32_bf16 v[52:55], v[160:163], v[186:189], v[52:55]
	v_mfma_f32_16x16x32_bf16 v[48:51], v[168:171], v[186:189], v[48:51]
	v_mfma_f32_16x16x32_bf16 v[36:39], v[160:163], v[194:197], v[36:39]
	v_mfma_f32_16x16x32_bf16 v[32:35], v[168:171], v[194:197], v[32:35]
	v_mfma_f32_16x16x32_bf16 v[20:23], v[160:163], v[202:205], v[20:23]
	v_mfma_f32_16x16x32_bf16 v[16:19], v[168:171], v[202:205], v[16:19]
	v_mfma_f32_16x16x32_bf16 v[4:7], v[160:163], v[210:213], v[4:7]
	v_mfma_f32_16x16x32_bf16 v[0:3], v[168:171], v[210:213], v[0:3]
	v_mfma_f32_16x16x32_bf16 v[52:55], v[164:167], v[190:193], v[52:55]
	v_mfma_f32_16x16x32_bf16 v[48:51], v[172:175], v[190:193], v[48:51]
	v_mfma_f32_16x16x32_bf16 v[36:39], v[164:167], v[198:201], v[36:39]
	v_mfma_f32_16x16x32_bf16 v[32:35], v[172:175], v[198:201], v[32:35]
	v_mfma_f32_16x16x32_bf16 v[20:23], v[164:167], v[206:209], v[20:23]
	v_mfma_f32_16x16x32_bf16 v[16:19], v[172:175], v[206:209], v[16:19]
	v_mfma_f32_16x16x32_bf16 v[4:7], v[164:167], v[214:217], v[4:7]
	v_mfma_f32_16x16x32_bf16 v[0:3], v[172:175], v[214:217], v[0:3]
	s_setprio 0
	s_barrier
	s_add_i32 s63, s63, 2
	s_add_u32 s0, s0, 0x100
	s_addc_u32 s1, s1, 0
	s_add_u32 s61, s61, 0x100
	s_addc_u32 s62, s62, 0
	s_cmp_gt_u32 s63, 41
	s_cbranch_scc0 .LBB0_1649
	s_and_b64 vcc, exec, s[16:17]
	s_cbranch_vccz .LBB0_1652
	s_barrier

; #define PG8_STAGE(bufoff, gbase, voff) do { _Pragma("unroll") for (int _i = 0; _i < 2; ++_i) \
;         __builtin_amdgcn_global_load_lds((const unsigned*)((const char*)(gbase) + (voff)[_i]), (LAS unsigned*)(lds + (bufoff) + ldsw + _i * 8192), 16, 0, 0); } while (0)
; #define PG8_LDA(dst, b, h) do { _Pragma("unroll") for (int m = 0; m < 4; ++m) _Pragma("unroll") for (int k = 0; k < 2; ++k) dst[m][k] = *(const LAS bf16x8*)(lds + PG8_SA(b, h) + aoff + m * 2048 + k * 1024); } while (0)
; #define PG8_LDB(dst, b, h) do { _Pragma("unroll") for (int n = 0; n < 2; ++n) _Pragma("unroll") for (int k = 0; k < 2; ++k) dst[n][k] = *(const LAS bf16x8*)(lds + PG8_SB(b, h) + boff + n * 2048 + k * 1024); } while (0)
; #define PG8_MMA(ai, bj, At, Bt) do { __builtin_amdgcn_s_setprio(1); _Pragma("unroll") for (int m = 0; m < 4; ++m) _Pragma("unroll") for (int n = 0; n < 2; ++n) _Pragma("unroll") for (int k = 0; k < 2; ++k) \
;         acc[ai][bj][m][n] = __builtin_amdgcn_mfma_f32_16x16x32_bf16(Bt[n][k], At[m][k], acc[ai][bj][m][n], 0, 0, 0); __builtin_amdgcn_s_setprio(0); } while (0)
; #define PG8_BAR __builtin_amdgcn_s_barrier()
; template <class Epi>
; __device__ __forceinline__ void gemm_phase(LAS unsigned char* lds, const Gemm g, const StaticOrder& S, const Epi& E) {
;     ...
;         const bool has_next = S.next(ui + 1, nxt);
;         const char* nA = has_next ? (const char*)g.A + (size_t)nxt.pm * tstepA : cA; const char* nB = has_next ? (const char*)g.Bt + (size_t)nxt.pn * tstepB : cB;
; #pragma nounroll
;         for (int t = 0; t < nt; t += 2) {
;             const bool last = (t == nt - 2);
;             const char* a1 = cA + (size_t)(t + 1) * kstep;
;             const char* a2 = last ? nA : cA + (size_t)(t + 2) * kstep; const char* b2 = last ? nB : cB + (size_t)(t + 2) * kstep;
;             const char* a3 = a2 + kstep; const char* b3 = b2 + kstep;
;             PG8_LDB(B0, 0, 0); PG8_LDB(B1, 0, 1); PG8_SCHED; PG8_LDA(At, 0, 0); PG8_STAGE(PG8_SA(1, 1), a1 + hstepA, voffA);
;             PG8_WAIT_V(8); PG8_WAIT_L(0); PG8_BAR; PG8_MMA(0, 0, At, B0); PG8_MMA(0, 1, At, B1); PG8_BAR; PG8_SCHED;
;             PG8_LDA(At, 0, 1); PG8_STAGE(PG8_SB(0, 0), b2, voffB); PG8_STAGE(PG8_SB(0, 1), b2 + hstepB, voffB); PG8_STAGE(PG8_SA(0, 0), a2, voffA);
;             PG8_WAIT_V(8); PG8_WAIT_L(0); PG8_BAR; PG8_MMA(1, 0, At, B0); PG8_MMA(1, 1, At, B1); PG8_BAR; PG8_SCHED;
.LBB0_1745:
	s_ashr_i32 s35, s34, 31
	s_lshl_b64 s[36:37], s[34:35], 19
	s_add_u32 s36, s30, s36
	s_addc_u32 s37, s31, s37
	s_and_b64 s[38:39], s[4:5], exec
	s_cselect_b32 s7, s37, s43
	s_cselect_b32 s9, s36, s42
	s_ashr_i32 s29, s28, 31
	s_lshl_b64 s[38:39], s[28:29], 19
	s_add_u32 s38, s3, s38
	s_addc_u32 s39, s33, s39
	s_and_b64 s[44:45], s[4:5], exec
	s_cselect_b32 s29, s39, s53
	s_cselect_b32 s35, s38, s52
	s_add_u32 s42, s42, 0x40080
	s_addc_u32 s43, s43, 0
	s_add_u32 s69, s52, 0x100
	s_addc_u32 s70, s53, 0
	s_mov_b32 s71, -2
	s_waitcnt lgkmcnt(0)
	ds_read_b128 v[40:43], v208
	ds_read_b128 v[44:47], v208 offset:1024
	ds_read_b128 v[56:59], v208 offset:2048
	ds_read_b128 v[60:63], v208 offset:3072
	ds_read_b128 v[144:147], v209
	ds_read_b128 v[148:151], v209 offset:1024
	ds_read_b128 v[152:155], v209 offset:2048
	ds_read_b128 v[156:159], v209 offset:3072
	s_add_u32 s44, s42, 0xfffc0080
	s_addc_u32 s45, s43, -1
	s_cmp_eq_u32 s71, 12
	s_cselect_b32 s53, s7, s45
	s_cselect_b32 s52, s9, s44
	s_cselect_b32 s45, s29, s70
	s_cselect_b32 s44, s35, s69
	v_lshl_add_u64 v[218:219], s[42:43], 0, v[178:179]
	s_add_i32 m0, s55, 0xc000
	ds_read_b128 v[160:163], v210
	ds_read_b128 v[164:167], v210 offset:1024
	ds_read_b128 v[186:189], v210 offset:2048
	ds_read_b128 v[190:193], v210 offset:3072
	ds_read_b128 v[194:197], v210 offset:4096
	ds_read_b128 v[198:201], v210 offset:5120
	ds_read_b128 v[202:205], v210 offset:6144
	ds_read_b128 v[214:217], v210 offset:7168
	global_load_lds_dwordx4 v[218:219], off
	v_lshl_add_u64 v[218:219], s[42:43], 0, v[180:181]
	s_add_i32 m0, s55, 0xe000
	s_nop 0
	global_load_lds_dwordx4 v[218:219], off
	s_waitcnt vmcnt(8)
	s_waitcnt lgkmcnt(0)
	s_nop 0
	s_barrier
	s_setprio 1
	s_waitcnt lgkmcnt(0)
	v_mfma_f32_16x16x32_bf16 v[140:143], v[40:43], v[160:163], 0
	v_mfma_f32_16x16x32_bf16 v[136:139], v[56:59], v[160:163], 0
	v_mfma_f32_16x16x32_bf16 v[124:127], v[40:43], v[186:189], 0
	v_mfma_f32_16x16x32_bf16 v[120:123], v[56:59], v[186:189], 0
	v_mfma_f32_16x16x32_bf16 v[108:111], v[40:43], v[194:197], 0
	v_mfma_f32_16x16x32_bf16 v[104:107], v[56:59], v[194:197], 0
	v_mfma_f32_16x16x32_bf16 v[92:95], v[40:43], v[202:205], 0
	v_mfma_f32_16x16x32_bf16 v[88:91], v[56:59], v[202:205], 0
	v_mfma_f32_16x16x32_bf16 v[140:143], v[44:47], v[164:167], v[140:143]
	v_mfma_f32_16x16x32_bf16 v[136:139], v[60:63], v[164:167], v[136:139]
	v_mfma_f32_16x16x32_bf16 v[124:127], v[44:47], v[190:193], v[124:127]
	v_mfma_f32_16x16x32_bf16 v[120:123], v[60:63], v[190:193], v[120:123]
	v_mfma_f32_16x16x32_bf16 v[108:111], v[44:47], v[198:201], v[108:111]
	v_mfma_f32_16x16x32_bf16 v[104:107], v[60:63], v[198:201], v[104:107]
	v_mfma_f32_16x16x32_bf16 v[92:95], v[44:47], v[214:217], v[92:95]
	v_mfma_f32_16x16x32_bf16 v[88:91], v[60:63], v[214:217], v[88:91]
	s_setprio 0
	s_setprio 1
	v_mfma_f32_16x16x32_bf16 v[132:135], v[144:147], v[160:163], 0
	v_mfma_f32_16x16x32_bf16 v[128:131], v[152:155], v[160:163], 0
	v_mfma_f32_16x16x32_bf16 v[116:119], v[144:147], v[186:189], 0
	v_mfma_f32_16x16x32_bf16 v[112:115], v[152:155], v[186:189], 0
	v_mfma_f32_16x16x32_bf16 v[100:103], v[144:147], v[194:197], 0
	v_mfma_f32_16x16x32_bf16 v[96:99], v[152:155], v[194:197], 0
	v_mfma_f32_16x16x32_bf16 v[84:87], v[144:147], v[202:205], 0
	v_mfma_f32_16x16x32_bf16 v[80:83], v[152:155], v[202:205], 0
	v_mfma_f32_16x16x32_bf16 v[132:135], v[148:151], v[164:167], v[132:135]
	v_mfma_f32_16x16x32_bf16 v[128:131], v[156:159], v[164:167], v[128:131]
	v_mfma_f32_16x16x32_bf16 v[116:119], v[148:151], v[190:193], v[116:119]
	v_mfma_f32_16x16x32_bf16 v[112:115], v[156:159], v[190:193], v[112:115]
	v_mfma_f32_16x16x32_bf16 v[100:103], v[148:151], v[198:201], v[100:103]
	v_mfma_f32_16x16x32_bf16 v[96:99], v[156:159], v[198:201], v[96:99]
	v_mfma_f32_16x16x32_bf16 v[84:87], v[148:151], v[214:217], v[84:87]
	v_mfma_f32_16x16x32_bf16 v[80:83], v[156:159], v[214:217], v[80:83]
	s_setprio 0
	s_barrier
	s_add_i32 s72, s67, s54
	v_lshl_add_u64 v[218:219], s[44:45], 0, v[170:171]
	s_mov_b32 m0, s72
	ds_read_b128 v[160:163], v210 offset:16384
	ds_read_b128 v[164:167], v210 offset:17408
	ds_read_b128 v[186:189], v210 offset:18432
	ds_read_b128 v[190:193], v210 offset:19456
	ds_read_b128 v[194:197], v210 offset:20480
	ds_read_b128 v[198:201], v210 offset:21504
	ds_read_b128 v[202:205], v210 offset:22528
	ds_read_b128 v[214:217], v210 offset:23552
	global_load_lds_dwordx4 v[218:219], off
	s_add_i32 m0, s72, 0x2000
	s_add_u32 s72, s44, 0x40000
	v_lshl_add_u64 v[220:221], s[44:45], 0, v[174:175]
	s_addc_u32 s73, s45, 0
	s_add_i32 s74, s68, s54
	global_load_lds_dwordx4 v[220:221], off
	v_lshl_add_u64 v[222:223], s[72:73], 0, v[170:171]
	s_mov_b32 m0, s74
	v_lshl_add_u64 v[224:225], s[52:53], 0, v[172:173]
	global_load_lds_dwordx4 v[222:223], off
	v_lshl_add_u64 v[222:223], s[72:73], 0, v[174:175]
	s_add_i32 m0, s74, 0x2000
	s_nop 0
	global_load_lds_dwordx4 v[222:223], off
	v_lshl_add_u64 v[222:223], s[52:53], 0, v[168:169]
	s_mov_b32 m0, s55
	s_nop 0
	global_load_lds_dwordx4 v[222:223], off
	s_mov_b32 m0, s56
	s_nop 0
	global_load_lds_dwordx4 v[224:225], off
	s_waitcnt vmcnt(8)
	s_waitcnt lgkmcnt(0)
	s_nop 0
	s_barrier
; #define PG8_STAGE(bufoff, gbase, voff) do { _Pragma("unroll") for (int _i = 0; _i < 2; ++_i) \
;         __builtin_amdgcn_global_load_lds((const unsigned*)((const char*)(gbase) + (voff)[_i]), (LAS unsigned*)(lds + (bufoff) + ldsw + _i * 8192), 16, 0, 0); } while (0)
; #define PG8_LDA(dst, b, h) do { _Pragma("unroll") for (int m = 0; m < 4; ++m) _Pragma("unroll") for (int k = 0; k < 2; ++k) dst[m][k] = *(const LAS bf16x8*)(lds + PG8_SA(b, h) + aoff + m * 2048 + k * 1024); } while (0)
; #define PG8_LDB(dst, b, h) do { _Pragma("unroll") for (int n = 0; n < 2; ++n) _Pragma("unroll") for (int k = 0; k < 2; ++k) dst[n][k] = *(const LAS bf16x8*)(lds + PG8_SB(b, h) + boff + n * 2048 + k * 1024); } while (0)
; #define PG8_MMA(ai, bj, At, Bt) do { __builtin_amdgcn_s_setprio(1); _Pragma("unroll") for (int m = 0; m < 4; ++m) _Pragma("unroll") for (int n = 0; n < 2; ++n) _Pragma("unroll") for (int k = 0; k < 2; ++k) \
;         acc[ai][bj][m][n] = __builtin_amdgcn_mfma_f32_16x16x32_bf16(Bt[n][k], At[m][k], acc[ai][bj][m][n], 0, 0, 0); __builtin_amdgcn_s_setprio(0); } while (0)
; #define PG8_WAIT_V(n) asm volatile("s_waitcnt vmcnt(" #n ")" ::: "memory")
; #define PG8_WAIT_L(n) asm volatile("s_waitcnt lgkmcnt(" #n ")" ::: "memory")
; #define PG8_BAR __builtin_amdgcn_s_barrier()
; #define PG8_SCHED __builtin_amdgcn_sched_barrier(0)
; template <class Epi>
; __device__ __forceinline__ void gemm_phase(LAS unsigned char* lds, const Gemm g, const StaticOrder& S, const Epi& E) {
;     ...
;             PG8_WAIT_V(8); PG8_WAIT_L(0); PG8_BAR; PG8_MMA(1, 0, At, B0); PG8_MMA(1, 1, At, B1); PG8_BAR; PG8_SCHED;
;             PG8_LDB(B0, 1, 0); PG8_LDB(B1, 1, 1); PG8_SCHED; PG8_LDA(At, 1, 0); PG8_STAGE(PG8_SA(0, 1), a2 + hstepA, voffA);
;             PG8_WAIT_V(8); PG8_WAIT_L(0); PG8_BAR; PG8_MMA(0, 0, At, B0); PG8_MMA(0, 1, At, B1); PG8_BAR; PG8_SCHED;
	s_setprio 1
	s_waitcnt lgkmcnt(0)
	v_mfma_f32_16x16x32_bf16 v[76:79], v[40:43], v[160:163], 0
	v_mfma_f32_16x16x32_bf16 v[72:75], v[56:59], v[160:163], 0
	v_mfma_f32_16x16x32_bf16 v[52:55], v[40:43], v[186:189], 0
	v_mfma_f32_16x16x32_bf16 v[48:51], v[56:59], v[186:189], 0
	v_mfma_f32_16x16x32_bf16 v[28:31], v[40:43], v[194:197], 0
	v_mfma_f32_16x16x32_bf16 v[24:27], v[56:59], v[194:197], 0
	v_mfma_f32_16x16x32_bf16 v[12:15], v[40:43], v[202:205], 0
	v_mfma_f32_16x16x32_bf16 v[8:11], v[56:59], v[202:205], 0
	v_mfma_f32_16x16x32_bf16 v[76:79], v[44:47], v[164:167], v[76:79]
	v_mfma_f32_16x16x32_bf16 v[72:75], v[60:63], v[164:167], v[72:75]
	v_mfma_f32_16x16x32_bf16 v[52:55], v[44:47], v[190:193], v[52:55]
	v_mfma_f32_16x16x32_bf16 v[48:51], v[60:63], v[190:193], v[48:51]
	v_mfma_f32_16x16x32_bf16 v[28:31], v[44:47], v[198:201], v[28:31]
	v_mfma_f32_16x16x32_bf16 v[24:27], v[60:63], v[198:201], v[24:27]
	v_mfma_f32_16x16x32_bf16 v[12:15], v[44:47], v[214:217], v[12:15]
	v_mfma_f32_16x16x32_bf16 v[8:11], v[60:63], v[214:217], v[8:11]
	s_setprio 0
	s_setprio 1
	v_mfma_f32_16x16x32_bf16 v[36:39], v[144:147], v[186:189], 0
	v_mfma_f32_16x16x32_bf16 v[32:35], v[152:155], v[186:189], 0
	v_mfma_f32_16x16x32_bf16 v[20:23], v[144:147], v[194:197], 0
	v_mfma_f32_16x16x32_bf16 v[16:19], v[152:155], v[194:197], 0
	v_mfma_f32_16x16x32_bf16 v[4:7], v[144:147], v[202:205], 0
	v_mfma_f32_16x16x32_bf16 v[0:3], v[152:155], v[202:205], 0
	v_mfma_f32_16x16x32_bf16 v[40:43], v[144:147], v[160:163], 0
	v_mfma_f32_16x16x32_bf16 v[44:47], v[152:155], v[160:163], 0
	v_mfma_f32_16x16x32_bf16 v[36:39], v[148:151], v[190:193], v[36:39]
	v_mfma_f32_16x16x32_bf16 v[32:35], v[156:159], v[190:193], v[32:35]
	v_mfma_f32_16x16x32_bf16 v[20:23], v[148:151], v[198:201], v[20:23]
	v_mfma_f32_16x16x32_bf16 v[16:19], v[156:159], v[198:201], v[16:19]
	v_mfma_f32_16x16x32_bf16 v[4:7], v[148:151], v[214:217], v[4:7]
	v_mfma_f32_16x16x32_bf16 v[0:3], v[156:159], v[214:217], v[0:3]
	v_mfma_f32_16x16x32_bf16 v[40:43], v[148:151], v[164:167], v[40:43]
	v_mfma_f32_16x16x32_bf16 v[44:47], v[156:159], v[164:167], v[44:47]
	s_setprio 0
	s_barrier
	s_add_i32 s72, 0, 0x18000
	s_add_i32 s73, 0, 0x1c000
	v_add_u32_e32 v68, s72, v207
	v_add_u32_e32 v156, s73, v207
	ds_read_b128 v[56:59], v68
	ds_read_b128 v[60:63], v68 offset:1024
	ds_read_b128 v[64:67], v68 offset:2048
	ds_read_b128 v[68:71], v68 offset:3072
	ds_read_b128 v[144:147], v156
	ds_read_b128 v[148:151], v156 offset:1024
	ds_read_b128 v[152:155], v156 offset:2048
	ds_read_b128 v[156:159], v156 offset:3072
	s_add_u32 s52, s52, 0x40000
	s_addc_u32 s53, s53, 0
	s_mov_b32 m0, s57
	v_lshl_add_u64 v[226:227], s[52:53], 0, v[168:169]
	ds_read_b128 v[160:163], v210 offset:32768
	ds_read_b128 v[164:167], v210 offset:33792
	ds_read_b128 v[186:189], v210 offset:34816
	ds_read_b128 v[190:193], v210 offset:35840
	ds_read_b128 v[194:197], v210 offset:36864
	ds_read_b128 v[198:201], v210 offset:37888
	ds_read_b128 v[202:205], v210 offset:38912
	ds_read_b128 v[214:217], v210 offset:39936
	global_load_lds_dwordx4 v[226:227], off
	v_lshl_add_u64 v[226:227], s[52:53], 0, v[172:173]
	s_mov_b32 m0, s58
	s_nop 0
	global_load_lds_dwordx4 v[226:227], off
	s_waitcnt vmcnt(8)
	s_waitcnt lgkmcnt(0)
	s_nop 0
	s_barrier
	s_setprio 1
	s_waitcnt lgkmcnt(0)
	v_mfma_f32_16x16x32_bf16 v[140:143], v[56:59], v[160:163], v[140:143]
	v_mfma_f32_16x16x32_bf16 v[136:139], v[64:67], v[160:163], v[136:139]
	v_mfma_f32_16x16x32_bf16 v[124:127], v[56:59], v[186:189], v[124:127]
	v_mfma_f32_16x16x32_bf16 v[120:123], v[64:67], v[186:189], v[120:123]
	v_mfma_f32_16x16x32_bf16 v[108:111], v[56:59], v[194:197], v[108:111]
	v_mfma_f32_16x16x32_bf16 v[104:107], v[64:67], v[194:197], v[104:107]
	v_mfma_f32_16x16x32_bf16 v[92:95], v[56:59], v[202:205], v[92:95]
	v_mfma_f32_16x16x32_bf16 v[88:91], v[64:67], v[202:205], v[88:91]
	v_mfma_f32_16x16x32_bf16 v[140:143], v[60:63], v[164:167], v[140:143]
	v_mfma_f32_16x16x32_bf16 v[136:139], v[68:71], v[164:167], v[136:139]
	v_mfma_f32_16x16x32_bf16 v[124:127], v[60:63], v[190:193], v[124:127]
	v_mfma_f32_16x16x32_bf16 v[120:123], v[68:71], v[190:193], v[120:123]
	v_mfma_f32_16x16x32_bf16 v[108:111], v[60:63], v[198:201], v[108:111]
	v_mfma_f32_16x16x32_bf16 v[104:107], v[68:71], v[198:201], v[104:107]
	v_mfma_f32_16x16x32_bf16 v[92:95], v[60:63], v[214:217], v[92:95]
	v_mfma_f32_16x16x32_bf16 v[88:91], v[68:71], v[214:217], v[88:91]
	s_setprio 0
	s_setprio 1
	v_mfma_f32_16x16x32_bf16 v[132:135], v[144:147], v[160:163], v[132:135]
	v_mfma_f32_16x16x32_bf16 v[128:131], v[152:155], v[160:163], v[128:131]
	v_mfma_f32_16x16x32_bf16 v[116:119], v[144:147], v[186:189], v[116:119]
	v_mfma_f32_16x16x32_bf16 v[112:115], v[152:155], v[186:189], v[112:115]
	v_mfma_f32_16x16x32_bf16 v[100:103], v[144:147], v[194:197], v[100:103]
	v_mfma_f32_16x16x32_bf16 v[96:99], v[152:155], v[194:197], v[96:99]
	v_mfma_f32_16x16x32_bf16 v[84:87], v[144:147], v[202:205], v[84:87]
	v_mfma_f32_16x16x32_bf16 v[80:83], v[152:155], v[202:205], v[80:83]
	v_mfma_f32_16x16x32_bf16 v[132:135], v[148:151], v[164:167], v[132:135]
	v_mfma_f32_16x16x32_bf16 v[128:131], v[156:159], v[164:167], v[128:131]
	v_mfma_f32_16x16x32_bf16 v[116:119], v[148:151], v[190:193], v[116:119]
	v_mfma_f32_16x16x32_bf16 v[112:115], v[156:159], v[190:193], v[112:115]
	v_mfma_f32_16x16x32_bf16 v[100:103], v[148:151], v[198:201], v[100:103]
	v_mfma_f32_16x16x32_bf16 v[96:99], v[156:159], v[198:201], v[96:99]
	v_mfma_f32_16x16x32_bf16 v[84:87], v[148:151], v[214:217], v[84:87]
	v_mfma_f32_16x16x32_bf16 v[80:83], v[156:159], v[214:217], v[80:83]
	s_setprio 0
	s_barrier
; #define PG8_STAGE(bufoff, gbase, voff) do { _Pragma("unroll") for (int _i = 0; _i < 2; ++_i) \
;         __builtin_amdgcn_global_load_lds((const unsigned*)((const char*)(gbase) + (voff)[_i]), (LAS unsigned*)(lds + (bufoff) + ldsw + _i * 8192), 16, 0, 0); } while (0)
; #define PG8_LDA(dst, b, h) do { _Pragma("unroll") for (int m = 0; m < 4; ++m) _Pragma("unroll") for (int k = 0; k < 2; ++k) dst[m][k] = *(const LAS bf16x8*)(lds + PG8_SA(b, h) + aoff + m * 2048 + k * 1024); } while (0)
; #define PG8_LDB(dst, b, h) do { _Pragma("unroll") for (int n = 0; n < 2; ++n) _Pragma("unroll") for (int k = 0; k < 2; ++k) dst[n][k] = *(const LAS bf16x8*)(lds + PG8_SB(b, h) + boff + n * 2048 + k * 1024); } while (0)
; #define PG8_MMA(ai, bj, At, Bt) do { __builtin_amdgcn_s_setprio(1); _Pragma("unroll") for (int m = 0; m < 4; ++m) _Pragma("unroll") for (int n = 0; n < 2; ++n) _Pragma("unroll") for (int k = 0; k < 2; ++k) \
;         acc[ai][bj][m][n] = __builtin_amdgcn_mfma_f32_16x16x32_bf16(Bt[n][k], At[m][k], acc[ai][bj][m][n], 0, 0, 0); __builtin_amdgcn_s_setprio(0); } while (0)
; #define PG8_WAIT_V(n) asm volatile("s_waitcnt vmcnt(" #n ")" ::: "memory")
; #define PG8_WAIT_L(n) asm volatile("s_waitcnt lgkmcnt(" #n ")" ::: "memory")
; #define PG8_BAR __builtin_amdgcn_s_barrier()
; #define PG8_SCHED __builtin_amdgcn_sched_barrier(0)
; template <class Epi>
; __device__ __forceinline__ void gemm_phase(LAS unsigned char* lds, const Gemm g, const StaticOrder& S, const Epi& E) {
;     ...
;             PG8_LDB(B0, 0, 0); PG8_LDB(B1, 0, 1); PG8_SCHED; PG8_LDA(At, 0, 0); PG8_STAGE(PG8_SA(1, 1), a1 + hstepA, voffA);
;             PG8_WAIT_V(8); PG8_WAIT_L(0); PG8_BAR; PG8_MMA(0, 0, At, B0); PG8_MMA(0, 1, At, B1); PG8_BAR; PG8_SCHED;
;     ...
;             PG8_LDA(At, 1, 1); PG8_STAGE(PG8_SB(1, 0), b3, voffB); PG8_STAGE(PG8_SB(1, 1), b3 + hstepB, voffB); PG8_STAGE(PG8_SA(1, 0), a3, voffA);
;             PG8_WAIT_V(8); PG8_WAIT_L(0); PG8_BAR; PG8_MMA(1, 0, At, B0); PG8_MMA(1, 1, At, B1); PG8_BAR; PG8_SCHED;
	s_add_i32 s52, s72, s54
	v_lshl_add_u64 v[218:219], v[218:219], 0, s[20:21]
	s_mov_b32 m0, s52
	ds_read_b128 v[160:163], v210 offset:49152
	ds_read_b128 v[164:167], v210 offset:50176
	ds_read_b128 v[186:189], v210 offset:51200
	ds_read_b128 v[190:193], v210 offset:52224
	ds_read_b128 v[194:197], v210 offset:53248
	ds_read_b128 v[198:201], v210 offset:54272
	ds_read_b128 v[202:205], v210 offset:55296
	ds_read_b128 v[214:217], v210 offset:56320
	global_load_lds_dwordx4 v[218:219], off
	s_add_i32 m0, s52, 0x2000
	s_add_u32 s44, s44, 0x40080
	v_lshl_add_u64 v[218:219], v[220:221], 0, s[20:21]
	s_addc_u32 s45, s45, 0
	s_add_i32 s52, s73, s54
	global_load_lds_dwordx4 v[218:219], off
	v_lshl_add_u64 v[218:219], s[44:45], 0, v[170:171]
	s_mov_b32 m0, s52
	s_nop 0
	global_load_lds_dwordx4 v[218:219], off
	v_lshl_add_u64 v[218:219], s[44:45], 0, v[174:175]
	s_add_i32 m0, s52, 0x2000
	s_nop 0
	global_load_lds_dwordx4 v[218:219], off
	v_lshl_add_u64 v[218:219], v[222:223], 0, s[20:21]
	s_mov_b32 m0, s62
	s_nop 0
	global_load_lds_dwordx4 v[218:219], off
	v_lshl_add_u64 v[218:219], v[224:225], 0, s[20:21]
	s_mov_b32 m0, s63
	s_nop 0
	global_load_lds_dwordx4 v[218:219], off
	s_waitcnt vmcnt(8)
	s_waitcnt lgkmcnt(0)
	s_barrier
	s_setprio 1
	s_waitcnt lgkmcnt(0)
	v_mfma_f32_16x16x32_bf16 v[76:79], v[56:59], v[160:163], v[76:79]
	v_mfma_f32_16x16x32_bf16 v[72:75], v[64:67], v[160:163], v[72:75]
	v_mfma_f32_16x16x32_bf16 v[52:55], v[56:59], v[186:189], v[52:55]
	v_mfma_f32_16x16x32_bf16 v[48:51], v[64:67], v[186:189], v[48:51]
	v_mfma_f32_16x16x32_bf16 v[28:31], v[56:59], v[194:197], v[28:31]
	v_mfma_f32_16x16x32_bf16 v[24:27], v[64:67], v[194:197], v[24:27]
	v_mfma_f32_16x16x32_bf16 v[12:15], v[56:59], v[202:205], v[12:15]
	v_mfma_f32_16x16x32_bf16 v[8:11], v[64:67], v[202:205], v[8:11]
	v_mfma_f32_16x16x32_bf16 v[76:79], v[60:63], v[164:167], v[76:79]
	v_mfma_f32_16x16x32_bf16 v[72:75], v[68:71], v[164:167], v[72:75]
	v_mfma_f32_16x16x32_bf16 v[52:55], v[60:63], v[190:193], v[52:55]
	v_mfma_f32_16x16x32_bf16 v[48:51], v[68:71], v[190:193], v[48:51]
	v_mfma_f32_16x16x32_bf16 v[28:31], v[60:63], v[198:201], v[28:31]
	v_mfma_f32_16x16x32_bf16 v[24:27], v[68:71], v[198:201], v[24:27]
	v_mfma_f32_16x16x32_bf16 v[12:15], v[60:63], v[214:217], v[12:15]
	v_mfma_f32_16x16x32_bf16 v[8:11], v[68:71], v[214:217], v[8:11]
	s_setprio 0
	s_setprio 1
	v_mfma_f32_16x16x32_bf16 v[40:43], v[144:147], v[160:163], v[40:43]
	v_mfma_f32_16x16x32_bf16 v[68:71], v[148:151], v[164:167], v[40:43]
	v_mfma_f32_16x16x32_bf16 v[40:43], v[152:155], v[160:163], v[44:47]
	v_mfma_f32_16x16x32_bf16 v[36:39], v[144:147], v[186:189], v[36:39]
	v_mfma_f32_16x16x32_bf16 v[32:35], v[152:155], v[186:189], v[32:35]
	v_mfma_f32_16x16x32_bf16 v[20:23], v[144:147], v[194:197], v[20:23]
	v_mfma_f32_16x16x32_bf16 v[16:19], v[152:155], v[194:197], v[16:19]
	v_mfma_f32_16x16x32_bf16 v[4:7], v[144:147], v[202:205], v[4:7]
	v_mfma_f32_16x16x32_bf16 v[0:3], v[152:155], v[202:205], v[0:3]
	v_mfma_f32_16x16x32_bf16 v[64:67], v[156:159], v[164:167], v[40:43]
	v_mfma_f32_16x16x32_bf16 v[36:39], v[148:151], v[190:193], v[36:39]
	v_mfma_f32_16x16x32_bf16 v[32:35], v[156:159], v[190:193], v[32:35]
	v_mfma_f32_16x16x32_bf16 v[20:23], v[148:151], v[198:201], v[20:23]
	v_mfma_f32_16x16x32_bf16 v[16:19], v[156:159], v[198:201], v[16:19]
	v_mfma_f32_16x16x32_bf16 v[4:7], v[148:151], v[214:217], v[4:7]
	v_mfma_f32_16x16x32_bf16 v[0:3], v[156:159], v[214:217], v[0:3]
	s_setprio 0
	s_barrier
	s_add_i32 s71, s71, 2
	s_add_u32 s42, s42, 0x100
	s_addc_u32 s43, s43, 0
	s_add_u32 s69, s69, 0x100
	s_addc_u32 s70, s70, 0
	s_cmp_gt_u32 s71, 13
.LBB0_1746:
	ds_read_b128 v[40:43], v208
	ds_read_b128 v[44:47], v208 offset:1024
	ds_read_b128 v[56:59], v208 offset:2048
	ds_read_b128 v[60:63], v208 offset:3072
	ds_read_b128 v[144:147], v209
	ds_read_b128 v[148:151], v209 offset:1024
	ds_read_b128 v[152:155], v209 offset:2048
	ds_read_b128 v[156:159], v209 offset:3072
	s_add_u32 s44, s42, 0xfffc0080
	s_addc_u32 s45, s43, -1
	s_cmp_eq_u32 s71, 12
	s_cselect_b32 s53, s7, s45
	s_cselect_b32 s52, s9, s44
	s_cselect_b32 s45, s29, s70
	s_cselect_b32 s44, s35, s69
	v_lshl_add_u64 v[218:219], s[42:43], 0, v[178:179]
	s_add_i32 m0, s55, 0xc000
	ds_read_b128 v[160:163], v210
	ds_read_b128 v[164:167], v210 offset:1024
	ds_read_b128 v[186:189], v210 offset:2048
	ds_read_b128 v[190:193], v210 offset:3072
	ds_read_b128 v[194:197], v210 offset:4096
	ds_read_b128 v[198:201], v210 offset:5120
	ds_read_b128 v[202:205], v210 offset:6144
	ds_read_b128 v[214:217], v210 offset:7168
	global_load_lds_dwordx4 v[218:219], off
	v_lshl_add_u64 v[218:219], s[42:43], 0, v[180:181]
	s_add_i32 m0, s55, 0xe000
	s_nop 0
	global_load_lds_dwordx4 v[218:219], off
	s_waitcnt vmcnt(8)
	s_waitcnt lgkmcnt(0)
	s_barrier
; #define PG8_STAGE(bufoff, gbase, voff) do { _Pragma("unroll") for (int _i = 0; _i < 2; ++_i) \
;         __builtin_amdgcn_global_load_lds((const unsigned*)((const char*)(gbase) + (voff)[_i]), (LAS unsigned*)(lds + (bufoff) + ldsw + _i * 8192), 16, 0, 0); } while (0)
; #define PG8_LDA(dst, b, h) do { _Pragma("unroll") for (int m = 0; m < 4; ++m) _Pragma("unroll") for (int k = 0; k < 2; ++k) dst[m][k] = *(const LAS bf16x8*)(lds + PG8_SA(b, h) + aoff + m * 2048 + k * 1024); } while (0)
; #define PG8_MMA(ai, bj, At, Bt) do { __builtin_amdgcn_s_setprio(1); _Pragma("unroll") for (int m = 0; m < 4; ++m) _Pragma("unroll") for (int n = 0; n < 2; ++n) _Pragma("unroll") for (int k = 0; k < 2; ++k) \
;         acc[ai][bj][m][n] = __builtin_amdgcn_mfma_f32_16x16x32_bf16(Bt[n][k], At[m][k], acc[ai][bj][m][n], 0, 0, 0); __builtin_amdgcn_s_setprio(0); } while (0)
; #define PG8_WAIT_V(n) asm volatile("s_waitcnt vmcnt(" #n ")" ::: "memory")
; #define PG8_WAIT_L(n) asm volatile("s_waitcnt lgkmcnt(" #n ")" ::: "memory")
; #define PG8_BAR __builtin_amdgcn_s_barrier()
; #define PG8_SCHED __builtin_amdgcn_sched_barrier(0)
; template <class Epi>
; __device__ __forceinline__ void gemm_phase(LAS unsigned char* lds, const Gemm g, const StaticOrder& S, const Epi& E) {
;     ...
;             PG8_WAIT_V(8); PG8_WAIT_L(0); PG8_BAR; PG8_MMA(0, 0, At, B0); PG8_MMA(0, 1, At, B1); PG8_BAR; PG8_SCHED;
;             PG8_LDA(At, 0, 1); PG8_STAGE(PG8_SB(0, 0), b2, voffB); PG8_STAGE(PG8_SB(0, 1), b2 + hstepB, voffB); PG8_STAGE(PG8_SA(0, 0), a2, voffA);
;             PG8_WAIT_V(8); PG8_WAIT_L(0); PG8_BAR; PG8_MMA(1, 0, At, B0); PG8_MMA(1, 1, At, B1); PG8_BAR; PG8_SCHED;
	s_setprio 1
	s_waitcnt lgkmcnt(0)
	v_mfma_f32_16x16x32_bf16 v[140:143], v[40:43], v[160:163], v[140:143]
	v_mfma_f32_16x16x32_bf16 v[136:139], v[56:59], v[160:163], v[136:139]
	v_mfma_f32_16x16x32_bf16 v[124:127], v[40:43], v[186:189], v[124:127]
	v_mfma_f32_16x16x32_bf16 v[120:123], v[56:59], v[186:189], v[120:123]
	v_mfma_f32_16x16x32_bf16 v[108:111], v[40:43], v[194:197], v[108:111]
	v_mfma_f32_16x16x32_bf16 v[104:107], v[56:59], v[194:197], v[104:107]
	v_mfma_f32_16x16x32_bf16 v[92:95], v[40:43], v[202:205], v[92:95]
	v_mfma_f32_16x16x32_bf16 v[88:91], v[56:59], v[202:205], v[88:91]
	v_mfma_f32_16x16x32_bf16 v[140:143], v[44:47], v[164:167], v[140:143]
	v_mfma_f32_16x16x32_bf16 v[136:139], v[60:63], v[164:167], v[136:139]
	v_mfma_f32_16x16x32_bf16 v[124:127], v[44:47], v[190:193], v[124:127]
	v_mfma_f32_16x16x32_bf16 v[120:123], v[60:63], v[190:193], v[120:123]
	v_mfma_f32_16x16x32_bf16 v[108:111], v[44:47], v[198:201], v[108:111]
	v_mfma_f32_16x16x32_bf16 v[104:107], v[60:63], v[198:201], v[104:107]
	v_mfma_f32_16x16x32_bf16 v[92:95], v[44:47], v[214:217], v[92:95]
	v_mfma_f32_16x16x32_bf16 v[88:91], v[60:63], v[214:217], v[88:91]
	s_setprio 0
	s_setprio 1
	v_mfma_f32_16x16x32_bf16 v[132:135], v[144:147], v[160:163], v[132:135]
	v_mfma_f32_16x16x32_bf16 v[128:131], v[152:155], v[160:163], v[128:131]
	v_mfma_f32_16x16x32_bf16 v[116:119], v[144:147], v[186:189], v[116:119]
	v_mfma_f32_16x16x32_bf16 v[112:115], v[152:155], v[186:189], v[112:115]
	v_mfma_f32_16x16x32_bf16 v[100:103], v[144:147], v[194:197], v[100:103]
	v_mfma_f32_16x16x32_bf16 v[96:99], v[152:155], v[194:197], v[96:99]
	v_mfma_f32_16x16x32_bf16 v[84:87], v[144:147], v[202:205], v[84:87]
	v_mfma_f32_16x16x32_bf16 v[80:83], v[152:155], v[202:205], v[80:83]
	v_mfma_f32_16x16x32_bf16 v[132:135], v[148:151], v[164:167], v[132:135]
	v_mfma_f32_16x16x32_bf16 v[128:131], v[156:159], v[164:167], v[128:131]
	v_mfma_f32_16x16x32_bf16 v[116:119], v[148:151], v[190:193], v[116:119]
	v_mfma_f32_16x16x32_bf16 v[112:115], v[156:159], v[190:193], v[112:115]
	v_mfma_f32_16x16x32_bf16 v[100:103], v[148:151], v[198:201], v[100:103]
	v_mfma_f32_16x16x32_bf16 v[96:99], v[156:159], v[198:201], v[96:99]
	v_mfma_f32_16x16x32_bf16 v[84:87], v[148:151], v[214:217], v[84:87]
	v_mfma_f32_16x16x32_bf16 v[80:83], v[156:159], v[214:217], v[80:83]
	s_setprio 0
	s_barrier
	s_add_i32 s72, s67, s54
	v_lshl_add_u64 v[218:219], s[44:45], 0, v[170:171]
	s_mov_b32 m0, s72
	ds_read_b128 v[160:163], v210 offset:16384
	ds_read_b128 v[164:167], v210 offset:17408
	ds_read_b128 v[186:189], v210 offset:18432
	ds_read_b128 v[190:193], v210 offset:19456
	ds_read_b128 v[194:197], v210 offset:20480
	ds_read_b128 v[198:201], v210 offset:21504
	ds_read_b128 v[202:205], v210 offset:22528
	ds_read_b128 v[214:217], v210 offset:23552
	global_load_lds_dwordx4 v[218:219], off
	s_add_i32 m0, s72, 0x2000
	s_add_u32 s72, s44, 0x40000
	v_lshl_add_u64 v[220:221], s[44:45], 0, v[174:175]
	s_addc_u32 s73, s45, 0
	s_add_i32 s74, s68, s54
	global_load_lds_dwordx4 v[220:221], off
	v_lshl_add_u64 v[222:223], s[72:73], 0, v[170:171]
	s_mov_b32 m0, s74
	v_lshl_add_u64 v[224:225], s[52:53], 0, v[172:173]
	global_load_lds_dwordx4 v[222:223], off
	v_lshl_add_u64 v[222:223], s[72:73], 0, v[174:175]
	s_add_i32 m0, s74, 0x2000
	s_nop 0
	global_load_lds_dwordx4 v[222:223], off
	v_lshl_add_u64 v[222:223], s[52:53], 0, v[168:169]
	s_mov_b32 m0, s55
	s_nop 0
	global_load_lds_dwordx4 v[222:223], off
	s_mov_b32 m0, s56
	s_nop 0
	global_load_lds_dwordx4 v[224:225], off
	s_waitcnt vmcnt(8)
	s_waitcnt lgkmcnt(0)
	s_nop 0
	s_barrier
	s_setprio 1
	s_waitcnt lgkmcnt(0)
	v_mfma_f32_16x16x32_bf16 v[76:79], v[40:43], v[160:163], v[76:79]
	v_mfma_f32_16x16x32_bf16 v[72:75], v[56:59], v[160:163], v[72:75]
	v_mfma_f32_16x16x32_bf16 v[52:55], v[40:43], v[186:189], v[52:55]
	v_mfma_f32_16x16x32_bf16 v[48:51], v[56:59], v[186:189], v[48:51]
	v_mfma_f32_16x16x32_bf16 v[28:31], v[40:43], v[194:197], v[28:31]
	v_mfma_f32_16x16x32_bf16 v[24:27], v[56:59], v[194:197], v[24:27]
	v_mfma_f32_16x16x32_bf16 v[12:15], v[40:43], v[202:205], v[12:15]
	v_mfma_f32_16x16x32_bf16 v[8:11], v[56:59], v[202:205], v[8:11]
	v_mfma_f32_16x16x32_bf16 v[76:79], v[44:47], v[164:167], v[76:79]
	v_mfma_f32_16x16x32_bf16 v[72:75], v[60:63], v[164:167], v[72:75]
	v_mfma_f32_16x16x32_bf16 v[52:55], v[44:47], v[190:193], v[52:55]
	v_mfma_f32_16x16x32_bf16 v[48:51], v[60:63], v[190:193], v[48:51]
	v_mfma_f32_16x16x32_bf16 v[28:31], v[44:47], v[198:201], v[28:31]
	v_mfma_f32_16x16x32_bf16 v[24:27], v[60:63], v[198:201], v[24:27]
	v_mfma_f32_16x16x32_bf16 v[12:15], v[44:47], v[214:217], v[12:15]
	v_mfma_f32_16x16x32_bf16 v[8:11], v[60:63], v[214:217], v[8:11]
	s_setprio 0
	s_setprio 1
	v_mfma_f32_16x16x32_bf16 v[36:39], v[144:147], v[186:189], v[36:39]
	v_mfma_f32_16x16x32_bf16 v[32:35], v[152:155], v[186:189], v[32:35]
	v_mfma_f32_16x16x32_bf16 v[20:23], v[144:147], v[194:197], v[20:23]
	v_mfma_f32_16x16x32_bf16 v[16:19], v[152:155], v[194:197], v[16:19]
	v_mfma_f32_16x16x32_bf16 v[4:7], v[144:147], v[202:205], v[4:7]
	v_mfma_f32_16x16x32_bf16 v[0:3], v[152:155], v[202:205], v[0:3]
	v_mfma_f32_16x16x32_bf16 v[40:43], v[144:147], v[160:163], v[68:71]
	v_mfma_f32_16x16x32_bf16 v[44:47], v[152:155], v[160:163], v[64:67]
	v_mfma_f32_16x16x32_bf16 v[36:39], v[148:151], v[190:193], v[36:39]
	v_mfma_f32_16x16x32_bf16 v[32:35], v[156:159], v[190:193], v[32:35]
	v_mfma_f32_16x16x32_bf16 v[20:23], v[148:151], v[198:201], v[20:23]
	v_mfma_f32_16x16x32_bf16 v[16:19], v[156:159], v[198:201], v[16:19]
	v_mfma_f32_16x16x32_bf16 v[4:7], v[148:151], v[214:217], v[4:7]
	v_mfma_f32_16x16x32_bf16 v[0:3], v[156:159], v[214:217], v[0:3]
	v_mfma_f32_16x16x32_bf16 v[40:43], v[148:151], v[164:167], v[40:43]
	v_mfma_f32_16x16x32_bf16 v[44:47], v[156:159], v[164:167], v[44:47]
	s_setprio 0
	s_barrier
; #define PG8_STAGE(bufoff, gbase, voff) do { _Pragma("unroll") for (int _i = 0; _i < 2; ++_i) \
;         __builtin_amdgcn_global_load_lds((const unsigned*)((const char*)(gbase) + (voff)[_i]), (LAS unsigned*)(lds + (bufoff) + ldsw + _i * 8192), 16, 0, 0); } while (0)
; #define PG8_LDA(dst, b, h) do { _Pragma("unroll") for (int m = 0; m < 4; ++m) _Pragma("unroll") for (int k = 0; k < 2; ++k) dst[m][k] = *(const LAS bf16x8*)(lds + PG8_SA(b, h) + aoff + m * 2048 + k * 1024); } while (0)
; #define PG8_LDB(dst, b, h) do { _Pragma("unroll") for (int n = 0; n < 2; ++n) _Pragma("unroll") for (int k = 0; k < 2; ++k) dst[n][k] = *(const LAS bf16x8*)(lds + PG8_SB(b, h) + boff + n * 2048 + k * 1024); } while (0)
; #define PG8_MMA(ai, bj, At, Bt) do { __builtin_amdgcn_s_setprio(1); _Pragma("unroll") for (int m = 0; m < 4; ++m) _Pragma("unroll") for (int n = 0; n < 2; ++n) _Pragma("unroll") for (int k = 0; k < 2; ++k) \
;         acc[ai][bj][m][n] = __builtin_amdgcn_mfma_f32_16x16x32_bf16(Bt[n][k], At[m][k], acc[ai][bj][m][n], 0, 0, 0); __builtin_amdgcn_s_setprio(0); } while (0)
; #define PG8_WAIT_V(n) asm volatile("s_waitcnt vmcnt(" #n ")" ::: "memory")
; #define PG8_WAIT_L(n) asm volatile("s_waitcnt lgkmcnt(" #n ")" ::: "memory")
; #define PG8_BAR __builtin_amdgcn_s_barrier()
; #define PG8_SCHED __builtin_amdgcn_sched_barrier(0)
; template <class Epi>
; __device__ __forceinline__ void gemm_phase(LAS unsigned char* lds, const Gemm g, const StaticOrder& S, const Epi& E) {
;     ...
;             PG8_LDB(B0, 1, 0); PG8_LDB(B1, 1, 1); PG8_SCHED; PG8_LDA(At, 1, 0); PG8_STAGE(PG8_SA(0, 1), a2 + hstepA, voffA);
;             PG8_WAIT_V(8); PG8_WAIT_L(0); PG8_BAR; PG8_MMA(0, 0, At, B0); PG8_MMA(0, 1, At, B1); PG8_BAR; PG8_SCHED;
	s_add_i32 s72, 0, 0x18000
	s_add_i32 s73, 0, 0x1c000
	v_add_u32_e32 v68, s72, v207
	v_add_u32_e32 v156, s73, v207
	ds_read_b128 v[56:59], v68
	ds_read_b128 v[60:63], v68 offset:1024
	ds_read_b128 v[64:67], v68 offset:2048
	ds_read_b128 v[68:71], v68 offset:3072
	ds_read_b128 v[144:147], v156
	ds_read_b128 v[148:151], v156 offset:1024
	ds_read_b128 v[152:155], v156 offset:2048
	ds_read_b128 v[156:159], v156 offset:3072
	s_add_u32 s52, s52, 0x40000
	s_addc_u32 s53, s53, 0
	s_mov_b32 m0, s57
	v_lshl_add_u64 v[226:227], s[52:53], 0, v[168:169]
	ds_read_b128 v[160:163], v210 offset:32768
	ds_read_b128 v[164:167], v210 offset:33792
	ds_read_b128 v[186:189], v210 offset:34816
	ds_read_b128 v[190:193], v210 offset:35840
	ds_read_b128 v[194:197], v210 offset:36864
	ds_read_b128 v[198:201], v210 offset:37888
	ds_read_b128 v[202:205], v210 offset:38912
	ds_read_b128 v[214:217], v210 offset:39936
	global_load_lds_dwordx4 v[226:227], off
	v_lshl_add_u64 v[226:227], s[52:53], 0, v[172:173]
	s_mov_b32 m0, s58
	s_nop 0
	global_load_lds_dwordx4 v[226:227], off
	s_waitcnt vmcnt(8)
	s_waitcnt lgkmcnt(0)
	s_nop 0
	s_barrier
	s_setprio 1
	s_waitcnt lgkmcnt(0)
	v_mfma_f32_16x16x32_bf16 v[140:143], v[56:59], v[160:163], v[140:143]
	v_mfma_f32_16x16x32_bf16 v[136:139], v[64:67], v[160:163], v[136:139]
	v_mfma_f32_16x16x32_bf16 v[124:127], v[56:59], v[186:189], v[124:127]
	v_mfma_f32_16x16x32_bf16 v[120:123], v[64:67], v[186:189], v[120:123]
	v_mfma_f32_16x16x32_bf16 v[108:111], v[56:59], v[194:197], v[108:111]
	v_mfma_f32_16x16x32_bf16 v[104:107], v[64:67], v[194:197], v[104:107]
	v_mfma_f32_16x16x32_bf16 v[92:95], v[56:59], v[202:205], v[92:95]
	v_mfma_f32_16x16x32_bf16 v[88:91], v[64:67], v[202:205], v[88:91]
	v_mfma_f32_16x16x32_bf16 v[140:143], v[60:63], v[164:167], v[140:143]
	v_mfma_f32_16x16x32_bf16 v[136:139], v[68:71], v[164:167], v[136:139]
	v_mfma_f32_16x16x32_bf16 v[124:127], v[60:63], v[190:193], v[124:127]
	v_mfma_f32_16x16x32_bf16 v[120:123], v[68:71], v[190:193], v[120:123]
	v_mfma_f32_16x16x32_bf16 v[108:111], v[60:63], v[198:201], v[108:111]
	v_mfma_f32_16x16x32_bf16 v[104:107], v[68:71], v[198:201], v[104:107]
	v_mfma_f32_16x16x32_bf16 v[92:95], v[60:63], v[214:217], v[92:95]
	v_mfma_f32_16x16x32_bf16 v[88:91], v[68:71], v[214:217], v[88:91]
	s_setprio 0
	s_setprio 1
	v_mfma_f32_16x16x32_bf16 v[132:135], v[144:147], v[160:163], v[132:135]
	v_mfma_f32_16x16x32_bf16 v[128:131], v[152:155], v[160:163], v[128:131]
	v_mfma_f32_16x16x32_bf16 v[116:119], v[144:147], v[186:189], v[116:119]
	v_mfma_f32_16x16x32_bf16 v[112:115], v[152:155], v[186:189], v[112:115]
	v_mfma_f32_16x16x32_bf16 v[100:103], v[144:147], v[194:197], v[100:103]
	v_mfma_f32_16x16x32_bf16 v[96:99], v[152:155], v[194:197], v[96:99]
	v_mfma_f32_16x16x32_bf16 v[84:87], v[144:147], v[202:205], v[84:87]
	v_mfma_f32_16x16x32_bf16 v[80:83], v[152:155], v[202:205], v[80:83]
	v_mfma_f32_16x16x32_bf16 v[132:135], v[148:151], v[164:167], v[132:135]
	v_mfma_f32_16x16x32_bf16 v[128:131], v[156:159], v[164:167], v[128:131]
	v_mfma_f32_16x16x32_bf16 v[116:119], v[148:151], v[190:193], v[116:119]
	v_mfma_f32_16x16x32_bf16 v[112:115], v[156:159], v[190:193], v[112:115]
	v_mfma_f32_16x16x32_bf16 v[100:103], v[148:151], v[198:201], v[100:103]
	v_mfma_f32_16x16x32_bf16 v[96:99], v[156:159], v[198:201], v[96:99]
	v_mfma_f32_16x16x32_bf16 v[84:87], v[148:151], v[214:217], v[84:87]
	v_mfma_f32_16x16x32_bf16 v[80:83], v[156:159], v[214:217], v[80:83]
	s_setprio 0
	s_barrier
; #define PG8_STAGE(bufoff, gbase, voff) do { _Pragma("unroll") for (int _i = 0; _i < 2; ++_i) \
;         __builtin_amdgcn_global_load_lds((const unsigned*)((const char*)(gbase) + (voff)[_i]), (LAS unsigned*)(lds + (bufoff) + ldsw + _i * 8192), 16, 0, 0); } while (0)
; #define PG8_LDA(dst, b, h) do { _Pragma("unroll") for (int m = 0; m < 4; ++m) _Pragma("unroll") for (int k = 0; k < 2; ++k) dst[m][k] = *(const LAS bf16x8*)(lds + PG8_SA(b, h) + aoff + m * 2048 + k * 1024); } while (0)
; #define PG8_MMA(ai, bj, At, Bt) do { __builtin_amdgcn_s_setprio(1); _Pragma("unroll") for (int m = 0; m < 4; ++m) _Pragma("unroll") for (int n = 0; n < 2; ++n) _Pragma("unroll") for (int k = 0; k < 2; ++k) \
;         acc[ai][bj][m][n] = __builtin_amdgcn_mfma_f32_16x16x32_bf16(Bt[n][k], At[m][k], acc[ai][bj][m][n], 0, 0, 0); __builtin_amdgcn_s_setprio(0); } while (0)
; #define PG8_WAIT_V(n) asm volatile("s_waitcnt vmcnt(" #n ")" ::: "memory")
; #define PG8_WAIT_L(n) asm volatile("s_waitcnt lgkmcnt(" #n ")" ::: "memory")
; #define PG8_BAR __builtin_amdgcn_s_barrier()
; #define PG8_SCHED __builtin_amdgcn_sched_barrier(0)
; template <class Epi>
; __device__ __forceinline__ void gemm_phase(LAS unsigned char* lds, const Gemm g, const StaticOrder& S, const Epi& E) {
;     ...
;             PG8_LDA(At, 1, 1); PG8_STAGE(PG8_SB(1, 0), b3, voffB); PG8_STAGE(PG8_SB(1, 1), b3 + hstepB, voffB); PG8_STAGE(PG8_SA(1, 0), a3, voffA);
;             PG8_WAIT_V(8); PG8_WAIT_L(0); PG8_BAR; PG8_MMA(1, 0, At, B0); PG8_MMA(1, 1, At, B1); PG8_BAR; PG8_SCHED;
;         }
;         if (wr == 0) PG8_BAR;
	s_add_i32 s52, s72, s54
	v_lshl_add_u64 v[218:219], v[218:219], 0, s[20:21]
	s_mov_b32 m0, s52
	ds_read_b128 v[160:163], v210 offset:49152
	ds_read_b128 v[164:167], v210 offset:50176
	ds_read_b128 v[186:189], v210 offset:51200
	ds_read_b128 v[190:193], v210 offset:52224
	ds_read_b128 v[194:197], v210 offset:53248
	ds_read_b128 v[198:201], v210 offset:54272
	ds_read_b128 v[202:205], v210 offset:55296
	ds_read_b128 v[214:217], v210 offset:56320
	global_load_lds_dwordx4 v[218:219], off
	s_add_i32 m0, s52, 0x2000
	s_add_u32 s44, s44, 0x40080
	v_lshl_add_u64 v[218:219], v[220:221], 0, s[20:21]
	s_addc_u32 s45, s45, 0
	s_add_i32 s52, s73, s54
	global_load_lds_dwordx4 v[218:219], off
	v_lshl_add_u64 v[218:219], s[44:45], 0, v[170:171]
	s_mov_b32 m0, s52
	s_nop 0
	global_load_lds_dwordx4 v[218:219], off
	v_lshl_add_u64 v[218:219], s[44:45], 0, v[174:175]
	s_add_i32 m0, s52, 0x2000
	s_nop 0
	global_load_lds_dwordx4 v[218:219], off
	v_lshl_add_u64 v[218:219], v[222:223], 0, s[20:21]
	s_mov_b32 m0, s62
	s_nop 0
	global_load_lds_dwordx4 v[218:219], off
	v_lshl_add_u64 v[218:219], v[224:225], 0, s[20:21]
	s_mov_b32 m0, s63
	s_nop 0
	global_load_lds_dwordx4 v[218:219], off
	s_waitcnt vmcnt(8)
	s_waitcnt lgkmcnt(0)
	s_barrier
	s_setprio 1
	s_waitcnt lgkmcnt(0)
	v_mfma_f32_16x16x32_bf16 v[76:79], v[56:59], v[160:163], v[76:79]
	v_mfma_f32_16x16x32_bf16 v[72:75], v[64:67], v[160:163], v[72:75]
	v_mfma_f32_16x16x32_bf16 v[52:55], v[56:59], v[186:189], v[52:55]
	v_mfma_f32_16x16x32_bf16 v[48:51], v[64:67], v[186:189], v[48:51]
	v_mfma_f32_16x16x32_bf16 v[28:31], v[56:59], v[194:197], v[28:31]
	v_mfma_f32_16x16x32_bf16 v[24:27], v[64:67], v[194:197], v[24:27]
	v_mfma_f32_16x16x32_bf16 v[12:15], v[56:59], v[202:205], v[12:15]
	v_mfma_f32_16x16x32_bf16 v[8:11], v[64:67], v[202:205], v[8:11]
	v_mfma_f32_16x16x32_bf16 v[76:79], v[60:63], v[164:167], v[76:79]
	v_mfma_f32_16x16x32_bf16 v[72:75], v[68:71], v[164:167], v[72:75]
	v_mfma_f32_16x16x32_bf16 v[52:55], v[60:63], v[190:193], v[52:55]
	v_mfma_f32_16x16x32_bf16 v[48:51], v[68:71], v[190:193], v[48:51]
	v_mfma_f32_16x16x32_bf16 v[28:31], v[60:63], v[198:201], v[28:31]
	v_mfma_f32_16x16x32_bf16 v[24:27], v[68:71], v[198:201], v[24:27]
	v_mfma_f32_16x16x32_bf16 v[12:15], v[60:63], v[214:217], v[12:15]
	v_mfma_f32_16x16x32_bf16 v[8:11], v[68:71], v[214:217], v[8:11]
	s_setprio 0
	s_setprio 1
	v_mfma_f32_16x16x32_bf16 v[40:43], v[144:147], v[160:163], v[40:43]
	v_mfma_f32_16x16x32_bf16 v[68:71], v[148:151], v[164:167], v[40:43]
	v_mfma_f32_16x16x32_bf16 v[40:43], v[152:155], v[160:163], v[44:47]
	v_mfma_f32_16x16x32_bf16 v[36:39], v[144:147], v[186:189], v[36:39]
	v_mfma_f32_16x16x32_bf16 v[32:35], v[152:155], v[186:189], v[32:35]
	v_mfma_f32_16x16x32_bf16 v[20:23], v[144:147], v[194:197], v[20:23]
	v_mfma_f32_16x16x32_bf16 v[16:19], v[152:155], v[194:197], v[16:19]
	v_mfma_f32_16x16x32_bf16 v[4:7], v[144:147], v[202:205], v[4:7]
	v_mfma_f32_16x16x32_bf16 v[0:3], v[152:155], v[202:205], v[0:3]
	v_mfma_f32_16x16x32_bf16 v[64:67], v[156:159], v[164:167], v[40:43]
	v_mfma_f32_16x16x32_bf16 v[36:39], v[148:151], v[190:193], v[36:39]
	v_mfma_f32_16x16x32_bf16 v[32:35], v[156:159], v[190:193], v[32:35]
	v_mfma_f32_16x16x32_bf16 v[20:23], v[148:151], v[198:201], v[20:23]
	v_mfma_f32_16x16x32_bf16 v[16:19], v[156:159], v[198:201], v[16:19]
	v_mfma_f32_16x16x32_bf16 v[4:7], v[148:151], v[214:217], v[4:7]
	v_mfma_f32_16x16x32_bf16 v[0:3], v[156:159], v[214:217], v[0:3]
	s_setprio 0
	s_barrier
	s_add_i32 s71, s71, 2
	s_add_u32 s42, s42, 0x100
	s_addc_u32 s43, s43, 0
	s_add_u32 s69, s69, 0x100
	s_addc_u32 s70, s70, 0
	s_cmp_gt_u32 s71, 13
	s_cbranch_scc0 .LBB0_1746
	s_and_b64 vcc, exec, s[22:23]
	s_cbranch_vccz .LBB0_1749
	s_barrier
